# v36 + L1-bypass (nt) loads of the read-once f32 residual rows and row statistics in the residual epilogues
# baseline (speedup 1.0000x reference)
; __device__ __forceinline__ float xsum16(float v) { const auto r = __builtin_amdgcn_permlane16_swap(__float_as_uint(v), __float_as_uint(v), false, false); return __uint_as_float(r[0]) + __uint_as_float(r[1]); }
; __device__ __forceinline__ float xsum32(float v) { const auto r = __builtin_amdgcn_permlane32_swap(__float_as_uint(v), __float_as_uint(v), false, false); return __uint_as_float(r[0]) + __uint_as_float(r[1]); }
; __device__ __forceinline__ void row_stats4(const float* st, int rowb, int fq, float (&mu)[4], float (&rs)[4]) {
;     ...
;     for (int m = 0; m < 4; ++m) { const f32x4* p = (const f32x4*)(st + (size_t)(rowb + m * 16) * 32 + fq * 8); a[m] = p[0]; b[m] = p[1]; }
; #pragma unroll
;     for (int m = 0; m < 4; ++m) { float s1 = (a[m][0] + a[m][2]) + (b[m][0] + b[m][2]), s2 = (a[m][1] + a[m][3]) + (b[m][1] + b[m][3]);
;         s1 = xsum32(xsum16(s1)); s2 = xsum32(xsum16(s2));
;         const float mm = s1 * (1.0f / 1024.0f); mu[m] = mm; rs[m] = rsqrtf(fmaxf(s2 * (1.0f / 1024.0f) - mm * mm, 0.f) + LN_EPS_); }
;     __device__ __forceinline__ void operator()(const f32x4 (&acc)[2][2][4][2], const pg8::Unit& u, int wr, int wc, int fr, int fq) const {
;     ...
;         for (int ai = 0; ai < 2; ++ai) { float mu4[4], rs4[4]; row_stats4(stp, row0 + ai * 128, fq, mu4, rs4);
; #pragma unroll
;             for (int m = 0; m < 4; ++m) { const int row = row0 + ai * 128 + m * 16; const float mu = mu4[m], rs = rs4[m];
;                 f32x4 yv[2][2], gq[2][2], bq_[2][2];
; #pragma unroll
;                 for (int bj = 0; bj < 2; ++bj)
; #pragma unroll
;                     for (int n = 0; n < 2; ++n) { yv[bj][n] = *(const f32x4*)(Yin + (size_t)row * D_ + col0 + bj * 128 + 4 * n); gq[bj][n] = *(const f32x4*)(g + col0 + bj * 128 + 4 * n); bq_[bj][n] = *(const f32x4*)(b + col0 + bj * 128 + 4 * n); }
;                 asm volatile("" ::: "memory");
;                 float s1 = 0.f, s2 = 0.f;
; #pragma unroll
;                 for (int bj = 0; bj < 2; ++bj) { float* yp = Y + (size_t)row * D_ + col0 + bj * 128; f32x4 v[2];
; #pragma unroll
;                     for (int n = 0; n < 2; ++n) { v[n] = (((yv[bj][n] - mu) * rs) * gq[bj][n] + bq_[bj][n]) * ALPHA_ + acc[ai][bj][m][n] * sc;
;                         *(f32x4*)(yp + 4 * n) = v[n]; s1 += (v[n][0] + v[n][1]) + (v[n][2] + v[n][3]); s2 += (v[n][0] * v[n][0] + v[n][1] * v[n][1]) + (v[n][2] * v[n][2] + v[n][3] * v[n][3]); }
.LBB0_372:
	s_lshl_b32 s3, s3, 8
	s_add_i32 s3, s3, s53
	v_or_b32_e32 v158, s3, v182
	v_ashrrev_i32_e32 v159, 31, v158
	v_lshlrev_b64 v[130:131], 7, v[158:159]
	v_lshl_add_u64 v[136:137], v[146:147], 0, v[130:131]
	v_or_b32_e32 v180, 16, v158
	global_load_dwordx4 v[132:135], v[136:137], off nt
	global_load_dwordx4 v[166:169], v[136:137], off offset:16 nt
	v_ashrrev_i32_e32 v181, 31, v180
	v_lshlrev_b64 v[172:173], 7, v[180:181]
	v_lshl_add_u64 v[136:137], v[146:147], 0, v[172:173]
	global_load_dwordx4 v[174:177], v[136:137], off nt
	global_load_dwordx4 v[186:189], v[136:137], off offset:16 nt
	v_or_b32_e32 v170, 32, v158
	v_ashrrev_i32_e32 v171, 31, v170
	v_lshlrev_b64 v[164:165], 7, v[170:171]
	v_lshl_add_u64 v[136:137], v[146:147], 0, v[164:165]
	global_load_dwordx4 v[190:193], v[136:137], off nt
	global_load_dwordx4 v[196:199], v[136:137], off offset:16 nt
	v_or_b32_e32 v162, 48, v158
	v_ashrrev_i32_e32 v163, 31, v162
	v_lshlrev_b64 v[160:161], 7, v[162:163]
	v_lshl_add_u64 v[204:205], v[146:147], 0, v[160:161]
	global_load_dwordx4 v[200:203], v[204:205], off nt
	s_nop 0
	global_load_dwordx4 v[204:207], v[204:205], off offset:16 nt
	s_lshl_b32 s16, s2, 8
	s_lshl_b32 s17, s2, 3
	s_or_b32 s2, s16, s54
	v_or_b32_e32 v152, s2, v183
	v_ashrrev_i32_e32 v153, 31, v152
	v_lshlrev_b64 v[136:137], 12, v[158:159]
	v_lshlrev_b64 v[152:153], 2, v[152:153]
	v_lshl_add_u64 v[178:179], s[12:13], 0, v[136:137]
	v_lshl_add_u64 v[178:179], v[178:179], 0, v[152:153]
	v_lshl_add_u64 v[154:155], s[8:9], 0, v[152:153]
	v_lshl_add_u64 v[156:157], s[10:11], 0, v[152:153]
	global_load_dwordx4 v[208:211], v[178:179], off offset:16 nt
	global_load_dwordx4 v[212:215], v[178:179], off nt
	global_load_dwordx4 v[216:219], v[154:155], off offset:16
	global_load_dwordx4 v[220:223], v[154:155], off
	global_load_dwordx4 v[234:237], v[156:157], off offset:16
	global_load_dwordx4 v[238:241], v[156:157], off
	s_mov_b32 s16, 0x3a800000
	s_mov_b32 s18, 0x3fd744fd
	s_load_dwordx16 s[60:75], s[34:35], 0x38
	s_or_b32 s24, s17, s57
	v_bitop3_b32 v194, s2, 56, v183 bitop3:0xc8
	s_ashr_i32 s40, s2, 6
	s_ashr_i32 s25, s24, 31
	s_waitcnt lgkmcnt(0)
	v_lshl_add_u64 v[136:137], s[74:75], 0, v[136:137]
	v_lshl_add_u64 v[136:137], v[136:137], 0, v[152:153]
	s_ashr_i32 s41, s40, 31
	s_waitcnt vmcnt(0)
	v_mov_b32_e32 v224, v132
	v_mov_b32_e32 v225, v166
	v_mov_b32_e32 v228, v134
	v_mov_b32_e32 v229, v168
	v_mov_b32_e32 v166, v133
	v_mov_b32_e32 v168, v135
	v_pk_add_f32 v[132:133], v[224:225], v[228:229]
	v_pk_add_f32 v[134:135], v[166:167], v[168:169]
	v_pk_add_f32 v[132:133], v[132:133], v[132:133] op_sel:[0,1] op_sel_hi:[1,0]
	v_pk_add_f32 v[134:135], v[134:135], v[134:135] op_sel:[0,1] op_sel_hi:[1,0]
	v_mov_b32_e32 v166, v174
	v_mov_b32_e32 v167, v186
	v_mov_b32_e32 v168, v176
	v_mov_b32_e32 v169, v188
	v_mov_b32_e32 v0, v132
	v_mov_b32_e32 v133, v134
	v_pk_add_f32 v[166:167], v[166:167], v[168:169]
	v_permlane16_swap_b32_e32 v132, v0
	v_permlane16_swap_b32_e32 v134, v133
	v_mov_b32_e32 v186, v175
	v_mov_b32_e32 v188, v177
	v_pk_add_f32 v[166:167], v[166:167], v[166:167] op_sel:[0,1] op_sel_hi:[1,0]
	v_add_f32_e32 v177, v132, v0
	v_add_f32_e32 v176, v134, v133
	v_pk_add_f32 v[168:169], v[186:187], v[188:189]
	v_mov_b32_e32 v135, v166
	v_mov_b32_e32 v187, v177
	v_mov_b32_e32 v186, v176
	v_permlane16_swap_b32_e32 v166, v135
	v_permlane32_swap_b32_e32 v177, v187
	v_permlane32_swap_b32_e32 v176, v186
	v_add_f32_e32 v133, v166, v135
	v_pk_add_f32 v[166:167], v[176:177], v[186:187]
	v_pk_add_f32 v[168:169], v[168:169], v[168:169] op_sel:[0,1] op_sel_hi:[1,0]
	v_pk_mul_f32 v[224:225], v[166:167], s[16:17] op_sel_hi:[1,0]
	v_mov_b32_e32 v159, v168
	v_fma_f32 v0, -v225, v225, v224
	v_max_f32_e32 v0, 0, v0
	v_permlane16_swap_b32_e32 v168, v159
	v_add_f32_e32 v0, 0x3727c5ac, v0
	s_mov_b32 s16, 0x800000
	v_add_f32_e32 v132, v168, v159
	v_mul_f32_e32 v159, 0x4b800000, v0
	v_cmp_gt_f32_e32 vcc, s16, v0
	v_mov_b32_e32 v174, v190
	v_mov_b32_e32 v175, v196
	v_cndmask_b32_e32 v0, v0, v159, vcc
	v_rsq_f32_e32 v0, v0
	v_mov_b32_e32 v166, v192
	v_mov_b32_e32 v167, v198
	v_pk_add_f32 v[166:167], v[174:175], v[166:167]
	v_mul_f32_e32 v159, 0x45800000, v0
	v_pk_add_f32 v[166:167], v[166:167], v[166:167] op_sel:[0,1] op_sel_hi:[1,0]
	v_mov_b32_e32 v196, v191
	v_mov_b32_e32 v198, v193
	v_cndmask_b32_e32 v0, v0, v159, vcc
	v_pk_add_f32 v[168:169], v[196:197], v[198:199]
	v_mov_b32_e32 v159, v166
	v_pk_add_f32 v[168:169], v[168:169], v[168:169] op_sel:[0,1] op_sel_hi:[1,0]
	s_nop 0
	v_permlane16_swap_b32_e32 v166, v159
	v_add_f32_e32 v175, v166, v159
	v_mov_b32_e32 v159, v168
	s_nop 1
	v_permlane16_swap_b32_e32 v168, v159
	global_load_dwordx4 v[186:189], v[178:179], off offset:528 nt
	global_load_dwordx4 v[190:193], v[178:179], off offset:512 nt
	v_add_f32_e32 v174, v168, v159
	v_mov_b32_e32 v166, v200
	v_mov_b32_e32 v167, v204
	v_mov_b32_e32 v168, v202
	v_mov_b32_e32 v169, v206
	v_mov_b32_e32 v204, v201
	v_mov_b32_e32 v206, v203
	v_pk_add_f32 v[166:167], v[166:167], v[168:169]
	v_pk_add_f32 v[168:169], v[204:205], v[206:207]
	global_load_dwordx4 v[196:199], v[154:155], off offset:528
	global_load_dwordx4 v[200:203], v[154:155], off offset:512
	global_load_dwordx4 v[204:207], v[156:157], off offset:528
	global_load_dwordx4 v[242:245], v[156:157], off offset:512
	v_sub_f32_e32 v179, v215, v225
	v_sub_f32_e32 v178, v214, v225
	v_sub_f32_e32 v213, v213, v225
	v_sub_f32_e32 v212, v212, v225
	v_pk_mul_f32 v[212:213], v[0:1], v[212:213] op_sel_hi:[0,1]
	v_pk_mul_f32 v[178:179], v[0:1], v[178:179] op_sel_hi:[0,1]
	v_pk_fma_f32 v[178:179], v[222:223], v[178:179], v[240:241]
	v_pk_fma_f32 v[212:213], v[220:221], v[212:213], v[238:239]
; __device__ __forceinline__ size_t blk_off(int r, int c, int K) { return (size_t)(r >> 8) * 256 * K + (size_t)(c >> 6) * (256 * 64) + (size_t)((r & 255) * 64 + (c & 63)); }
; __device__ __forceinline__ u32x4 pack8(const f32x4 a, const f32x4 b) { u32x4 w; w.x = cvt_pk_bf16(a[0], a[1]); w.y = cvt_pk_bf16(a[2], a[3]); w.z = cvt_pk_bf16(b[0], b[1]); w.w = cvt_pk_bf16(b[2], b[3]); return w; }
;     __device__ __forceinline__ void operator()(const f32x4 (&acc)[2][2][4][2], const pg8::Unit& u, int wr, int wc, int fr, int fq) const {
;     ...
;                     for (int n = 0; n < 2; ++n) { yv[bj][n] = *(const f32x4*)(Yin + (size_t)row * D_ + col0 + bj * 128 + 4 * n); gq[bj][n] = *(const f32x4*)(g + col0 + bj * 128 + 4 * n); bq_[bj][n] = *(const f32x4*)(b + col0 + bj * 128 + 4 * n); }
;                 asm volatile("" ::: "memory");
;                 float s1 = 0.f, s2 = 0.f;
; #pragma unroll
;                 for (int bj = 0; bj < 2; ++bj) { float* yp = Y + (size_t)row * D_ + col0 + bj * 128; f32x4 v[2];
; #pragma unroll
;                     for (int n = 0; n < 2; ++n) { v[n] = (((yv[bj][n] - mu) * rs) * gq[bj][n] + bq_[bj][n]) * ALPHA_ + acc[ai][bj][m][n] * sc;
;                         *(f32x4*)(yp + 4 * n) = v[n]; s1 += (v[n][0] + v[n][1]) + (v[n][2] + v[n][3]); s2 += (v[n][0] * v[n][0] + v[n][1] * v[n][1]) + (v[n][2] * v[n][2] + v[n][3] * v[n][3]); }
;                     *(u32x4*)(Yb + blk_off(row, col0 + bj * 128, D_)) = pack8(v[0], v[1]); }
	v_pk_mul_f32 v[178:179], v[178:179], s[18:19] op_sel_hi:[1,0]
	v_pk_mul_f32 v[212:213], v[212:213], s[18:19] op_sel_hi:[1,0]
	v_pk_fma_f32 v[128:129], v[128:129], 0.5, v[178:179] op_sel_hi:[1,0,1]
	v_pk_fma_f32 v[126:127], v[126:127], 0.5, v[212:213] op_sel_hi:[1,0,1]
	v_add_f32_e32 v179, v128, v129
	v_add_f32_e32 v178, v126, v127
	v_add_f32_e32 v178, v178, v179
	v_add_f32_e32 v195, 0, v178
	v_mul_f32_e32 v178, v127, v127
	v_mul_f32_e32 v179, v129, v129
	v_fmac_f32_e32 v178, v126, v126
	v_fmac_f32_e32 v179, v128, v128
	v_add_f32_e32 v212, v178, v179
	v_sub_f32_e32 v179, v211, v225
	v_sub_f32_e32 v178, v210, v225
	v_sub_f32_e32 v209, v209, v225
	v_sub_f32_e32 v208, v208, v225
	v_pk_mul_f32 v[208:209], v[0:1], v[208:209] op_sel_hi:[0,1]
	v_pk_mul_f32 v[178:179], v[0:1], v[178:179] op_sel_hi:[0,1]
	v_pk_fma_f32 v[178:179], v[218:219], v[178:179], v[236:237]
	v_pk_fma_f32 v[208:209], v[216:217], v[208:209], v[234:235]
	v_pk_mul_f32 v[178:179], v[178:179], s[18:19] op_sel_hi:[1,0]
	v_pk_mul_f32 v[208:209], v[208:209], s[18:19] op_sel_hi:[1,0]
	v_pk_add_f32 v[166:167], v[166:167], v[166:167] op_sel:[0,1] op_sel_hi:[1,0]
	v_pk_fma_f32 v[124:125], v[124:125], 0.5, v[178:179] op_sel_hi:[1,0,1]
	v_pk_fma_f32 v[122:123], v[122:123], 0.5, v[208:209] op_sel_hi:[1,0,1]
	v_mov_b32_e32 v159, v166
	v_add_f32_e32 v178, v122, v123
	v_add_f32_e32 v179, v124, v125
	v_pk_add_f32 v[168:169], v[168:169], v[168:169] op_sel:[0,1] op_sel_hi:[1,0]
	v_permlane16_swap_b32_e32 v166, v159
	v_add_f32_e32 v178, v178, v179
	v_add_f32_e32 v167, v166, v159
	v_mov_b32_e32 v159, v168
	v_add_f32_e32 v178, v195, v178
	v_mul_f32_e32 v179, v123, v123
	v_mul_f32_e32 v195, v125, v125
	v_permlane16_swap_b32_e32 v168, v159
	s_ashr_i32 s16, s3, 8
	s_nop 0
	s_nop 1
	v_bfe_u32 v135, v227, 4, 2
	v_sub_u32_e32 v134, 0, v135
	v_lshlrev_b32_e32 v134, 4, v134
	v_ashrrev_i32_e32 v135, 31, v134
	v_lshl_add_u64 v[134:135], v[136:137], 0, v[134:135]
	v_permlane16_swap_b32_e32 v126, v122
	v_permlane16_swap_b32_e32 v127, v123
	v_permlane16_swap_b32_e32 v128, v124
	v_permlane16_swap_b32_e32 v129, v125
	v_permlane32_swap_b32_e32 v126, v122
	v_permlane32_swap_b32_e32 v127, v123
	v_permlane32_swap_b32_e32 v128, v124
	v_permlane32_swap_b32_e32 v129, v125
	global_store_dwordx4 v[134:135], v[126:129], off
	global_store_dwordx4 v[134:135], v[122:125], off offset:64
	s_nop 1
	v_permlane32_swap_b32_e32 v126, v122
	v_permlane32_swap_b32_e32 v127, v123
	v_permlane32_swap_b32_e32 v128, v124
	v_permlane32_swap_b32_e32 v129, v125
	v_permlane16_swap_b32_e32 v126, v122
	v_permlane16_swap_b32_e32 v127, v123
	v_permlane16_swap_b32_e32 v128, v124
	v_permlane16_swap_b32_e32 v129, v125
	v_fmac_f32_e32 v179, v122, v122
	v_fmac_f32_e32 v195, v124, v124
	v_cvt_pk_bf16_f32 v126, v126, v127
	v_cvt_pk_bf16_f32 v127, v128, v129
	v_cvt_pk_bf16_f32 v128, v122, v123
	v_cvt_pk_bf16_f32 v129, v124, v125
	v_add_f32_e32 v166, v168, v159
	s_ashr_i32 s17, s16, 31
	v_lshlrev_b32_e32 v159, 6, v158
	s_movk_i32 s3, 0x33c0
	s_lshl_b64 s[16:17], s[16:17], 19
	v_and_or_b32 v159, v159, s3, v194
	v_readlane_b32 s2, v253, 59
	v_readlane_b32 s3, v253, 60
	s_add_u32 s16, s2, s16
	s_addc_u32 s17, s3, s17
	s_lshl_b64 s[28:29], s[40:41], 15
	s_waitcnt vmcnt(6)
	v_sub_f32_e32 v123, v193, v225
	v_sub_f32_e32 v122, v192, v225
	v_sub_f32_e32 v125, v191, v225
	v_sub_f32_e32 v124, v190, v225
	v_pk_mul_f32 v[124:125], v[0:1], v[124:125] op_sel_hi:[0,1]
	v_pk_mul_f32 v[122:123], v[0:1], v[122:123] op_sel_hi:[0,1]
	s_add_u32 s50, s16, s28
	s_addc_u32 s51, s17, s29
	v_lshlrev_b32_e32 v159, 1, v159
	global_store_dwordx4 v159, v[126:129], s[50:51]
	s_waitcnt vmcnt(3)
	v_pk_fma_f32 v[122:123], v[202:203], v[122:123], v[244:245]
	v_pk_fma_f32 v[124:125], v[200:201], v[124:125], v[242:243]
	v_pk_mul_f32 v[122:123], v[122:123], s[18:19] op_sel_hi:[1,0]
	v_pk_mul_f32 v[124:125], v[124:125], s[18:19] op_sel_hi:[1,0]
	v_pk_fma_f32 v[120:121], v[120:121], 0.5, v[122:123] op_sel_hi:[1,0,1]
	v_pk_fma_f32 v[118:119], v[118:119], 0.5, v[124:125] op_sel_hi:[1,0,1]
	v_add_f32_e32 v123, v120, v121
	v_add_f32_e32 v122, v118, v119
	v_add_f32_e32 v122, v122, v123
	v_add_f32_e32 v126, v178, v122
	v_mul_f32_e32 v122, v119, v119
	v_mul_f32_e32 v123, v121, v121
	v_add_f32_e32 v179, v179, v195
	v_fmac_f32_e32 v122, v118, v118
	v_fmac_f32_e32 v123, v120, v120
	v_add_f32_e32 v179, v212, v179
	v_add_f32_e32 v122, v122, v123
	v_add_f32_e32 v127, v179, v122
	v_sub_f32_e32 v123, v189, v225
	v_sub_f32_e32 v122, v188, v225
	v_sub_f32_e32 v125, v187, v225
	v_sub_f32_e32 v124, v186, v225
	v_pk_mul_f32 v[124:125], v[0:1], v[124:125] op_sel_hi:[0,1]
	v_pk_mul_f32 v[122:123], v[0:1], v[122:123] op_sel_hi:[0,1]
	v_pk_fma_f32 v[122:123], v[198:199], v[122:123], v[206:207]
	v_pk_fma_f32 v[124:125], v[196:197], v[124:125], v[204:205]
	v_pk_mul_f32 v[122:123], v[122:123], s[18:19] op_sel_hi:[1,0]
	v_pk_mul_f32 v[124:125], v[124:125], s[18:19] op_sel_hi:[1,0]
	v_pk_fma_f32 v[116:117], v[116:117], 0.5, v[122:123] op_sel_hi:[1,0,1]
	v_pk_fma_f32 v[114:115], v[114:115], 0.5, v[124:125] op_sel_hi:[1,0,1]
	v_add_f32_e32 v122, v116, v117
	v_add_f32_e32 v0, v114, v115
	v_add_f32_e32 v0, v0, v122
	v_mul_f32_e32 v122, v115, v115
	v_mul_f32_e32 v123, v117, v117
	v_add_f32_e32 v0, v126, v0
	v_fmac_f32_e32 v122, v114, v114
	v_fmac_f32_e32 v123, v116, v116
	s_nop 0
	s_nop 1
	v_bfe_u32 v125, v227, 4, 2
	v_sub_u32_e32 v124, 0, v125
	v_lshlrev_b32_e32 v124, 4, v124
	v_ashrrev_i32_e32 v125, 31, v124
	v_lshl_add_u64 v[124:125], v[136:137], 0, v[124:125]
	v_permlane16_swap_b32_e32 v118, v114
	v_permlane16_swap_b32_e32 v119, v115
	v_permlane16_swap_b32_e32 v120, v116
	v_permlane16_swap_b32_e32 v121, v117
; __device__ __forceinline__ float xsum16(float v) { const auto r = __builtin_amdgcn_permlane16_swap(__float_as_uint(v), __float_as_uint(v), false, false); return __uint_as_float(r[0]) + __uint_as_float(r[1]); }
; __device__ __forceinline__ float xsum32(float v) { const auto r = __builtin_amdgcn_permlane32_swap(__float_as_uint(v), __float_as_uint(v), false, false); return __uint_as_float(r[0]) + __uint_as_float(r[1]); }
; __device__ __forceinline__ size_t blk_off(int r, int c, int K) { return (size_t)(r >> 8) * 256 * K + (size_t)(c >> 6) * (256 * 64) + (size_t)((r & 255) * 64 + (c & 63)); }
; __device__ __forceinline__ u32x4 pack8(const f32x4 a, const f32x4 b) { u32x4 w; w.x = cvt_pk_bf16(a[0], a[1]); w.y = cvt_pk_bf16(a[2], a[3]); w.z = cvt_pk_bf16(b[0], b[1]); w.w = cvt_pk_bf16(b[2], b[3]); return w; }
;     __device__ __forceinline__ void operator()(const f32x4 (&acc)[2][2][4][2], const pg8::Unit& u, int wr, int wc, int fr, int fq) const {
;     ...
;             for (int m = 0; m < 4; ++m) { const int row = row0 + ai * 128 + m * 16; const float mu = mu4[m], rs = rs4[m];
;                 f32x4 yv[2][2], gq[2][2], bq_[2][2];
; #pragma unroll
;                 for (int bj = 0; bj < 2; ++bj)
; #pragma unroll
;                     for (int n = 0; n < 2; ++n) { yv[bj][n] = *(const f32x4*)(Yin + (size_t)row * D_ + col0 + bj * 128 + 4 * n); gq[bj][n] = *(const f32x4*)(g + col0 + bj * 128 + 4 * n); bq_[bj][n] = *(const f32x4*)(b + col0 + bj * 128 + 4 * n); }
;                 asm volatile("" ::: "memory");
;                 float s1 = 0.f, s2 = 0.f;
; #pragma unroll
;                 for (int bj = 0; bj < 2; ++bj) { float* yp = Y + (size_t)row * D_ + col0 + bj * 128; f32x4 v[2];
; #pragma unroll
;                     for (int n = 0; n < 2; ++n) { v[n] = (((yv[bj][n] - mu) * rs) * gq[bj][n] + bq_[bj][n]) * ALPHA_ + acc[ai][bj][m][n] * sc;
;                         *(f32x4*)(yp + 4 * n) = v[n]; s1 += (v[n][0] + v[n][1]) + (v[n][2] + v[n][3]); s2 += (v[n][0] * v[n][0] + v[n][1] * v[n][1]) + (v[n][2] * v[n][2] + v[n][3] * v[n][3]); }
;                     *(u32x4*)(Yb + blk_off(row, col0 + bj * 128, D_)) = pack8(v[0], v[1]); }
;                 s1 = xsum32(xsum16(s1)); s2 = xsum32(xsum16(s2));
;                 if (fq == 0) *(f32x2*)(stn + (size_t)row * 32 + (u.pn * 4 + wc) * 2) = (f32x2){s1, s2}; asm volatile("" ::: "memory"); } }
	v_permlane32_swap_b32_e32 v118, v114
	v_permlane32_swap_b32_e32 v119, v115
	v_permlane32_swap_b32_e32 v120, v116
	v_permlane32_swap_b32_e32 v121, v117
	global_store_dwordx4 v[124:125], v[118:121], off offset:512
	global_store_dwordx4 v[124:125], v[114:117], off offset:576
	s_nop 1
	v_permlane32_swap_b32_e32 v118, v114
	v_permlane32_swap_b32_e32 v119, v115
	v_permlane32_swap_b32_e32 v120, v116
	v_permlane32_swap_b32_e32 v121, v117
	v_permlane16_swap_b32_e32 v118, v114
	v_permlane16_swap_b32_e32 v119, v115
	v_permlane16_swap_b32_e32 v120, v116
	v_permlane16_swap_b32_e32 v121, v117
	v_add_f32_e32 v122, v122, v123
	v_cvt_pk_bf16_f32 v118, v118, v119
	v_cvt_pk_bf16_f32 v119, v120, v121
	v_cvt_pk_bf16_f32 v120, v114, v115
	v_mov_b32_e32 v114, v0
	v_add_f32_e32 v122, v127, v122
	s_nop 0
	v_permlane16_swap_b32_e32 v0, v114
	s_or_b32 s2, s40, 2
	v_add_f32_e32 v114, v0, v114
	v_mov_b32_e32 v0, v122
	s_ashr_i32 s3, s2, 31
	s_nop 0
	v_permlane16_swap_b32_e32 v122, v0
	s_lshl_b64 s[40:41], s[2:3], 15
	v_add_f32_e32 v115, v122, v0
	v_mov_b32_e32 v135, v133
	v_mov_b32_e32 v134, v132
	v_mov_b32_e32 v177, v175
	v_mov_b32_e32 v176, v174
	v_mov_b32_e32 v169, v167
	v_mov_b32_e32 v168, v166
	v_cvt_pk_bf16_f32 v121, v116, v117
	s_add_u32 s42, s16, s40
	v_mov_b32_e32 v116, v114
	v_mov_b32_e32 v117, v115
	v_permlane32_swap_b32_e32 v133, v135
	v_permlane32_swap_b32_e32 v132, v134
	v_permlane32_swap_b32_e32 v175, v177
	v_permlane32_swap_b32_e32 v174, v176
	v_permlane32_swap_b32_e32 v167, v169
	v_permlane32_swap_b32_e32 v166, v168
	s_addc_u32 s43, s17, s41
	v_permlane32_swap_b32_e32 v114, v116
	v_permlane32_swap_b32_e32 v115, v117
	global_store_dwordx4 v159, v[118:121], s[42:43]
	s_and_saveexec_b64 s[26:27], s[44:45]
	s_cbranch_execz .LBB0_374
	v_pk_add_f32 v[114:115], v[114:115], v[116:117]
	v_lshl_add_u64 v[116:117], s[30:31], 0, v[130:131]
	v_lshl_add_u64 v[116:117], s[24:25], 2, v[116:117]
	global_store_dwordx2 v[116:117], v[114:115], off
.LBB0_374:
	s_or_b64 exec, exec, s[26:27]
	v_pk_add_f32 v[114:115], v[132:133], v[134:135]
	s_mov_b32 s2, 0x3a800000
	v_pk_mul_f32 v[178:179], v[114:115], s[2:3] op_sel_hi:[1,0]
	s_mov_b32 s2, 0x800000
	v_fma_f32 v0, -v179, v179, v178
	v_max_f32_e32 v0, 0, v0
	v_add_f32_e32 v0, 0x3727c5ac, v0
	v_cmp_gt_f32_e32 vcc, s2, v0
	v_mul_f32_e32 v114, 0x4b800000, v0
	v_lshlrev_b64 v[212:213], 12, v[180:181]
	v_cndmask_b32_e32 v0, v0, v114, vcc
	v_rsq_f32_e32 v0, v0
	v_lshlrev_b32_e32 v159, 6, v180
	s_movk_i32 s2, 0x37c0
	v_mul_f32_e32 v114, 0x45800000, v0
	v_cndmask_b32_e32 v0, v0, v114, vcc
	v_lshl_add_u64 v[114:115], s[12:13], 0, v[212:213]
	v_lshl_add_u64 v[118:119], v[114:115], 0, v[152:153]
	global_load_dwordx4 v[186:189], v[118:119], off offset:16 nt
	global_load_dwordx4 v[190:193], v[118:119], off nt
	global_load_dwordx4 v[196:199], v[154:155], off offset:16
	global_load_dwordx4 v[200:203], v[154:155], off
	global_load_dwordx4 v[204:207], v[156:157], off offset:16
	global_load_dwordx4 v[208:211], v[156:157], off
	global_load_dwordx4 v[114:117], v[118:119], off offset:528 nt
	global_load_dwordx4 v[134:137], v[118:119], off offset:512 nt
	s_nop 0
	global_load_dwordx4 v[118:121], v[154:155], off offset:528
	global_load_dwordx4 v[126:129], v[154:155], off offset:512
	global_load_dwordx4 v[122:125], v[156:157], off offset:528
	global_load_dwordx4 v[130:133], v[156:157], off offset:512
	v_and_or_b32 v159, v159, s2, v194
	s_load_dwordx16 s[60:75], s[34:35], 0x38
	s_mov_b32 s2, 0x3fd744fd
	v_lshlrev_b32_e32 v159, 1, v159
	s_waitcnt lgkmcnt(0)
	v_lshl_add_u64 v[180:181], s[74:75], 0, v[212:213]
	v_lshl_add_u64 v[180:181], v[180:181], 0, v[152:153]
	s_waitcnt vmcnt(11)
	v_sub_f32_e32 v189, v189, v179
	s_waitcnt vmcnt(10)
	v_sub_f32_e32 v193, v193, v179
	v_sub_f32_e32 v192, v192, v179
	v_sub_f32_e32 v191, v191, v179
	v_sub_f32_e32 v190, v190, v179
	v_pk_mul_f32 v[190:191], v[0:1], v[190:191] op_sel_hi:[0,1]
	v_pk_mul_f32 v[192:193], v[0:1], v[192:193] op_sel_hi:[0,1]
	v_sub_f32_e32 v188, v188, v179
	v_sub_f32_e32 v187, v187, v179
	v_sub_f32_e32 v186, v186, v179
	s_waitcnt vmcnt(6)
	v_pk_fma_f32 v[192:193], v[202:203], v[192:193], v[210:211]
	v_pk_fma_f32 v[190:191], v[200:201], v[190:191], v[208:209]
	v_pk_mul_f32 v[186:187], v[0:1], v[186:187] op_sel_hi:[0,1]
	v_pk_mul_f32 v[188:189], v[0:1], v[188:189] op_sel_hi:[0,1]
	v_pk_mul_f32 v[190:191], v[190:191], s[2:3] op_sel_hi:[1,0]
	v_pk_mul_f32 v[192:193], v[192:193], s[2:3] op_sel_hi:[1,0]
	v_pk_fma_f32 v[188:189], v[198:199], v[188:189], v[206:207]
	v_pk_fma_f32 v[186:187], v[196:197], v[186:187], v[204:205]
	v_pk_fma_f32 v[112:113], v[112:113], 0.5, v[192:193] op_sel_hi:[1,0,1]
	v_pk_fma_f32 v[110:111], v[110:111], 0.5, v[190:191] op_sel_hi:[1,0,1]
	v_pk_mul_f32 v[186:187], v[186:187], s[2:3] op_sel_hi:[1,0]
	v_pk_mul_f32 v[188:189], v[188:189], s[2:3] op_sel_hi:[1,0]
	v_add_f32_e32 v178, v110, v111
	v_add_f32_e32 v190, v112, v113
	v_pk_fma_f32 v[108:109], v[108:109], 0.5, v[188:189] op_sel_hi:[1,0,1]
	v_pk_fma_f32 v[106:107], v[106:107], 0.5, v[186:187] op_sel_hi:[1,0,1]
	v_add_f32_e32 v178, v178, v190
	v_add_f32_e32 v186, v106, v107
	v_add_f32_e32 v187, v108, v109
	v_add_f32_e32 v178, 0, v178
	v_add_f32_e32 v186, v186, v187
	v_mul_f32_e32 v190, v111, v111
	v_mul_f32_e32 v191, v113, v113
	v_add_f32_e32 v178, v178, v186
	v_mul_f32_e32 v186, v107, v107
	v_mul_f32_e32 v187, v109, v109
	s_nop 0
	v_fmac_f32_e32 v190, v110, v110
	v_fmac_f32_e32 v191, v112, v112
	s_nop 1
	v_bfe_u32 v189, v227, 4, 2
	v_sub_u32_e32 v188, 0, v189
	v_lshlrev_b32_e32 v188, 4, v188
	v_ashrrev_i32_e32 v189, 31, v188
	v_lshl_add_u64 v[188:189], v[180:181], 0, v[188:189]
	v_permlane16_swap_b32_e32 v110, v106
	v_permlane16_swap_b32_e32 v111, v107
	v_permlane16_swap_b32_e32 v112, v108
	v_permlane16_swap_b32_e32 v113, v109
	v_permlane32_swap_b32_e32 v110, v106
	v_permlane32_swap_b32_e32 v111, v107
	v_permlane32_swap_b32_e32 v112, v108
	v_permlane32_swap_b32_e32 v113, v109
	global_store_dwordx4 v[188:189], v[110:113], off
	global_store_dwordx4 v[188:189], v[106:109], off offset:64
	s_nop 1
	v_permlane32_swap_b32_e32 v110, v106
	v_permlane32_swap_b32_e32 v111, v107
	v_permlane32_swap_b32_e32 v112, v108
	v_permlane32_swap_b32_e32 v113, v109
	v_permlane16_swap_b32_e32 v110, v106
	v_permlane16_swap_b32_e32 v111, v107
	v_permlane16_swap_b32_e32 v112, v108
	v_permlane16_swap_b32_e32 v113, v109
	v_fmac_f32_e32 v186, v106, v106
	v_fmac_f32_e32 v187, v108, v108
	v_cvt_pk_bf16_f32 v110, v110, v111
	v_cvt_pk_bf16_f32 v111, v112, v113
	v_cvt_pk_bf16_f32 v112, v106, v107
	v_cvt_pk_bf16_f32 v113, v108, v109
	s_waitcnt vmcnt(6)
; __device__ __forceinline__ float xsum16(float v) { const auto r = __builtin_amdgcn_permlane16_swap(__float_as_uint(v), __float_as_uint(v), false, false); return __uint_as_float(r[0]) + __uint_as_float(r[1]); }
; __device__ __forceinline__ float xsum32(float v) { const auto r = __builtin_amdgcn_permlane32_swap(__float_as_uint(v), __float_as_uint(v), false, false); return __uint_as_float(r[0]) + __uint_as_float(r[1]); }
; __device__ __forceinline__ size_t blk_off(int r, int c, int K) { return (size_t)(r >> 8) * 256 * K + (size_t)(c >> 6) * (256 * 64) + (size_t)((r & 255) * 64 + (c & 63)); }
; __device__ __forceinline__ u32x4 pack8(const f32x4 a, const f32x4 b) { u32x4 w; w.x = cvt_pk_bf16(a[0], a[1]); w.y = cvt_pk_bf16(a[2], a[3]); w.z = cvt_pk_bf16(b[0], b[1]); w.w = cvt_pk_bf16(b[2], b[3]); return w; }
;     __device__ __forceinline__ void operator()(const f32x4 (&acc)[2][2][4][2], const pg8::Unit& u, int wr, int wc, int fr, int fq) const {
;     ...
;             for (int m = 0; m < 4; ++m) { const int row = row0 + ai * 128 + m * 16; const float mu = mu4[m], rs = rs4[m];
;                 f32x4 yv[2][2], gq[2][2], bq_[2][2];
; #pragma unroll
;                 for (int bj = 0; bj < 2; ++bj)
; #pragma unroll
;                     for (int n = 0; n < 2; ++n) { yv[bj][n] = *(const f32x4*)(Yin + (size_t)row * D_ + col0 + bj * 128 + 4 * n); gq[bj][n] = *(const f32x4*)(g + col0 + bj * 128 + 4 * n); bq_[bj][n] = *(const f32x4*)(b + col0 + bj * 128 + 4 * n); }
;                 asm volatile("" ::: "memory");
;                 float s1 = 0.f, s2 = 0.f;
; #pragma unroll
;                 for (int bj = 0; bj < 2; ++bj) { float* yp = Y + (size_t)row * D_ + col0 + bj * 128; f32x4 v[2];
; #pragma unroll
;                     for (int n = 0; n < 2; ++n) { v[n] = (((yv[bj][n] - mu) * rs) * gq[bj][n] + bq_[bj][n]) * ALPHA_ + acc[ai][bj][m][n] * sc;
;                         *(f32x4*)(yp + 4 * n) = v[n]; s1 += (v[n][0] + v[n][1]) + (v[n][2] + v[n][3]); s2 += (v[n][0] * v[n][0] + v[n][1] * v[n][1]) + (v[n][2] * v[n][2] + v[n][3] * v[n][3]); }
;                     *(u32x4*)(Yb + blk_off(row, col0 + bj * 128, D_)) = pack8(v[0], v[1]); }
;                 s1 = xsum32(xsum16(s1)); s2 = xsum32(xsum16(s2));
;                 if (fq == 0) *(f32x2*)(stn + (size_t)row * 32 + (u.pn * 4 + wc) * 2) = (f32x2){s1, s2}; asm volatile("" ::: "memory"); } }
	v_sub_f32_e32 v107, v137, v179
	v_sub_f32_e32 v106, v136, v179
	v_sub_f32_e32 v109, v135, v179
	v_sub_f32_e32 v108, v134, v179
	v_pk_mul_f32 v[108:109], v[0:1], v[108:109] op_sel_hi:[0,1]
	v_pk_mul_f32 v[106:107], v[0:1], v[106:107] op_sel_hi:[0,1]
	s_waitcnt vmcnt(2)
	v_pk_fma_f32 v[106:107], v[128:129], v[106:107], v[132:133]
	v_pk_fma_f32 v[108:109], v[126:127], v[108:109], v[130:131]
	v_pk_mul_f32 v[106:107], v[106:107], s[2:3] op_sel_hi:[1,0]
	v_pk_mul_f32 v[108:109], v[108:109], s[2:3] op_sel_hi:[1,0]
	v_pk_fma_f32 v[104:105], v[104:105], 0.5, v[106:107] op_sel_hi:[1,0,1]
	v_pk_fma_f32 v[102:103], v[102:103], 0.5, v[108:109] op_sel_hi:[1,0,1]
	v_add_f32_e32 v107, v104, v105
	v_add_f32_e32 v106, v102, v103
	v_add_f32_e32 v106, v106, v107
	global_store_dwordx4 v159, v[110:113], s[50:51]
	v_mul_f32_e32 v107, v105, v105
	v_add_f32_e32 v190, v190, v191
	v_add_f32_e32 v110, v178, v106
	v_mul_f32_e32 v106, v103, v103
	v_add_f32_e32 v186, v186, v187
	v_fmac_f32_e32 v106, v102, v102
	v_fmac_f32_e32 v107, v104, v104
	v_add_f32_e32 v186, v190, v186
	v_add_f32_e32 v106, v106, v107
	v_add_f32_e32 v111, v186, v106
	v_sub_f32_e32 v107, v117, v179
	v_sub_f32_e32 v106, v116, v179
	v_sub_f32_e32 v109, v115, v179
	v_sub_f32_e32 v108, v114, v179
	v_pk_mul_f32 v[108:109], v[0:1], v[108:109] op_sel_hi:[0,1]
	v_pk_mul_f32 v[106:107], v[0:1], v[106:107] op_sel_hi:[0,1]
	v_pk_fma_f32 v[106:107], v[120:121], v[106:107], v[124:125]
	v_pk_fma_f32 v[108:109], v[118:119], v[108:109], v[122:123]
	v_pk_mul_f32 v[106:107], v[106:107], s[2:3] op_sel_hi:[1,0]
	v_pk_mul_f32 v[108:109], v[108:109], s[2:3] op_sel_hi:[1,0]
	v_pk_fma_f32 v[100:101], v[100:101], 0.5, v[106:107] op_sel_hi:[1,0,1]
	v_pk_fma_f32 v[98:99], v[98:99], 0.5, v[108:109] op_sel_hi:[1,0,1]
	v_add_f32_e32 v106, v100, v101
	v_add_f32_e32 v0, v98, v99
	v_add_f32_e32 v0, v0, v106
	v_mul_f32_e32 v106, v99, v99
	v_mul_f32_e32 v107, v101, v101
	v_add_f32_e32 v0, v110, v0
	v_fmac_f32_e32 v106, v98, v98
	v_fmac_f32_e32 v107, v100, v100
	s_nop 0
	s_nop 1
	v_bfe_u32 v109, v227, 4, 2
	v_sub_u32_e32 v108, 0, v109
	v_lshlrev_b32_e32 v108, 4, v108
	v_ashrrev_i32_e32 v109, 31, v108
	v_lshl_add_u64 v[108:109], v[180:181], 0, v[108:109]
	v_permlane16_swap_b32_e32 v102, v98
	v_permlane16_swap_b32_e32 v103, v99
	v_permlane16_swap_b32_e32 v104, v100
	v_permlane16_swap_b32_e32 v105, v101
	v_permlane32_swap_b32_e32 v102, v98
	v_permlane32_swap_b32_e32 v103, v99
	v_permlane32_swap_b32_e32 v104, v100
	v_permlane32_swap_b32_e32 v105, v101
	global_store_dwordx4 v[108:109], v[102:105], off offset:512
	global_store_dwordx4 v[108:109], v[98:101], off offset:576
	s_nop 1
	v_permlane32_swap_b32_e32 v102, v98
	v_permlane32_swap_b32_e32 v103, v99
	v_permlane32_swap_b32_e32 v104, v100
	v_permlane32_swap_b32_e32 v105, v101
	v_permlane16_swap_b32_e32 v102, v98
	v_permlane16_swap_b32_e32 v103, v99
	v_permlane16_swap_b32_e32 v104, v100
	v_permlane16_swap_b32_e32 v105, v101
	v_add_f32_e32 v106, v106, v107
	v_cvt_pk_bf16_f32 v102, v102, v103
	v_cvt_pk_bf16_f32 v103, v104, v105
	v_cvt_pk_bf16_f32 v104, v98, v99
	v_mov_b32_e32 v98, v0
	v_add_f32_e32 v106, v111, v106
	s_nop 0
	v_permlane16_swap_b32_e32 v0, v98
	v_add_f32_e32 v98, v0, v98
	v_mov_b32_e32 v0, v106
	s_nop 1
	v_permlane16_swap_b32_e32 v106, v0
	v_add_f32_e32 v99, v106, v0
	v_cvt_pk_bf16_f32 v105, v100, v101
	v_mov_b32_e32 v100, v98
	v_mov_b32_e32 v101, v99
	s_nop 0
	v_permlane32_swap_b32_e32 v98, v100
	v_permlane32_swap_b32_e32 v99, v101
	global_store_dwordx4 v159, v[102:105], s[42:43]
	s_and_saveexec_b64 s[26:27], s[44:45]
	s_cbranch_execz .LBB0_376
	v_pk_add_f32 v[98:99], v[98:99], v[100:101]
	v_lshl_add_u64 v[100:101], s[30:31], 0, v[172:173]
	v_lshl_add_u64 v[100:101], s[24:25], 2, v[100:101]
	global_store_dwordx2 v[100:101], v[98:99], off
.LBB0_376:
	s_or_b64 exec, exec, s[26:27]
	v_pk_add_f32 v[98:99], v[174:175], v[176:177]
	s_mov_b32 s2, 0x3a800000
	v_pk_mul_f32 v[122:123], v[98:99], s[2:3] op_sel_hi:[1,0]
	s_mov_b32 s2, 0x800000
	v_fma_f32 v0, -v123, v123, v122
	v_max_f32_e32 v0, 0, v0
	v_add_f32_e32 v0, 0x3727c5ac, v0
	v_cmp_gt_f32_e32 vcc, s2, v0
	v_mul_f32_e32 v98, 0x4b800000, v0
	v_lshlrev_b64 v[124:125], 12, v[170:171]
	v_cndmask_b32_e32 v0, v0, v98, vcc
	v_rsq_f32_e32 v0, v0
	s_load_dwordx16 s[60:75], s[34:35], 0x38
	v_lshlrev_b32_e32 v122, 6, v170
	v_mul_f32_e32 v98, 0x45800000, v0
	v_cndmask_b32_e32 v0, v0, v98, vcc
	v_lshl_add_u64 v[98:99], s[12:13], 0, v[124:125]
	v_lshl_add_u64 v[102:103], v[98:99], 0, v[152:153]
	global_load_dwordx4 v[126:129], v[102:103], off offset:16 nt
	global_load_dwordx4 v[130:133], v[102:103], off nt
	global_load_dwordx4 v[134:137], v[154:155], off offset:16
	global_load_dwordx4 v[172:175], v[154:155], off
	global_load_dwordx4 v[176:179], v[156:157], off offset:16
	global_load_dwordx4 v[186:189], v[156:157], off
	global_load_dwordx4 v[98:101], v[102:103], off offset:528 nt
	global_load_dwordx4 v[118:121], v[102:103], off offset:512 nt
	s_nop 0
	global_load_dwordx4 v[102:105], v[154:155], off offset:528
	global_load_dwordx4 v[110:113], v[154:155], off offset:512
	global_load_dwordx4 v[106:109], v[156:157], off offset:528
	global_load_dwordx4 v[114:117], v[156:157], off offset:512
	s_movk_i32 s2, 0x3bc0
	v_and_or_b32 v122, v122, s2, v194
	s_mov_b32 s2, 0x3fd744fd
	s_waitcnt lgkmcnt(0)
	v_lshl_add_u64 v[124:125], s[74:75], 0, v[124:125]
	v_lshl_add_u64 v[124:125], v[124:125], 0, v[152:153]
	v_lshlrev_b32_e32 v122, 1, v122
	s_waitcnt vmcnt(11)
	v_sub_f32_e32 v129, v129, v123
	s_waitcnt vmcnt(10)
; __device__ __forceinline__ float xsum16(float v) { const auto r = __builtin_amdgcn_permlane16_swap(__float_as_uint(v), __float_as_uint(v), false, false); return __uint_as_float(r[0]) + __uint_as_float(r[1]); }
; __device__ __forceinline__ float xsum32(float v) { const auto r = __builtin_amdgcn_permlane32_swap(__float_as_uint(v), __float_as_uint(v), false, false); return __uint_as_float(r[0]) + __uint_as_float(r[1]); }
; __device__ __forceinline__ size_t blk_off(int r, int c, int K) { return (size_t)(r >> 8) * 256 * K + (size_t)(c >> 6) * (256 * 64) + (size_t)((r & 255) * 64 + (c & 63)); }
; __device__ __forceinline__ u32x4 pack8(const f32x4 a, const f32x4 b) { u32x4 w; w.x = cvt_pk_bf16(a[0], a[1]); w.y = cvt_pk_bf16(a[2], a[3]); w.z = cvt_pk_bf16(b[0], b[1]); w.w = cvt_pk_bf16(b[2], b[3]); return w; }
;     __device__ __forceinline__ void operator()(const f32x4 (&acc)[2][2][4][2], const pg8::Unit& u, int wr, int wc, int fr, int fq) const {
;     ...
;                     for (int n = 0; n < 2; ++n) { yv[bj][n] = *(const f32x4*)(Yin + (size_t)row * D_ + col0 + bj * 128 + 4 * n); gq[bj][n] = *(const f32x4*)(g + col0 + bj * 128 + 4 * n); bq_[bj][n] = *(const f32x4*)(b + col0 + bj * 128 + 4 * n); }
;                 asm volatile("" ::: "memory");
;                 float s1 = 0.f, s2 = 0.f;
; #pragma unroll
;                 for (int bj = 0; bj < 2; ++bj) { float* yp = Y + (size_t)row * D_ + col0 + bj * 128; f32x4 v[2];
; #pragma unroll
;                     for (int n = 0; n < 2; ++n) { v[n] = (((yv[bj][n] - mu) * rs) * gq[bj][n] + bq_[bj][n]) * ALPHA_ + acc[ai][bj][m][n] * sc;
;                         *(f32x4*)(yp + 4 * n) = v[n]; s1 += (v[n][0] + v[n][1]) + (v[n][2] + v[n][3]); s2 += (v[n][0] * v[n][0] + v[n][1] * v[n][1]) + (v[n][2] * v[n][2] + v[n][3] * v[n][3]); }
;                     *(u32x4*)(Yb + blk_off(row, col0 + bj * 128, D_)) = pack8(v[0], v[1]); }
;                 s1 = xsum32(xsum16(s1)); s2 = xsum32(xsum16(s2));
;                 if (fq == 0) *(f32x2*)(stn + (size_t)row * 32 + (u.pn * 4 + wc) * 2) = (f32x2){s1, s2}; asm volatile("" ::: "memory"); } }
	v_sub_f32_e32 v133, v133, v123
	v_sub_f32_e32 v132, v132, v123
	v_sub_f32_e32 v131, v131, v123
	v_sub_f32_e32 v130, v130, v123
	v_sub_f32_e32 v128, v128, v123
	v_sub_f32_e32 v127, v127, v123
	v_sub_f32_e32 v126, v126, v123
	v_pk_mul_f32 v[130:131], v[0:1], v[130:131] op_sel_hi:[0,1]
	v_pk_mul_f32 v[132:133], v[0:1], v[132:133] op_sel_hi:[0,1]
	v_pk_mul_f32 v[126:127], v[0:1], v[126:127] op_sel_hi:[0,1]
	v_pk_mul_f32 v[128:129], v[0:1], v[128:129] op_sel_hi:[0,1]
	s_waitcnt vmcnt(6)
	v_pk_fma_f32 v[132:133], v[174:175], v[132:133], v[188:189]
	v_pk_fma_f32 v[130:131], v[172:173], v[130:131], v[186:187]
	v_pk_fma_f32 v[128:129], v[136:137], v[128:129], v[178:179]
	v_pk_fma_f32 v[126:127], v[134:135], v[126:127], v[176:177]
	v_pk_mul_f32 v[130:131], v[130:131], s[2:3] op_sel_hi:[1,0]
	v_pk_mul_f32 v[132:133], v[132:133], s[2:3] op_sel_hi:[1,0]
	v_pk_mul_f32 v[126:127], v[126:127], s[2:3] op_sel_hi:[1,0]
	v_pk_mul_f32 v[128:129], v[128:129], s[2:3] op_sel_hi:[1,0]
	v_pk_fma_f32 v[96:97], v[96:97], 0.5, v[132:133] op_sel_hi:[1,0,1]
	v_pk_fma_f32 v[94:95], v[94:95], 0.5, v[130:131] op_sel_hi:[1,0,1]
	v_pk_fma_f32 v[92:93], v[92:93], 0.5, v[128:129] op_sel_hi:[1,0,1]
	v_pk_fma_f32 v[90:91], v[90:91], 0.5, v[126:127] op_sel_hi:[1,0,1]
	v_add_f32_e32 v130, v94, v95
	v_add_f32_e32 v131, v96, v97
	v_add_f32_e32 v126, v90, v91
	v_add_f32_e32 v127, v92, v93
	v_add_f32_e32 v130, v130, v131
	v_mul_f32_e32 v131, v95, v95
	v_mul_f32_e32 v132, v97, v97
	v_add_f32_e32 v126, v126, v127
	v_mul_f32_e32 v127, v91, v91
	v_mul_f32_e32 v128, v93, v93
	s_nop 0
	v_fmac_f32_e32 v131, v94, v94
	v_fmac_f32_e32 v132, v96, v96
	s_nop 1
	v_bfe_u32 v135, v227, 4, 2
	v_sub_u32_e32 v134, 0, v135
	v_lshlrev_b32_e32 v134, 4, v134
	v_ashrrev_i32_e32 v135, 31, v134
	v_lshl_add_u64 v[134:135], v[124:125], 0, v[134:135]
	v_permlane16_swap_b32_e32 v94, v90
	v_permlane16_swap_b32_e32 v95, v91
	v_permlane16_swap_b32_e32 v96, v92
	v_permlane16_swap_b32_e32 v97, v93
	v_permlane32_swap_b32_e32 v94, v90
	v_permlane32_swap_b32_e32 v95, v91
	v_permlane32_swap_b32_e32 v96, v92
	v_permlane32_swap_b32_e32 v97, v93
	global_store_dwordx4 v[134:135], v[94:97], off
	global_store_dwordx4 v[134:135], v[90:93], off offset:64
	s_nop 1
	v_permlane32_swap_b32_e32 v94, v90
	v_permlane32_swap_b32_e32 v95, v91
	v_permlane32_swap_b32_e32 v96, v92
	v_permlane32_swap_b32_e32 v97, v93
	v_permlane16_swap_b32_e32 v94, v90
	v_permlane16_swap_b32_e32 v95, v91
	v_permlane16_swap_b32_e32 v96, v92
	v_permlane16_swap_b32_e32 v97, v93
	v_fmac_f32_e32 v127, v90, v90
	v_fmac_f32_e32 v128, v92, v92
	v_cvt_pk_bf16_f32 v94, v94, v95
	v_cvt_pk_bf16_f32 v95, v96, v97
	v_cvt_pk_bf16_f32 v96, v90, v91
	v_cvt_pk_bf16_f32 v97, v92, v93
	s_waitcnt vmcnt(6)
	v_sub_f32_e32 v91, v121, v123
	v_sub_f32_e32 v90, v120, v123
	v_sub_f32_e32 v93, v119, v123
	v_sub_f32_e32 v92, v118, v123
	v_pk_mul_f32 v[92:93], v[0:1], v[92:93] op_sel_hi:[0,1]
	v_pk_mul_f32 v[90:91], v[0:1], v[90:91] op_sel_hi:[0,1]
	s_waitcnt vmcnt(2)
	v_pk_fma_f32 v[90:91], v[112:113], v[90:91], v[116:117]
	v_pk_fma_f32 v[92:93], v[110:111], v[92:93], v[114:115]
	v_pk_mul_f32 v[90:91], v[90:91], s[2:3] op_sel_hi:[1,0]
	v_pk_mul_f32 v[92:93], v[92:93], s[2:3] op_sel_hi:[1,0]
	v_pk_fma_f32 v[88:89], v[88:89], 0.5, v[90:91] op_sel_hi:[1,0,1]
	v_pk_fma_f32 v[86:87], v[86:87], 0.5, v[92:93] op_sel_hi:[1,0,1]
	v_add_f32_e32 v130, 0, v130
	v_add_f32_e32 v90, v86, v87
	v_add_f32_e32 v91, v88, v89
	v_add_f32_e32 v126, v130, v126
	v_add_f32_e32 v90, v90, v91
	global_store_dwordx4 v122, v[94:97], s[50:51]
	v_mul_f32_e32 v91, v89, v89
	v_add_f32_e32 v131, v131, v132
	v_add_f32_e32 v94, v126, v90
	v_mul_f32_e32 v90, v87, v87
	v_add_f32_e32 v127, v127, v128
	v_fmac_f32_e32 v90, v86, v86
	v_fmac_f32_e32 v91, v88, v88
	v_add_f32_e32 v127, v131, v127
	v_add_f32_e32 v90, v90, v91
	v_add_f32_e32 v95, v127, v90
	v_sub_f32_e32 v91, v101, v123
	v_sub_f32_e32 v90, v100, v123
	v_sub_f32_e32 v93, v99, v123
	v_sub_f32_e32 v92, v98, v123
	v_pk_mul_f32 v[92:93], v[0:1], v[92:93] op_sel_hi:[0,1]
	v_pk_mul_f32 v[90:91], v[0:1], v[90:91] op_sel_hi:[0,1]
	v_pk_fma_f32 v[90:91], v[104:105], v[90:91], v[108:109]
	v_pk_fma_f32 v[92:93], v[102:103], v[92:93], v[106:107]
	v_pk_mul_f32 v[90:91], v[90:91], s[2:3] op_sel_hi:[1,0]
	v_pk_mul_f32 v[92:93], v[92:93], s[2:3] op_sel_hi:[1,0]
	v_pk_fma_f32 v[84:85], v[84:85], 0.5, v[90:91] op_sel_hi:[1,0,1]
	v_pk_fma_f32 v[82:83], v[82:83], 0.5, v[92:93] op_sel_hi:[1,0,1]
	v_add_f32_e32 v90, v84, v85
	v_add_f32_e32 v0, v82, v83
	v_add_f32_e32 v0, v0, v90
	v_mul_f32_e32 v90, v83, v83
	v_mul_f32_e32 v91, v85, v85
	v_add_f32_e32 v0, v94, v0
	v_fmac_f32_e32 v90, v82, v82
	v_fmac_f32_e32 v91, v84, v84
	s_nop 0
	s_nop 1
	v_bfe_u32 v93, v227, 4, 2
	v_sub_u32_e32 v92, 0, v93
	v_lshlrev_b32_e32 v92, 4, v92
	v_ashrrev_i32_e32 v93, 31, v92
	v_lshl_add_u64 v[92:93], v[124:125], 0, v[92:93]
	v_permlane16_swap_b32_e32 v86, v82
	v_permlane16_swap_b32_e32 v87, v83
	v_permlane16_swap_b32_e32 v88, v84
	v_permlane16_swap_b32_e32 v89, v85
	v_permlane32_swap_b32_e32 v86, v82
	v_permlane32_swap_b32_e32 v87, v83
	v_permlane32_swap_b32_e32 v88, v84
	v_permlane32_swap_b32_e32 v89, v85
	global_store_dwordx4 v[92:93], v[86:89], off offset:512
	global_store_dwordx4 v[92:93], v[82:85], off offset:576
	s_nop 1
	v_permlane32_swap_b32_e32 v86, v82
	v_permlane32_swap_b32_e32 v87, v83
	v_permlane32_swap_b32_e32 v88, v84
	v_permlane32_swap_b32_e32 v89, v85
	v_permlane16_swap_b32_e32 v86, v82
	v_permlane16_swap_b32_e32 v87, v83
	v_permlane16_swap_b32_e32 v88, v84
	v_permlane16_swap_b32_e32 v89, v85
	v_add_f32_e32 v90, v90, v91
	v_cvt_pk_bf16_f32 v86, v86, v87
	v_cvt_pk_bf16_f32 v87, v88, v89
	v_cvt_pk_bf16_f32 v88, v82, v83
	v_mov_b32_e32 v82, v0
	v_add_f32_e32 v90, v95, v90
	s_nop 0
	v_permlane16_swap_b32_e32 v0, v82
	v_add_f32_e32 v82, v0, v82
	v_mov_b32_e32 v0, v90
	s_nop 1
	v_permlane16_swap_b32_e32 v90, v0
	v_add_f32_e32 v83, v90, v0
	v_cvt_pk_bf16_f32 v89, v84, v85
	v_mov_b32_e32 v84, v82
	v_mov_b32_e32 v85, v83
	s_nop 0
	v_permlane32_swap_b32_e32 v82, v84
	v_permlane32_swap_b32_e32 v83, v85
	global_store_dwordx4 v122, v[86:89], s[42:43]
	s_and_saveexec_b64 s[26:27], s[44:45]
	s_cbranch_execz .LBB0_378
	v_pk_add_f32 v[82:83], v[82:83], v[84:85]
	v_lshl_add_u64 v[84:85], s[30:31], 0, v[164:165]
	v_lshl_add_u64 v[84:85], s[24:25], 2, v[84:85]
	global_store_dwordx2 v[84:85], v[82:83], off
; __device__ __forceinline__ float xsum16(float v) { const auto r = __builtin_amdgcn_permlane16_swap(__float_as_uint(v), __float_as_uint(v), false, false); return __uint_as_float(r[0]) + __uint_as_float(r[1]); }
; __device__ __forceinline__ float xsum32(float v) { const auto r = __builtin_amdgcn_permlane32_swap(__float_as_uint(v), __float_as_uint(v), false, false); return __uint_as_float(r[0]) + __uint_as_float(r[1]); }
; __device__ __forceinline__ size_t blk_off(int r, int c, int K) { return (size_t)(r >> 8) * 256 * K + (size_t)(c >> 6) * (256 * 64) + (size_t)((r & 255) * 64 + (c & 63)); }
; __device__ __forceinline__ u32x4 pack8(const f32x4 a, const f32x4 b) { u32x4 w; w.x = cvt_pk_bf16(a[0], a[1]); w.y = cvt_pk_bf16(a[2], a[3]); w.z = cvt_pk_bf16(b[0], b[1]); w.w = cvt_pk_bf16(b[2], b[3]); return w; }
; __device__ __forceinline__ void row_stats(const float* st, int row, int fq, float& mu, float& rstd) {
;     ...
;     mu = s1 * (1.0f / 1024.0f); const float var = fmaxf(s2 * (1.0f / 1024.0f) - mu * mu, 0.f); rstd = rsqrtf(var + LN_EPS_);
;     __device__ __forceinline__ void operator()(const f32x4 (&acc)[2][2][4][2], const pg8::Unit& u, int wr, int wc, int fr, int fq) const {
;     ...
;                     for (int n = 0; n < 2; ++n) { yv[bj][n] = *(const f32x4*)(Yin + (size_t)row * D_ + col0 + bj * 128 + 4 * n); gq[bj][n] = *(const f32x4*)(g + col0 + bj * 128 + 4 * n); bq_[bj][n] = *(const f32x4*)(b + col0 + bj * 128 + 4 * n); }
;                 asm volatile("" ::: "memory");
;                 float s1 = 0.f, s2 = 0.f;
; #pragma unroll
;                 for (int bj = 0; bj < 2; ++bj) { float* yp = Y + (size_t)row * D_ + col0 + bj * 128; f32x4 v[2];
; #pragma unroll
;                     for (int n = 0; n < 2; ++n) { v[n] = (((yv[bj][n] - mu) * rs) * gq[bj][n] + bq_[bj][n]) * ALPHA_ + acc[ai][bj][m][n] * sc;
;                         *(f32x4*)(yp + 4 * n) = v[n]; s1 += (v[n][0] + v[n][1]) + (v[n][2] + v[n][3]); s2 += (v[n][0] * v[n][0] + v[n][1] * v[n][1]) + (v[n][2] * v[n][2] + v[n][3] * v[n][3]); }
;                     *(u32x4*)(Yb + blk_off(row, col0 + bj * 128, D_)) = pack8(v[0], v[1]); }
;                 s1 = xsum32(xsum16(s1)); s2 = xsum32(xsum16(s2));
;                 if (fq == 0) *(f32x2*)(stn + (size_t)row * 32 + (u.pn * 4 + wc) * 2) = (f32x2){s1, s2}; asm volatile("" ::: "memory"); } }
.LBB0_378:
	s_or_b64 exec, exec, s[26:27]
	v_pk_add_f32 v[82:83], v[166:167], v[168:169]
	s_mov_b32 s2, 0x3a800000
	v_pk_mul_f32 v[106:107], v[82:83], s[2:3] op_sel_hi:[1,0]
	s_mov_b32 s2, 0x800000
	v_fma_f32 v0, -v107, v107, v106
	v_max_f32_e32 v0, 0, v0
	v_add_f32_e32 v0, 0x3727c5ac, v0
	v_cmp_gt_f32_e32 vcc, s2, v0
	v_mul_f32_e32 v82, 0x4b800000, v0
	v_lshlrev_b64 v[108:109], 12, v[162:163]
	v_cndmask_b32_e32 v0, v0, v82, vcc
	v_rsq_f32_e32 v0, v0
	s_load_dwordx16 s[60:75], s[34:35], 0x38
	v_lshlrev_b32_e32 v106, 6, v162
	v_mul_f32_e32 v82, 0x45800000, v0
	v_cndmask_b32_e32 v0, v0, v82, vcc
	v_lshl_add_u64 v[82:83], s[12:13], 0, v[108:109]
	v_lshl_add_u64 v[86:87], v[82:83], 0, v[152:153]
	global_load_dwordx4 v[110:113], v[86:87], off offset:16 nt
	global_load_dwordx4 v[114:117], v[86:87], off nt
	global_load_dwordx4 v[118:121], v[154:155], off offset:16
	global_load_dwordx4 v[122:125], v[154:155], off
	global_load_dwordx4 v[126:129], v[156:157], off offset:16
	global_load_dwordx4 v[130:133], v[156:157], off
	global_load_dwordx4 v[82:85], v[86:87], off offset:528 nt
	global_load_dwordx4 v[102:105], v[86:87], off offset:512 nt
	s_nop 0
	global_load_dwordx4 v[86:89], v[154:155], off offset:528
	global_load_dwordx4 v[94:97], v[154:155], off offset:512
	global_load_dwordx4 v[90:93], v[156:157], off offset:528
	global_load_dwordx4 v[98:101], v[156:157], off offset:512
	s_movk_i32 s2, 0x3fc0
	v_and_or_b32 v106, v106, s2, v194
	s_mov_b32 s2, 0x3fd744fd
	s_waitcnt lgkmcnt(0)
	v_lshl_add_u64 v[108:109], s[74:75], 0, v[108:109]
	v_lshl_add_u64 v[108:109], v[108:109], 0, v[152:153]
	v_lshlrev_b32_e32 v106, 1, v106
	s_waitcnt vmcnt(11)
	v_sub_f32_e32 v113, v113, v107
	s_waitcnt vmcnt(10)
	v_sub_f32_e32 v117, v117, v107
	v_sub_f32_e32 v116, v116, v107
	v_sub_f32_e32 v115, v115, v107
	v_sub_f32_e32 v114, v114, v107
	v_sub_f32_e32 v112, v112, v107
	v_sub_f32_e32 v111, v111, v107
	v_sub_f32_e32 v110, v110, v107
	v_pk_mul_f32 v[114:115], v[0:1], v[114:115] op_sel_hi:[0,1]
	v_pk_mul_f32 v[116:117], v[0:1], v[116:117] op_sel_hi:[0,1]
	v_pk_mul_f32 v[110:111], v[0:1], v[110:111] op_sel_hi:[0,1]
	v_pk_mul_f32 v[112:113], v[0:1], v[112:113] op_sel_hi:[0,1]
	s_waitcnt vmcnt(6)
	v_pk_fma_f32 v[116:117], v[124:125], v[116:117], v[132:133]
	v_pk_fma_f32 v[114:115], v[122:123], v[114:115], v[130:131]
	v_pk_fma_f32 v[112:113], v[120:121], v[112:113], v[128:129]
	v_pk_fma_f32 v[110:111], v[118:119], v[110:111], v[126:127]
	v_pk_mul_f32 v[114:115], v[114:115], s[2:3] op_sel_hi:[1,0]
	v_pk_mul_f32 v[116:117], v[116:117], s[2:3] op_sel_hi:[1,0]
	v_pk_mul_f32 v[110:111], v[110:111], s[2:3] op_sel_hi:[1,0]
	v_pk_mul_f32 v[112:113], v[112:113], s[2:3] op_sel_hi:[1,0]
	v_pk_fma_f32 v[80:81], v[80:81], 0.5, v[116:117] op_sel_hi:[1,0,1]
	v_pk_fma_f32 v[78:79], v[78:79], 0.5, v[114:115] op_sel_hi:[1,0,1]
	v_pk_fma_f32 v[76:77], v[76:77], 0.5, v[112:113] op_sel_hi:[1,0,1]
	v_pk_fma_f32 v[74:75], v[74:75], 0.5, v[110:111] op_sel_hi:[1,0,1]
	v_add_f32_e32 v114, v78, v79
	v_add_f32_e32 v115, v80, v81
	v_add_f32_e32 v110, v74, v75
	v_add_f32_e32 v111, v76, v77
	v_add_f32_e32 v114, v114, v115
	v_mul_f32_e32 v115, v79, v79
	v_mul_f32_e32 v116, v81, v81
	v_add_f32_e32 v110, v110, v111
	v_mul_f32_e32 v111, v75, v75
	v_mul_f32_e32 v112, v77, v77
	s_nop 0
	v_fmac_f32_e32 v115, v78, v78
	v_fmac_f32_e32 v116, v80, v80
	s_nop 1
	v_bfe_u32 v119, v227, 4, 2
	v_sub_u32_e32 v118, 0, v119
	v_lshlrev_b32_e32 v118, 4, v118
	v_ashrrev_i32_e32 v119, 31, v118
	v_lshl_add_u64 v[118:119], v[108:109], 0, v[118:119]
	v_permlane16_swap_b32_e32 v78, v74
	v_permlane16_swap_b32_e32 v79, v75
	v_permlane16_swap_b32_e32 v80, v76
	v_permlane16_swap_b32_e32 v81, v77
	v_permlane32_swap_b32_e32 v78, v74
	v_permlane32_swap_b32_e32 v79, v75
	v_permlane32_swap_b32_e32 v80, v76
	v_permlane32_swap_b32_e32 v81, v77
	global_store_dwordx4 v[118:119], v[78:81], off
	global_store_dwordx4 v[118:119], v[74:77], off offset:64
	s_nop 1
	v_permlane32_swap_b32_e32 v78, v74
	v_permlane32_swap_b32_e32 v79, v75
	v_permlane32_swap_b32_e32 v80, v76
	v_permlane32_swap_b32_e32 v81, v77
	v_permlane16_swap_b32_e32 v78, v74
	v_permlane16_swap_b32_e32 v79, v75
	v_permlane16_swap_b32_e32 v80, v76
	v_permlane16_swap_b32_e32 v81, v77
	v_fmac_f32_e32 v111, v74, v74
	v_fmac_f32_e32 v112, v76, v76
	v_cvt_pk_bf16_f32 v78, v78, v79
	v_cvt_pk_bf16_f32 v79, v80, v81
	v_cvt_pk_bf16_f32 v80, v74, v75
	v_cvt_pk_bf16_f32 v81, v76, v77
	s_waitcnt vmcnt(6)
	v_sub_f32_e32 v75, v105, v107
	v_sub_f32_e32 v74, v104, v107
	v_sub_f32_e32 v77, v103, v107
	v_sub_f32_e32 v76, v102, v107
	v_pk_mul_f32 v[76:77], v[0:1], v[76:77] op_sel_hi:[0,1]
	v_pk_mul_f32 v[74:75], v[0:1], v[74:75] op_sel_hi:[0,1]
	s_waitcnt vmcnt(2)
; __device__ __forceinline__ float xsum16(float v) { const auto r = __builtin_amdgcn_permlane16_swap(__float_as_uint(v), __float_as_uint(v), false, false); return __uint_as_float(r[0]) + __uint_as_float(r[1]); }
; __device__ __forceinline__ float xsum32(float v) { const auto r = __builtin_amdgcn_permlane32_swap(__float_as_uint(v), __float_as_uint(v), false, false); return __uint_as_float(r[0]) + __uint_as_float(r[1]); }
; __device__ __forceinline__ void row_stats4(const float* st, int rowb, int fq, float (&mu)[4], float (&rs)[4]) {
;     f32x4 a[4], b[4];
; #pragma unroll
;     for (int m = 0; m < 4; ++m) { const f32x4* p = (const f32x4*)(st + (size_t)(rowb + m * 16) * 32 + fq * 8); a[m] = p[0]; b[m] = p[1]; }
; #pragma unroll
;     for (int m = 0; m < 4; ++m) { float s1 = (a[m][0] + a[m][2]) + (b[m][0] + b[m][2]), s2 = (a[m][1] + a[m][3]) + (b[m][1] + b[m][3]);
;         s1 = xsum32(xsum16(s1)); s2 = xsum32(xsum16(s2));
;         const float mm = s1 * (1.0f / 1024.0f); mu[m] = mm; rs[m] = rsqrtf(fmaxf(s2 * (1.0f / 1024.0f) - mm * mm, 0.f) + LN_EPS_); }
;     __device__ __forceinline__ void operator()(const f32x4 (&acc)[2][2][4][2], const pg8::Unit& u, int wr, int wc, int fr, int fq) const {
;     ...
;                     for (int n = 0; n < 2; ++n) { yv[bj][n] = *(const f32x4*)(Yin + (size_t)row * D_ + col0 + bj * 128 + 4 * n); gq[bj][n] = *(const f32x4*)(g + col0 + bj * 128 + 4 * n); bq_[bj][n] = *(const f32x4*)(b + col0 + bj * 128 + 4 * n); }
;                 asm volatile("" ::: "memory");
;                 float s1 = 0.f, s2 = 0.f;
; #pragma unroll
;                 for (int bj = 0; bj < 2; ++bj) { float* yp = Y + (size_t)row * D_ + col0 + bj * 128; f32x4 v[2];
; #pragma unroll
;                     for (int n = 0; n < 2; ++n) { v[n] = (((yv[bj][n] - mu) * rs) * gq[bj][n] + bq_[bj][n]) * ALPHA_ + acc[ai][bj][m][n] * sc;
;                         *(f32x4*)(yp + 4 * n) = v[n]; s1 += (v[n][0] + v[n][1]) + (v[n][2] + v[n][3]); s2 += (v[n][0] * v[n][0] + v[n][1] * v[n][1]) + (v[n][2] * v[n][2] + v[n][3] * v[n][3]); }
;                     *(u32x4*)(Yb + blk_off(row, col0 + bj * 128, D_)) = pack8(v[0], v[1]); }
;                 s1 = xsum32(xsum16(s1)); s2 = xsum32(xsum16(s2));
;                 if (fq == 0) *(f32x2*)(stn + (size_t)row * 32 + (u.pn * 4 + wc) * 2) = (f32x2){s1, s2}; asm volatile("" ::: "memory"); } }
	v_pk_fma_f32 v[74:75], v[96:97], v[74:75], v[100:101]
	v_pk_fma_f32 v[76:77], v[94:95], v[76:77], v[98:99]
	v_pk_mul_f32 v[74:75], v[74:75], s[2:3] op_sel_hi:[1,0]
	v_pk_mul_f32 v[76:77], v[76:77], s[2:3] op_sel_hi:[1,0]
	v_pk_fma_f32 v[72:73], v[72:73], 0.5, v[74:75] op_sel_hi:[1,0,1]
	v_pk_fma_f32 v[70:71], v[70:71], 0.5, v[76:77] op_sel_hi:[1,0,1]
	v_add_f32_e32 v114, 0, v114
	v_add_f32_e32 v74, v70, v71
	v_add_f32_e32 v75, v72, v73
	v_add_f32_e32 v110, v114, v110
	v_add_f32_e32 v74, v74, v75
	global_store_dwordx4 v106, v[78:81], s[50:51]
	v_mul_f32_e32 v75, v73, v73
	v_add_f32_e32 v115, v115, v116
	v_add_f32_e32 v78, v110, v74
	v_mul_f32_e32 v74, v71, v71
	v_add_f32_e32 v111, v111, v112
	v_fmac_f32_e32 v74, v70, v70
	v_fmac_f32_e32 v75, v72, v72
	v_add_f32_e32 v111, v115, v111
	v_add_f32_e32 v74, v74, v75
	v_add_f32_e32 v79, v111, v74
	v_sub_f32_e32 v75, v85, v107
	v_sub_f32_e32 v74, v84, v107
	v_sub_f32_e32 v77, v83, v107
	v_sub_f32_e32 v76, v82, v107
	v_pk_mul_f32 v[76:77], v[0:1], v[76:77] op_sel_hi:[0,1]
	v_pk_mul_f32 v[74:75], v[0:1], v[74:75] op_sel_hi:[0,1]
	v_pk_fma_f32 v[74:75], v[88:89], v[74:75], v[92:93]
	v_pk_fma_f32 v[76:77], v[86:87], v[76:77], v[90:91]
	v_pk_mul_f32 v[74:75], v[74:75], s[2:3] op_sel_hi:[1,0]
	v_pk_mul_f32 v[76:77], v[76:77], s[2:3] op_sel_hi:[1,0]
	v_pk_fma_f32 v[68:69], v[68:69], 0.5, v[74:75] op_sel_hi:[1,0,1]
	v_pk_fma_f32 v[66:67], v[66:67], 0.5, v[76:77] op_sel_hi:[1,0,1]
	v_add_f32_e32 v74, v68, v69
	v_add_f32_e32 v0, v66, v67
	v_add_f32_e32 v0, v0, v74
	v_mul_f32_e32 v74, v67, v67
	v_mul_f32_e32 v75, v69, v69
	v_add_f32_e32 v0, v78, v0
	v_fmac_f32_e32 v74, v66, v66
	v_fmac_f32_e32 v75, v68, v68
	s_nop 0
	s_nop 1
	v_bfe_u32 v77, v227, 4, 2
	v_sub_u32_e32 v76, 0, v77
	v_lshlrev_b32_e32 v76, 4, v76
	v_ashrrev_i32_e32 v77, 31, v76
	v_lshl_add_u64 v[76:77], v[108:109], 0, v[76:77]
	v_permlane16_swap_b32_e32 v70, v66
	v_permlane16_swap_b32_e32 v71, v67
	v_permlane16_swap_b32_e32 v72, v68
	v_permlane16_swap_b32_e32 v73, v69
	v_permlane32_swap_b32_e32 v70, v66
	v_permlane32_swap_b32_e32 v71, v67
	v_permlane32_swap_b32_e32 v72, v68
	v_permlane32_swap_b32_e32 v73, v69
	global_store_dwordx4 v[76:77], v[70:73], off offset:512
	global_store_dwordx4 v[76:77], v[66:69], off offset:576
	s_nop 1
	v_permlane32_swap_b32_e32 v70, v66
	v_permlane32_swap_b32_e32 v71, v67
	v_permlane32_swap_b32_e32 v72, v68
	v_permlane32_swap_b32_e32 v73, v69
	v_permlane16_swap_b32_e32 v70, v66
	v_permlane16_swap_b32_e32 v71, v67
	v_permlane16_swap_b32_e32 v72, v68
	v_permlane16_swap_b32_e32 v73, v69
	v_add_f32_e32 v74, v74, v75
	v_cvt_pk_bf16_f32 v70, v70, v71
	v_cvt_pk_bf16_f32 v71, v72, v73
	v_cvt_pk_bf16_f32 v72, v66, v67
	v_mov_b32_e32 v66, v0
	v_add_f32_e32 v74, v79, v74
	s_nop 0
	v_permlane16_swap_b32_e32 v0, v66
	v_add_f32_e32 v66, v0, v66
	v_mov_b32_e32 v0, v74
	s_nop 1
	v_permlane16_swap_b32_e32 v74, v0
	v_add_f32_e32 v67, v74, v0
	v_cvt_pk_bf16_f32 v73, v68, v69
	v_mov_b32_e32 v68, v66
	v_mov_b32_e32 v69, v67
	s_nop 0
	v_permlane32_swap_b32_e32 v66, v68
	v_permlane32_swap_b32_e32 v67, v69
	global_store_dwordx4 v106, v[70:73], s[42:43]
	s_and_saveexec_b64 s[26:27], s[44:45]
	s_cbranch_execz .LBB0_380
	v_pk_add_f32 v[66:67], v[66:67], v[68:69]
	v_lshl_add_u64 v[68:69], s[30:31], 0, v[160:161]
	v_lshl_add_u64 v[68:69], s[24:25], 2, v[68:69]
	global_store_dwordx2 v[68:69], v[66:67], off
.LBB0_380:
	s_or_b64 exec, exec, s[26:27]
	v_add_u32_e32 v68, 0x80, v158
	v_ashrrev_i32_e32 v69, 31, v68
	v_add_u32_e32 v94, 0x90, v158
	v_lshlrev_b64 v[66:67], 7, v[68:69]
	v_ashrrev_i32_e32 v95, 31, v94
	v_lshl_add_u64 v[74:75], v[146:147], 0, v[66:67]
	v_lshlrev_b64 v[86:87], 7, v[94:95]
	v_add_u32_e32 v76, 0xa0, v158
	global_load_dwordx4 v[70:73], v[74:75], off nt
	global_load_dwordx4 v[78:81], v[74:75], off offset:16 nt
	v_lshl_add_u64 v[74:75], v[146:147], 0, v[86:87]
	v_ashrrev_i32_e32 v77, 31, v76
	global_load_dwordx4 v[82:85], v[74:75], off nt
	global_load_dwordx4 v[88:91], v[74:75], off offset:16 nt
	v_lshlrev_b64 v[74:75], 7, v[76:77]
	v_lshl_add_u64 v[74:75], v[146:147], 0, v[74:75]
	global_load_dwordx4 v[96:99], v[74:75], off nt
	global_load_dwordx4 v[100:103], v[74:75], off offset:16 nt
	v_add_u32_e32 v74, 0xb0, v158
	v_ashrrev_i32_e32 v75, 31, v74
	v_lshlrev_b64 v[92:93], 7, v[74:75]
	v_lshl_add_u64 v[92:93], v[146:147], 0, v[92:93]
	global_load_dwordx4 v[104:107], v[92:93], off nt
	global_load_dwordx4 v[108:111], v[92:93], off offset:16 nt
	v_lshlrev_b64 v[136:137], 12, v[68:69]
	v_lshl_add_u64 v[112:113], s[12:13], 0, v[136:137]
	v_lshl_add_u64 v[92:93], v[112:113], 0, v[152:153]
	global_load_dwordx4 v[112:115], v[92:93], off offset:16 nt
	global_load_dwordx4 v[116:119], v[92:93], off nt
	global_load_dwordx4 v[120:123], v[154:155], off offset:16
	global_load_dwordx4 v[124:127], v[154:155], off
	global_load_dwordx4 v[128:131], v[156:157], off offset:16
	global_load_dwordx4 v[132:135], v[156:157], off
	s_mov_b32 s2, 0x3a800000
	s_mov_b32 s16, 0x3fd744fd
	s_load_dwordx16 s[60:75], s[34:35], 0x38
	s_waitcnt vmcnt(13)
	v_mov_b32_e32 v158, v70
	s_waitcnt vmcnt(12)
	v_mov_b32_e32 v159, v78
	v_mov_b32_e32 v160, v72
	v_mov_b32_e32 v161, v80
	v_mov_b32_e32 v78, v71
	v_mov_b32_e32 v80, v73
	s_waitcnt vmcnt(11)
	v_mov_b32_e32 v70, v82
	s_waitcnt vmcnt(10)
	v_mov_b32_e32 v71, v88
	v_mov_b32_e32 v72, v84
	v_mov_b32_e32 v73, v90
	v_mov_b32_e32 v88, v83
	v_mov_b32_e32 v90, v85
	s_waitcnt vmcnt(9)
	v_mov_b32_e32 v82, v96
	s_waitcnt vmcnt(8)
; __device__ __forceinline__ float xsum16(float v) { const auto r = __builtin_amdgcn_permlane16_swap(__float_as_uint(v), __float_as_uint(v), false, false); return __uint_as_float(r[0]) + __uint_as_float(r[1]); }
; __device__ __forceinline__ float xsum32(float v) { const auto r = __builtin_amdgcn_permlane32_swap(__float_as_uint(v), __float_as_uint(v), false, false); return __uint_as_float(r[0]) + __uint_as_float(r[1]); }
; __device__ __forceinline__ void row_stats4(const float* st, int rowb, int fq, float (&mu)[4], float (&rs)[4]) {
;     f32x4 a[4], b[4];
; #pragma unroll
;     for (int m = 0; m < 4; ++m) { const f32x4* p = (const f32x4*)(st + (size_t)(rowb + m * 16) * 32 + fq * 8); a[m] = p[0]; b[m] = p[1]; }
; #pragma unroll
;     for (int m = 0; m < 4; ++m) { float s1 = (a[m][0] + a[m][2]) + (b[m][0] + b[m][2]), s2 = (a[m][1] + a[m][3]) + (b[m][1] + b[m][3]);
;         s1 = xsum32(xsum16(s1)); s2 = xsum32(xsum16(s2));
;         const float mm = s1 * (1.0f / 1024.0f); mu[m] = mm; rs[m] = rsqrtf(fmaxf(s2 * (1.0f / 1024.0f) - mm * mm, 0.f) + LN_EPS_); }
;     __device__ __forceinline__ void operator()(const f32x4 (&acc)[2][2][4][2], const pg8::Unit& u, int wr, int wc, int fr, int fq) const {
;     ...
;                     for (int n = 0; n < 2; ++n) { yv[bj][n] = *(const f32x4*)(Yin + (size_t)row * D_ + col0 + bj * 128 + 4 * n); gq[bj][n] = *(const f32x4*)(g + col0 + bj * 128 + 4 * n); bq_[bj][n] = *(const f32x4*)(b + col0 + bj * 128 + 4 * n); }
;                 asm volatile("" ::: "memory");
;                 float s1 = 0.f, s2 = 0.f;
; #pragma unroll
;                 for (int bj = 0; bj < 2; ++bj) { float* yp = Y + (size_t)row * D_ + col0 + bj * 128; f32x4 v[2];
; #pragma unroll
;                     for (int n = 0; n < 2; ++n) { v[n] = (((yv[bj][n] - mu) * rs) * gq[bj][n] + bq_[bj][n]) * ALPHA_ + acc[ai][bj][m][n] * sc;
;                         *(f32x4*)(yp + 4 * n) = v[n]; s1 += (v[n][0] + v[n][1]) + (v[n][2] + v[n][3]); s2 += (v[n][0] * v[n][0] + v[n][1] * v[n][1]) + (v[n][2] * v[n][2] + v[n][3] * v[n][3]); }
;                     *(u32x4*)(Yb + blk_off(row, col0 + bj * 128, D_)) = pack8(v[0], v[1]); }
;                 s1 = xsum32(xsum16(s1)); s2 = xsum32(xsum16(s2));
;                 if (fq == 0) *(f32x2*)(stn + (size_t)row * 32 + (u.pn * 4 + wc) * 2) = (f32x2){s1, s2}; asm volatile("" ::: "memory"); } }
	v_mov_b32_e32 v83, v100
	v_mov_b32_e32 v84, v98
	v_mov_b32_e32 v85, v102
	v_mov_b32_e32 v100, v97
	v_pk_add_f32 v[96:97], v[158:159], v[160:161]
	v_pk_add_f32 v[78:79], v[78:79], v[80:81]
	v_pk_add_f32 v[80:81], v[82:83], v[84:85]
	v_pk_add_f32 v[84:85], v[96:97], v[96:97] op_sel:[0,1] op_sel_hi:[1,0]
	v_pk_add_f32 v[78:79], v[78:79], v[78:79] op_sel:[0,1] op_sel_hi:[1,0]
	v_mov_b32_e32 v0, v84
	v_mov_b32_e32 v69, v78
	s_nop 0
	v_permlane16_swap_b32_e32 v84, v0
	v_permlane16_swap_b32_e32 v78, v69
	v_add_f32_e32 v79, v84, v0
	v_add_f32_e32 v78, v78, v69
	v_mov_b32_e32 v85, v79
	v_mov_b32_e32 v84, v78
	s_nop 0
	v_permlane32_swap_b32_e32 v79, v85
	v_permlane32_swap_b32_e32 v78, v84
	v_pk_add_f32 v[78:79], v[78:79], v[84:85]
	v_mov_b32_e32 v102, v99
	v_pk_mul_f32 v[78:79], v[78:79], s[2:3] op_sel_hi:[1,0]
	s_mov_b32 s2, 0x800000
	v_fma_f32 v0, -v79, v79, v78
	v_max_f32_e32 v0, 0, v0
	v_add_f32_e32 v0, 0x3727c5ac, v0
	v_mul_f32_e32 v69, 0x4b800000, v0
	v_cmp_gt_f32_e32 vcc, s2, v0
	v_pk_add_f32 v[82:83], v[100:101], v[102:103]
	v_pk_add_f32 v[80:81], v[80:81], v[80:81] op_sel:[0,1] op_sel_hi:[1,0]
	v_cndmask_b32_e32 v0, v0, v69, vcc
	v_rsq_f32_e32 v0, v0
	v_pk_add_f32 v[82:83], v[82:83], v[82:83] op_sel:[0,1] op_sel_hi:[1,0]
	v_mov_b32_e32 v81, v80
	s_nop 1
	v_permlane16_swap_b32_e32 v80, v81
	v_mul_f32_e32 v69, 0x45800000, v0
	v_cndmask_b32_e32 v78, v0, v69, vcc
	v_mov_b32_e32 v0, v82
	s_nop 1
	v_permlane16_swap_b32_e32 v82, v0
	global_load_dwordx4 v[96:99], v[92:93], off offset:528 nt
	global_load_dwordx4 v[100:103], v[92:93], off offset:512 nt
	v_pk_add_f32 v[70:71], v[70:71], v[72:73]
	v_pk_add_f32 v[72:73], v[88:89], v[90:91]
	v_add_f32_e32 v89, v80, v81
	v_add_f32_e32 v88, v82, v0
	s_waitcnt vmcnt(9)
	v_mov_b32_e32 v80, v104
	s_waitcnt vmcnt(8)
	v_mov_b32_e32 v81, v108
	v_mov_b32_e32 v82, v106
	v_mov_b32_e32 v83, v110
	v_mov_b32_e32 v108, v105
	v_mov_b32_e32 v110, v107
	v_pk_add_f32 v[80:81], v[80:81], v[82:83]
	v_pk_add_f32 v[82:83], v[108:109], v[110:111]
	global_load_dwordx4 v[104:107], v[154:155], off offset:528
	global_load_dwordx4 v[108:111], v[154:155], off offset:512
	global_load_dwordx4 v[158:161], v[156:157], off offset:528
	global_load_dwordx4 v[162:165], v[156:157], off offset:512
	s_waitcnt vmcnt(10)
	v_sub_f32_e32 v93, v119, v79
	v_sub_f32_e32 v92, v118, v79
	v_sub_f32_e32 v117, v117, v79
	v_sub_f32_e32 v116, v116, v79
	v_pk_mul_f32 v[116:117], v[78:79], v[116:117] op_sel_hi:[0,1]
	v_pk_mul_f32 v[92:93], v[78:79], v[92:93] op_sel_hi:[0,1]
	s_waitcnt vmcnt(6)
	v_pk_fma_f32 v[92:93], v[126:127], v[92:93], v[134:135]
	v_pk_fma_f32 v[116:117], v[124:125], v[116:117], v[132:133]
	v_pk_mul_f32 v[92:93], v[92:93], s[16:17] op_sel_hi:[1,0]
	v_pk_mul_f32 v[116:117], v[116:117], s[16:17] op_sel_hi:[1,0]
	v_pk_fma_f32 v[64:65], v[64:65], 0.5, v[92:93] op_sel_hi:[1,0,1]
	v_pk_fma_f32 v[62:63], v[62:63], 0.5, v[116:117] op_sel_hi:[1,0,1]
	v_add_f32_e32 v93, v64, v65
	v_add_f32_e32 v92, v62, v63
	v_add_f32_e32 v92, v92, v93
	v_add_f32_e32 v116, 0, v92
	v_mul_f32_e32 v92, v63, v63
	v_mul_f32_e32 v93, v65, v65
	v_pk_add_f32 v[80:81], v[80:81], v[80:81] op_sel:[0,1] op_sel_hi:[1,0]
	v_fmac_f32_e32 v92, v62, v62
	v_fmac_f32_e32 v93, v64, v64
	v_mov_b32_e32 v0, v80
	v_add_f32_e32 v117, v92, v93
	v_sub_f32_e32 v93, v115, v79
	v_sub_f32_e32 v92, v114, v79
	v_sub_f32_e32 v113, v113, v79
	v_sub_f32_e32 v112, v112, v79
	v_pk_add_f32 v[82:83], v[82:83], v[82:83] op_sel:[0,1] op_sel_hi:[1,0]
	v_permlane16_swap_b32_e32 v80, v0
	v_pk_mul_f32 v[112:113], v[78:79], v[112:113] op_sel_hi:[0,1]
	v_pk_mul_f32 v[92:93], v[78:79], v[92:93] op_sel_hi:[0,1]
	v_add_f32_e32 v83, v80, v0
	v_mov_b32_e32 v0, v82
	v_pk_fma_f32 v[92:93], v[122:123], v[92:93], v[130:131]
	v_pk_fma_f32 v[112:113], v[120:121], v[112:113], v[128:129]
	v_permlane16_swap_b32_e32 v82, v0
	v_pk_mul_f32 v[112:113], v[112:113], s[16:17] op_sel_hi:[1,0]
	v_pk_mul_f32 v[92:93], v[92:93], s[16:17] op_sel_hi:[1,0]
	v_add_f32_e32 v82, v82, v0
	v_ashrrev_i32_e32 v80, 8, v68
	v_lshlrev_b32_e32 v0, 6, v68
	s_movk_i32 s2, 0x33c0
	v_pk_fma_f32 v[60:61], v[60:61], 0.5, v[92:93] op_sel_hi:[1,0,1]
	v_pk_fma_f32 v[58:59], v[58:59], 0.5, v[112:113] op_sel_hi:[1,0,1]
	v_ashrrev_i32_e32 v81, 31, v80
	v_and_or_b32 v0, v0, s2, v194
	s_waitcnt lgkmcnt(0)
	v_lshl_add_u64 v[68:69], s[74:75], 0, v[136:137]
	v_add_f32_e32 v92, v58, v59
	v_add_f32_e32 v93, v60, v61
	v_readlane_b32 s2, v253, 59
	v_lshlrev_b64 v[80:81], 19, v[80:81]
	v_lshl_add_u64 v[68:69], v[68:69], 0, v[152:153]
	v_add_f32_e32 v92, v92, v93
	v_mul_f32_e32 v93, v59, v59
	v_readlane_b32 s3, v253, 60
	s_nop 0
	s_nop 1
	v_bfe_u32 v85, v227, 4, 2
	v_sub_u32_e32 v84, 0, v85
	v_lshlrev_b32_e32 v84, 4, v84
	v_ashrrev_i32_e32 v85, 31, v84
	v_lshl_add_u64 v[84:85], v[68:69], 0, v[84:85]
	v_permlane16_swap_b32_e32 v62, v58
	v_permlane16_swap_b32_e32 v63, v59
	v_permlane16_swap_b32_e32 v64, v60
	v_permlane16_swap_b32_e32 v65, v61
	v_permlane32_swap_b32_e32 v62, v58
	v_permlane32_swap_b32_e32 v63, v59
	v_permlane32_swap_b32_e32 v64, v60
	v_permlane32_swap_b32_e32 v65, v61
	global_store_dwordx4 v[84:85], v[62:65], off
	global_store_dwordx4 v[84:85], v[58:61], off offset:64
	s_nop 1
	v_permlane32_swap_b32_e32 v62, v58
	v_permlane32_swap_b32_e32 v63, v59
	v_permlane32_swap_b32_e32 v64, v60
	v_permlane32_swap_b32_e32 v65, v61
	v_permlane16_swap_b32_e32 v62, v58
	v_permlane16_swap_b32_e32 v63, v59
	v_permlane16_swap_b32_e32 v64, v60
	v_permlane16_swap_b32_e32 v65, v61
	v_fmac_f32_e32 v93, v58, v58
	v_cvt_pk_bf16_f32 v62, v62, v63
	v_cvt_pk_bf16_f32 v63, v64, v65
	v_cvt_pk_bf16_f32 v64, v58, v59
	v_lshl_add_u64 v[58:59], s[2:3], 0, v[80:81]
	v_mul_f32_e32 v112, v61, v61
	v_lshl_add_u64 v[80:81], v[58:59], 0, s[28:29]
	v_lshlrev_b32_e32 v0, 1, v0
	v_fmac_f32_e32 v112, v60, v60
	v_cvt_pk_bf16_f32 v65, v60, v61
	v_lshl_add_u64 v[60:61], v[80:81], 0, v[0:1]
	global_store_dwordx4 v[60:61], v[62:65], off
	s_waitcnt vmcnt(7)
; __device__ __forceinline__ float xsum16(float v) { const auto r = __builtin_amdgcn_permlane16_swap(__float_as_uint(v), __float_as_uint(v), false, false); return __uint_as_float(r[0]) + __uint_as_float(r[1]); }
; __device__ __forceinline__ float xsum32(float v) { const auto r = __builtin_amdgcn_permlane32_swap(__float_as_uint(v), __float_as_uint(v), false, false); return __uint_as_float(r[0]) + __uint_as_float(r[1]); }
; __device__ __forceinline__ size_t blk_off(int r, int c, int K) { return (size_t)(r >> 8) * 256 * K + (size_t)(c >> 6) * (256 * 64) + (size_t)((r & 255) * 64 + (c & 63)); }
; __device__ __forceinline__ u32x4 pack8(const f32x4 a, const f32x4 b) { u32x4 w; w.x = cvt_pk_bf16(a[0], a[1]); w.y = cvt_pk_bf16(a[2], a[3]); w.z = cvt_pk_bf16(b[0], b[1]); w.w = cvt_pk_bf16(b[2], b[3]); return w; }
;     __device__ __forceinline__ void operator()(const f32x4 (&acc)[2][2][4][2], const pg8::Unit& u, int wr, int wc, int fr, int fq) const {
;     ...
;                     for (int n = 0; n < 2; ++n) { yv[bj][n] = *(const f32x4*)(Yin + (size_t)row * D_ + col0 + bj * 128 + 4 * n); gq[bj][n] = *(const f32x4*)(g + col0 + bj * 128 + 4 * n); bq_[bj][n] = *(const f32x4*)(b + col0 + bj * 128 + 4 * n); }
;                 asm volatile("" ::: "memory");
;                 float s1 = 0.f, s2 = 0.f;
; #pragma unroll
;                 for (int bj = 0; bj < 2; ++bj) { float* yp = Y + (size_t)row * D_ + col0 + bj * 128; f32x4 v[2];
; #pragma unroll
;                     for (int n = 0; n < 2; ++n) { v[n] = (((yv[bj][n] - mu) * rs) * gq[bj][n] + bq_[bj][n]) * ALPHA_ + acc[ai][bj][m][n] * sc;
;                         *(f32x4*)(yp + 4 * n) = v[n]; s1 += (v[n][0] + v[n][1]) + (v[n][2] + v[n][3]); s2 += (v[n][0] * v[n][0] + v[n][1] * v[n][1]) + (v[n][2] * v[n][2] + v[n][3] * v[n][3]); }
;                     *(u32x4*)(Yb + blk_off(row, col0 + bj * 128, D_)) = pack8(v[0], v[1]); }
;                 s1 = xsum32(xsum16(s1)); s2 = xsum32(xsum16(s2));
;                 if (fq == 0) *(f32x2*)(stn + (size_t)row * 32 + (u.pn * 4 + wc) * 2) = (f32x2){s1, s2}; asm volatile("" ::: "memory"); } }
	v_sub_f32_e32 v61, v103, v79
	v_sub_f32_e32 v60, v102, v79
	v_sub_f32_e32 v63, v101, v79
	v_sub_f32_e32 v62, v100, v79
	v_pk_mul_f32 v[62:63], v[78:79], v[62:63] op_sel_hi:[0,1]
	v_pk_mul_f32 v[60:61], v[78:79], v[60:61] op_sel_hi:[0,1]
	v_add_f32_e32 v92, v116, v92
	s_waitcnt vmcnt(3)
	v_pk_fma_f32 v[60:61], v[110:111], v[60:61], v[164:165]
	v_pk_fma_f32 v[62:63], v[108:109], v[62:63], v[162:163]
	v_pk_mul_f32 v[60:61], v[60:61], s[16:17] op_sel_hi:[1,0]
	v_pk_mul_f32 v[62:63], v[62:63], s[16:17] op_sel_hi:[1,0]
	v_pk_fma_f32 v[56:57], v[56:57], 0.5, v[60:61] op_sel_hi:[1,0,1]
	v_pk_fma_f32 v[54:55], v[54:55], 0.5, v[62:63] op_sel_hi:[1,0,1]
	v_add_f32_e32 v61, v56, v57
	v_add_f32_e32 v60, v54, v55
	v_add_f32_e32 v60, v60, v61
	v_add_f32_e32 v64, v92, v60
	v_mul_f32_e32 v60, v55, v55
	v_mul_f32_e32 v61, v57, v57
	v_add_f32_e32 v93, v93, v112
	v_fmac_f32_e32 v60, v54, v54
	v_fmac_f32_e32 v61, v56, v56
	v_add_f32_e32 v93, v117, v93
	v_add_f32_e32 v60, v60, v61
	v_add_f32_e32 v65, v93, v60
	v_sub_f32_e32 v61, v99, v79
	v_sub_f32_e32 v60, v98, v79
	v_sub_f32_e32 v63, v97, v79
	v_sub_f32_e32 v62, v96, v79
	v_pk_mul_f32 v[62:63], v[78:79], v[62:63] op_sel_hi:[0,1]
	v_pk_mul_f32 v[60:61], v[78:79], v[60:61] op_sel_hi:[0,1]
	v_pk_fma_f32 v[60:61], v[106:107], v[60:61], v[160:161]
	v_pk_fma_f32 v[62:63], v[104:105], v[62:63], v[158:159]
	v_pk_mul_f32 v[60:61], v[60:61], s[16:17] op_sel_hi:[1,0]
	v_pk_mul_f32 v[62:63], v[62:63], s[16:17] op_sel_hi:[1,0]
	v_pk_fma_f32 v[52:53], v[52:53], 0.5, v[60:61] op_sel_hi:[1,0,1]
	v_pk_fma_f32 v[50:51], v[50:51], 0.5, v[62:63] op_sel_hi:[1,0,1]
	v_add_f32_e32 v61, v52, v53
	v_add_f32_e32 v60, v50, v51
	v_add_f32_e32 v60, v60, v61
	v_mul_f32_e32 v61, v51, v51
	v_mul_f32_e32 v62, v53, v53
	v_add_f32_e32 v60, v64, v60
	v_fmac_f32_e32 v61, v50, v50
	v_fmac_f32_e32 v62, v52, v52
	v_lshl_add_u64 v[78:79], v[58:59], 0, s[40:41]
	s_nop 0
	s_nop 1
	v_bfe_u32 v85, v227, 4, 2
	v_sub_u32_e32 v84, 0, v85
	v_lshlrev_b32_e32 v84, 4, v84
	v_ashrrev_i32_e32 v85, 31, v84
	v_lshl_add_u64 v[84:85], v[68:69], 0, v[84:85]
	v_permlane16_swap_b32_e32 v54, v50
	v_permlane16_swap_b32_e32 v55, v51
	v_permlane16_swap_b32_e32 v56, v52
	v_permlane16_swap_b32_e32 v57, v53
	v_permlane32_swap_b32_e32 v54, v50
	v_permlane32_swap_b32_e32 v55, v51
	v_permlane32_swap_b32_e32 v56, v52
	v_permlane32_swap_b32_e32 v57, v53
	global_store_dwordx4 v[84:85], v[54:57], off offset:512
	global_store_dwordx4 v[84:85], v[50:53], off offset:576
	s_nop 1
	v_permlane32_swap_b32_e32 v54, v50
	v_permlane32_swap_b32_e32 v55, v51
	v_permlane32_swap_b32_e32 v56, v52
	v_permlane32_swap_b32_e32 v57, v53
	v_permlane16_swap_b32_e32 v54, v50
	v_permlane16_swap_b32_e32 v55, v51
	v_permlane16_swap_b32_e32 v56, v52
	v_permlane16_swap_b32_e32 v57, v53
	v_add_f32_e32 v61, v61, v62
	v_cvt_pk_bf16_f32 v54, v54, v55
	v_cvt_pk_bf16_f32 v55, v56, v57
	v_cvt_pk_bf16_f32 v56, v50, v51
	v_lshl_add_u64 v[50:51], v[78:79], 0, v[0:1]
	v_mov_b32_e32 v0, v60
	v_pk_add_f32 v[70:71], v[70:71], v[70:71] op_sel:[0,1] op_sel_hi:[1,0]
	v_pk_add_f32 v[72:73], v[72:73], v[72:73] op_sel:[0,1] op_sel_hi:[1,0]
	v_add_f32_e32 v61, v65, v61
	v_cvt_pk_bf16_f32 v57, v52, v53
	v_permlane16_swap_b32_e32 v60, v0
	v_mov_b32_e32 v71, v70
	v_mov_b32_e32 v73, v72
	global_store_dwordx4 v[50:51], v[54:57], off
	v_add_f32_e32 v50, v60, v0
	v_mov_b32_e32 v0, v61
	v_permlane16_swap_b32_e32 v70, v71
	v_permlane16_swap_b32_e32 v72, v73
	v_permlane16_swap_b32_e32 v61, v0
	v_add_f32_e32 v71, v70, v71
	v_add_f32_e32 v70, v72, v73
	v_add_f32_e32 v51, v61, v0
	v_mov_b32_e32 v73, v71
	v_mov_b32_e32 v72, v70
	v_mov_b32_e32 v91, v89
	v_mov_b32_e32 v90, v88
	v_mov_b32_e32 v85, v83
	v_mov_b32_e32 v84, v82
	v_mov_b32_e32 v52, v50
	v_mov_b32_e32 v53, v51
	v_permlane32_swap_b32_e32 v71, v73
	v_permlane32_swap_b32_e32 v70, v72
	v_permlane32_swap_b32_e32 v89, v91
	v_permlane32_swap_b32_e32 v88, v90
	v_permlane32_swap_b32_e32 v83, v85
	v_permlane32_swap_b32_e32 v82, v84
	v_permlane32_swap_b32_e32 v50, v52
	v_permlane32_swap_b32_e32 v51, v53
	s_and_saveexec_b64 s[26:27], s[44:45]
	s_cbranch_execz .LBB0_382
	v_pk_add_f32 v[50:51], v[50:51], v[52:53]
	v_lshl_add_u64 v[52:53], s[30:31], 0, v[66:67]
	v_lshl_add_u64 v[52:53], s[24:25], 2, v[52:53]
	global_store_dwordx2 v[52:53], v[50:51], off
; __device__ __forceinline__ float xsum16(float v) { const auto r = __builtin_amdgcn_permlane16_swap(__float_as_uint(v), __float_as_uint(v), false, false); return __uint_as_float(r[0]) + __uint_as_float(r[1]); }
; __device__ __forceinline__ float xsum32(float v) { const auto r = __builtin_amdgcn_permlane32_swap(__float_as_uint(v), __float_as_uint(v), false, false); return __uint_as_float(r[0]) + __uint_as_float(r[1]); }
; __device__ __forceinline__ size_t blk_off(int r, int c, int K) { return (size_t)(r >> 8) * 256 * K + (size_t)(c >> 6) * (256 * 64) + (size_t)((r & 255) * 64 + (c & 63)); }
; __device__ __forceinline__ u32x4 pack8(const f32x4 a, const f32x4 b) { u32x4 w; w.x = cvt_pk_bf16(a[0], a[1]); w.y = cvt_pk_bf16(a[2], a[3]); w.z = cvt_pk_bf16(b[0], b[1]); w.w = cvt_pk_bf16(b[2], b[3]); return w; }
; __device__ __forceinline__ void row_stats(const float* st, int row, int fq, float& mu, float& rstd) {
;     ...
;     mu = s1 * (1.0f / 1024.0f); const float var = fmaxf(s2 * (1.0f / 1024.0f) - mu * mu, 0.f); rstd = rsqrtf(var + LN_EPS_);
;     __device__ __forceinline__ void operator()(const f32x4 (&acc)[2][2][4][2], const pg8::Unit& u, int wr, int wc, int fr, int fq) const {
;     ...
;                     for (int n = 0; n < 2; ++n) { yv[bj][n] = *(const f32x4*)(Yin + (size_t)row * D_ + col0 + bj * 128 + 4 * n); gq[bj][n] = *(const f32x4*)(g + col0 + bj * 128 + 4 * n); bq_[bj][n] = *(const f32x4*)(b + col0 + bj * 128 + 4 * n); }
;                 asm volatile("" ::: "memory");
;                 float s1 = 0.f, s2 = 0.f;
; #pragma unroll
;                 for (int bj = 0; bj < 2; ++bj) { float* yp = Y + (size_t)row * D_ + col0 + bj * 128; f32x4 v[2];
; #pragma unroll
;                     for (int n = 0; n < 2; ++n) { v[n] = (((yv[bj][n] - mu) * rs) * gq[bj][n] + bq_[bj][n]) * ALPHA_ + acc[ai][bj][m][n] * sc;
;                         *(f32x4*)(yp + 4 * n) = v[n]; s1 += (v[n][0] + v[n][1]) + (v[n][2] + v[n][3]); s2 += (v[n][0] * v[n][0] + v[n][1] * v[n][1]) + (v[n][2] * v[n][2] + v[n][3] * v[n][3]); }
;                     *(u32x4*)(Yb + blk_off(row, col0 + bj * 128, D_)) = pack8(v[0], v[1]); }
;                 s1 = xsum32(xsum16(s1)); s2 = xsum32(xsum16(s2));
;                 if (fq == 0) *(f32x2*)(stn + (size_t)row * 32 + (u.pn * 4 + wc) * 2) = (f32x2){s1, s2}; asm volatile("" ::: "memory"); } }
.LBB0_382:
	s_or_b64 exec, exec, s[26:27]
	v_pk_add_f32 v[50:51], v[70:71], v[72:73]
	s_mov_b32 s2, 0x3a800000
	v_pk_mul_f32 v[92:93], v[50:51], s[2:3] op_sel_hi:[1,0]
	s_mov_b32 s2, 0x800000
	v_fma_f32 v0, -v93, v93, v92
	v_max_f32_e32 v0, 0, v0
	v_add_f32_e32 v0, 0x3727c5ac, v0
	v_cmp_gt_f32_e32 vcc, s2, v0
	v_mul_f32_e32 v50, 0x4b800000, v0
	v_lshlrev_b64 v[120:121], 12, v[94:95]
	v_cndmask_b32_e32 v0, v0, v50, vcc
	v_rsq_f32_e32 v0, v0
	s_movk_i32 s2, 0x37c0
	s_load_dwordx16 s[60:75], s[34:35], 0x38
	v_mul_f32_e32 v50, 0x45800000, v0
	v_cndmask_b32_e32 v92, v0, v50, vcc
	v_lshl_add_u64 v[50:51], s[12:13], 0, v[120:121]
	v_lshl_add_u64 v[54:55], v[50:51], 0, v[152:153]
	global_load_dwordx4 v[96:99], v[54:55], off offset:16 nt
	global_load_dwordx4 v[100:103], v[54:55], off nt
	global_load_dwordx4 v[104:107], v[154:155], off offset:16
	global_load_dwordx4 v[108:111], v[154:155], off
	global_load_dwordx4 v[112:115], v[156:157], off offset:16
	global_load_dwordx4 v[116:119], v[156:157], off
	global_load_dwordx4 v[50:53], v[54:55], off offset:528 nt
	global_load_dwordx4 v[70:73], v[54:55], off offset:512 nt
	s_nop 0
	global_load_dwordx4 v[54:57], v[154:155], off offset:528
	global_load_dwordx4 v[62:65], v[154:155], off offset:512
	global_load_dwordx4 v[58:61], v[156:157], off offset:528
	global_load_dwordx4 v[66:69], v[156:157], off offset:512
	v_lshlrev_b32_e32 v0, 6, v94
	v_and_or_b32 v0, v0, s2, v194
	s_mov_b32 s2, 0x3fd744fd
	s_waitcnt lgkmcnt(0)
	v_lshl_add_u64 v[94:95], s[74:75], 0, v[120:121]
	v_lshlrev_b32_e32 v0, 1, v0
	v_lshl_add_u64 v[94:95], v[94:95], 0, v[152:153]
	s_waitcnt vmcnt(10)
	v_sub_f32_e32 v103, v103, v93
	v_sub_f32_e32 v102, v102, v93
	v_sub_f32_e32 v101, v101, v93
	v_sub_f32_e32 v100, v100, v93
	v_pk_mul_f32 v[100:101], v[92:93], v[100:101] op_sel_hi:[0,1]
	v_pk_mul_f32 v[102:103], v[92:93], v[102:103] op_sel_hi:[0,1]
	s_waitcnt vmcnt(6)
	v_pk_fma_f32 v[102:103], v[110:111], v[102:103], v[118:119]
	v_pk_fma_f32 v[100:101], v[108:109], v[100:101], v[116:117]
	v_pk_mul_f32 v[102:103], v[102:103], s[2:3] op_sel_hi:[1,0]
	v_pk_mul_f32 v[100:101], v[100:101], s[2:3] op_sel_hi:[1,0]
	v_pk_fma_f32 v[102:103], v[48:49], 0.5, v[102:103] op_sel_hi:[1,0,1]
	v_pk_fma_f32 v[100:101], v[46:47], 0.5, v[100:101] op_sel_hi:[1,0,1]
	v_add_f32_e32 v47, v102, v103
	v_add_f32_e32 v46, v100, v101
	v_add_f32_e32 v46, v46, v47
	v_add_f32_e32 v108, 0, v46
	v_mul_f32_e32 v46, v101, v101
	v_mul_f32_e32 v47, v103, v103
	v_fmac_f32_e32 v46, v100, v100
	v_fmac_f32_e32 v47, v102, v102
	v_add_f32_e32 v109, v46, v47
	v_sub_f32_e32 v47, v99, v93
	v_sub_f32_e32 v46, v98, v93
	v_sub_f32_e32 v49, v97, v93
	v_sub_f32_e32 v48, v96, v93
	v_pk_mul_f32 v[48:49], v[92:93], v[48:49] op_sel_hi:[0,1]
	v_pk_mul_f32 v[46:47], v[92:93], v[46:47] op_sel_hi:[0,1]
	v_pk_fma_f32 v[46:47], v[106:107], v[46:47], v[114:115]
	v_pk_fma_f32 v[48:49], v[104:105], v[48:49], v[112:113]
	v_pk_mul_f32 v[46:47], v[46:47], s[2:3] op_sel_hi:[1,0]
	v_pk_mul_f32 v[48:49], v[48:49], s[2:3] op_sel_hi:[1,0]
	v_pk_fma_f32 v[98:99], v[44:45], 0.5, v[46:47] op_sel_hi:[1,0,1]
	v_pk_fma_f32 v[96:97], v[42:43], 0.5, v[48:49] op_sel_hi:[1,0,1]
	v_add_f32_e32 v43, v98, v99
	v_add_f32_e32 v42, v96, v97
	v_add_f32_e32 v42, v42, v43
	v_add_f32_e32 v47, v108, v42
	v_mul_f32_e32 v42, v97, v97
	v_mul_f32_e32 v43, v99, v99
	v_fmac_f32_e32 v42, v96, v96
	v_fmac_f32_e32 v43, v98, v98
	v_add_f32_e32 v42, v42, v43
	v_add_f32_e32 v46, v109, v42
	v_cvt_pk_bf16_f32 v42, v100, v101
	v_cvt_pk_bf16_f32 v43, v102, v103
	v_cvt_pk_bf16_f32 v44, v96, v97
	v_cvt_pk_bf16_f32 v45, v98, v99
	v_lshl_add_u64 v[48:49], v[80:81], 0, v[0:1]
	s_nop 0
	s_nop 1
	v_bfe_u32 v105, v227, 4, 2
	v_sub_u32_e32 v104, 0, v105
	v_lshlrev_b32_e32 v104, 4, v104
	v_ashrrev_i32_e32 v105, 31, v104
	v_lshl_add_u64 v[104:105], v[94:95], 0, v[104:105]
	v_permlane16_swap_b32_e32 v100, v96
	v_permlane16_swap_b32_e32 v101, v97
	v_permlane16_swap_b32_e32 v102, v98
	v_permlane16_swap_b32_e32 v103, v99
	v_permlane32_swap_b32_e32 v100, v96
	v_permlane32_swap_b32_e32 v101, v97
	v_permlane32_swap_b32_e32 v102, v98
	v_permlane32_swap_b32_e32 v103, v99
	global_store_dwordx4 v[104:105], v[100:103], off
	global_store_dwordx4 v[104:105], v[96:99], off offset:64
	s_nop 1
	v_permlane32_swap_b32_e32 v100, v96
	v_permlane32_swap_b32_e32 v101, v97
	v_permlane32_swap_b32_e32 v102, v98
	v_permlane32_swap_b32_e32 v103, v99
	v_permlane16_swap_b32_e32 v100, v96
	v_permlane16_swap_b32_e32 v101, v97
	v_permlane16_swap_b32_e32 v102, v98
	v_permlane16_swap_b32_e32 v103, v99
	global_store_dwordx4 v[48:49], v[42:45], off
	s_waitcnt vmcnt(7)
	s_nop 0
	v_sub_f32_e32 v43, v73, v93
	v_sub_f32_e32 v42, v72, v93
	v_sub_f32_e32 v45, v71, v93
	v_sub_f32_e32 v44, v70, v93
	v_pk_mul_f32 v[44:45], v[92:93], v[44:45] op_sel_hi:[0,1]
	v_pk_mul_f32 v[42:43], v[92:93], v[42:43] op_sel_hi:[0,1]
	s_waitcnt vmcnt(3)
; __device__ __forceinline__ float xsum16(float v) { const auto r = __builtin_amdgcn_permlane16_swap(__float_as_uint(v), __float_as_uint(v), false, false); return __uint_as_float(r[0]) + __uint_as_float(r[1]); }
; __device__ __forceinline__ float xsum32(float v) { const auto r = __builtin_amdgcn_permlane32_swap(__float_as_uint(v), __float_as_uint(v), false, false); return __uint_as_float(r[0]) + __uint_as_float(r[1]); }
; __device__ __forceinline__ size_t blk_off(int r, int c, int K) { return (size_t)(r >> 8) * 256 * K + (size_t)(c >> 6) * (256 * 64) + (size_t)((r & 255) * 64 + (c & 63)); }
; __device__ __forceinline__ u32x4 pack8(const f32x4 a, const f32x4 b) { u32x4 w; w.x = cvt_pk_bf16(a[0], a[1]); w.y = cvt_pk_bf16(a[2], a[3]); w.z = cvt_pk_bf16(b[0], b[1]); w.w = cvt_pk_bf16(b[2], b[3]); return w; }
; __device__ __forceinline__ void row_stats(const float* st, int row, int fq, float& mu, float& rstd) {
;     ...
;     mu = s1 * (1.0f / 1024.0f); const float var = fmaxf(s2 * (1.0f / 1024.0f) - mu * mu, 0.f); rstd = rsqrtf(var + LN_EPS_);
;     __device__ __forceinline__ void operator()(const f32x4 (&acc)[2][2][4][2], const pg8::Unit& u, int wr, int wc, int fr, int fq) const {
;     ...
;                     for (int n = 0; n < 2; ++n) { yv[bj][n] = *(const f32x4*)(Yin + (size_t)row * D_ + col0 + bj * 128 + 4 * n); gq[bj][n] = *(const f32x4*)(g + col0 + bj * 128 + 4 * n); bq_[bj][n] = *(const f32x4*)(b + col0 + bj * 128 + 4 * n); }
;                 asm volatile("" ::: "memory");
;                 float s1 = 0.f, s2 = 0.f;
; #pragma unroll
;                 for (int bj = 0; bj < 2; ++bj) { float* yp = Y + (size_t)row * D_ + col0 + bj * 128; f32x4 v[2];
; #pragma unroll
;                     for (int n = 0; n < 2; ++n) { v[n] = (((yv[bj][n] - mu) * rs) * gq[bj][n] + bq_[bj][n]) * ALPHA_ + acc[ai][bj][m][n] * sc;
;                         *(f32x4*)(yp + 4 * n) = v[n]; s1 += (v[n][0] + v[n][1]) + (v[n][2] + v[n][3]); s2 += (v[n][0] * v[n][0] + v[n][1] * v[n][1]) + (v[n][2] * v[n][2] + v[n][3] * v[n][3]); }
;                     *(u32x4*)(Yb + blk_off(row, col0 + bj * 128, D_)) = pack8(v[0], v[1]); }
;                 s1 = xsum32(xsum16(s1)); s2 = xsum32(xsum16(s2));
;                 if (fq == 0) *(f32x2*)(stn + (size_t)row * 32 + (u.pn * 4 + wc) * 2) = (f32x2){s1, s2}; asm volatile("" ::: "memory"); } }
	v_pk_fma_f32 v[42:43], v[64:65], v[42:43], v[68:69]
	v_pk_fma_f32 v[44:45], v[62:63], v[44:45], v[66:67]
	v_pk_mul_f32 v[42:43], v[42:43], s[2:3] op_sel_hi:[1,0]
	v_pk_mul_f32 v[44:45], v[44:45], s[2:3] op_sel_hi:[1,0]
	v_pk_fma_f32 v[40:41], v[40:41], 0.5, v[42:43] op_sel_hi:[1,0,1]
	v_pk_fma_f32 v[38:39], v[38:39], 0.5, v[44:45] op_sel_hi:[1,0,1]
	v_add_f32_e32 v43, v40, v41
	v_add_f32_e32 v42, v38, v39
	v_add_f32_e32 v42, v42, v43
	v_add_f32_e32 v47, v47, v42
	v_mul_f32_e32 v42, v39, v39
	v_mul_f32_e32 v43, v41, v41
	v_fmac_f32_e32 v42, v38, v38
	v_fmac_f32_e32 v43, v40, v40
	v_add_f32_e32 v42, v42, v43
	v_add_f32_e32 v46, v46, v42
	v_sub_f32_e32 v43, v53, v93
	v_sub_f32_e32 v42, v52, v93
	v_sub_f32_e32 v45, v51, v93
	v_sub_f32_e32 v44, v50, v93
	v_pk_mul_f32 v[44:45], v[92:93], v[44:45] op_sel_hi:[0,1]
	v_pk_mul_f32 v[42:43], v[92:93], v[42:43] op_sel_hi:[0,1]
	v_pk_fma_f32 v[42:43], v[56:57], v[42:43], v[60:61]
	v_pk_fma_f32 v[44:45], v[54:55], v[44:45], v[58:59]
	v_pk_mul_f32 v[42:43], v[42:43], s[2:3] op_sel_hi:[1,0]
	v_pk_mul_f32 v[44:45], v[44:45], s[2:3] op_sel_hi:[1,0]
	v_pk_fma_f32 v[36:37], v[36:37], 0.5, v[42:43] op_sel_hi:[1,0,1]
	v_pk_fma_f32 v[34:35], v[34:35], 0.5, v[44:45] op_sel_hi:[1,0,1]
	v_add_f32_e32 v43, v36, v37
	v_add_f32_e32 v42, v34, v35
	v_add_f32_e32 v42, v42, v43
	v_mul_f32_e32 v43, v35, v35
	v_mul_f32_e32 v44, v37, v37
	v_add_f32_e32 v42, v47, v42
	v_fmac_f32_e32 v43, v34, v34
	v_fmac_f32_e32 v44, v36, v36
	s_nop 0
	s_nop 1
	v_bfe_u32 v49, v227, 4, 2
	v_sub_u32_e32 v48, 0, v49
	v_lshlrev_b32_e32 v48, 4, v48
	v_ashrrev_i32_e32 v49, 31, v48
	v_lshl_add_u64 v[48:49], v[94:95], 0, v[48:49]
	v_permlane16_swap_b32_e32 v38, v34
	v_permlane16_swap_b32_e32 v39, v35
	v_permlane16_swap_b32_e32 v40, v36
	v_permlane16_swap_b32_e32 v41, v37
	v_permlane32_swap_b32_e32 v38, v34
	v_permlane32_swap_b32_e32 v39, v35
	v_permlane32_swap_b32_e32 v40, v36
	v_permlane32_swap_b32_e32 v41, v37
	global_store_dwordx4 v[48:49], v[38:41], off offset:512
	global_store_dwordx4 v[48:49], v[34:37], off offset:576
	s_nop 1
	v_permlane32_swap_b32_e32 v38, v34
	v_permlane32_swap_b32_e32 v39, v35
	v_permlane32_swap_b32_e32 v40, v36
	v_permlane32_swap_b32_e32 v41, v37
	v_permlane16_swap_b32_e32 v38, v34
	v_permlane16_swap_b32_e32 v39, v35
	v_permlane16_swap_b32_e32 v40, v36
	v_permlane16_swap_b32_e32 v41, v37
	v_add_f32_e32 v43, v43, v44
	v_cvt_pk_bf16_f32 v38, v38, v39
	v_cvt_pk_bf16_f32 v39, v40, v41
	v_cvt_pk_bf16_f32 v40, v34, v35
	v_lshl_add_u64 v[34:35], v[78:79], 0, v[0:1]
	v_mov_b32_e32 v0, v42
	v_add_f32_e32 v43, v46, v43
	v_cvt_pk_bf16_f32 v41, v36, v37
	v_permlane16_swap_b32_e32 v42, v0
	global_store_dwordx4 v[34:35], v[38:41], off
	v_add_f32_e32 v34, v42, v0
	v_mov_b32_e32 v0, v43
	s_nop 1
	v_permlane16_swap_b32_e32 v43, v0
	v_add_f32_e32 v35, v43, v0
	v_mov_b32_e32 v36, v34
	v_mov_b32_e32 v37, v35
	s_nop 0
	v_permlane32_swap_b32_e32 v34, v36
	v_permlane32_swap_b32_e32 v35, v37
	s_and_saveexec_b64 s[26:27], s[44:45]
	s_cbranch_execz .LBB0_384
	v_pk_add_f32 v[34:35], v[34:35], v[36:37]
	v_lshl_add_u64 v[36:37], s[30:31], 0, v[86:87]
	v_lshl_add_u64 v[36:37], s[24:25], 2, v[36:37]
	global_store_dwordx2 v[36:37], v[34:35], off
.LBB0_384:
	s_or_b64 exec, exec, s[26:27]
	v_pk_add_f32 v[34:35], v[88:89], v[90:91]
	s_mov_b32 s2, 0x3a800000
	v_pk_mul_f32 v[58:59], v[34:35], s[2:3] op_sel_hi:[1,0]
	s_mov_b32 s2, 0x800000
	v_fma_f32 v0, -v59, v59, v58
	v_max_f32_e32 v0, 0, v0
	v_add_f32_e32 v0, 0x3727c5ac, v0
	v_cmp_gt_f32_e32 vcc, s2, v0
	v_mul_f32_e32 v34, 0x4b800000, v0
	v_lshlrev_b64 v[60:61], 12, v[76:77]
	v_cndmask_b32_e32 v0, v0, v34, vcc
	v_rsq_f32_e32 v0, v0
	s_movk_i32 s2, 0x3bc0
	s_load_dwordx16 s[60:75], s[34:35], 0x38
	v_mul_f32_e32 v34, 0x45800000, v0
	v_cndmask_b32_e32 v58, v0, v34, vcc
	v_lshl_add_u64 v[34:35], s[12:13], 0, v[60:61]
	v_lshl_add_u64 v[38:39], v[34:35], 0, v[152:153]
	global_load_dwordx4 v[62:65], v[38:39], off offset:16 nt
	global_load_dwordx4 v[66:69], v[38:39], off nt
	global_load_dwordx4 v[70:73], v[154:155], off offset:16
	global_load_dwordx4 v[86:89], v[154:155], off
	global_load_dwordx4 v[90:93], v[156:157], off offset:16
	global_load_dwordx4 v[94:97], v[156:157], off
	global_load_dwordx4 v[34:37], v[38:39], off offset:528 nt
	global_load_dwordx4 v[54:57], v[38:39], off offset:512 nt
	s_nop 0
	global_load_dwordx4 v[38:41], v[154:155], off offset:528
	global_load_dwordx4 v[46:49], v[154:155], off offset:512
	global_load_dwordx4 v[42:45], v[156:157], off offset:528
	global_load_dwordx4 v[50:53], v[156:157], off offset:512
	v_lshlrev_b32_e32 v0, 6, v76
	v_and_or_b32 v0, v0, s2, v194
	s_mov_b32 s2, 0x3fd744fd
	s_waitcnt lgkmcnt(0)
	v_lshl_add_u64 v[60:61], s[74:75], 0, v[60:61]
	v_lshlrev_b32_e32 v0, 1, v0
	v_lshl_add_u64 v[60:61], v[60:61], 0, v[152:153]
	s_waitcnt vmcnt(10)
	v_sub_f32_e32 v69, v69, v59
	v_sub_f32_e32 v68, v68, v59
	v_sub_f32_e32 v67, v67, v59
	v_sub_f32_e32 v66, v66, v59
	v_pk_mul_f32 v[66:67], v[58:59], v[66:67] op_sel_hi:[0,1]
	v_pk_mul_f32 v[68:69], v[58:59], v[68:69] op_sel_hi:[0,1]
	s_waitcnt vmcnt(6)
; __device__ __forceinline__ float xsum16(float v) { const auto r = __builtin_amdgcn_permlane16_swap(__float_as_uint(v), __float_as_uint(v), false, false); return __uint_as_float(r[0]) + __uint_as_float(r[1]); }
; __device__ __forceinline__ float xsum32(float v) { const auto r = __builtin_amdgcn_permlane32_swap(__float_as_uint(v), __float_as_uint(v), false, false); return __uint_as_float(r[0]) + __uint_as_float(r[1]); }
; __device__ __forceinline__ size_t blk_off(int r, int c, int K) { return (size_t)(r >> 8) * 256 * K + (size_t)(c >> 6) * (256 * 64) + (size_t)((r & 255) * 64 + (c & 63)); }
; __device__ __forceinline__ u32x4 pack8(const f32x4 a, const f32x4 b) { u32x4 w; w.x = cvt_pk_bf16(a[0], a[1]); w.y = cvt_pk_bf16(a[2], a[3]); w.z = cvt_pk_bf16(b[0], b[1]); w.w = cvt_pk_bf16(b[2], b[3]); return w; }
;     __device__ __forceinline__ void operator()(const f32x4 (&acc)[2][2][4][2], const pg8::Unit& u, int wr, int wc, int fr, int fq) const {
;     ...
;                     for (int n = 0; n < 2; ++n) { yv[bj][n] = *(const f32x4*)(Yin + (size_t)row * D_ + col0 + bj * 128 + 4 * n); gq[bj][n] = *(const f32x4*)(g + col0 + bj * 128 + 4 * n); bq_[bj][n] = *(const f32x4*)(b + col0 + bj * 128 + 4 * n); }
;                 asm volatile("" ::: "memory");
;                 float s1 = 0.f, s2 = 0.f;
; #pragma unroll
;                 for (int bj = 0; bj < 2; ++bj) { float* yp = Y + (size_t)row * D_ + col0 + bj * 128; f32x4 v[2];
; #pragma unroll
;                     for (int n = 0; n < 2; ++n) { v[n] = (((yv[bj][n] - mu) * rs) * gq[bj][n] + bq_[bj][n]) * ALPHA_ + acc[ai][bj][m][n] * sc;
;                         *(f32x4*)(yp + 4 * n) = v[n]; s1 += (v[n][0] + v[n][1]) + (v[n][2] + v[n][3]); s2 += (v[n][0] * v[n][0] + v[n][1] * v[n][1]) + (v[n][2] * v[n][2] + v[n][3] * v[n][3]); }
;                     *(u32x4*)(Yb + blk_off(row, col0 + bj * 128, D_)) = pack8(v[0], v[1]); }
;                 s1 = xsum32(xsum16(s1)); s2 = xsum32(xsum16(s2));
;                 if (fq == 0) *(f32x2*)(stn + (size_t)row * 32 + (u.pn * 4 + wc) * 2) = (f32x2){s1, s2}; asm volatile("" ::: "memory"); } }
	v_pk_fma_f32 v[68:69], v[88:89], v[68:69], v[96:97]
	v_pk_fma_f32 v[66:67], v[86:87], v[66:67], v[94:95]
	v_pk_mul_f32 v[68:69], v[68:69], s[2:3] op_sel_hi:[1,0]
	v_pk_mul_f32 v[66:67], v[66:67], s[2:3] op_sel_hi:[1,0]
	v_pk_fma_f32 v[68:69], v[32:33], 0.5, v[68:69] op_sel_hi:[1,0,1]
	v_pk_fma_f32 v[66:67], v[30:31], 0.5, v[66:67] op_sel_hi:[1,0,1]
	v_add_f32_e32 v31, v68, v69
	v_add_f32_e32 v30, v66, v67
	v_add_f32_e32 v30, v30, v31
	v_add_f32_e32 v86, 0, v30
	v_mul_f32_e32 v30, v67, v67
	v_mul_f32_e32 v31, v69, v69
	v_fmac_f32_e32 v30, v66, v66
	v_fmac_f32_e32 v31, v68, v68
	v_add_f32_e32 v87, v30, v31
	v_sub_f32_e32 v31, v65, v59
	v_sub_f32_e32 v30, v64, v59
	v_sub_f32_e32 v33, v63, v59
	v_sub_f32_e32 v32, v62, v59
	v_pk_mul_f32 v[32:33], v[58:59], v[32:33] op_sel_hi:[0,1]
	v_pk_mul_f32 v[30:31], v[58:59], v[30:31] op_sel_hi:[0,1]
	v_pk_fma_f32 v[30:31], v[72:73], v[30:31], v[92:93]
	v_pk_fma_f32 v[32:33], v[70:71], v[32:33], v[90:91]
	v_pk_mul_f32 v[30:31], v[30:31], s[2:3] op_sel_hi:[1,0]
	v_pk_mul_f32 v[32:33], v[32:33], s[2:3] op_sel_hi:[1,0]
	v_pk_fma_f32 v[64:65], v[28:29], 0.5, v[30:31] op_sel_hi:[1,0,1]
	v_pk_fma_f32 v[62:63], v[26:27], 0.5, v[32:33] op_sel_hi:[1,0,1]
	v_add_f32_e32 v27, v64, v65
	v_add_f32_e32 v26, v62, v63
	v_add_f32_e32 v26, v26, v27
	v_add_f32_e32 v31, v86, v26
	v_mul_f32_e32 v26, v63, v63
	v_mul_f32_e32 v27, v65, v65
	v_fmac_f32_e32 v26, v62, v62
	v_fmac_f32_e32 v27, v64, v64
	v_add_f32_e32 v26, v26, v27
	v_add_f32_e32 v30, v87, v26
	v_cvt_pk_bf16_f32 v26, v66, v67
	v_cvt_pk_bf16_f32 v27, v68, v69
	v_cvt_pk_bf16_f32 v28, v62, v63
	v_cvt_pk_bf16_f32 v29, v64, v65
	v_lshl_add_u64 v[32:33], v[80:81], 0, v[0:1]
	s_nop 0
	s_nop 1
	v_bfe_u32 v71, v227, 4, 2
	v_sub_u32_e32 v70, 0, v71
	v_lshlrev_b32_e32 v70, 4, v70
	v_ashrrev_i32_e32 v71, 31, v70
	v_lshl_add_u64 v[70:71], v[60:61], 0, v[70:71]
	v_permlane16_swap_b32_e32 v66, v62
	v_permlane16_swap_b32_e32 v67, v63
	v_permlane16_swap_b32_e32 v68, v64
	v_permlane16_swap_b32_e32 v69, v65
	v_permlane32_swap_b32_e32 v66, v62
	v_permlane32_swap_b32_e32 v67, v63
	v_permlane32_swap_b32_e32 v68, v64
	v_permlane32_swap_b32_e32 v69, v65
	global_store_dwordx4 v[70:71], v[66:69], off
	global_store_dwordx4 v[70:71], v[62:65], off offset:64
	s_nop 1
	v_permlane32_swap_b32_e32 v66, v62
	v_permlane32_swap_b32_e32 v67, v63
	v_permlane32_swap_b32_e32 v68, v64
	v_permlane32_swap_b32_e32 v69, v65
	v_permlane16_swap_b32_e32 v66, v62
	v_permlane16_swap_b32_e32 v67, v63
	v_permlane16_swap_b32_e32 v68, v64
	v_permlane16_swap_b32_e32 v69, v65
	global_store_dwordx4 v[32:33], v[26:29], off
	s_waitcnt vmcnt(7)
	s_nop 0
	v_sub_f32_e32 v27, v57, v59
	v_sub_f32_e32 v26, v56, v59
	v_sub_f32_e32 v29, v55, v59
	v_sub_f32_e32 v28, v54, v59
	v_pk_mul_f32 v[28:29], v[58:59], v[28:29] op_sel_hi:[0,1]
	v_pk_mul_f32 v[26:27], v[58:59], v[26:27] op_sel_hi:[0,1]
	s_waitcnt vmcnt(3)
	v_pk_fma_f32 v[26:27], v[48:49], v[26:27], v[52:53]
	v_pk_fma_f32 v[28:29], v[46:47], v[28:29], v[50:51]
	v_pk_mul_f32 v[26:27], v[26:27], s[2:3] op_sel_hi:[1,0]
	v_pk_mul_f32 v[28:29], v[28:29], s[2:3] op_sel_hi:[1,0]
	v_pk_fma_f32 v[24:25], v[24:25], 0.5, v[26:27] op_sel_hi:[1,0,1]
	v_pk_fma_f32 v[22:23], v[22:23], 0.5, v[28:29] op_sel_hi:[1,0,1]
	v_add_f32_e32 v27, v24, v25
	v_add_f32_e32 v26, v22, v23
	v_add_f32_e32 v26, v26, v27
	v_add_f32_e32 v31, v31, v26
	v_mul_f32_e32 v26, v23, v23
	v_mul_f32_e32 v27, v25, v25
	v_fmac_f32_e32 v26, v22, v22
	v_fmac_f32_e32 v27, v24, v24
	v_add_f32_e32 v26, v26, v27
	v_add_f32_e32 v30, v30, v26
	v_sub_f32_e32 v27, v37, v59
	v_sub_f32_e32 v26, v36, v59
	v_sub_f32_e32 v29, v35, v59
	v_sub_f32_e32 v28, v34, v59
	v_pk_mul_f32 v[28:29], v[58:59], v[28:29] op_sel_hi:[0,1]
	v_pk_mul_f32 v[26:27], v[58:59], v[26:27] op_sel_hi:[0,1]
	v_pk_fma_f32 v[26:27], v[40:41], v[26:27], v[44:45]
	v_pk_fma_f32 v[28:29], v[38:39], v[28:29], v[42:43]
	v_pk_mul_f32 v[26:27], v[26:27], s[2:3] op_sel_hi:[1,0]
	v_pk_mul_f32 v[28:29], v[28:29], s[2:3] op_sel_hi:[1,0]
	v_pk_fma_f32 v[20:21], v[20:21], 0.5, v[26:27] op_sel_hi:[1,0,1]
	v_pk_fma_f32 v[18:19], v[18:19], 0.5, v[28:29] op_sel_hi:[1,0,1]
	v_add_f32_e32 v27, v20, v21
	v_add_f32_e32 v26, v18, v19
	v_add_f32_e32 v26, v26, v27
	v_mul_f32_e32 v27, v19, v19
	v_mul_f32_e32 v28, v21, v21
	v_add_f32_e32 v26, v31, v26
	v_fmac_f32_e32 v27, v18, v18
	v_fmac_f32_e32 v28, v20, v20
	s_nop 0
	s_nop 1
	v_bfe_u32 v33, v227, 4, 2
	v_sub_u32_e32 v32, 0, v33
	v_lshlrev_b32_e32 v32, 4, v32
	v_ashrrev_i32_e32 v33, 31, v32
	v_lshl_add_u64 v[32:33], v[60:61], 0, v[32:33]
	v_permlane16_swap_b32_e32 v22, v18
	v_permlane16_swap_b32_e32 v23, v19
	v_permlane16_swap_b32_e32 v24, v20
	v_permlane16_swap_b32_e32 v25, v21
	v_permlane32_swap_b32_e32 v22, v18
	v_permlane32_swap_b32_e32 v23, v19
	v_permlane32_swap_b32_e32 v24, v20
	v_permlane32_swap_b32_e32 v25, v21
	global_store_dwordx4 v[32:33], v[22:25], off offset:512
	global_store_dwordx4 v[32:33], v[18:21], off offset:576
	s_nop 1
	v_permlane32_swap_b32_e32 v22, v18
	v_permlane32_swap_b32_e32 v23, v19
	v_permlane32_swap_b32_e32 v24, v20
	v_permlane32_swap_b32_e32 v25, v21
	v_permlane16_swap_b32_e32 v22, v18
	v_permlane16_swap_b32_e32 v23, v19
	v_permlane16_swap_b32_e32 v24, v20
	v_permlane16_swap_b32_e32 v25, v21
	v_add_f32_e32 v27, v27, v28
	v_cvt_pk_bf16_f32 v22, v22, v23
	v_cvt_pk_bf16_f32 v23, v24, v25
	v_cvt_pk_bf16_f32 v24, v18, v19
	v_lshl_add_u64 v[18:19], v[78:79], 0, v[0:1]
	v_mov_b32_e32 v0, v26
	v_add_f32_e32 v27, v30, v27
	v_cvt_pk_bf16_f32 v25, v20, v21
	v_permlane16_swap_b32_e32 v26, v0
	global_store_dwordx4 v[18:19], v[22:25], off
	v_add_f32_e32 v18, v26, v0
	v_mov_b32_e32 v0, v27
	s_nop 1
	v_permlane16_swap_b32_e32 v27, v0
	v_add_f32_e32 v19, v27, v0
	v_mov_b32_e32 v20, v18
	v_mov_b32_e32 v21, v19
	s_nop 0
	v_permlane32_swap_b32_e32 v18, v20
	v_permlane32_swap_b32_e32 v19, v21
	s_and_saveexec_b64 s[26:27], s[44:45]
	s_cbranch_execz .LBB0_386
	v_pk_add_f32 v[18:19], v[18:19], v[20:21]
	v_lshlrev_b64 v[20:21], 7, v[76:77]
	v_lshl_add_u64 v[20:21], s[30:31], 0, v[20:21]
	v_lshl_add_u64 v[20:21], s[24:25], 2, v[20:21]
	global_store_dwordx2 v[20:21], v[18:19], off
; __device__ __forceinline__ float xsum16(float v) { const auto r = __builtin_amdgcn_permlane16_swap(__float_as_uint(v), __float_as_uint(v), false, false); return __uint_as_float(r[0]) + __uint_as_float(r[1]); }
; __device__ __forceinline__ float xsum32(float v) { const auto r = __builtin_amdgcn_permlane32_swap(__float_as_uint(v), __float_as_uint(v), false, false); return __uint_as_float(r[0]) + __uint_as_float(r[1]); }
; __device__ __forceinline__ size_t blk_off(int r, int c, int K) { return (size_t)(r >> 8) * 256 * K + (size_t)(c >> 6) * (256 * 64) + (size_t)((r & 255) * 64 + (c & 63)); }
; __device__ __forceinline__ u32x4 pack8(const f32x4 a, const f32x4 b) { u32x4 w; w.x = cvt_pk_bf16(a[0], a[1]); w.y = cvt_pk_bf16(a[2], a[3]); w.z = cvt_pk_bf16(b[0], b[1]); w.w = cvt_pk_bf16(b[2], b[3]); return w; }
; __device__ __forceinline__ void row_stats(const float* st, int row, int fq, float& mu, float& rstd) {
;     ...
;     mu = s1 * (1.0f / 1024.0f); const float var = fmaxf(s2 * (1.0f / 1024.0f) - mu * mu, 0.f); rstd = rsqrtf(var + LN_EPS_);
;     __device__ __forceinline__ void operator()(const f32x4 (&acc)[2][2][4][2], const pg8::Unit& u, int wr, int wc, int fr, int fq) const {
;     ...
;                     for (int n = 0; n < 2; ++n) { yv[bj][n] = *(const f32x4*)(Yin + (size_t)row * D_ + col0 + bj * 128 + 4 * n); gq[bj][n] = *(const f32x4*)(g + col0 + bj * 128 + 4 * n); bq_[bj][n] = *(const f32x4*)(b + col0 + bj * 128 + 4 * n); }
;                 asm volatile("" ::: "memory");
;                 float s1 = 0.f, s2 = 0.f;
; #pragma unroll
;                 for (int bj = 0; bj < 2; ++bj) { float* yp = Y + (size_t)row * D_ + col0 + bj * 128; f32x4 v[2];
; #pragma unroll
;                     for (int n = 0; n < 2; ++n) { v[n] = (((yv[bj][n] - mu) * rs) * gq[bj][n] + bq_[bj][n]) * ALPHA_ + acc[ai][bj][m][n] * sc;
;                         *(f32x4*)(yp + 4 * n) = v[n]; s1 += (v[n][0] + v[n][1]) + (v[n][2] + v[n][3]); s2 += (v[n][0] * v[n][0] + v[n][1] * v[n][1]) + (v[n][2] * v[n][2] + v[n][3] * v[n][3]); }
;                     *(u32x4*)(Yb + blk_off(row, col0 + bj * 128, D_)) = pack8(v[0], v[1]); }
;                 s1 = xsum32(xsum16(s1)); s2 = xsum32(xsum16(s2));
;                 if (fq == 0) *(f32x2*)(stn + (size_t)row * 32 + (u.pn * 4 + wc) * 2) = (f32x2){s1, s2}; asm volatile("" ::: "memory"); } }
.LBB0_386:
	s_or_b64 exec, exec, s[26:27]
	v_lshlrev_b64 v[26:27], 12, v[74:75]
	v_lshl_add_u64 v[18:19], s[12:13], 0, v[26:27]
	v_lshl_add_u64 v[28:29], v[18:19], 0, v[152:153]
	global_load_dwordx4 v[34:37], v[28:29], off nt
	global_load_dwordx4 v[38:41], v[28:29], off offset:16 nt
	global_load_dwordx4 v[42:45], v[28:29], off offset:512 nt
	global_load_dwordx4 v[46:49], v[156:157], off
	global_load_dwordx4 v[50:53], v[154:155], off
	global_load_dwordx4 v[54:57], v[154:155], off offset:16
	global_load_dwordx4 v[58:61], v[156:157], off offset:16
	global_load_dwordx4 v[62:65], v[154:155], off offset:512
	global_load_dwordx4 v[66:69], v[156:157], off offset:512
	s_load_dwordx16 s[60:75], s[34:35], 0x38
	v_pk_add_f32 v[18:19], v[82:83], v[84:85]
	s_mov_b32 s2, 0x3a800000
	v_pk_mul_f32 v[32:33], v[18:19], s[2:3] op_sel_hi:[1,0]
	global_load_dwordx4 v[18:21], v[154:155], off offset:528
	global_load_dwordx4 v[22:25], v[156:157], off offset:528
	s_waitcnt lgkmcnt(0)
	v_lshl_add_u64 v[26:27], s[74:75], 0, v[26:27]
	v_lshl_add_u64 v[30:31], v[26:27], 0, v[152:153]
	global_load_dwordx4 v[26:29], v[28:29], off offset:528 nt
	v_fma_f32 v32, -v33, v33, v32
	v_lshlrev_b32_e32 v0, 6, v74
	s_movk_i32 s2, 0x3fc0
	v_max_f32_e32 v32, 0, v32
	v_and_or_b32 v0, v0, s2, v194
	v_add_f32_e32 v32, 0x3727c5ac, v32
	s_mov_b32 s2, 0x800000
	v_mul_f32_e32 v70, 0x4b800000, v32
	v_cmp_gt_f32_e32 vcc, s2, v32
	s_mov_b32 s2, 0x3fd744fd
	v_lshlrev_b32_e32 v0, 1, v0
	v_cndmask_b32_e32 v32, v32, v70, vcc
	v_rsq_f32_e32 v32, v32
	v_lshl_add_u64 v[70:71], v[80:81], 0, v[0:1]
	v_mul_f32_e32 v72, 0x45800000, v32
	v_cndmask_b32_e32 v32, v32, v72, vcc
	s_waitcnt vmcnt(11)
	v_sub_f32_e32 v37, v37, v33
	v_sub_f32_e32 v36, v36, v33
	v_sub_f32_e32 v35, v35, v33
	v_sub_f32_e32 v34, v34, v33
	s_waitcnt vmcnt(10)
	v_sub_f32_e32 v41, v41, v33
	v_sub_f32_e32 v40, v40, v33
	v_sub_f32_e32 v39, v39, v33
	v_sub_f32_e32 v38, v38, v33
	v_pk_mul_f32 v[34:35], v[32:33], v[34:35] op_sel_hi:[0,1]
	v_pk_mul_f32 v[36:37], v[32:33], v[36:37] op_sel_hi:[0,1]
	v_pk_mul_f32 v[38:39], v[32:33], v[38:39] op_sel_hi:[0,1]
	v_pk_mul_f32 v[40:41], v[32:33], v[40:41] op_sel_hi:[0,1]
	s_waitcnt vmcnt(7)
	v_pk_fma_f32 v[36:37], v[52:53], v[36:37], v[48:49]
	v_pk_fma_f32 v[34:35], v[50:51], v[34:35], v[46:47]
	s_waitcnt vmcnt(5)
	v_pk_fma_f32 v[40:41], v[56:57], v[40:41], v[60:61]
	v_pk_fma_f32 v[38:39], v[54:55], v[38:39], v[58:59]
	v_pk_mul_f32 v[34:35], v[34:35], s[2:3] op_sel_hi:[1,0]
	v_pk_mul_f32 v[36:37], v[36:37], s[2:3] op_sel_hi:[1,0]
	v_pk_mul_f32 v[38:39], v[38:39], s[2:3] op_sel_hi:[1,0]
	v_pk_mul_f32 v[40:41], v[40:41], s[2:3] op_sel_hi:[1,0]
	v_pk_fma_f32 v[16:17], v[16:17], 0.5, v[36:37] op_sel_hi:[1,0,1]
	v_pk_fma_f32 v[14:15], v[14:15], 0.5, v[34:35] op_sel_hi:[1,0,1]
	v_pk_fma_f32 v[12:13], v[12:13], 0.5, v[40:41] op_sel_hi:[1,0,1]
	v_pk_fma_f32 v[10:11], v[10:11], 0.5, v[38:39] op_sel_hi:[1,0,1]
	v_sub_f32_e32 v45, v45, v33
	v_sub_f32_e32 v44, v44, v33
	v_sub_f32_e32 v43, v43, v33
	v_sub_f32_e32 v42, v42, v33
	v_add_f32_e32 v38, v14, v15
	v_add_f32_e32 v39, v16, v17
	v_mul_f32_e32 v40, v15, v15
	v_mul_f32_e32 v41, v17, v17
	v_mul_f32_e32 v48, v11, v11
	v_mul_f32_e32 v49, v13, v13
	v_pk_mul_f32 v[42:43], v[32:33], v[42:43] op_sel_hi:[0,1]
	v_pk_mul_f32 v[44:45], v[32:33], v[44:45] op_sel_hi:[0,1]
	global_store_dwordx4 v[30:31], v[10:13], off offset:16
	v_add_f32_e32 v46, v10, v11
	v_add_f32_e32 v47, v12, v13
	v_cvt_pk_bf16_f32 v36, v10, v11
	v_add_f32_e32 v11, v38, v39
	v_fmac_f32_e32 v40, v14, v14
	v_fmac_f32_e32 v41, v16, v16
	v_fmac_f32_e32 v48, v10, v10
	v_fmac_f32_e32 v49, v12, v12
	s_waitcnt vmcnt(4)
	v_pk_fma_f32 v[44:45], v[64:65], v[44:45], v[68:69]
	v_pk_fma_f32 v[42:43], v[62:63], v[42:43], v[66:67]
	v_cvt_pk_bf16_f32 v37, v12, v13
	v_add_f32_e32 v13, v46, v47
	v_add_f32_e32 v10, 0, v11
	v_add_f32_e32 v11, v40, v41
	v_add_f32_e32 v12, v48, v49
	global_store_dwordx4 v[30:31], v[14:17], off
	v_cvt_pk_bf16_f32 v34, v14, v15
	v_cvt_pk_bf16_f32 v35, v16, v17
	v_add_f32_e32 v14, v10, v13
	v_add_f32_e32 v15, v11, v12
	v_pk_mul_f32 v[10:11], v[42:43], s[2:3] op_sel_hi:[1,0]
	v_pk_mul_f32 v[12:13], v[44:45], s[2:3] op_sel_hi:[1,0]
	v_pk_fma_f32 v[6:7], v[6:7], 0.5, v[10:11] op_sel_hi:[1,0,1]
	v_pk_fma_f32 v[8:9], v[8:9], 0.5, v[12:13] op_sel_hi:[1,0,1]
	v_add_f32_e32 v10, v6, v7
	v_add_f32_e32 v11, v8, v9
	v_add_f32_e32 v10, v10, v11
	v_add_f32_e32 v14, v14, v10
	v_mul_f32_e32 v10, v7, v7
	v_mul_f32_e32 v11, v9, v9
	v_fmac_f32_e32 v10, v6, v6
	v_fmac_f32_e32 v11, v8, v8
	v_add_f32_e32 v10, v10, v11
	v_add_f32_e32 v15, v15, v10
	s_waitcnt vmcnt(2)
	v_sub_f32_e32 v11, v29, v33
	v_sub_f32_e32 v10, v28, v33
	v_sub_f32_e32 v13, v27, v33
	v_sub_f32_e32 v12, v26, v33
	v_pk_mul_f32 v[12:13], v[32:33], v[12:13] op_sel_hi:[0,1]
	v_pk_mul_f32 v[10:11], v[32:33], v[10:11] op_sel_hi:[0,1]
	v_pk_fma_f32 v[10:11], v[20:21], v[10:11], v[24:25]
	v_pk_fma_f32 v[12:13], v[18:19], v[12:13], v[22:23]
	v_pk_mul_f32 v[10:11], v[10:11], s[2:3] op_sel_hi:[1,0]
	v_pk_mul_f32 v[12:13], v[12:13], s[2:3] op_sel_hi:[1,0]
	v_pk_fma_f32 v[4:5], v[4:5], 0.5, v[10:11] op_sel_hi:[1,0,1]
	v_pk_fma_f32 v[2:3], v[2:3], 0.5, v[12:13] op_sel_hi:[1,0,1]
	v_add_f32_e32 v11, v4, v5
	v_add_f32_e32 v10, v2, v3
	v_add_f32_e32 v10, v10, v11
	v_mul_f32_e32 v11, v3, v3
	v_mul_f32_e32 v12, v5, v5
	v_add_f32_e32 v10, v14, v10
	v_fmac_f32_e32 v11, v2, v2
	v_fmac_f32_e32 v12, v4, v4
	global_store_dwordx4 v[70:71], v[34:37], off
	s_nop 0
	s_nop 1
	v_bfe_u32 v17, v227, 4, 2
	v_sub_u32_e32 v16, 0, v17
	v_lshlrev_b32_e32 v16, 4, v16
	v_ashrrev_i32_e32 v17, 31, v16
	v_lshl_add_u64 v[16:17], v[30:31], 0, v[16:17]
	v_permlane16_swap_b32_e32 v6, v2
	v_permlane16_swap_b32_e32 v7, v3
	v_permlane16_swap_b32_e32 v8, v4
	v_permlane16_swap_b32_e32 v9, v5
	v_permlane32_swap_b32_e32 v6, v2
	v_permlane32_swap_b32_e32 v7, v3
	v_permlane32_swap_b32_e32 v8, v4
	v_permlane32_swap_b32_e32 v9, v5
	global_store_dwordx4 v[16:17], v[6:9], off offset:512
	global_store_dwordx4 v[16:17], v[2:5], off offset:576
	s_nop 1
	v_permlane32_swap_b32_e32 v6, v2
	v_permlane32_swap_b32_e32 v7, v3
	v_permlane32_swap_b32_e32 v8, v4
	v_permlane32_swap_b32_e32 v9, v5
	v_permlane16_swap_b32_e32 v6, v2
	v_permlane16_swap_b32_e32 v7, v3
	v_permlane16_swap_b32_e32 v8, v4
	v_permlane16_swap_b32_e32 v9, v5
	v_add_f32_e32 v11, v11, v12
	v_cvt_pk_bf16_f32 v6, v6, v7
	v_cvt_pk_bf16_f32 v7, v8, v9
	v_cvt_pk_bf16_f32 v8, v2, v3
	v_lshl_add_u64 v[2:3], v[78:79], 0, v[0:1]
	v_mov_b32_e32 v0, v10
	v_add_f32_e32 v11, v15, v11
	v_cvt_pk_bf16_f32 v9, v4, v5
	v_permlane16_swap_b32_e32 v10, v0
	global_store_dwordx4 v[2:3], v[6:9], off
	v_add_f32_e32 v2, v10, v0
	v_mov_b32_e32 v0, v11
	s_nop 1
	v_permlane16_swap_b32_e32 v11, v0
	v_add_f32_e32 v3, v11, v0
	v_mov_b32_e32 v4, v2
	v_mov_b32_e32 v5, v3
	s_nop 0
	v_permlane32_swap_b32_e32 v2, v4
	v_permlane32_swap_b32_e32 v3, v5
	s_and_saveexec_b64 s[26:27], s[44:45]
	s_cbranch_execz .LBB0_388
;     __device__ __forceinline__ void operator()(const f32x4 (&acc)[2][2][4][2], const pg8::Unit& u, int wr, int wc, int fr, int fq) const {
;     ...
;                 if (fq == 0) *(f32x2*)(stn + (size_t)row * 32 + (u.pn * 4 + wc) * 2) = (f32x2){s1, s2}; asm volatile("" ::: "memory"); } }
	v_pk_add_f32 v[2:3], v[2:3], v[4:5]
	v_lshlrev_b64 v[4:5], 7, v[74:75]
	v_lshl_add_u64 v[4:5], s[30:31], 0, v[4:5]
	v_lshl_add_u64 v[4:5], s[24:25], 2, v[4:5]
	global_store_dwordx2 v[4:5], v[2:3], off

; __device__ __forceinline__ float xsum16(float v) { const auto r = __builtin_amdgcn_permlane16_swap(__float_as_uint(v), __float_as_uint(v), false, false); return __uint_as_float(r[0]) + __uint_as_float(r[1]); }
; __device__ __forceinline__ void row_stats4(const float* st, int rowb, int fq, float (&mu)[4], float (&rs)[4]) {
;     f32x4 a[4], b[4];
; #pragma unroll
;     for (int m = 0; m < 4; ++m) { const f32x4* p = (const f32x4*)(st + (size_t)(rowb + m * 16) * 32 + fq * 8); a[m] = p[0]; b[m] = p[1]; }
; #pragma unroll
;     for (int m = 0; m < 4; ++m) { float s1 = (a[m][0] + a[m][2]) + (b[m][0] + b[m][2]), s2 = (a[m][1] + a[m][3]) + (b[m][1] + b[m][3]);
;         s1 = xsum32(xsum16(s1)); s2 = xsum32(xsum16(s2));
;         const float mm = s1 * (1.0f / 1024.0f); mu[m] = mm; rs[m] = rsqrtf(fmaxf(s2 * (1.0f / 1024.0f) - mm * mm, 0.f) + LN_EPS_); }
;     __device__ __forceinline__ void operator()(const f32x4 (&acc)[2][2][4][2], const pg8::Unit& u, int wr, int wc, int fr, int fq) const {
;         const int row0 = u.pm * 256 + wr * 64 + fr, col0 = u.pn * 256 + wc * 32 + fq * 8;
; #pragma unroll
;         for (int ai = 0; ai < 2; ++ai) { float mu4[4], rs4[4]; row_stats4(stp, row0 + ai * 128, fq, mu4, rs4);
; #pragma unroll
;             for (int m = 0; m < 4; ++m) { const int row = row0 + ai * 128 + m * 16; const float mu = mu4[m], rs = rs4[m];
;                 f32x4 yv[2][2], gq[2][2], bq_[2][2];
; #pragma unroll
;                 for (int bj = 0; bj < 2; ++bj)
; #pragma unroll
;                     for (int n = 0; n < 2; ++n) { yv[bj][n] = *(const f32x4*)(Yin + (size_t)row * D_ + col0 + bj * 128 + 4 * n); gq[bj][n] = *(const f32x4*)(g + col0 + bj * 128 + 4 * n); bq_[bj][n] = *(const f32x4*)(b + col0 + bj * 128 + 4 * n); }
;                 asm volatile("" ::: "memory");
;                 float s1 = 0.f, s2 = 0.f;
; #pragma unroll
;                 for (int bj = 0; bj < 2; ++bj) { float* yp = Y + (size_t)row * D_ + col0 + bj * 128; f32x4 v[2];
; #pragma unroll
;                     for (int n = 0; n < 2; ++n) { v[n] = (((yv[bj][n] - mu) * rs) * gq[bj][n] + bq_[bj][n]) * ALPHA_ + acc[ai][bj][m][n] * sc;
;                         *(f32x4*)(yp + 4 * n) = v[n]; s1 += (v[n][0] + v[n][1]) + (v[n][2] + v[n][3]); s2 += (v[n][0] * v[n][0] + v[n][1] * v[n][1]) + (v[n][2] * v[n][2] + v[n][3] * v[n][3]); }
.LBB0_1535:
	s_lshl_b32 s3, s3, 8
	s_add_i32 s3, s3, s0
	v_or_b32_e32 v158, s3, v184
	v_ashrrev_i32_e32 v159, 31, v158
	v_lshlrev_b64 v[130:131], 7, v[158:159]
	v_lshl_add_u64 v[136:137], v[146:147], 0, v[130:131]
	v_or_b32_e32 v180, 16, v158
	global_load_dwordx4 v[132:135], v[136:137], off nt
	global_load_dwordx4 v[166:169], v[136:137], off offset:16 nt
	v_ashrrev_i32_e32 v181, 31, v180
	v_lshlrev_b64 v[172:173], 7, v[180:181]
	v_lshl_add_u64 v[136:137], v[146:147], 0, v[172:173]
	global_load_dwordx4 v[174:177], v[136:137], off nt
	global_load_dwordx4 v[186:189], v[136:137], off offset:16 nt
	v_or_b32_e32 v170, 32, v158
	v_ashrrev_i32_e32 v171, 31, v170
	v_lshlrev_b64 v[164:165], 7, v[170:171]
	v_lshl_add_u64 v[136:137], v[146:147], 0, v[164:165]
	global_load_dwordx4 v[190:193], v[136:137], off nt
	global_load_dwordx4 v[198:201], v[136:137], off offset:16 nt
	v_or_b32_e32 v162, 48, v158
	v_ashrrev_i32_e32 v163, 31, v162
	v_lshlrev_b64 v[160:161], 7, v[162:163]
	v_lshl_add_u64 v[182:183], v[146:147], 0, v[160:161]
	global_load_dwordx4 v[202:205], v[182:183], off nt
	global_load_dwordx4 v[206:209], v[182:183], off offset:16 nt
	s_load_dwordx16 s[64:79], s[34:35], 0x38
	s_lshl_b32 s1, s2, 8
	s_lshl_b32 s14, s2, 3
	s_or_b32 s2, s1, s57
	v_or_b32_e32 v152, s2, v185
	v_ashrrev_i32_e32 v153, 31, v152
	v_lshlrev_b64 v[136:137], 12, v[158:159]
	v_lshlrev_b64 v[178:179], 2, v[152:153]
	s_waitcnt lgkmcnt(0)
	v_lshl_add_u64 v[136:137], s[78:79], 0, v[136:137]
	v_lshl_add_u64 v[156:157], s[8:9], 0, v[178:179]
	v_lshl_add_u64 v[154:155], s[10:11], 0, v[178:179]
	v_lshl_add_u64 v[136:137], v[136:137], 0, v[178:179]
	s_or_b32 s52, s14, s61
	s_mov_b32 s14, 0x3a800000
	global_load_dwordx4 v[210:213], v[136:137], off offset:16 nt
	global_load_dwordx4 v[214:217], v[136:137], off nt
	global_load_dwordx4 v[218:221], v[156:157], off offset:16
	global_load_dwordx4 v[222:225], v[156:157], off
	global_load_dwordx4 v[234:237], v[154:155], off offset:16
	global_load_dwordx4 v[238:241], v[154:155], off
	s_mov_b32 s1, 0x800000
	s_mov_b32 s18, 0x3fd744fd
	v_bitop3_b32 v196, s2, 56, v185 bitop3:0xc8
	s_ashr_i32 s2, s2, 6
	s_ashr_i32 s53, s52, 31
	v_readlane_b32 s16, v253, 59
	v_readlane_b32 s17, v253, 60
	s_waitcnt vmcnt(0)
	v_mov_b32_e32 v178, v132
	v_mov_b32_e32 v179, v166
	v_mov_b32_e32 v182, v134
	v_mov_b32_e32 v183, v168
	v_mov_b32_e32 v166, v133
	v_mov_b32_e32 v168, v135
	v_pk_add_f32 v[132:133], v[178:179], v[182:183]
	v_pk_add_f32 v[134:135], v[166:167], v[168:169]
	v_pk_add_f32 v[132:133], v[132:133], v[132:133] op_sel:[0,1] op_sel_hi:[1,0]
	v_pk_add_f32 v[134:135], v[134:135], v[134:135] op_sel:[0,1] op_sel_hi:[1,0]
	v_mov_b32_e32 v166, v174
	v_mov_b32_e32 v167, v186
	v_mov_b32_e32 v168, v176
	v_mov_b32_e32 v169, v188
	v_mov_b32_e32 v0, v132
	v_mov_b32_e32 v133, v134
	v_pk_add_f32 v[166:167], v[166:167], v[168:169]
	v_permlane16_swap_b32_e32 v132, v0
	v_permlane16_swap_b32_e32 v134, v133
	v_mov_b32_e32 v188, v177
	v_pk_add_f32 v[166:167], v[166:167], v[166:167] op_sel:[0,1] op_sel_hi:[1,0]
	v_add_f32_e32 v177, v132, v0
	v_add_f32_e32 v176, v134, v133
	v_mov_b32_e32 v135, v166
	v_mov_b32_e32 v179, v177
	v_mov_b32_e32 v178, v176
	v_permlane16_swap_b32_e32 v166, v135
	v_permlane32_swap_b32_e32 v177, v179
	v_permlane32_swap_b32_e32 v176, v178
	v_mov_b32_e32 v186, v175
	v_add_f32_e32 v133, v166, v135
	v_pk_add_f32 v[166:167], v[176:177], v[178:179]
	v_pk_add_f32 v[168:169], v[186:187], v[188:189]
	v_pk_mul_f32 v[178:179], v[166:167], s[14:15] op_sel_hi:[1,0]
	v_pk_add_f32 v[168:169], v[168:169], v[168:169] op_sel:[0,1] op_sel_hi:[1,0]
	v_fma_f32 v0, -v179, v179, v178
	v_mov_b32_e32 v159, v168
	v_max_f32_e32 v0, 0, v0
	s_nop 0
	v_permlane16_swap_b32_e32 v168, v159
	v_add_f32_e32 v0, 0x3727c5ac, v0
	v_add_f32_e32 v132, v168, v159
	v_mul_f32_e32 v159, 0x4b800000, v0
	v_cmp_gt_f32_e32 vcc, s1, v0
	v_mov_b32_e32 v174, v190
	v_mov_b32_e32 v175, v198
	v_cndmask_b32_e32 v0, v0, v159, vcc
	v_rsq_f32_e32 v0, v0
	v_mov_b32_e32 v166, v192
	v_mov_b32_e32 v167, v200
	v_pk_add_f32 v[166:167], v[174:175], v[166:167]
	v_mul_f32_e32 v159, 0x45800000, v0
	v_pk_add_f32 v[166:167], v[166:167], v[166:167] op_sel:[0,1] op_sel_hi:[1,0]
	v_mov_b32_e32 v198, v191
	v_mov_b32_e32 v200, v193
	v_cndmask_b32_e32 v0, v0, v159, vcc
	v_pk_add_f32 v[168:169], v[198:199], v[200:201]
	v_mov_b32_e32 v159, v166
	v_pk_add_f32 v[168:169], v[168:169], v[168:169] op_sel:[0,1] op_sel_hi:[1,0]
	s_nop 0
	v_permlane16_swap_b32_e32 v166, v159
	v_add_f32_e32 v175, v166, v159
	v_mov_b32_e32 v159, v168
	s_nop 1
	v_permlane16_swap_b32_e32 v168, v159
	global_load_dwordx4 v[186:189], v[136:137], off offset:528 nt
	global_load_dwordx4 v[190:193], v[136:137], off offset:512 nt
	v_add_f32_e32 v174, v168, v159
	v_mov_b32_e32 v166, v202
	v_mov_b32_e32 v167, v206
	v_mov_b32_e32 v168, v204
	v_mov_b32_e32 v169, v208
	v_mov_b32_e32 v206, v203
	v_mov_b32_e32 v208, v205
	v_pk_add_f32 v[166:167], v[166:167], v[168:169]
	v_pk_add_f32 v[168:169], v[206:207], v[208:209]
	global_load_dwordx4 v[198:201], v[156:157], off offset:528
	global_load_dwordx4 v[202:205], v[156:157], off offset:512
	global_load_dwordx4 v[206:209], v[154:155], off offset:528
	global_load_dwordx4 v[242:245], v[154:155], off offset:512
	v_sub_f32_e32 v183, v215, v179
	v_sub_f32_e32 v182, v214, v179
	v_sub_f32_e32 v215, v217, v179
	v_sub_f32_e32 v214, v216, v179
	v_pk_mul_f32 v[214:215], v[0:1], v[214:215] op_sel_hi:[0,1]
	v_pk_mul_f32 v[182:183], v[0:1], v[182:183] op_sel_hi:[0,1]
	v_pk_fma_f32 v[182:183], v[222:223], v[182:183], v[238:239]
	v_pk_fma_f32 v[214:215], v[224:225], v[214:215], v[240:241]
	v_pk_fma_f32 v[126:127], v[182:183], s[18:19], v[126:127] op_sel_hi:[1,0,1]
; __device__ __forceinline__ float xsum16(float v) { const auto r = __builtin_amdgcn_permlane16_swap(__float_as_uint(v), __float_as_uint(v), false, false); return __uint_as_float(r[0]) + __uint_as_float(r[1]); }
; __device__ __forceinline__ float xsum32(float v) { const auto r = __builtin_amdgcn_permlane32_swap(__float_as_uint(v), __float_as_uint(v), false, false); return __uint_as_float(r[0]) + __uint_as_float(r[1]); }
; __device__ __forceinline__ size_t blk_off(int r, int c, int K) { return (size_t)(r >> 8) * 256 * K + (size_t)(c >> 6) * (256 * 64) + (size_t)((r & 255) * 64 + (c & 63)); }
; __device__ __forceinline__ u32x4 pack8(const f32x4 a, const f32x4 b) { u32x4 w; w.x = cvt_pk_bf16(a[0], a[1]); w.y = cvt_pk_bf16(a[2], a[3]); w.z = cvt_pk_bf16(b[0], b[1]); w.w = cvt_pk_bf16(b[2], b[3]); return w; }
;     __device__ __forceinline__ void operator()(const f32x4 (&acc)[2][2][4][2], const pg8::Unit& u, int wr, int wc, int fr, int fq) const {
;     ...
;                     for (int n = 0; n < 2; ++n) { yv[bj][n] = *(const f32x4*)(Yin + (size_t)row * D_ + col0 + bj * 128 + 4 * n); gq[bj][n] = *(const f32x4*)(g + col0 + bj * 128 + 4 * n); bq_[bj][n] = *(const f32x4*)(b + col0 + bj * 128 + 4 * n); }
;                 asm volatile("" ::: "memory");
;                 float s1 = 0.f, s2 = 0.f;
; #pragma unroll
;                 for (int bj = 0; bj < 2; ++bj) { float* yp = Y + (size_t)row * D_ + col0 + bj * 128; f32x4 v[2];
; #pragma unroll
;                     for (int n = 0; n < 2; ++n) { v[n] = (((yv[bj][n] - mu) * rs) * gq[bj][n] + bq_[bj][n]) * ALPHA_ + acc[ai][bj][m][n] * sc;
;                         *(f32x4*)(yp + 4 * n) = v[n]; s1 += (v[n][0] + v[n][1]) + (v[n][2] + v[n][3]); s2 += (v[n][0] * v[n][0] + v[n][1] * v[n][1]) + (v[n][2] * v[n][2] + v[n][3] * v[n][3]); }
;                     *(u32x4*)(Yb + blk_off(row, col0 + bj * 128, D_)) = pack8(v[0], v[1]); }
;                 s1 = xsum32(xsum16(s1)); s2 = xsum32(xsum16(s2));
;                 if (fq == 0) *(f32x2*)(stn + (size_t)row * 32 + (u.pn * 4 + wc) * 2) = (f32x2){s1, s2}; asm volatile("" ::: "memory"); } }
	v_pk_fma_f32 v[128:129], v[214:215], s[18:19], v[128:129] op_sel_hi:[1,0,1]
	v_add_f32_e32 v178, v126, v127
	v_add_f32_e32 v182, v128, v129
	v_add_f32_e32 v178, v178, v182
	v_mul_f32_e32 v182, v127, v127
	v_mul_f32_e32 v183, v129, v129
	v_fmac_f32_e32 v182, v126, v126
	v_fmac_f32_e32 v183, v128, v128
	v_add_f32_e32 v197, v182, v183
	v_sub_f32_e32 v183, v211, v179
	v_sub_f32_e32 v182, v210, v179
	v_sub_f32_e32 v211, v213, v179
	v_sub_f32_e32 v210, v212, v179
	v_pk_mul_f32 v[210:211], v[0:1], v[210:211] op_sel_hi:[0,1]
	v_pk_mul_f32 v[182:183], v[0:1], v[182:183] op_sel_hi:[0,1]
	v_pk_fma_f32 v[182:183], v[218:219], v[182:183], v[234:235]
	v_pk_fma_f32 v[210:211], v[220:221], v[210:211], v[236:237]
	v_pk_add_f32 v[166:167], v[166:167], v[166:167] op_sel:[0,1] op_sel_hi:[1,0]
	v_pk_fma_f32 v[124:125], v[210:211], s[18:19], v[124:125] op_sel_hi:[1,0,1]
	v_pk_fma_f32 v[122:123], v[182:183], s[18:19], v[122:123] op_sel_hi:[1,0,1]
	v_mov_b32_e32 v159, v166
	v_add_f32_e32 v182, v122, v123
	v_add_f32_e32 v183, v124, v125
	v_pk_add_f32 v[168:169], v[168:169], v[168:169] op_sel:[0,1] op_sel_hi:[1,0]
	v_permlane16_swap_b32_e32 v166, v159
	v_add_f32_e32 v178, 0, v178
	v_add_f32_e32 v182, v182, v183
	v_add_f32_e32 v167, v166, v159
	v_mov_b32_e32 v159, v168
	s_ashr_i32 s14, s3, 8
	v_add_f32_e32 v178, v178, v182
	v_mul_f32_e32 v182, v123, v123
	v_mul_f32_e32 v183, v125, v125
	v_permlane16_swap_b32_e32 v168, v159
	s_ashr_i32 s15, s14, 31
	s_nop 0
	s_nop 1
	v_bfe_u32 v135, v227, 4, 2
	v_sub_u32_e32 v134, 0, v135
	v_lshlrev_b32_e32 v134, 4, v134
	v_ashrrev_i32_e32 v135, 31, v134
	v_lshl_add_u64 v[134:135], v[136:137], 0, v[134:135]
	v_permlane16_swap_b32_e32 v126, v122
	v_permlane16_swap_b32_e32 v127, v123
	v_permlane16_swap_b32_e32 v128, v124
	v_permlane16_swap_b32_e32 v129, v125
	v_permlane32_swap_b32_e32 v126, v122
	v_permlane32_swap_b32_e32 v127, v123
	v_permlane32_swap_b32_e32 v128, v124
	v_permlane32_swap_b32_e32 v129, v125
	global_store_dwordx4 v[134:135], v[126:129], off
	global_store_dwordx4 v[134:135], v[122:125], off offset:64
	s_nop 1
	v_permlane32_swap_b32_e32 v126, v122
	v_permlane32_swap_b32_e32 v127, v123
	v_permlane32_swap_b32_e32 v128, v124
	v_permlane32_swap_b32_e32 v129, v125
	v_permlane16_swap_b32_e32 v126, v122
	v_permlane16_swap_b32_e32 v127, v123
	v_permlane16_swap_b32_e32 v128, v124
	v_permlane16_swap_b32_e32 v129, v125
	v_fmac_f32_e32 v182, v122, v122
	v_fmac_f32_e32 v183, v124, v124
	v_cvt_pk_bf16_f32 v126, v126, v127
	v_cvt_pk_bf16_f32 v127, v128, v129
	v_cvt_pk_bf16_f32 v128, v122, v123
	v_cvt_pk_bf16_f32 v129, v124, v125
	v_add_f32_e32 v166, v168, v159
	s_lshl_b64 s[14:15], s[14:15], 19
	v_lshlrev_b32_e32 v159, 6, v158
	s_movk_i32 s1, 0x33c0
	s_ashr_i32 s3, s2, 31
	v_and_or_b32 v159, v159, s1, v196
	s_add_u32 s1, s16, s14
	s_addc_u32 s14, s17, s15
	s_lshl_b64 s[24:25], s[2:3], 15
	s_add_u32 s42, s1, s24
	s_addc_u32 s43, s14, s25
	v_lshlrev_b32_e32 v159, 1, v159
	global_store_dwordx4 v159, v[126:129], s[42:43]
	v_add_f32_e32 v182, v182, v183
	s_waitcnt vmcnt(7)
	v_sub_f32_e32 v123, v191, v179
	v_sub_f32_e32 v122, v190, v179
	v_sub_f32_e32 v125, v193, v179
	v_sub_f32_e32 v124, v192, v179
	v_pk_mul_f32 v[124:125], v[0:1], v[124:125] op_sel_hi:[0,1]
	v_pk_mul_f32 v[122:123], v[0:1], v[122:123] op_sel_hi:[0,1]
	v_add_f32_e32 v182, v197, v182
	s_or_b32 s2, s2, 2
	s_ashr_i32 s3, s2, 31
	s_lshl_b64 s[28:29], s[2:3], 15
	s_waitcnt vmcnt(3)
	v_pk_fma_f32 v[122:123], v[202:203], v[122:123], v[242:243]
	v_pk_fma_f32 v[124:125], v[204:205], v[124:125], v[244:245]
	v_pk_fma_f32 v[118:119], v[122:123], s[18:19], v[118:119] op_sel_hi:[1,0,1]
	v_pk_fma_f32 v[120:121], v[124:125], s[18:19], v[120:121] op_sel_hi:[1,0,1]
	v_add_f32_e32 v122, v118, v119
	v_add_f32_e32 v123, v120, v121
	v_add_f32_e32 v122, v122, v123
	v_add_f32_e32 v126, v178, v122
	v_mul_f32_e32 v122, v119, v119
	v_mul_f32_e32 v123, v121, v121
	v_fmac_f32_e32 v122, v118, v118
	v_fmac_f32_e32 v123, v120, v120
	v_add_f32_e32 v122, v122, v123
	v_add_f32_e32 v127, v182, v122
	v_sub_f32_e32 v123, v187, v179
	v_sub_f32_e32 v122, v186, v179
	v_sub_f32_e32 v125, v189, v179
	v_sub_f32_e32 v124, v188, v179
	v_pk_mul_f32 v[124:125], v[0:1], v[124:125] op_sel_hi:[0,1]
	v_pk_mul_f32 v[122:123], v[0:1], v[122:123] op_sel_hi:[0,1]
	v_pk_fma_f32 v[122:123], v[198:199], v[122:123], v[206:207]
	v_pk_fma_f32 v[124:125], v[200:201], v[124:125], v[208:209]
	v_pk_fma_f32 v[114:115], v[122:123], s[18:19], v[114:115] op_sel_hi:[1,0,1]
	v_pk_fma_f32 v[116:117], v[124:125], s[18:19], v[116:117] op_sel_hi:[1,0,1]
	v_add_f32_e32 v0, v114, v115
	v_add_f32_e32 v122, v116, v117
	v_add_f32_e32 v0, v0, v122
	v_mul_f32_e32 v122, v115, v115
	v_mul_f32_e32 v123, v117, v117
	v_add_f32_e32 v0, v126, v0
	v_fmac_f32_e32 v122, v114, v114
	v_fmac_f32_e32 v123, v116, v116
	s_nop 0
	s_nop 1
	v_bfe_u32 v125, v227, 4, 2
	v_sub_u32_e32 v124, 0, v125
	v_lshlrev_b32_e32 v124, 4, v124
	v_ashrrev_i32_e32 v125, 31, v124
	v_lshl_add_u64 v[124:125], v[136:137], 0, v[124:125]
	v_permlane16_swap_b32_e32 v118, v114
	v_permlane16_swap_b32_e32 v119, v115
	v_permlane16_swap_b32_e32 v120, v116
	v_permlane16_swap_b32_e32 v121, v117
	v_permlane32_swap_b32_e32 v118, v114
	v_permlane32_swap_b32_e32 v119, v115
	v_permlane32_swap_b32_e32 v120, v116
	v_permlane32_swap_b32_e32 v121, v117
	global_store_dwordx4 v[124:125], v[118:121], off offset:512
	global_store_dwordx4 v[124:125], v[114:117], off offset:576
	s_nop 1
	v_permlane32_swap_b32_e32 v118, v114
	v_permlane32_swap_b32_e32 v119, v115
	v_permlane32_swap_b32_e32 v120, v116
	v_permlane32_swap_b32_e32 v121, v117
	v_permlane16_swap_b32_e32 v118, v114
	v_permlane16_swap_b32_e32 v119, v115
	v_permlane16_swap_b32_e32 v120, v116
	v_permlane16_swap_b32_e32 v121, v117
	v_add_f32_e32 v122, v122, v123
	v_cvt_pk_bf16_f32 v118, v118, v119
	v_cvt_pk_bf16_f32 v119, v120, v121
	v_cvt_pk_bf16_f32 v120, v114, v115
	v_mov_b32_e32 v114, v0
	v_add_f32_e32 v122, v127, v122
	s_nop 0
	v_permlane16_swap_b32_e32 v0, v114
	v_add_f32_e32 v114, v0, v114
	v_mov_b32_e32 v0, v122
	s_nop 1
	v_permlane16_swap_b32_e32 v122, v0
	v_add_f32_e32 v115, v122, v0
	v_mov_b32_e32 v135, v133
	v_mov_b32_e32 v134, v132
	v_mov_b32_e32 v177, v175
	v_mov_b32_e32 v176, v174
	v_mov_b32_e32 v169, v167
	v_mov_b32_e32 v168, v166
	v_cvt_pk_bf16_f32 v121, v116, v117
	s_add_u32 s40, s1, s28
	v_mov_b32_e32 v116, v114
	v_mov_b32_e32 v117, v115
	v_permlane32_swap_b32_e32 v133, v135
	v_permlane32_swap_b32_e32 v132, v134
	v_permlane32_swap_b32_e32 v175, v177
	v_permlane32_swap_b32_e32 v174, v176
	v_permlane32_swap_b32_e32 v167, v169
	v_permlane32_swap_b32_e32 v166, v168
	s_addc_u32 s41, s14, s29
	v_permlane32_swap_b32_e32 v114, v116
	v_permlane32_swap_b32_e32 v115, v117
	global_store_dwordx4 v159, v[118:121], s[40:41]
	s_and_saveexec_b64 s[26:27], s[44:45]
	s_cbranch_execz .LBB0_1537
	v_pk_add_f32 v[114:115], v[114:115], v[116:117]
	v_lshl_add_u64 v[116:117], s[6:7], 0, v[130:131]
	v_lshl_add_u64 v[116:117], s[52:53], 2, v[116:117]
	global_store_dwordx2 v[116:117], v[114:115], off
; __device__ __forceinline__ float xsum16(float v) { const auto r = __builtin_amdgcn_permlane16_swap(__float_as_uint(v), __float_as_uint(v), false, false); return __uint_as_float(r[0]) + __uint_as_float(r[1]); }
; __device__ __forceinline__ float xsum32(float v) { const auto r = __builtin_amdgcn_permlane32_swap(__float_as_uint(v), __float_as_uint(v), false, false); return __uint_as_float(r[0]) + __uint_as_float(r[1]); }
; __device__ __forceinline__ size_t blk_off(int r, int c, int K) { return (size_t)(r >> 8) * 256 * K + (size_t)(c >> 6) * (256 * 64) + (size_t)((r & 255) * 64 + (c & 63)); }
; __device__ __forceinline__ u32x4 pack8(const f32x4 a, const f32x4 b) { u32x4 w; w.x = cvt_pk_bf16(a[0], a[1]); w.y = cvt_pk_bf16(a[2], a[3]); w.z = cvt_pk_bf16(b[0], b[1]); w.w = cvt_pk_bf16(b[2], b[3]); return w; }
; __device__ __forceinline__ void row_stats(const float* st, int row, int fq, float& mu, float& rstd) {
;     ...
;     mu = s1 * (1.0f / 1024.0f); const float var = fmaxf(s2 * (1.0f / 1024.0f) - mu * mu, 0.f); rstd = rsqrtf(var + LN_EPS_);
;     __device__ __forceinline__ void operator()(const f32x4 (&acc)[2][2][4][2], const pg8::Unit& u, int wr, int wc, int fr, int fq) const {
;     ...
;                     for (int n = 0; n < 2; ++n) { yv[bj][n] = *(const f32x4*)(Yin + (size_t)row * D_ + col0 + bj * 128 + 4 * n); gq[bj][n] = *(const f32x4*)(g + col0 + bj * 128 + 4 * n); bq_[bj][n] = *(const f32x4*)(b + col0 + bj * 128 + 4 * n); }
;                 asm volatile("" ::: "memory");
;                 float s1 = 0.f, s2 = 0.f;
; #pragma unroll
;                 for (int bj = 0; bj < 2; ++bj) { float* yp = Y + (size_t)row * D_ + col0 + bj * 128; f32x4 v[2];
; #pragma unroll
;                     for (int n = 0; n < 2; ++n) { v[n] = (((yv[bj][n] - mu) * rs) * gq[bj][n] + bq_[bj][n]) * ALPHA_ + acc[ai][bj][m][n] * sc;
;                         *(f32x4*)(yp + 4 * n) = v[n]; s1 += (v[n][0] + v[n][1]) + (v[n][2] + v[n][3]); s2 += (v[n][0] * v[n][0] + v[n][1] * v[n][1]) + (v[n][2] * v[n][2] + v[n][3] * v[n][3]); }
;                     *(u32x4*)(Yb + blk_off(row, col0 + bj * 128, D_)) = pack8(v[0], v[1]); }
;                 s1 = xsum32(xsum16(s1)); s2 = xsum32(xsum16(s2));
;                 if (fq == 0) *(f32x2*)(stn + (size_t)row * 32 + (u.pn * 4 + wc) * 2) = (f32x2){s1, s2}; asm volatile("" ::: "memory"); } }
.LBB0_1537:
	s_or_b64 exec, exec, s[26:27]
	v_pk_add_f32 v[114:115], v[132:133], v[134:135]
	s_mov_b32 s2, 0x3a800000
	v_pk_mul_f32 v[178:179], v[114:115], s[2:3] op_sel_hi:[1,0]
	s_mov_b32 s1, 0x800000
	v_fma_f32 v0, -v179, v179, v178
	v_max_f32_e32 v0, 0, v0
	v_add_f32_e32 v0, 0x3727c5ac, v0
	v_cmp_gt_f32_e32 vcc, s1, v0
	v_mul_f32_e32 v114, 0x4b800000, v0
	s_load_dwordx16 s[64:79], s[34:35], 0x38
	v_cndmask_b32_e32 v0, v0, v114, vcc
	v_rsq_f32_e32 v0, v0
	v_lshlrev_b32_e32 v159, 6, v180
	s_mov_b32 s2, 0x3fd744fd
	v_mul_f32_e32 v114, 0x45800000, v0
	v_cndmask_b32_e32 v0, v0, v114, vcc
	v_lshlrev_b64 v[114:115], 12, v[180:181]
	s_waitcnt lgkmcnt(0)
	v_lshl_add_u64 v[114:115], s[78:79], 0, v[114:115]
	v_lshl_add_u64 v[182:183], v[152:153], 2, v[114:115]
	global_load_dwordx4 v[186:189], v[182:183], off offset:16 nt
	global_load_dwordx4 v[190:193], v[182:183], off nt
	global_load_dwordx4 v[198:201], v[156:157], off offset:16
	global_load_dwordx4 v[202:205], v[156:157], off
	global_load_dwordx4 v[206:209], v[154:155], off offset:16
	global_load_dwordx4 v[210:213], v[154:155], off
	global_load_dwordx4 v[114:117], v[182:183], off offset:528 nt
	global_load_dwordx4 v[134:137], v[182:183], off offset:512 nt
	global_load_dwordx4 v[118:121], v[156:157], off offset:528
	global_load_dwordx4 v[126:129], v[156:157], off offset:512
	global_load_dwordx4 v[122:125], v[154:155], off offset:528
	global_load_dwordx4 v[130:133], v[154:155], off offset:512
	s_movk_i32 s1, 0x37c0
	v_and_or_b32 v159, v159, s1, v196
	v_lshlrev_b32_e32 v159, 1, v159
	s_waitcnt vmcnt(10)
	v_sub_f32_e32 v181, v191, v179
	v_sub_f32_e32 v180, v190, v179
	v_sub_f32_e32 v191, v193, v179
	v_sub_f32_e32 v190, v192, v179
	v_pk_mul_f32 v[190:191], v[0:1], v[190:191] op_sel_hi:[0,1]
	v_pk_mul_f32 v[180:181], v[0:1], v[180:181] op_sel_hi:[0,1]
	s_waitcnt vmcnt(6)
	v_pk_fma_f32 v[180:181], v[202:203], v[180:181], v[210:211]
	v_pk_fma_f32 v[190:191], v[204:205], v[190:191], v[212:213]
	v_pk_fma_f32 v[110:111], v[180:181], s[2:3], v[110:111] op_sel_hi:[1,0,1]
	v_pk_fma_f32 v[112:113], v[190:191], s[2:3], v[112:113] op_sel_hi:[1,0,1]
	v_add_f32_e32 v178, v110, v111
	v_add_f32_e32 v180, v112, v113
	v_add_f32_e32 v178, v178, v180
	v_mul_f32_e32 v180, v111, v111
	v_mul_f32_e32 v181, v113, v113
	v_fmac_f32_e32 v180, v110, v110
	v_fmac_f32_e32 v181, v112, v112
	v_add_f32_e32 v190, v180, v181
	v_sub_f32_e32 v181, v187, v179
	v_sub_f32_e32 v180, v186, v179
	v_sub_f32_e32 v187, v189, v179
	v_sub_f32_e32 v186, v188, v179
	v_pk_mul_f32 v[186:187], v[0:1], v[186:187] op_sel_hi:[0,1]
	v_pk_mul_f32 v[180:181], v[0:1], v[180:181] op_sel_hi:[0,1]
	v_pk_fma_f32 v[180:181], v[198:199], v[180:181], v[206:207]
	v_pk_fma_f32 v[186:187], v[200:201], v[186:187], v[208:209]
	v_pk_fma_f32 v[106:107], v[180:181], s[2:3], v[106:107] op_sel_hi:[1,0,1]
	v_pk_fma_f32 v[108:109], v[186:187], s[2:3], v[108:109] op_sel_hi:[1,0,1]
	v_add_f32_e32 v180, v106, v107
	v_add_f32_e32 v181, v108, v109
	v_add_f32_e32 v178, 0, v178
	v_add_f32_e32 v180, v180, v181
	v_add_f32_e32 v178, v178, v180
	v_mul_f32_e32 v180, v107, v107
	v_mul_f32_e32 v181, v109, v109
	s_nop 0
	s_nop 1
	v_bfe_u32 v187, v227, 4, 2
	v_sub_u32_e32 v186, 0, v187
	v_lshlrev_b32_e32 v186, 4, v186
	v_ashrrev_i32_e32 v187, 31, v186
	v_lshl_add_u64 v[186:187], v[182:183], 0, v[186:187]
	v_permlane16_swap_b32_e32 v110, v106
	v_permlane16_swap_b32_e32 v111, v107
	v_permlane16_swap_b32_e32 v112, v108
	v_permlane16_swap_b32_e32 v113, v109
	v_permlane32_swap_b32_e32 v110, v106
	v_permlane32_swap_b32_e32 v111, v107
	v_permlane32_swap_b32_e32 v112, v108
	v_permlane32_swap_b32_e32 v113, v109
	global_store_dwordx4 v[186:187], v[110:113], off
	global_store_dwordx4 v[186:187], v[106:109], off offset:64
	s_nop 1
	v_permlane32_swap_b32_e32 v110, v106
	v_permlane32_swap_b32_e32 v111, v107
	v_permlane32_swap_b32_e32 v112, v108
	v_permlane32_swap_b32_e32 v113, v109
	v_permlane16_swap_b32_e32 v110, v106
	v_permlane16_swap_b32_e32 v111, v107
	v_permlane16_swap_b32_e32 v112, v108
	v_permlane16_swap_b32_e32 v113, v109
	v_fmac_f32_e32 v180, v106, v106
	v_fmac_f32_e32 v181, v108, v108
	v_cvt_pk_bf16_f32 v110, v110, v111
	v_cvt_pk_bf16_f32 v111, v112, v113
	v_cvt_pk_bf16_f32 v112, v106, v107
	v_cvt_pk_bf16_f32 v113, v108, v109
	s_waitcnt vmcnt(6)
	v_sub_f32_e32 v107, v135, v179
	v_sub_f32_e32 v106, v134, v179
	v_sub_f32_e32 v109, v137, v179
	v_sub_f32_e32 v108, v136, v179
	v_pk_mul_f32 v[108:109], v[0:1], v[108:109] op_sel_hi:[0,1]
	v_pk_mul_f32 v[106:107], v[0:1], v[106:107] op_sel_hi:[0,1]
	s_waitcnt vmcnt(2)
; __device__ __forceinline__ float xsum16(float v) { const auto r = __builtin_amdgcn_permlane16_swap(__float_as_uint(v), __float_as_uint(v), false, false); return __uint_as_float(r[0]) + __uint_as_float(r[1]); }
; __device__ __forceinline__ float xsum32(float v) { const auto r = __builtin_amdgcn_permlane32_swap(__float_as_uint(v), __float_as_uint(v), false, false); return __uint_as_float(r[0]) + __uint_as_float(r[1]); }
; __device__ __forceinline__ size_t blk_off(int r, int c, int K) { return (size_t)(r >> 8) * 256 * K + (size_t)(c >> 6) * (256 * 64) + (size_t)((r & 255) * 64 + (c & 63)); }
; __device__ __forceinline__ u32x4 pack8(const f32x4 a, const f32x4 b) { u32x4 w; w.x = cvt_pk_bf16(a[0], a[1]); w.y = cvt_pk_bf16(a[2], a[3]); w.z = cvt_pk_bf16(b[0], b[1]); w.w = cvt_pk_bf16(b[2], b[3]); return w; }
; __device__ __forceinline__ void row_stats(const float* st, int row, int fq, float& mu, float& rstd) {
;     ...
;     mu = s1 * (1.0f / 1024.0f); const float var = fmaxf(s2 * (1.0f / 1024.0f) - mu * mu, 0.f); rstd = rsqrtf(var + LN_EPS_);
;     __device__ __forceinline__ void operator()(const f32x4 (&acc)[2][2][4][2], const pg8::Unit& u, int wr, int wc, int fr, int fq) const {
;     ...
;                     for (int n = 0; n < 2; ++n) { yv[bj][n] = *(const f32x4*)(Yin + (size_t)row * D_ + col0 + bj * 128 + 4 * n); gq[bj][n] = *(const f32x4*)(g + col0 + bj * 128 + 4 * n); bq_[bj][n] = *(const f32x4*)(b + col0 + bj * 128 + 4 * n); }
;                 asm volatile("" ::: "memory");
;                 float s1 = 0.f, s2 = 0.f;
; #pragma unroll
;                 for (int bj = 0; bj < 2; ++bj) { float* yp = Y + (size_t)row * D_ + col0 + bj * 128; f32x4 v[2];
; #pragma unroll
;                     for (int n = 0; n < 2; ++n) { v[n] = (((yv[bj][n] - mu) * rs) * gq[bj][n] + bq_[bj][n]) * ALPHA_ + acc[ai][bj][m][n] * sc;
;                         *(f32x4*)(yp + 4 * n) = v[n]; s1 += (v[n][0] + v[n][1]) + (v[n][2] + v[n][3]); s2 += (v[n][0] * v[n][0] + v[n][1] * v[n][1]) + (v[n][2] * v[n][2] + v[n][3] * v[n][3]); }
;                     *(u32x4*)(Yb + blk_off(row, col0 + bj * 128, D_)) = pack8(v[0], v[1]); }
;                 s1 = xsum32(xsum16(s1)); s2 = xsum32(xsum16(s2));
;                 if (fq == 0) *(f32x2*)(stn + (size_t)row * 32 + (u.pn * 4 + wc) * 2) = (f32x2){s1, s2}; asm volatile("" ::: "memory"); } }
	v_pk_fma_f32 v[106:107], v[126:127], v[106:107], v[130:131]
	v_pk_fma_f32 v[108:109], v[128:129], v[108:109], v[132:133]
	v_pk_fma_f32 v[102:103], v[106:107], s[2:3], v[102:103] op_sel_hi:[1,0,1]
	v_pk_fma_f32 v[104:105], v[108:109], s[2:3], v[104:105] op_sel_hi:[1,0,1]
	v_add_f32_e32 v106, v102, v103
	v_add_f32_e32 v107, v104, v105
	v_add_f32_e32 v106, v106, v107
	global_store_dwordx4 v159, v[110:113], s[42:43]
	v_mul_f32_e32 v107, v105, v105
	v_add_f32_e32 v180, v180, v181
	v_add_f32_e32 v110, v178, v106
	v_mul_f32_e32 v106, v103, v103
	v_fmac_f32_e32 v106, v102, v102
	v_fmac_f32_e32 v107, v104, v104
	v_add_f32_e32 v180, v190, v180
	v_add_f32_e32 v106, v106, v107
	v_add_f32_e32 v111, v180, v106
	v_sub_f32_e32 v107, v115, v179
	v_sub_f32_e32 v106, v114, v179
	v_sub_f32_e32 v109, v117, v179
	v_sub_f32_e32 v108, v116, v179
	v_pk_mul_f32 v[108:109], v[0:1], v[108:109] op_sel_hi:[0,1]
	v_pk_mul_f32 v[106:107], v[0:1], v[106:107] op_sel_hi:[0,1]
	v_pk_fma_f32 v[106:107], v[118:119], v[106:107], v[122:123]
	v_pk_fma_f32 v[108:109], v[120:121], v[108:109], v[124:125]
	v_pk_fma_f32 v[98:99], v[106:107], s[2:3], v[98:99] op_sel_hi:[1,0,1]
	v_pk_fma_f32 v[100:101], v[108:109], s[2:3], v[100:101] op_sel_hi:[1,0,1]
	v_add_f32_e32 v0, v98, v99
	v_add_f32_e32 v106, v100, v101
	v_add_f32_e32 v0, v0, v106
	v_mul_f32_e32 v106, v99, v99
	v_mul_f32_e32 v107, v101, v101
	v_add_f32_e32 v0, v110, v0
	v_fmac_f32_e32 v106, v98, v98
	v_fmac_f32_e32 v107, v100, v100
	s_nop 0
	s_nop 1
	v_bfe_u32 v109, v227, 4, 2
	v_sub_u32_e32 v108, 0, v109
	v_lshlrev_b32_e32 v108, 4, v108
	v_ashrrev_i32_e32 v109, 31, v108
	v_lshl_add_u64 v[108:109], v[182:183], 0, v[108:109]
	v_permlane16_swap_b32_e32 v102, v98
	v_permlane16_swap_b32_e32 v103, v99
	v_permlane16_swap_b32_e32 v104, v100
	v_permlane16_swap_b32_e32 v105, v101
	v_permlane32_swap_b32_e32 v102, v98
	v_permlane32_swap_b32_e32 v103, v99
	v_permlane32_swap_b32_e32 v104, v100
	v_permlane32_swap_b32_e32 v105, v101
	global_store_dwordx4 v[108:109], v[102:105], off offset:512
	global_store_dwordx4 v[108:109], v[98:101], off offset:576
	s_nop 1
	v_permlane32_swap_b32_e32 v102, v98
	v_permlane32_swap_b32_e32 v103, v99
	v_permlane32_swap_b32_e32 v104, v100
	v_permlane32_swap_b32_e32 v105, v101
	v_permlane16_swap_b32_e32 v102, v98
	v_permlane16_swap_b32_e32 v103, v99
	v_permlane16_swap_b32_e32 v104, v100
	v_permlane16_swap_b32_e32 v105, v101
	v_add_f32_e32 v106, v106, v107
	v_cvt_pk_bf16_f32 v102, v102, v103
	v_cvt_pk_bf16_f32 v103, v104, v105
	v_cvt_pk_bf16_f32 v104, v98, v99
	v_mov_b32_e32 v98, v0
	v_add_f32_e32 v106, v111, v106
	s_nop 0
	v_permlane16_swap_b32_e32 v0, v98
	v_add_f32_e32 v98, v0, v98
	v_mov_b32_e32 v0, v106
	s_nop 1
	v_permlane16_swap_b32_e32 v106, v0
	v_add_f32_e32 v99, v106, v0
	v_cvt_pk_bf16_f32 v105, v100, v101
	v_mov_b32_e32 v100, v98
	v_mov_b32_e32 v101, v99
	s_nop 0
	v_permlane32_swap_b32_e32 v98, v100
	v_permlane32_swap_b32_e32 v99, v101
	global_store_dwordx4 v159, v[102:105], s[40:41]
	s_and_saveexec_b64 s[26:27], s[44:45]
	s_cbranch_execz .LBB0_1539
	v_pk_add_f32 v[98:99], v[98:99], v[100:101]
	v_lshl_add_u64 v[100:101], s[6:7], 0, v[172:173]
	v_lshl_add_u64 v[100:101], s[52:53], 2, v[100:101]
	global_store_dwordx2 v[100:101], v[98:99], off
.LBB0_1539:
	s_or_b64 exec, exec, s[26:27]
	v_pk_add_f32 v[98:99], v[174:175], v[176:177]
	s_mov_b32 s2, 0x3a800000
	v_pk_mul_f32 v[122:123], v[98:99], s[2:3] op_sel_hi:[1,0]
	s_mov_b32 s1, 0x800000
	v_fma_f32 v0, -v123, v123, v122
	v_max_f32_e32 v0, 0, v0
	v_add_f32_e32 v0, 0x3727c5ac, v0
	v_cmp_gt_f32_e32 vcc, s1, v0
	v_mul_f32_e32 v98, 0x4b800000, v0
	s_load_dwordx16 s[64:79], s[34:35], 0x38
	v_cndmask_b32_e32 v0, v0, v98, vcc
	v_rsq_f32_e32 v0, v0
	s_mov_b32 s2, 0x3fd744fd
	v_lshlrev_b32_e32 v122, 6, v170
	v_mul_f32_e32 v98, 0x45800000, v0
	v_cndmask_b32_e32 v0, v0, v98, vcc
	v_lshlrev_b64 v[98:99], 12, v[170:171]
	s_waitcnt lgkmcnt(0)
	v_lshl_add_u64 v[98:99], s[78:79], 0, v[98:99]
	v_lshl_add_u64 v[124:125], v[152:153], 2, v[98:99]
	global_load_dwordx4 v[126:129], v[124:125], off offset:16 nt
	global_load_dwordx4 v[130:133], v[124:125], off nt
	global_load_dwordx4 v[134:137], v[156:157], off offset:16
	global_load_dwordx4 v[172:175], v[156:157], off
	global_load_dwordx4 v[176:179], v[154:155], off offset:16
	global_load_dwordx4 v[180:183], v[154:155], off
	global_load_dwordx4 v[98:101], v[124:125], off offset:528 nt
	global_load_dwordx4 v[118:121], v[124:125], off offset:512 nt
	global_load_dwordx4 v[102:105], v[156:157], off offset:528
	global_load_dwordx4 v[110:113], v[156:157], off offset:512
	global_load_dwordx4 v[106:109], v[154:155], off offset:528
	global_load_dwordx4 v[114:117], v[154:155], off offset:512
	s_movk_i32 s1, 0x3bc0
	v_and_or_b32 v122, v122, s1, v196
	v_lshlrev_b32_e32 v122, 1, v122
	s_waitcnt vmcnt(11)
	v_sub_f32_e32 v127, v127, v123
	s_waitcnt vmcnt(10)
	v_sub_f32_e32 v131, v131, v123
	v_sub_f32_e32 v130, v130, v123
	v_sub_f32_e32 v133, v133, v123
	v_sub_f32_e32 v132, v132, v123
	v_sub_f32_e32 v126, v126, v123
	v_sub_f32_e32 v129, v129, v123
	v_sub_f32_e32 v128, v128, v123
	v_pk_mul_f32 v[132:133], v[0:1], v[132:133] op_sel_hi:[0,1]
	v_pk_mul_f32 v[130:131], v[0:1], v[130:131] op_sel_hi:[0,1]
	v_pk_mul_f32 v[128:129], v[0:1], v[128:129] op_sel_hi:[0,1]
	v_pk_mul_f32 v[126:127], v[0:1], v[126:127] op_sel_hi:[0,1]
	s_waitcnt vmcnt(6)
; __device__ __forceinline__ float xsum16(float v) { const auto r = __builtin_amdgcn_permlane16_swap(__float_as_uint(v), __float_as_uint(v), false, false); return __uint_as_float(r[0]) + __uint_as_float(r[1]); }
; __device__ __forceinline__ float xsum32(float v) { const auto r = __builtin_amdgcn_permlane32_swap(__float_as_uint(v), __float_as_uint(v), false, false); return __uint_as_float(r[0]) + __uint_as_float(r[1]); }
; __device__ __forceinline__ size_t blk_off(int r, int c, int K) { return (size_t)(r >> 8) * 256 * K + (size_t)(c >> 6) * (256 * 64) + (size_t)((r & 255) * 64 + (c & 63)); }
; __device__ __forceinline__ u32x4 pack8(const f32x4 a, const f32x4 b) { u32x4 w; w.x = cvt_pk_bf16(a[0], a[1]); w.y = cvt_pk_bf16(a[2], a[3]); w.z = cvt_pk_bf16(b[0], b[1]); w.w = cvt_pk_bf16(b[2], b[3]); return w; }
;     __device__ __forceinline__ void operator()(const f32x4 (&acc)[2][2][4][2], const pg8::Unit& u, int wr, int wc, int fr, int fq) const {
;     ...
;                     for (int n = 0; n < 2; ++n) { yv[bj][n] = *(const f32x4*)(Yin + (size_t)row * D_ + col0 + bj * 128 + 4 * n); gq[bj][n] = *(const f32x4*)(g + col0 + bj * 128 + 4 * n); bq_[bj][n] = *(const f32x4*)(b + col0 + bj * 128 + 4 * n); }
;                 asm volatile("" ::: "memory");
;                 float s1 = 0.f, s2 = 0.f;
; #pragma unroll
;                 for (int bj = 0; bj < 2; ++bj) { float* yp = Y + (size_t)row * D_ + col0 + bj * 128; f32x4 v[2];
; #pragma unroll
;                     for (int n = 0; n < 2; ++n) { v[n] = (((yv[bj][n] - mu) * rs) * gq[bj][n] + bq_[bj][n]) * ALPHA_ + acc[ai][bj][m][n] * sc;
;                         *(f32x4*)(yp + 4 * n) = v[n]; s1 += (v[n][0] + v[n][1]) + (v[n][2] + v[n][3]); s2 += (v[n][0] * v[n][0] + v[n][1] * v[n][1]) + (v[n][2] * v[n][2] + v[n][3] * v[n][3]); }
;                     *(u32x4*)(Yb + blk_off(row, col0 + bj * 128, D_)) = pack8(v[0], v[1]); }
;                 s1 = xsum32(xsum16(s1)); s2 = xsum32(xsum16(s2));
;                 if (fq == 0) *(f32x2*)(stn + (size_t)row * 32 + (u.pn * 4 + wc) * 2) = (f32x2){s1, s2}; asm volatile("" ::: "memory"); } }
	v_pk_fma_f32 v[130:131], v[172:173], v[130:131], v[180:181]
	v_pk_fma_f32 v[132:133], v[174:175], v[132:133], v[182:183]
	v_pk_fma_f32 v[126:127], v[134:135], v[126:127], v[176:177]
	v_pk_fma_f32 v[128:129], v[136:137], v[128:129], v[178:179]
	v_pk_fma_f32 v[96:97], v[132:133], s[2:3], v[96:97] op_sel_hi:[1,0,1]
	v_pk_fma_f32 v[94:95], v[130:131], s[2:3], v[94:95] op_sel_hi:[1,0,1]
	v_pk_fma_f32 v[92:93], v[128:129], s[2:3], v[92:93] op_sel_hi:[1,0,1]
	v_pk_fma_f32 v[90:91], v[126:127], s[2:3], v[90:91] op_sel_hi:[1,0,1]
	v_add_f32_e32 v130, v94, v95
	v_add_f32_e32 v131, v96, v97
	v_add_f32_e32 v126, v90, v91
	v_add_f32_e32 v127, v92, v93
	v_add_f32_e32 v130, v130, v131
	v_mul_f32_e32 v131, v95, v95
	v_mul_f32_e32 v132, v97, v97
	v_add_f32_e32 v126, v126, v127
	v_mul_f32_e32 v127, v91, v91
	v_mul_f32_e32 v128, v93, v93
	s_nop 0
	v_fmac_f32_e32 v131, v94, v94
	v_fmac_f32_e32 v132, v96, v96
	s_nop 1
	v_bfe_u32 v135, v227, 4, 2
	v_sub_u32_e32 v134, 0, v135
	v_lshlrev_b32_e32 v134, 4, v134
	v_ashrrev_i32_e32 v135, 31, v134
	v_lshl_add_u64 v[134:135], v[124:125], 0, v[134:135]
	v_permlane16_swap_b32_e32 v94, v90
	v_permlane16_swap_b32_e32 v95, v91
	v_permlane16_swap_b32_e32 v96, v92
	v_permlane16_swap_b32_e32 v97, v93
	v_permlane32_swap_b32_e32 v94, v90
	v_permlane32_swap_b32_e32 v95, v91
	v_permlane32_swap_b32_e32 v96, v92
	v_permlane32_swap_b32_e32 v97, v93
	global_store_dwordx4 v[134:135], v[94:97], off
	global_store_dwordx4 v[134:135], v[90:93], off offset:64
	s_nop 1
	v_permlane32_swap_b32_e32 v94, v90
	v_permlane32_swap_b32_e32 v95, v91
	v_permlane32_swap_b32_e32 v96, v92
	v_permlane32_swap_b32_e32 v97, v93
	v_permlane16_swap_b32_e32 v94, v90
	v_permlane16_swap_b32_e32 v95, v91
	v_permlane16_swap_b32_e32 v96, v92
	v_permlane16_swap_b32_e32 v97, v93
	v_fmac_f32_e32 v127, v90, v90
	v_fmac_f32_e32 v128, v92, v92
	v_cvt_pk_bf16_f32 v94, v94, v95
	v_cvt_pk_bf16_f32 v95, v96, v97
	v_cvt_pk_bf16_f32 v96, v90, v91
	v_cvt_pk_bf16_f32 v97, v92, v93
	s_waitcnt vmcnt(6)
	v_sub_f32_e32 v91, v119, v123
	v_sub_f32_e32 v90, v118, v123
	v_sub_f32_e32 v93, v121, v123
	v_sub_f32_e32 v92, v120, v123
	v_pk_mul_f32 v[92:93], v[0:1], v[92:93] op_sel_hi:[0,1]
	v_pk_mul_f32 v[90:91], v[0:1], v[90:91] op_sel_hi:[0,1]
	s_waitcnt vmcnt(2)
	v_pk_fma_f32 v[90:91], v[110:111], v[90:91], v[114:115]
	v_pk_fma_f32 v[92:93], v[112:113], v[92:93], v[116:117]
	v_pk_fma_f32 v[86:87], v[90:91], s[2:3], v[86:87] op_sel_hi:[1,0,1]
	v_pk_fma_f32 v[88:89], v[92:93], s[2:3], v[88:89] op_sel_hi:[1,0,1]
	v_add_f32_e32 v130, 0, v130
	v_add_f32_e32 v90, v86, v87
	v_add_f32_e32 v91, v88, v89
	v_add_f32_e32 v126, v130, v126
	v_add_f32_e32 v90, v90, v91
	global_store_dwordx4 v122, v[94:97], s[42:43]
	v_mul_f32_e32 v91, v89, v89
	v_add_f32_e32 v131, v131, v132
	v_add_f32_e32 v94, v126, v90
	v_mul_f32_e32 v90, v87, v87
	v_add_f32_e32 v127, v127, v128
	v_fmac_f32_e32 v90, v86, v86
	v_fmac_f32_e32 v91, v88, v88
	v_add_f32_e32 v127, v131, v127
	v_add_f32_e32 v90, v90, v91
	v_add_f32_e32 v95, v127, v90
	v_sub_f32_e32 v91, v99, v123
	v_sub_f32_e32 v90, v98, v123
	v_sub_f32_e32 v93, v101, v123
	v_sub_f32_e32 v92, v100, v123
	v_pk_mul_f32 v[92:93], v[0:1], v[92:93] op_sel_hi:[0,1]
	v_pk_mul_f32 v[90:91], v[0:1], v[90:91] op_sel_hi:[0,1]
	v_pk_fma_f32 v[90:91], v[102:103], v[90:91], v[106:107]
	v_pk_fma_f32 v[92:93], v[104:105], v[92:93], v[108:109]
	v_pk_fma_f32 v[82:83], v[90:91], s[2:3], v[82:83] op_sel_hi:[1,0,1]
	v_pk_fma_f32 v[84:85], v[92:93], s[2:3], v[84:85] op_sel_hi:[1,0,1]
	v_add_f32_e32 v0, v82, v83
	v_add_f32_e32 v90, v84, v85
	v_add_f32_e32 v0, v0, v90
	v_mul_f32_e32 v90, v83, v83
	v_mul_f32_e32 v91, v85, v85
	v_add_f32_e32 v0, v94, v0
	v_fmac_f32_e32 v90, v82, v82
	v_fmac_f32_e32 v91, v84, v84
	s_nop 0
	s_nop 1
	v_bfe_u32 v93, v227, 4, 2
	v_sub_u32_e32 v92, 0, v93
	v_lshlrev_b32_e32 v92, 4, v92
	v_ashrrev_i32_e32 v93, 31, v92
	v_lshl_add_u64 v[92:93], v[124:125], 0, v[92:93]
	v_permlane16_swap_b32_e32 v86, v82
	v_permlane16_swap_b32_e32 v87, v83
	v_permlane16_swap_b32_e32 v88, v84
	v_permlane16_swap_b32_e32 v89, v85
	v_permlane32_swap_b32_e32 v86, v82
	v_permlane32_swap_b32_e32 v87, v83
	v_permlane32_swap_b32_e32 v88, v84
	v_permlane32_swap_b32_e32 v89, v85
	global_store_dwordx4 v[92:93], v[86:89], off offset:512
	global_store_dwordx4 v[92:93], v[82:85], off offset:576
	s_nop 1
	v_permlane32_swap_b32_e32 v86, v82
	v_permlane32_swap_b32_e32 v87, v83
	v_permlane32_swap_b32_e32 v88, v84
	v_permlane32_swap_b32_e32 v89, v85
	v_permlane16_swap_b32_e32 v86, v82
	v_permlane16_swap_b32_e32 v87, v83
	v_permlane16_swap_b32_e32 v88, v84
	v_permlane16_swap_b32_e32 v89, v85
	v_add_f32_e32 v90, v90, v91
	v_cvt_pk_bf16_f32 v86, v86, v87
	v_cvt_pk_bf16_f32 v87, v88, v89
	v_cvt_pk_bf16_f32 v88, v82, v83
	v_mov_b32_e32 v82, v0
	v_add_f32_e32 v90, v95, v90
	s_nop 0
	v_permlane16_swap_b32_e32 v0, v82
	v_add_f32_e32 v82, v0, v82
	v_mov_b32_e32 v0, v90
	s_nop 1
	v_permlane16_swap_b32_e32 v90, v0
	v_add_f32_e32 v83, v90, v0
	v_cvt_pk_bf16_f32 v89, v84, v85
	v_mov_b32_e32 v84, v82
	v_mov_b32_e32 v85, v83
	s_nop 0
	v_permlane32_swap_b32_e32 v82, v84
	v_permlane32_swap_b32_e32 v83, v85
	global_store_dwordx4 v122, v[86:89], s[40:41]
	s_and_saveexec_b64 s[26:27], s[44:45]
	s_cbranch_execz .LBB0_1541
	v_pk_add_f32 v[82:83], v[82:83], v[84:85]
	v_lshl_add_u64 v[84:85], s[6:7], 0, v[164:165]
	v_lshl_add_u64 v[84:85], s[52:53], 2, v[84:85]
	global_store_dwordx2 v[84:85], v[82:83], off
; __device__ __forceinline__ float xsum16(float v) { const auto r = __builtin_amdgcn_permlane16_swap(__float_as_uint(v), __float_as_uint(v), false, false); return __uint_as_float(r[0]) + __uint_as_float(r[1]); }
; __device__ __forceinline__ float xsum32(float v) { const auto r = __builtin_amdgcn_permlane32_swap(__float_as_uint(v), __float_as_uint(v), false, false); return __uint_as_float(r[0]) + __uint_as_float(r[1]); }
; __device__ __forceinline__ size_t blk_off(int r, int c, int K) { return (size_t)(r >> 8) * 256 * K + (size_t)(c >> 6) * (256 * 64) + (size_t)((r & 255) * 64 + (c & 63)); }
; __device__ __forceinline__ u32x4 pack8(const f32x4 a, const f32x4 b) { u32x4 w; w.x = cvt_pk_bf16(a[0], a[1]); w.y = cvt_pk_bf16(a[2], a[3]); w.z = cvt_pk_bf16(b[0], b[1]); w.w = cvt_pk_bf16(b[2], b[3]); return w; }
; __device__ __forceinline__ void row_stats(const float* st, int row, int fq, float& mu, float& rstd) {
;     ...
;     mu = s1 * (1.0f / 1024.0f); const float var = fmaxf(s2 * (1.0f / 1024.0f) - mu * mu, 0.f); rstd = rsqrtf(var + LN_EPS_);
;     __device__ __forceinline__ void operator()(const f32x4 (&acc)[2][2][4][2], const pg8::Unit& u, int wr, int wc, int fr, int fq) const {
;     ...
;                     for (int n = 0; n < 2; ++n) { yv[bj][n] = *(const f32x4*)(Yin + (size_t)row * D_ + col0 + bj * 128 + 4 * n); gq[bj][n] = *(const f32x4*)(g + col0 + bj * 128 + 4 * n); bq_[bj][n] = *(const f32x4*)(b + col0 + bj * 128 + 4 * n); }
;                 asm volatile("" ::: "memory");
;                 float s1 = 0.f, s2 = 0.f;
; #pragma unroll
;                 for (int bj = 0; bj < 2; ++bj) { float* yp = Y + (size_t)row * D_ + col0 + bj * 128; f32x4 v[2];
; #pragma unroll
;                     for (int n = 0; n < 2; ++n) { v[n] = (((yv[bj][n] - mu) * rs) * gq[bj][n] + bq_[bj][n]) * ALPHA_ + acc[ai][bj][m][n] * sc;
;                         *(f32x4*)(yp + 4 * n) = v[n]; s1 += (v[n][0] + v[n][1]) + (v[n][2] + v[n][3]); s2 += (v[n][0] * v[n][0] + v[n][1] * v[n][1]) + (v[n][2] * v[n][2] + v[n][3] * v[n][3]); }
;                     *(u32x4*)(Yb + blk_off(row, col0 + bj * 128, D_)) = pack8(v[0], v[1]); }
;                 s1 = xsum32(xsum16(s1)); s2 = xsum32(xsum16(s2));
;                 if (fq == 0) *(f32x2*)(stn + (size_t)row * 32 + (u.pn * 4 + wc) * 2) = (f32x2){s1, s2}; asm volatile("" ::: "memory"); } }
.LBB0_1541:
	s_or_b64 exec, exec, s[26:27]
	v_pk_add_f32 v[82:83], v[166:167], v[168:169]
	s_mov_b32 s2, 0x3a800000
	v_pk_mul_f32 v[106:107], v[82:83], s[2:3] op_sel_hi:[1,0]
	s_mov_b32 s1, 0x800000
	v_fma_f32 v0, -v107, v107, v106
	v_max_f32_e32 v0, 0, v0
	v_add_f32_e32 v0, 0x3727c5ac, v0
	v_cmp_gt_f32_e32 vcc, s1, v0
	v_mul_f32_e32 v82, 0x4b800000, v0
	s_load_dwordx16 s[64:79], s[34:35], 0x38
	v_cndmask_b32_e32 v0, v0, v82, vcc
	v_rsq_f32_e32 v0, v0
	s_mov_b32 s2, 0x3fd744fd
	v_lshlrev_b32_e32 v106, 6, v162
	v_mul_f32_e32 v82, 0x45800000, v0
	v_cndmask_b32_e32 v0, v0, v82, vcc
	v_lshlrev_b64 v[82:83], 12, v[162:163]
	s_waitcnt lgkmcnt(0)
	v_lshl_add_u64 v[82:83], s[78:79], 0, v[82:83]
	v_lshl_add_u64 v[108:109], v[152:153], 2, v[82:83]
	global_load_dwordx4 v[110:113], v[108:109], off offset:16 nt
	global_load_dwordx4 v[114:117], v[108:109], off nt
	global_load_dwordx4 v[118:121], v[156:157], off offset:16
	global_load_dwordx4 v[122:125], v[156:157], off
	global_load_dwordx4 v[126:129], v[154:155], off offset:16
	global_load_dwordx4 v[130:133], v[154:155], off
	global_load_dwordx4 v[82:85], v[108:109], off offset:528 nt
	global_load_dwordx4 v[102:105], v[108:109], off offset:512 nt
	global_load_dwordx4 v[86:89], v[156:157], off offset:528
	global_load_dwordx4 v[94:97], v[156:157], off offset:512
	global_load_dwordx4 v[90:93], v[154:155], off offset:528
	global_load_dwordx4 v[98:101], v[154:155], off offset:512
	s_movk_i32 s1, 0x3fc0
	v_and_or_b32 v106, v106, s1, v196
	v_lshlrev_b32_e32 v106, 1, v106
	s_waitcnt vmcnt(11)
	v_sub_f32_e32 v111, v111, v107
	s_waitcnt vmcnt(10)
	v_sub_f32_e32 v115, v115, v107
	v_sub_f32_e32 v114, v114, v107
	v_sub_f32_e32 v117, v117, v107
	v_sub_f32_e32 v116, v116, v107
	v_sub_f32_e32 v110, v110, v107
	v_sub_f32_e32 v113, v113, v107
	v_sub_f32_e32 v112, v112, v107
	v_pk_mul_f32 v[116:117], v[0:1], v[116:117] op_sel_hi:[0,1]
	v_pk_mul_f32 v[114:115], v[0:1], v[114:115] op_sel_hi:[0,1]
	v_pk_mul_f32 v[112:113], v[0:1], v[112:113] op_sel_hi:[0,1]
	v_pk_mul_f32 v[110:111], v[0:1], v[110:111] op_sel_hi:[0,1]
	s_waitcnt vmcnt(6)
	v_pk_fma_f32 v[114:115], v[122:123], v[114:115], v[130:131]
	v_pk_fma_f32 v[116:117], v[124:125], v[116:117], v[132:133]
	v_pk_fma_f32 v[110:111], v[118:119], v[110:111], v[126:127]
	v_pk_fma_f32 v[112:113], v[120:121], v[112:113], v[128:129]
	v_pk_fma_f32 v[80:81], v[116:117], s[2:3], v[80:81] op_sel_hi:[1,0,1]
	v_pk_fma_f32 v[78:79], v[114:115], s[2:3], v[78:79] op_sel_hi:[1,0,1]
	v_pk_fma_f32 v[76:77], v[112:113], s[2:3], v[76:77] op_sel_hi:[1,0,1]
	v_pk_fma_f32 v[74:75], v[110:111], s[2:3], v[74:75] op_sel_hi:[1,0,1]
	v_add_f32_e32 v114, v78, v79
	v_add_f32_e32 v115, v80, v81
	v_add_f32_e32 v110, v74, v75
	v_add_f32_e32 v111, v76, v77
	v_add_f32_e32 v114, v114, v115
	v_mul_f32_e32 v115, v79, v79
	v_mul_f32_e32 v116, v81, v81
	v_add_f32_e32 v110, v110, v111
	v_mul_f32_e32 v111, v75, v75
	v_mul_f32_e32 v112, v77, v77
	s_nop 0
	v_fmac_f32_e32 v115, v78, v78
	v_fmac_f32_e32 v116, v80, v80
	s_nop 1
	v_bfe_u32 v119, v227, 4, 2
	v_sub_u32_e32 v118, 0, v119
	v_lshlrev_b32_e32 v118, 4, v118
	v_ashrrev_i32_e32 v119, 31, v118
	v_lshl_add_u64 v[118:119], v[108:109], 0, v[118:119]
	v_permlane16_swap_b32_e32 v78, v74
	v_permlane16_swap_b32_e32 v79, v75
	v_permlane16_swap_b32_e32 v80, v76
	v_permlane16_swap_b32_e32 v81, v77
	v_permlane32_swap_b32_e32 v78, v74
	v_permlane32_swap_b32_e32 v79, v75
	v_permlane32_swap_b32_e32 v80, v76
	v_permlane32_swap_b32_e32 v81, v77
	global_store_dwordx4 v[118:119], v[78:81], off
	global_store_dwordx4 v[118:119], v[74:77], off offset:64
	s_nop 1
	v_permlane32_swap_b32_e32 v78, v74
	v_permlane32_swap_b32_e32 v79, v75
	v_permlane32_swap_b32_e32 v80, v76
	v_permlane32_swap_b32_e32 v81, v77
	v_permlane16_swap_b32_e32 v78, v74
	v_permlane16_swap_b32_e32 v79, v75
	v_permlane16_swap_b32_e32 v80, v76
	v_permlane16_swap_b32_e32 v81, v77
	v_fmac_f32_e32 v111, v74, v74
	v_fmac_f32_e32 v112, v76, v76
	v_cvt_pk_bf16_f32 v78, v78, v79
	v_cvt_pk_bf16_f32 v79, v80, v81
	v_cvt_pk_bf16_f32 v80, v74, v75
	v_cvt_pk_bf16_f32 v81, v76, v77
	s_waitcnt vmcnt(6)
	v_sub_f32_e32 v75, v103, v107
	v_sub_f32_e32 v74, v102, v107
	v_sub_f32_e32 v77, v105, v107
	v_sub_f32_e32 v76, v104, v107
	v_pk_mul_f32 v[76:77], v[0:1], v[76:77] op_sel_hi:[0,1]
	v_pk_mul_f32 v[74:75], v[0:1], v[74:75] op_sel_hi:[0,1]
	s_waitcnt vmcnt(2)
; __device__ __forceinline__ float xsum16(float v) { const auto r = __builtin_amdgcn_permlane16_swap(__float_as_uint(v), __float_as_uint(v), false, false); return __uint_as_float(r[0]) + __uint_as_float(r[1]); }
; __device__ __forceinline__ float xsum32(float v) { const auto r = __builtin_amdgcn_permlane32_swap(__float_as_uint(v), __float_as_uint(v), false, false); return __uint_as_float(r[0]) + __uint_as_float(r[1]); }
; __device__ __forceinline__ void row_stats4(const float* st, int rowb, int fq, float (&mu)[4], float (&rs)[4]) {
;     f32x4 a[4], b[4];
; #pragma unroll
;     for (int m = 0; m < 4; ++m) { const f32x4* p = (const f32x4*)(st + (size_t)(rowb + m * 16) * 32 + fq * 8); a[m] = p[0]; b[m] = p[1]; }
; #pragma unroll
;     for (int m = 0; m < 4; ++m) { float s1 = (a[m][0] + a[m][2]) + (b[m][0] + b[m][2]), s2 = (a[m][1] + a[m][3]) + (b[m][1] + b[m][3]);
;         s1 = xsum32(xsum16(s1)); s2 = xsum32(xsum16(s2));
;         const float mm = s1 * (1.0f / 1024.0f); mu[m] = mm; rs[m] = rsqrtf(fmaxf(s2 * (1.0f / 1024.0f) - mm * mm, 0.f) + LN_EPS_); }
;     __device__ __forceinline__ void operator()(const f32x4 (&acc)[2][2][4][2], const pg8::Unit& u, int wr, int wc, int fr, int fq) const {
;     ...
;                     for (int n = 0; n < 2; ++n) { yv[bj][n] = *(const f32x4*)(Yin + (size_t)row * D_ + col0 + bj * 128 + 4 * n); gq[bj][n] = *(const f32x4*)(g + col0 + bj * 128 + 4 * n); bq_[bj][n] = *(const f32x4*)(b + col0 + bj * 128 + 4 * n); }
;                 asm volatile("" ::: "memory");
;                 float s1 = 0.f, s2 = 0.f;
; #pragma unroll
;                 for (int bj = 0; bj < 2; ++bj) { float* yp = Y + (size_t)row * D_ + col0 + bj * 128; f32x4 v[2];
; #pragma unroll
;                     for (int n = 0; n < 2; ++n) { v[n] = (((yv[bj][n] - mu) * rs) * gq[bj][n] + bq_[bj][n]) * ALPHA_ + acc[ai][bj][m][n] * sc;
;                         *(f32x4*)(yp + 4 * n) = v[n]; s1 += (v[n][0] + v[n][1]) + (v[n][2] + v[n][3]); s2 += (v[n][0] * v[n][0] + v[n][1] * v[n][1]) + (v[n][2] * v[n][2] + v[n][3] * v[n][3]); }
;                     *(u32x4*)(Yb + blk_off(row, col0 + bj * 128, D_)) = pack8(v[0], v[1]); }
;                 s1 = xsum32(xsum16(s1)); s2 = xsum32(xsum16(s2));
;                 if (fq == 0) *(f32x2*)(stn + (size_t)row * 32 + (u.pn * 4 + wc) * 2) = (f32x2){s1, s2}; asm volatile("" ::: "memory"); } }
	v_pk_fma_f32 v[74:75], v[94:95], v[74:75], v[98:99]
	v_pk_fma_f32 v[76:77], v[96:97], v[76:77], v[100:101]
	v_pk_fma_f32 v[70:71], v[74:75], s[2:3], v[70:71] op_sel_hi:[1,0,1]
	v_pk_fma_f32 v[72:73], v[76:77], s[2:3], v[72:73] op_sel_hi:[1,0,1]
	v_add_f32_e32 v114, 0, v114
	v_add_f32_e32 v74, v70, v71
	v_add_f32_e32 v75, v72, v73
	v_add_f32_e32 v110, v114, v110
	v_add_f32_e32 v74, v74, v75
	global_store_dwordx4 v106, v[78:81], s[42:43]
	v_mul_f32_e32 v75, v73, v73
	v_add_f32_e32 v115, v115, v116
	v_add_f32_e32 v78, v110, v74
	v_mul_f32_e32 v74, v71, v71
	v_add_f32_e32 v111, v111, v112
	v_fmac_f32_e32 v74, v70, v70
	v_fmac_f32_e32 v75, v72, v72
	v_add_f32_e32 v111, v115, v111
	v_add_f32_e32 v74, v74, v75
	v_add_f32_e32 v79, v111, v74
	v_sub_f32_e32 v75, v83, v107
	v_sub_f32_e32 v74, v82, v107
	v_sub_f32_e32 v77, v85, v107
	v_sub_f32_e32 v76, v84, v107
	v_pk_mul_f32 v[76:77], v[0:1], v[76:77] op_sel_hi:[0,1]
	v_pk_mul_f32 v[74:75], v[0:1], v[74:75] op_sel_hi:[0,1]
	v_pk_fma_f32 v[74:75], v[86:87], v[74:75], v[90:91]
	v_pk_fma_f32 v[76:77], v[88:89], v[76:77], v[92:93]
	v_pk_fma_f32 v[66:67], v[74:75], s[2:3], v[66:67] op_sel_hi:[1,0,1]
	v_pk_fma_f32 v[68:69], v[76:77], s[2:3], v[68:69] op_sel_hi:[1,0,1]
	v_add_f32_e32 v0, v66, v67
	v_add_f32_e32 v74, v68, v69
	v_add_f32_e32 v0, v0, v74
	v_mul_f32_e32 v74, v67, v67
	v_mul_f32_e32 v75, v69, v69
	v_add_f32_e32 v0, v78, v0
	v_fmac_f32_e32 v74, v66, v66
	v_fmac_f32_e32 v75, v68, v68
	s_nop 0
	s_nop 1
	v_bfe_u32 v77, v227, 4, 2
	v_sub_u32_e32 v76, 0, v77
	v_lshlrev_b32_e32 v76, 4, v76
	v_ashrrev_i32_e32 v77, 31, v76
	v_lshl_add_u64 v[76:77], v[108:109], 0, v[76:77]
	v_permlane16_swap_b32_e32 v70, v66
	v_permlane16_swap_b32_e32 v71, v67
	v_permlane16_swap_b32_e32 v72, v68
	v_permlane16_swap_b32_e32 v73, v69
	v_permlane32_swap_b32_e32 v70, v66
	v_permlane32_swap_b32_e32 v71, v67
	v_permlane32_swap_b32_e32 v72, v68
	v_permlane32_swap_b32_e32 v73, v69
	global_store_dwordx4 v[76:77], v[70:73], off offset:512
	global_store_dwordx4 v[76:77], v[66:69], off offset:576
	s_nop 1
	v_permlane32_swap_b32_e32 v70, v66
	v_permlane32_swap_b32_e32 v71, v67
	v_permlane32_swap_b32_e32 v72, v68
	v_permlane32_swap_b32_e32 v73, v69
	v_permlane16_swap_b32_e32 v70, v66
	v_permlane16_swap_b32_e32 v71, v67
	v_permlane16_swap_b32_e32 v72, v68
	v_permlane16_swap_b32_e32 v73, v69
	v_add_f32_e32 v74, v74, v75
	v_cvt_pk_bf16_f32 v70, v70, v71
	v_cvt_pk_bf16_f32 v71, v72, v73
	v_cvt_pk_bf16_f32 v72, v66, v67
	v_mov_b32_e32 v66, v0
	v_add_f32_e32 v74, v79, v74
	s_nop 0
	v_permlane16_swap_b32_e32 v0, v66
	v_add_f32_e32 v66, v0, v66
	v_mov_b32_e32 v0, v74
	s_nop 1
	v_permlane16_swap_b32_e32 v74, v0
	v_add_f32_e32 v67, v74, v0
	v_cvt_pk_bf16_f32 v73, v68, v69
	v_mov_b32_e32 v68, v66
	v_mov_b32_e32 v69, v67
	s_nop 0
	v_permlane32_swap_b32_e32 v66, v68
	v_permlane32_swap_b32_e32 v67, v69
	global_store_dwordx4 v106, v[70:73], s[40:41]
	s_and_saveexec_b64 s[26:27], s[44:45]
	s_cbranch_execz .LBB0_1543
	v_pk_add_f32 v[66:67], v[66:67], v[68:69]
	v_lshl_add_u64 v[68:69], s[6:7], 0, v[160:161]
	v_lshl_add_u64 v[68:69], s[52:53], 2, v[68:69]
	global_store_dwordx2 v[68:69], v[66:67], off
.LBB0_1543:
	s_or_b64 exec, exec, s[26:27]
	v_add_u32_e32 v118, 0x80, v158
	v_ashrrev_i32_e32 v119, 31, v118
	v_lshlrev_b64 v[110:111], 7, v[118:119]
	v_lshl_add_u64 v[70:71], v[146:147], 0, v[110:111]
	global_load_dwordx4 v[66:69], v[70:71], off nt
	s_nop 0
	global_load_dwordx4 v[70:73], v[70:71], off offset:16 nt
	v_add_u32_e32 v108, 0x90, v158
	v_ashrrev_i32_e32 v109, 31, v108
	v_lshlrev_b64 v[102:103], 7, v[108:109]
	v_lshl_add_u64 v[78:79], v[146:147], 0, v[102:103]
	global_load_dwordx4 v[74:77], v[78:79], off nt
	s_nop 0
	global_load_dwordx4 v[78:81], v[78:79], off offset:16 nt
	v_add_u32_e32 v96, 0xa0, v158
	v_ashrrev_i32_e32 v97, 31, v96
	v_lshlrev_b64 v[82:83], 7, v[96:97]
	v_lshl_add_u64 v[86:87], v[146:147], 0, v[82:83]
	global_load_dwordx4 v[82:85], v[86:87], off nt
	s_nop 0
	global_load_dwordx4 v[86:89], v[86:87], off offset:16 nt
	v_add_u32_e32 v94, 0xb0, v158
	v_ashrrev_i32_e32 v95, 31, v94
	v_lshlrev_b64 v[90:91], 7, v[94:95]
	v_lshl_add_u64 v[98:99], v[146:147], 0, v[90:91]
	global_load_dwordx4 v[90:93], v[98:99], off nt
	s_nop 0
	global_load_dwordx4 v[98:101], v[98:99], off offset:16 nt
	s_mov_b32 s2, 0x3a800000
	s_mov_b32 s1, 0x800000
	s_load_dwordx16 s[64:79], s[34:35], 0x38
	s_mov_b32 s14, 0x3fd744fd
	s_waitcnt vmcnt(7)
	v_mov_b32_e32 v104, v66
	s_waitcnt vmcnt(6)
	v_mov_b32_e32 v105, v70
	v_mov_b32_e32 v106, v68
	v_mov_b32_e32 v107, v72
	v_pk_add_f32 v[104:105], v[104:105], v[106:107]
	v_mov_b32_e32 v70, v67
	v_pk_add_f32 v[104:105], v[104:105], v[104:105] op_sel:[0,1] op_sel_hi:[1,0]
	v_mov_b32_e32 v72, v69
	v_pk_add_f32 v[66:67], v[70:71], v[72:73]
	v_mov_b32_e32 v0, v104
	v_pk_add_f32 v[66:67], v[66:67], v[66:67] op_sel:[0,1] op_sel_hi:[1,0]
	s_nop 0
	v_permlane16_swap_b32_e32 v104, v0
	v_add_f32_e32 v67, v104, v0
	v_mov_b32_e32 v0, v66
	s_nop 1
	v_permlane16_swap_b32_e32 v66, v0
	v_add_f32_e32 v66, v66, v0
	v_mov_b32_e32 v69, v67
	v_mov_b32_e32 v68, v66
	s_nop 0
	v_permlane32_swap_b32_e32 v67, v69
	v_permlane32_swap_b32_e32 v66, v68
	v_pk_add_f32 v[66:67], v[66:67], v[68:69]
	s_waitcnt vmcnt(5)
	v_mov_b32_e32 v68, v76
	v_pk_mul_f32 v[116:117], v[66:67], s[2:3] op_sel_hi:[1,0]
	s_waitcnt vmcnt(4)
; __device__ __forceinline__ float xsum16(float v) { const auto r = __builtin_amdgcn_permlane16_swap(__float_as_uint(v), __float_as_uint(v), false, false); return __uint_as_float(r[0]) + __uint_as_float(r[1]); }
; __device__ __forceinline__ float xsum32(float v) { const auto r = __builtin_amdgcn_permlane32_swap(__float_as_uint(v), __float_as_uint(v), false, false); return __uint_as_float(r[0]) + __uint_as_float(r[1]); }
; __device__ __forceinline__ void row_stats4(const float* st, int rowb, int fq, float (&mu)[4], float (&rs)[4]) {
;     f32x4 a[4], b[4];
; #pragma unroll
;     for (int m = 0; m < 4; ++m) { const f32x4* p = (const f32x4*)(st + (size_t)(rowb + m * 16) * 32 + fq * 8); a[m] = p[0]; b[m] = p[1]; }
; #pragma unroll
;     for (int m = 0; m < 4; ++m) { float s1 = (a[m][0] + a[m][2]) + (b[m][0] + b[m][2]), s2 = (a[m][1] + a[m][3]) + (b[m][1] + b[m][3]);
;         s1 = xsum32(xsum16(s1)); s2 = xsum32(xsum16(s2));
;         const float mm = s1 * (1.0f / 1024.0f); mu[m] = mm; rs[m] = rsqrtf(fmaxf(s2 * (1.0f / 1024.0f) - mm * mm, 0.f) + LN_EPS_); }
;     __device__ __forceinline__ void operator()(const f32x4 (&acc)[2][2][4][2], const pg8::Unit& u, int wr, int wc, int fr, int fq) const {
;     ...
;                     for (int n = 0; n < 2; ++n) { yv[bj][n] = *(const f32x4*)(Yin + (size_t)row * D_ + col0 + bj * 128 + 4 * n); gq[bj][n] = *(const f32x4*)(g + col0 + bj * 128 + 4 * n); bq_[bj][n] = *(const f32x4*)(b + col0 + bj * 128 + 4 * n); }
;                 asm volatile("" ::: "memory");
;                 float s1 = 0.f, s2 = 0.f;
; #pragma unroll
;                 for (int bj = 0; bj < 2; ++bj) { float* yp = Y + (size_t)row * D_ + col0 + bj * 128; f32x4 v[2];
; #pragma unroll
;                     for (int n = 0; n < 2; ++n) { v[n] = (((yv[bj][n] - mu) * rs) * gq[bj][n] + bq_[bj][n]) * ALPHA_ + acc[ai][bj][m][n] * sc;
;                         *(f32x4*)(yp + 4 * n) = v[n]; s1 += (v[n][0] + v[n][1]) + (v[n][2] + v[n][3]); s2 += (v[n][0] * v[n][0] + v[n][1] * v[n][1]) + (v[n][2] * v[n][2] + v[n][3] * v[n][3]); }
;                     *(u32x4*)(Yb + blk_off(row, col0 + bj * 128, D_)) = pack8(v[0], v[1]); }
;                 s1 = xsum32(xsum16(s1)); s2 = xsum32(xsum16(s2));
;                 if (fq == 0) *(f32x2*)(stn + (size_t)row * 32 + (u.pn * 4 + wc) * 2) = (f32x2){s1, s2}; asm volatile("" ::: "memory"); } }
	v_mov_b32_e32 v67, v78
	v_fma_f32 v0, -v117, v117, v116
	v_max_f32_e32 v0, 0, v0
	v_add_f32_e32 v0, 0x3727c5ac, v0
	v_cmp_gt_f32_e32 vcc, s1, v0
	v_mul_f32_e32 v66, 0x4b800000, v0
	v_mov_b32_e32 v69, v80
	v_cndmask_b32_e32 v0, v0, v66, vcc
	v_rsq_f32_e32 v0, v0
	v_mov_b32_e32 v78, v75
	v_mov_b32_e32 v80, v77
	v_readlane_b32 s2, v253, 59
	v_mul_f32_e32 v66, 0x45800000, v0
	v_cndmask_b32_e32 v116, v0, v66, vcc
	v_mov_b32_e32 v66, v74
	v_pk_add_f32 v[66:67], v[66:67], v[68:69]
	v_pk_add_f32 v[68:69], v[78:79], v[80:81]
	v_pk_add_f32 v[66:67], v[66:67], v[66:67] op_sel:[0,1] op_sel_hi:[1,0]
	v_pk_add_f32 v[68:69], v[68:69], v[68:69] op_sel:[0,1] op_sel_hi:[1,0]
	v_mov_b32_e32 v0, v66
	s_nop 1
	v_permlane16_swap_b32_e32 v66, v0
	v_add_f32_e32 v113, v66, v0
	v_mov_b32_e32 v0, v68
	s_nop 1
	v_permlane16_swap_b32_e32 v68, v0
	v_add_f32_e32 v112, v68, v0
	s_waitcnt vmcnt(3)
	v_mov_b32_e32 v66, v82
	s_waitcnt vmcnt(2)
	v_mov_b32_e32 v67, v86
	v_mov_b32_e32 v68, v84
	v_mov_b32_e32 v69, v88
	v_pk_add_f32 v[66:67], v[66:67], v[68:69]
	v_mov_b32_e32 v86, v83
	v_pk_add_f32 v[66:67], v[66:67], v[66:67] op_sel:[0,1] op_sel_hi:[1,0]
	v_mov_b32_e32 v88, v85
	v_pk_add_f32 v[68:69], v[86:87], v[88:89]
	v_mov_b32_e32 v0, v66
	v_pk_add_f32 v[68:69], v[68:69], v[68:69] op_sel:[0,1] op_sel_hi:[1,0]
	s_nop 0
	v_permlane16_swap_b32_e32 v66, v0
	v_add_f32_e32 v105, v66, v0
	v_mov_b32_e32 v0, v68
	s_nop 1
	v_permlane16_swap_b32_e32 v68, v0
	v_add_f32_e32 v104, v68, v0
	s_waitcnt vmcnt(1)
	v_mov_b32_e32 v66, v90
	s_waitcnt vmcnt(0)
	v_mov_b32_e32 v67, v98
	v_mov_b32_e32 v68, v92
	v_mov_b32_e32 v69, v100
	v_pk_add_f32 v[66:67], v[66:67], v[68:69]
	v_mov_b32_e32 v98, v91
	v_pk_add_f32 v[66:67], v[66:67], v[66:67] op_sel:[0,1] op_sel_hi:[1,0]
	v_mov_b32_e32 v100, v93
	v_mov_b32_e32 v0, v66
	s_nop 1
	v_permlane16_swap_b32_e32 v66, v0
	v_pk_add_f32 v[68:69], v[98:99], v[100:101]
	v_add_f32_e32 v99, v66, v0
	v_ashrrev_i32_e32 v66, 8, v118
	v_ashrrev_i32_e32 v67, 31, v66
	v_pk_add_f32 v[68:69], v[68:69], v[68:69] op_sel:[0,1] op_sel_hi:[1,0]
	v_lshlrev_b64 v[120:121], 19, v[66:67]
	v_lshlrev_b64 v[66:67], 12, v[118:119]
	v_mov_b32_e32 v0, v68
	s_waitcnt lgkmcnt(0)
	v_lshl_add_u64 v[66:67], s[78:79], 0, v[66:67]
	v_permlane16_swap_b32_e32 v68, v0
	v_lshl_add_u64 v[122:123], v[152:153], 2, v[66:67]
	v_add_f32_e32 v98, v68, v0
	global_load_dwordx4 v[74:77], v[122:123], off offset:16 nt
	global_load_dwordx4 v[86:89], v[122:123], off nt
	global_load_dwordx4 v[66:69], v[156:157], off offset:16
	global_load_dwordx4 v[78:81], v[156:157], off
	global_load_dwordx4 v[70:73], v[154:155], off offset:16
	global_load_dwordx4 v[82:85], v[154:155], off
	global_load_dwordx4 v[90:93], v[122:123], off offset:528 nt
	global_load_dwordx4 v[124:127], v[122:123], off offset:512 nt
	global_load_dwordx4 v[128:131], v[156:157], off offset:528
	global_load_dwordx4 v[132:135], v[156:157], off offset:512
	global_load_dwordx4 v[158:161], v[154:155], off offset:528
	global_load_dwordx4 v[162:165], v[154:155], off offset:512
	v_lshlrev_b32_e32 v0, 6, v118
	s_movk_i32 s1, 0x33c0
	v_readlane_b32 s3, v253, 60
	v_and_or_b32 v0, v0, s1, v196
	v_lshlrev_b32_e32 v0, 1, v0
	v_mov_b32_e32 v115, v113
	v_mov_b32_e32 v114, v112
	v_mov_b32_e32 v107, v105
	v_mov_b32_e32 v106, v104
	v_mov_b32_e32 v101, v99
	v_mov_b32_e32 v100, v98
	v_permlane32_swap_b32_e32 v113, v115
	v_permlane32_swap_b32_e32 v112, v114
	v_permlane32_swap_b32_e32 v105, v107
	v_permlane32_swap_b32_e32 v104, v106
	v_permlane32_swap_b32_e32 v99, v101
	v_permlane32_swap_b32_e32 v98, v100
	s_waitcnt vmcnt(11)
	v_sub_f32_e32 v75, v75, v117
	s_waitcnt vmcnt(10)
	v_sub_f32_e32 v87, v87, v117
	v_sub_f32_e32 v86, v86, v117
	v_sub_f32_e32 v89, v89, v117
	v_sub_f32_e32 v88, v88, v117
	v_sub_f32_e32 v74, v74, v117
	v_sub_f32_e32 v77, v77, v117
	v_sub_f32_e32 v76, v76, v117
	v_pk_mul_f32 v[88:89], v[116:117], v[88:89] op_sel_hi:[0,1]
	v_pk_mul_f32 v[86:87], v[116:117], v[86:87] op_sel_hi:[0,1]
	v_pk_mul_f32 v[76:77], v[116:117], v[76:77] op_sel_hi:[0,1]
	v_pk_mul_f32 v[74:75], v[116:117], v[74:75] op_sel_hi:[0,1]
	s_waitcnt vmcnt(6)
	v_pk_fma_f32 v[78:79], v[78:79], v[86:87], v[82:83]
	v_pk_fma_f32 v[80:81], v[80:81], v[88:89], v[84:85]
	v_pk_fma_f32 v[66:67], v[66:67], v[74:75], v[70:71]
	v_pk_fma_f32 v[68:69], v[68:69], v[76:77], v[72:73]
	v_pk_fma_f32 v[64:65], v[80:81], s[14:15], v[64:65] op_sel_hi:[1,0,1]
	v_pk_fma_f32 v[62:63], v[78:79], s[14:15], v[62:63] op_sel_hi:[1,0,1]
	v_pk_fma_f32 v[60:61], v[68:69], s[14:15], v[60:61] op_sel_hi:[1,0,1]
	v_pk_fma_f32 v[58:59], v[66:67], s[14:15], v[58:59] op_sel_hi:[1,0,1]
	v_add_f32_e32 v78, v62, v63
	v_add_f32_e32 v79, v64, v65
	v_add_f32_e32 v66, v58, v59
	v_add_f32_e32 v67, v60, v61
	v_add_f32_e32 v78, v78, v79
	v_mul_f32_e32 v79, v63, v63
	v_mul_f32_e32 v80, v65, v65
	v_add_f32_e32 v66, v66, v67
	v_mul_f32_e32 v67, v59, v59
	s_nop 0
	v_fmac_f32_e32 v79, v62, v62
	v_fmac_f32_e32 v80, v64, v64
	s_nop 1
	v_bfe_u32 v69, v227, 4, 2
	v_sub_u32_e32 v68, 0, v69
	v_lshlrev_b32_e32 v68, 4, v68
	v_ashrrev_i32_e32 v69, 31, v68
	v_lshl_add_u64 v[68:69], v[122:123], 0, v[68:69]
	v_permlane16_swap_b32_e32 v62, v58
	v_permlane16_swap_b32_e32 v63, v59
	v_permlane16_swap_b32_e32 v64, v60
	v_permlane16_swap_b32_e32 v65, v61
	v_permlane32_swap_b32_e32 v62, v58
	v_permlane32_swap_b32_e32 v63, v59
	v_permlane32_swap_b32_e32 v64, v60
	v_permlane32_swap_b32_e32 v65, v61
	global_store_dwordx4 v[68:69], v[62:65], off
	global_store_dwordx4 v[68:69], v[58:61], off offset:64
	s_nop 1
	v_permlane32_swap_b32_e32 v62, v58
	v_permlane32_swap_b32_e32 v63, v59
	v_permlane32_swap_b32_e32 v64, v60
	v_permlane32_swap_b32_e32 v65, v61
	v_permlane16_swap_b32_e32 v62, v58
	v_permlane16_swap_b32_e32 v63, v59
	v_permlane16_swap_b32_e32 v64, v60
	v_permlane16_swap_b32_e32 v65, v61
	v_fmac_f32_e32 v67, v58, v58
	v_cvt_pk_bf16_f32 v62, v62, v63
	v_cvt_pk_bf16_f32 v63, v64, v65
	v_cvt_pk_bf16_f32 v64, v58, v59
	v_lshl_add_u64 v[58:59], s[2:3], 0, v[120:121]
	v_mul_f32_e32 v68, v61, v61
	v_lshl_add_u64 v[76:77], v[58:59], 0, s[24:25]
	v_fmac_f32_e32 v68, v60, v60
	v_cvt_pk_bf16_f32 v65, v60, v61
	v_lshl_add_u64 v[60:61], v[76:77], 0, v[0:1]
	global_store_dwordx4 v[60:61], v[62:65], off
	s_waitcnt vmcnt(7)
; __device__ __forceinline__ float xsum16(float v) { const auto r = __builtin_amdgcn_permlane16_swap(__float_as_uint(v), __float_as_uint(v), false, false); return __uint_as_float(r[0]) + __uint_as_float(r[1]); }
; __device__ __forceinline__ float xsum32(float v) { const auto r = __builtin_amdgcn_permlane32_swap(__float_as_uint(v), __float_as_uint(v), false, false); return __uint_as_float(r[0]) + __uint_as_float(r[1]); }
; __device__ __forceinline__ size_t blk_off(int r, int c, int K) { return (size_t)(r >> 8) * 256 * K + (size_t)(c >> 6) * (256 * 64) + (size_t)((r & 255) * 64 + (c & 63)); }
; __device__ __forceinline__ u32x4 pack8(const f32x4 a, const f32x4 b) { u32x4 w; w.x = cvt_pk_bf16(a[0], a[1]); w.y = cvt_pk_bf16(a[2], a[3]); w.z = cvt_pk_bf16(b[0], b[1]); w.w = cvt_pk_bf16(b[2], b[3]); return w; }
; __device__ __forceinline__ void row_stats(const float* st, int row, int fq, float& mu, float& rstd) {
;     ...
;     mu = s1 * (1.0f / 1024.0f); const float var = fmaxf(s2 * (1.0f / 1024.0f) - mu * mu, 0.f); rstd = rsqrtf(var + LN_EPS_);
;     __device__ __forceinline__ void operator()(const f32x4 (&acc)[2][2][4][2], const pg8::Unit& u, int wr, int wc, int fr, int fq) const {
;     ...
;                     for (int n = 0; n < 2; ++n) { yv[bj][n] = *(const f32x4*)(Yin + (size_t)row * D_ + col0 + bj * 128 + 4 * n); gq[bj][n] = *(const f32x4*)(g + col0 + bj * 128 + 4 * n); bq_[bj][n] = *(const f32x4*)(b + col0 + bj * 128 + 4 * n); }
;                 asm volatile("" ::: "memory");
;                 float s1 = 0.f, s2 = 0.f;
; #pragma unroll
;                 for (int bj = 0; bj < 2; ++bj) { float* yp = Y + (size_t)row * D_ + col0 + bj * 128; f32x4 v[2];
; #pragma unroll
;                     for (int n = 0; n < 2; ++n) { v[n] = (((yv[bj][n] - mu) * rs) * gq[bj][n] + bq_[bj][n]) * ALPHA_ + acc[ai][bj][m][n] * sc;
;                         *(f32x4*)(yp + 4 * n) = v[n]; s1 += (v[n][0] + v[n][1]) + (v[n][2] + v[n][3]); s2 += (v[n][0] * v[n][0] + v[n][1] * v[n][1]) + (v[n][2] * v[n][2] + v[n][3] * v[n][3]); }
;                     *(u32x4*)(Yb + blk_off(row, col0 + bj * 128, D_)) = pack8(v[0], v[1]); }
;                 s1 = xsum32(xsum16(s1)); s2 = xsum32(xsum16(s2));
;                 if (fq == 0) *(f32x2*)(stn + (size_t)row * 32 + (u.pn * 4 + wc) * 2) = (f32x2){s1, s2}; asm volatile("" ::: "memory"); } }
	v_sub_f32_e32 v61, v125, v117
	v_sub_f32_e32 v60, v124, v117
	v_sub_f32_e32 v63, v127, v117
	v_sub_f32_e32 v62, v126, v117
	v_pk_mul_f32 v[62:63], v[116:117], v[62:63] op_sel_hi:[0,1]
	v_pk_mul_f32 v[60:61], v[116:117], v[60:61] op_sel_hi:[0,1]
	s_waitcnt vmcnt(3)
	v_pk_fma_f32 v[60:61], v[132:133], v[60:61], v[162:163]
	v_pk_fma_f32 v[62:63], v[134:135], v[62:63], v[164:165]
	v_pk_fma_f32 v[54:55], v[60:61], s[14:15], v[54:55] op_sel_hi:[1,0,1]
	v_pk_fma_f32 v[56:57], v[62:63], s[14:15], v[56:57] op_sel_hi:[1,0,1]
	v_add_f32_e32 v78, 0, v78
	v_add_f32_e32 v60, v54, v55
	v_add_f32_e32 v61, v56, v57
	v_add_f32_e32 v66, v78, v66
	v_add_f32_e32 v60, v60, v61
	v_add_f32_e32 v64, v66, v60
	v_mul_f32_e32 v60, v55, v55
	v_mul_f32_e32 v61, v57, v57
	v_add_f32_e32 v79, v79, v80
	v_add_f32_e32 v67, v67, v68
	v_fmac_f32_e32 v60, v54, v54
	v_fmac_f32_e32 v61, v56, v56
	v_add_f32_e32 v67, v79, v67
	v_add_f32_e32 v60, v60, v61
	v_add_f32_e32 v65, v67, v60
	v_sub_f32_e32 v61, v91, v117
	v_sub_f32_e32 v60, v90, v117
	v_sub_f32_e32 v63, v93, v117
	v_sub_f32_e32 v62, v92, v117
	v_pk_mul_f32 v[62:63], v[116:117], v[62:63] op_sel_hi:[0,1]
	v_pk_mul_f32 v[60:61], v[116:117], v[60:61] op_sel_hi:[0,1]
	v_pk_fma_f32 v[60:61], v[128:129], v[60:61], v[158:159]
	v_pk_fma_f32 v[62:63], v[130:131], v[62:63], v[160:161]
	v_pk_fma_f32 v[50:51], v[60:61], s[14:15], v[50:51] op_sel_hi:[1,0,1]
	v_pk_fma_f32 v[52:53], v[62:63], s[14:15], v[52:53] op_sel_hi:[1,0,1]
	v_add_f32_e32 v60, v50, v51
	v_add_f32_e32 v61, v52, v53
	v_add_f32_e32 v60, v60, v61
	v_mul_f32_e32 v61, v51, v51
	v_mul_f32_e32 v62, v53, v53
	v_add_f32_e32 v60, v64, v60
	v_fmac_f32_e32 v61, v50, v50
	v_fmac_f32_e32 v62, v52, v52
	v_lshl_add_u64 v[74:75], v[58:59], 0, s[28:29]
	s_nop 0
	s_nop 1
	v_bfe_u32 v67, v227, 4, 2
	v_sub_u32_e32 v66, 0, v67
	v_lshlrev_b32_e32 v66, 4, v66
	v_ashrrev_i32_e32 v67, 31, v66
	v_lshl_add_u64 v[66:67], v[122:123], 0, v[66:67]
	v_permlane16_swap_b32_e32 v54, v50
	v_permlane16_swap_b32_e32 v55, v51
	v_permlane16_swap_b32_e32 v56, v52
	v_permlane16_swap_b32_e32 v57, v53
	v_permlane32_swap_b32_e32 v54, v50
	v_permlane32_swap_b32_e32 v55, v51
	v_permlane32_swap_b32_e32 v56, v52
	v_permlane32_swap_b32_e32 v57, v53
	global_store_dwordx4 v[66:67], v[54:57], off offset:512
	global_store_dwordx4 v[66:67], v[50:53], off offset:576
	s_nop 1
	v_permlane32_swap_b32_e32 v54, v50
	v_permlane32_swap_b32_e32 v55, v51
	v_permlane32_swap_b32_e32 v56, v52
	v_permlane32_swap_b32_e32 v57, v53
	v_permlane16_swap_b32_e32 v54, v50
	v_permlane16_swap_b32_e32 v55, v51
	v_permlane16_swap_b32_e32 v56, v52
	v_permlane16_swap_b32_e32 v57, v53
	v_add_f32_e32 v61, v61, v62
	v_cvt_pk_bf16_f32 v54, v54, v55
	v_cvt_pk_bf16_f32 v55, v56, v57
	v_cvt_pk_bf16_f32 v56, v50, v51
	v_lshl_add_u64 v[50:51], v[74:75], 0, v[0:1]
	v_mov_b32_e32 v0, v60
	v_add_f32_e32 v61, v65, v61
	v_cvt_pk_bf16_f32 v57, v52, v53
	v_permlane16_swap_b32_e32 v60, v0
	global_store_dwordx4 v[50:51], v[54:57], off
	v_add_f32_e32 v50, v60, v0
	v_mov_b32_e32 v0, v61
	s_nop 1
	v_permlane16_swap_b32_e32 v61, v0
	v_add_f32_e32 v51, v61, v0
	v_mov_b32_e32 v52, v50
	v_mov_b32_e32 v53, v51
	s_nop 0
	v_permlane32_swap_b32_e32 v50, v52
	v_permlane32_swap_b32_e32 v51, v53
	s_and_saveexec_b64 s[24:25], s[44:45]
	s_cbranch_execz .LBB0_1545
	v_pk_add_f32 v[50:51], v[50:51], v[52:53]
	v_lshl_add_u64 v[52:53], s[6:7], 0, v[110:111]
	v_lshl_add_u64 v[52:53], s[52:53], 2, v[52:53]
	global_store_dwordx2 v[52:53], v[50:51], off
.LBB0_1545:
	s_or_b64 exec, exec, s[24:25]
	v_pk_add_f32 v[50:51], v[112:113], v[114:115]
	s_mov_b32 s2, 0x3a800000
	v_pk_mul_f32 v[78:79], v[50:51], s[2:3] op_sel_hi:[1,0]
	s_mov_b32 s1, 0x800000
	v_fma_f32 v0, -v79, v79, v78
	v_max_f32_e32 v0, 0, v0
	v_add_f32_e32 v0, 0x3727c5ac, v0
	v_cmp_gt_f32_e32 vcc, s1, v0
	v_mul_f32_e32 v50, 0x4b800000, v0
	s_load_dwordx16 s[64:79], s[34:35], 0x38
	v_cndmask_b32_e32 v0, v0, v50, vcc
	v_rsq_f32_e32 v0, v0
	s_mov_b32 s2, 0x3fd744fd
	s_movk_i32 s1, 0x37c0
	v_mul_f32_e32 v50, 0x45800000, v0
	v_cndmask_b32_e32 v78, v0, v50, vcc
	v_lshlrev_b64 v[50:51], 12, v[108:109]
	s_waitcnt lgkmcnt(0)
	v_lshl_add_u64 v[50:51], s[78:79], 0, v[50:51]
	v_lshl_add_u64 v[80:81], v[152:153], 2, v[50:51]
	global_load_dwordx4 v[82:85], v[80:81], off offset:16 nt
	global_load_dwordx4 v[86:89], v[80:81], off nt
	global_load_dwordx4 v[90:93], v[156:157], off offset:16
	global_load_dwordx4 v[110:113], v[156:157], off
	global_load_dwordx4 v[114:117], v[154:155], off offset:16
	global_load_dwordx4 v[118:121], v[154:155], off
	global_load_dwordx4 v[50:53], v[80:81], off offset:528 nt
	global_load_dwordx4 v[70:73], v[80:81], off offset:512 nt
	global_load_dwordx4 v[54:57], v[156:157], off offset:528
	global_load_dwordx4 v[62:65], v[156:157], off offset:512
	global_load_dwordx4 v[58:61], v[154:155], off offset:528
	global_load_dwordx4 v[66:69], v[154:155], off offset:512
	v_lshlrev_b32_e32 v0, 6, v108
	v_and_or_b32 v0, v0, s1, v196
	v_lshlrev_b32_e32 v0, 1, v0
	s_waitcnt vmcnt(10)
	v_sub_f32_e32 v87, v87, v79
	v_sub_f32_e32 v86, v86, v79
	v_sub_f32_e32 v89, v89, v79
	v_sub_f32_e32 v88, v88, v79
	v_pk_mul_f32 v[88:89], v[78:79], v[88:89] op_sel_hi:[0,1]
	v_pk_mul_f32 v[86:87], v[78:79], v[86:87] op_sel_hi:[0,1]
	s_waitcnt vmcnt(6)
; __device__ __forceinline__ float xsum16(float v) { const auto r = __builtin_amdgcn_permlane16_swap(__float_as_uint(v), __float_as_uint(v), false, false); return __uint_as_float(r[0]) + __uint_as_float(r[1]); }
; __device__ __forceinline__ float xsum32(float v) { const auto r = __builtin_amdgcn_permlane32_swap(__float_as_uint(v), __float_as_uint(v), false, false); return __uint_as_float(r[0]) + __uint_as_float(r[1]); }
; __device__ __forceinline__ size_t blk_off(int r, int c, int K) { return (size_t)(r >> 8) * 256 * K + (size_t)(c >> 6) * (256 * 64) + (size_t)((r & 255) * 64 + (c & 63)); }
; __device__ __forceinline__ u32x4 pack8(const f32x4 a, const f32x4 b) { u32x4 w; w.x = cvt_pk_bf16(a[0], a[1]); w.y = cvt_pk_bf16(a[2], a[3]); w.z = cvt_pk_bf16(b[0], b[1]); w.w = cvt_pk_bf16(b[2], b[3]); return w; }
;     __device__ __forceinline__ void operator()(const f32x4 (&acc)[2][2][4][2], const pg8::Unit& u, int wr, int wc, int fr, int fq) const {
;     ...
;                     for (int n = 0; n < 2; ++n) { yv[bj][n] = *(const f32x4*)(Yin + (size_t)row * D_ + col0 + bj * 128 + 4 * n); gq[bj][n] = *(const f32x4*)(g + col0 + bj * 128 + 4 * n); bq_[bj][n] = *(const f32x4*)(b + col0 + bj * 128 + 4 * n); }
;                 asm volatile("" ::: "memory");
;                 float s1 = 0.f, s2 = 0.f;
; #pragma unroll
;                 for (int bj = 0; bj < 2; ++bj) { float* yp = Y + (size_t)row * D_ + col0 + bj * 128; f32x4 v[2];
; #pragma unroll
;                     for (int n = 0; n < 2; ++n) { v[n] = (((yv[bj][n] - mu) * rs) * gq[bj][n] + bq_[bj][n]) * ALPHA_ + acc[ai][bj][m][n] * sc;
;                         *(f32x4*)(yp + 4 * n) = v[n]; s1 += (v[n][0] + v[n][1]) + (v[n][2] + v[n][3]); s2 += (v[n][0] * v[n][0] + v[n][1] * v[n][1]) + (v[n][2] * v[n][2] + v[n][3] * v[n][3]); }
;                     *(u32x4*)(Yb + blk_off(row, col0 + bj * 128, D_)) = pack8(v[0], v[1]); }
;                 s1 = xsum32(xsum16(s1)); s2 = xsum32(xsum16(s2));
;                 if (fq == 0) *(f32x2*)(stn + (size_t)row * 32 + (u.pn * 4 + wc) * 2) = (f32x2){s1, s2}; asm volatile("" ::: "memory"); } }
	v_pk_fma_f32 v[86:87], v[110:111], v[86:87], v[118:119]
	v_pk_fma_f32 v[88:89], v[112:113], v[88:89], v[120:121]
	v_pk_fma_f32 v[86:87], v[86:87], s[2:3], v[46:47] op_sel_hi:[1,0,1]
	v_pk_fma_f32 v[88:89], v[88:89], s[2:3], v[48:49] op_sel_hi:[1,0,1]
	v_add_f32_e32 v46, v86, v87
	v_add_f32_e32 v47, v88, v89
	v_add_f32_e32 v46, v46, v47
	v_add_f32_e32 v108, 0, v46
	v_mul_f32_e32 v46, v87, v87
	v_mul_f32_e32 v47, v89, v89
	v_fmac_f32_e32 v46, v86, v86
	v_fmac_f32_e32 v47, v88, v88
	v_add_f32_e32 v109, v46, v47
	v_sub_f32_e32 v47, v83, v79
	v_sub_f32_e32 v46, v82, v79
	v_sub_f32_e32 v49, v85, v79
	v_sub_f32_e32 v48, v84, v79
	v_pk_mul_f32 v[48:49], v[78:79], v[48:49] op_sel_hi:[0,1]
	v_pk_mul_f32 v[46:47], v[78:79], v[46:47] op_sel_hi:[0,1]
	v_pk_fma_f32 v[46:47], v[90:91], v[46:47], v[114:115]
	v_pk_fma_f32 v[48:49], v[92:93], v[48:49], v[116:117]
	v_pk_fma_f32 v[82:83], v[46:47], s[2:3], v[42:43] op_sel_hi:[1,0,1]
	v_pk_fma_f32 v[84:85], v[48:49], s[2:3], v[44:45] op_sel_hi:[1,0,1]
	v_add_f32_e32 v42, v82, v83
	v_add_f32_e32 v43, v84, v85
	v_add_f32_e32 v42, v42, v43
	v_add_f32_e32 v47, v108, v42
	v_mul_f32_e32 v42, v83, v83
	v_mul_f32_e32 v43, v85, v85
	v_fmac_f32_e32 v42, v82, v82
	v_fmac_f32_e32 v43, v84, v84
	v_add_f32_e32 v42, v42, v43
	v_add_f32_e32 v46, v109, v42
	v_cvt_pk_bf16_f32 v42, v86, v87
	v_cvt_pk_bf16_f32 v43, v88, v89
	v_cvt_pk_bf16_f32 v44, v82, v83
	v_cvt_pk_bf16_f32 v45, v84, v85
	v_lshl_add_u64 v[48:49], v[76:77], 0, v[0:1]
	s_nop 0
	s_nop 1
	v_bfe_u32 v91, v227, 4, 2
	v_sub_u32_e32 v90, 0, v91
	v_lshlrev_b32_e32 v90, 4, v90
	v_ashrrev_i32_e32 v91, 31, v90
	v_lshl_add_u64 v[90:91], v[80:81], 0, v[90:91]
	v_permlane16_swap_b32_e32 v86, v82
	v_permlane16_swap_b32_e32 v87, v83
	v_permlane16_swap_b32_e32 v88, v84
	v_permlane16_swap_b32_e32 v89, v85
	v_permlane32_swap_b32_e32 v86, v82
	v_permlane32_swap_b32_e32 v87, v83
	v_permlane32_swap_b32_e32 v88, v84
	v_permlane32_swap_b32_e32 v89, v85
	global_store_dwordx4 v[90:91], v[86:89], off
	global_store_dwordx4 v[90:91], v[82:85], off offset:64
	s_nop 1
	v_permlane32_swap_b32_e32 v86, v82
	v_permlane32_swap_b32_e32 v87, v83
	v_permlane32_swap_b32_e32 v88, v84
	v_permlane32_swap_b32_e32 v89, v85
	v_permlane16_swap_b32_e32 v86, v82
	v_permlane16_swap_b32_e32 v87, v83
	v_permlane16_swap_b32_e32 v88, v84
	v_permlane16_swap_b32_e32 v89, v85
	global_store_dwordx4 v[48:49], v[42:45], off
	s_waitcnt vmcnt(7)
	s_nop 0
	v_sub_f32_e32 v43, v71, v79
	v_sub_f32_e32 v42, v70, v79
	v_sub_f32_e32 v45, v73, v79
	v_sub_f32_e32 v44, v72, v79
	v_pk_mul_f32 v[44:45], v[78:79], v[44:45] op_sel_hi:[0,1]
	v_pk_mul_f32 v[42:43], v[78:79], v[42:43] op_sel_hi:[0,1]
	s_waitcnt vmcnt(3)
	v_pk_fma_f32 v[42:43], v[62:63], v[42:43], v[66:67]
	v_pk_fma_f32 v[44:45], v[64:65], v[44:45], v[68:69]
	v_pk_fma_f32 v[38:39], v[42:43], s[2:3], v[38:39] op_sel_hi:[1,0,1]
	v_pk_fma_f32 v[40:41], v[44:45], s[2:3], v[40:41] op_sel_hi:[1,0,1]
	v_add_f32_e32 v42, v38, v39
	v_add_f32_e32 v43, v40, v41
	v_add_f32_e32 v42, v42, v43
	v_add_f32_e32 v47, v47, v42
	v_mul_f32_e32 v42, v39, v39
	v_mul_f32_e32 v43, v41, v41
	v_fmac_f32_e32 v42, v38, v38
	v_fmac_f32_e32 v43, v40, v40
	v_add_f32_e32 v42, v42, v43
	v_add_f32_e32 v46, v46, v42
	v_sub_f32_e32 v43, v51, v79
	v_sub_f32_e32 v42, v50, v79
	v_sub_f32_e32 v45, v53, v79
	v_sub_f32_e32 v44, v52, v79
	v_pk_mul_f32 v[44:45], v[78:79], v[44:45] op_sel_hi:[0,1]
	v_pk_mul_f32 v[42:43], v[78:79], v[42:43] op_sel_hi:[0,1]
	v_pk_fma_f32 v[42:43], v[54:55], v[42:43], v[58:59]
	v_pk_fma_f32 v[44:45], v[56:57], v[44:45], v[60:61]
	v_pk_fma_f32 v[34:35], v[42:43], s[2:3], v[34:35] op_sel_hi:[1,0,1]
	v_pk_fma_f32 v[36:37], v[44:45], s[2:3], v[36:37] op_sel_hi:[1,0,1]
	v_add_f32_e32 v42, v34, v35
	v_add_f32_e32 v43, v36, v37
	v_add_f32_e32 v42, v42, v43
	v_mul_f32_e32 v43, v35, v35
	v_mul_f32_e32 v44, v37, v37
	v_add_f32_e32 v42, v47, v42
	v_fmac_f32_e32 v43, v34, v34
	v_fmac_f32_e32 v44, v36, v36
	s_nop 0
	s_nop 1
	v_bfe_u32 v49, v227, 4, 2
	v_sub_u32_e32 v48, 0, v49
	v_lshlrev_b32_e32 v48, 4, v48
	v_ashrrev_i32_e32 v49, 31, v48
	v_lshl_add_u64 v[48:49], v[80:81], 0, v[48:49]
	v_permlane16_swap_b32_e32 v38, v34
	v_permlane16_swap_b32_e32 v39, v35
	v_permlane16_swap_b32_e32 v40, v36
	v_permlane16_swap_b32_e32 v41, v37
	v_permlane32_swap_b32_e32 v38, v34
	v_permlane32_swap_b32_e32 v39, v35
	v_permlane32_swap_b32_e32 v40, v36
	v_permlane32_swap_b32_e32 v41, v37
	global_store_dwordx4 v[48:49], v[38:41], off offset:512
	global_store_dwordx4 v[48:49], v[34:37], off offset:576
	s_nop 1
	v_permlane32_swap_b32_e32 v38, v34
	v_permlane32_swap_b32_e32 v39, v35
	v_permlane32_swap_b32_e32 v40, v36
	v_permlane32_swap_b32_e32 v41, v37
	v_permlane16_swap_b32_e32 v38, v34
	v_permlane16_swap_b32_e32 v39, v35
	v_permlane16_swap_b32_e32 v40, v36
	v_permlane16_swap_b32_e32 v41, v37
	v_add_f32_e32 v43, v43, v44
	v_cvt_pk_bf16_f32 v38, v38, v39
	v_cvt_pk_bf16_f32 v39, v40, v41
	v_cvt_pk_bf16_f32 v40, v34, v35
	v_lshl_add_u64 v[34:35], v[74:75], 0, v[0:1]
	v_mov_b32_e32 v0, v42
	v_add_f32_e32 v43, v46, v43
	v_cvt_pk_bf16_f32 v41, v36, v37
	v_permlane16_swap_b32_e32 v42, v0
	global_store_dwordx4 v[34:35], v[38:41], off
	v_add_f32_e32 v34, v42, v0
	v_mov_b32_e32 v0, v43
	s_nop 1
	v_permlane16_swap_b32_e32 v43, v0
	v_add_f32_e32 v35, v43, v0
	v_mov_b32_e32 v36, v34
	v_mov_b32_e32 v37, v35
	s_nop 0
	v_permlane32_swap_b32_e32 v34, v36
	v_permlane32_swap_b32_e32 v35, v37
	s_and_saveexec_b64 s[24:25], s[44:45]
	s_cbranch_execz .LBB0_1547
	v_pk_add_f32 v[34:35], v[34:35], v[36:37]
	v_lshl_add_u64 v[36:37], s[6:7], 0, v[102:103]
	v_lshl_add_u64 v[36:37], s[52:53], 2, v[36:37]
	global_store_dwordx2 v[36:37], v[34:35], off
; __device__ __forceinline__ float xsum16(float v) { const auto r = __builtin_amdgcn_permlane16_swap(__float_as_uint(v), __float_as_uint(v), false, false); return __uint_as_float(r[0]) + __uint_as_float(r[1]); }
; __device__ __forceinline__ float xsum32(float v) { const auto r = __builtin_amdgcn_permlane32_swap(__float_as_uint(v), __float_as_uint(v), false, false); return __uint_as_float(r[0]) + __uint_as_float(r[1]); }
; __device__ __forceinline__ size_t blk_off(int r, int c, int K) { return (size_t)(r >> 8) * 256 * K + (size_t)(c >> 6) * (256 * 64) + (size_t)((r & 255) * 64 + (c & 63)); }
; __device__ __forceinline__ u32x4 pack8(const f32x4 a, const f32x4 b) { u32x4 w; w.x = cvt_pk_bf16(a[0], a[1]); w.y = cvt_pk_bf16(a[2], a[3]); w.z = cvt_pk_bf16(b[0], b[1]); w.w = cvt_pk_bf16(b[2], b[3]); return w; }
; __device__ __forceinline__ void row_stats(const float* st, int row, int fq, float& mu, float& rstd) {
;     ...
;     mu = s1 * (1.0f / 1024.0f); const float var = fmaxf(s2 * (1.0f / 1024.0f) - mu * mu, 0.f); rstd = rsqrtf(var + LN_EPS_);
;     __device__ __forceinline__ void operator()(const f32x4 (&acc)[2][2][4][2], const pg8::Unit& u, int wr, int wc, int fr, int fq) const {
;     ...
;                     for (int n = 0; n < 2; ++n) { yv[bj][n] = *(const f32x4*)(Yin + (size_t)row * D_ + col0 + bj * 128 + 4 * n); gq[bj][n] = *(const f32x4*)(g + col0 + bj * 128 + 4 * n); bq_[bj][n] = *(const f32x4*)(b + col0 + bj * 128 + 4 * n); }
;                 asm volatile("" ::: "memory");
;                 float s1 = 0.f, s2 = 0.f;
; #pragma unroll
;                 for (int bj = 0; bj < 2; ++bj) { float* yp = Y + (size_t)row * D_ + col0 + bj * 128; f32x4 v[2];
; #pragma unroll
;                     for (int n = 0; n < 2; ++n) { v[n] = (((yv[bj][n] - mu) * rs) * gq[bj][n] + bq_[bj][n]) * ALPHA_ + acc[ai][bj][m][n] * sc;
;                         *(f32x4*)(yp + 4 * n) = v[n]; s1 += (v[n][0] + v[n][1]) + (v[n][2] + v[n][3]); s2 += (v[n][0] * v[n][0] + v[n][1] * v[n][1]) + (v[n][2] * v[n][2] + v[n][3] * v[n][3]); }
;                     *(u32x4*)(Yb + blk_off(row, col0 + bj * 128, D_)) = pack8(v[0], v[1]); }
;                 s1 = xsum32(xsum16(s1)); s2 = xsum32(xsum16(s2));
;                 if (fq == 0) *(f32x2*)(stn + (size_t)row * 32 + (u.pn * 4 + wc) * 2) = (f32x2){s1, s2}; asm volatile("" ::: "memory"); } }
.LBB0_1547:
	s_or_b64 exec, exec, s[24:25]
	v_pk_add_f32 v[34:35], v[104:105], v[106:107]
	s_mov_b32 s2, 0x3a800000
	v_pk_mul_f32 v[58:59], v[34:35], s[2:3] op_sel_hi:[1,0]
	s_mov_b32 s1, 0x800000
	v_fma_f32 v0, -v59, v59, v58
	v_max_f32_e32 v0, 0, v0
	v_add_f32_e32 v0, 0x3727c5ac, v0
	v_cmp_gt_f32_e32 vcc, s1, v0
	v_mul_f32_e32 v34, 0x4b800000, v0
	s_load_dwordx16 s[64:79], s[34:35], 0x38
	v_cndmask_b32_e32 v0, v0, v34, vcc
	v_rsq_f32_e32 v0, v0
	s_mov_b32 s2, 0x3fd744fd
	s_movk_i32 s1, 0x3bc0
	v_mul_f32_e32 v34, 0x45800000, v0
	v_cndmask_b32_e32 v58, v0, v34, vcc
	v_lshlrev_b64 v[34:35], 12, v[96:97]
	s_waitcnt lgkmcnt(0)
	v_lshl_add_u64 v[34:35], s[78:79], 0, v[34:35]
	v_lshl_add_u64 v[60:61], v[152:153], 2, v[34:35]
	global_load_dwordx4 v[62:65], v[60:61], off offset:16 nt
	global_load_dwordx4 v[66:69], v[60:61], off nt
	global_load_dwordx4 v[70:73], v[156:157], off offset:16
	global_load_dwordx4 v[78:81], v[156:157], off
	global_load_dwordx4 v[82:85], v[154:155], off offset:16
	global_load_dwordx4 v[86:89], v[154:155], off
	global_load_dwordx4 v[34:37], v[60:61], off offset:528 nt
	global_load_dwordx4 v[54:57], v[60:61], off offset:512 nt
	global_load_dwordx4 v[38:41], v[156:157], off offset:528
	global_load_dwordx4 v[46:49], v[156:157], off offset:512
	global_load_dwordx4 v[42:45], v[154:155], off offset:528
	global_load_dwordx4 v[50:53], v[154:155], off offset:512
	v_lshlrev_b32_e32 v0, 6, v96
	v_and_or_b32 v0, v0, s1, v196
	v_lshlrev_b32_e32 v0, 1, v0
	s_waitcnt vmcnt(10)
	v_sub_f32_e32 v67, v67, v59
	v_sub_f32_e32 v66, v66, v59
	v_sub_f32_e32 v69, v69, v59
	v_sub_f32_e32 v68, v68, v59
	v_pk_mul_f32 v[68:69], v[58:59], v[68:69] op_sel_hi:[0,1]
	v_pk_mul_f32 v[66:67], v[58:59], v[66:67] op_sel_hi:[0,1]
	s_waitcnt vmcnt(6)
	v_pk_fma_f32 v[66:67], v[78:79], v[66:67], v[86:87]
	v_pk_fma_f32 v[68:69], v[80:81], v[68:69], v[88:89]
	v_pk_fma_f32 v[66:67], v[66:67], s[2:3], v[30:31] op_sel_hi:[1,0,1]
	v_pk_fma_f32 v[68:69], v[68:69], s[2:3], v[32:33] op_sel_hi:[1,0,1]
	v_add_f32_e32 v30, v66, v67
	v_add_f32_e32 v31, v68, v69
	v_add_f32_e32 v30, v30, v31
	v_add_f32_e32 v78, 0, v30
	v_mul_f32_e32 v30, v67, v67
	v_mul_f32_e32 v31, v69, v69
	v_fmac_f32_e32 v30, v66, v66
	v_fmac_f32_e32 v31, v68, v68
	v_add_f32_e32 v79, v30, v31
	v_sub_f32_e32 v31, v63, v59
	v_sub_f32_e32 v30, v62, v59
	v_sub_f32_e32 v33, v65, v59
	v_sub_f32_e32 v32, v64, v59
	v_pk_mul_f32 v[32:33], v[58:59], v[32:33] op_sel_hi:[0,1]
	v_pk_mul_f32 v[30:31], v[58:59], v[30:31] op_sel_hi:[0,1]
	v_pk_fma_f32 v[30:31], v[70:71], v[30:31], v[82:83]
	v_pk_fma_f32 v[32:33], v[72:73], v[32:33], v[84:85]
	v_pk_fma_f32 v[62:63], v[30:31], s[2:3], v[26:27] op_sel_hi:[1,0,1]
	v_pk_fma_f32 v[64:65], v[32:33], s[2:3], v[28:29] op_sel_hi:[1,0,1]
	v_add_f32_e32 v26, v62, v63
	v_add_f32_e32 v27, v64, v65
	v_add_f32_e32 v26, v26, v27
	v_add_f32_e32 v31, v78, v26
	v_mul_f32_e32 v26, v63, v63
	v_mul_f32_e32 v27, v65, v65
	v_fmac_f32_e32 v26, v62, v62
	v_fmac_f32_e32 v27, v64, v64
	v_add_f32_e32 v26, v26, v27
	v_add_f32_e32 v30, v79, v26
	v_cvt_pk_bf16_f32 v26, v66, v67
	v_cvt_pk_bf16_f32 v27, v68, v69
	v_cvt_pk_bf16_f32 v28, v62, v63
	v_cvt_pk_bf16_f32 v29, v64, v65
	v_lshl_add_u64 v[32:33], v[76:77], 0, v[0:1]
	s_nop 0
	s_nop 1
	v_bfe_u32 v71, v227, 4, 2
	v_sub_u32_e32 v70, 0, v71
	v_lshlrev_b32_e32 v70, 4, v70
	v_ashrrev_i32_e32 v71, 31, v70
	v_lshl_add_u64 v[70:71], v[60:61], 0, v[70:71]
	v_permlane16_swap_b32_e32 v66, v62
	v_permlane16_swap_b32_e32 v67, v63
	v_permlane16_swap_b32_e32 v68, v64
	v_permlane16_swap_b32_e32 v69, v65
	v_permlane32_swap_b32_e32 v66, v62
	v_permlane32_swap_b32_e32 v67, v63
	v_permlane32_swap_b32_e32 v68, v64
	v_permlane32_swap_b32_e32 v69, v65
	global_store_dwordx4 v[70:71], v[66:69], off
	global_store_dwordx4 v[70:71], v[62:65], off offset:64
	s_nop 1
	v_permlane32_swap_b32_e32 v66, v62
	v_permlane32_swap_b32_e32 v67, v63
	v_permlane32_swap_b32_e32 v68, v64
	v_permlane32_swap_b32_e32 v69, v65
	v_permlane16_swap_b32_e32 v66, v62
	v_permlane16_swap_b32_e32 v67, v63
	v_permlane16_swap_b32_e32 v68, v64
	v_permlane16_swap_b32_e32 v69, v65
	global_store_dwordx4 v[32:33], v[26:29], off
	s_waitcnt vmcnt(7)
	s_nop 0
	v_sub_f32_e32 v27, v55, v59
	v_sub_f32_e32 v26, v54, v59
	v_sub_f32_e32 v29, v57, v59
	v_sub_f32_e32 v28, v56, v59
	v_pk_mul_f32 v[28:29], v[58:59], v[28:29] op_sel_hi:[0,1]
	v_pk_mul_f32 v[26:27], v[58:59], v[26:27] op_sel_hi:[0,1]
	s_waitcnt vmcnt(3)
; __device__ __forceinline__ float xsum16(float v) { const auto r = __builtin_amdgcn_permlane16_swap(__float_as_uint(v), __float_as_uint(v), false, false); return __uint_as_float(r[0]) + __uint_as_float(r[1]); }
; __device__ __forceinline__ float xsum32(float v) { const auto r = __builtin_amdgcn_permlane32_swap(__float_as_uint(v), __float_as_uint(v), false, false); return __uint_as_float(r[0]) + __uint_as_float(r[1]); }
; __device__ __forceinline__ size_t blk_off(int r, int c, int K) { return (size_t)(r >> 8) * 256 * K + (size_t)(c >> 6) * (256 * 64) + (size_t)((r & 255) * 64 + (c & 63)); }
; __device__ __forceinline__ u32x4 pack8(const f32x4 a, const f32x4 b) { u32x4 w; w.x = cvt_pk_bf16(a[0], a[1]); w.y = cvt_pk_bf16(a[2], a[3]); w.z = cvt_pk_bf16(b[0], b[1]); w.w = cvt_pk_bf16(b[2], b[3]); return w; }
; __device__ __forceinline__ void row_stats(const float* st, int row, int fq, float& mu, float& rstd) {
;     ...
;     mu = s1 * (1.0f / 1024.0f); const float var = fmaxf(s2 * (1.0f / 1024.0f) - mu * mu, 0.f); rstd = rsqrtf(var + LN_EPS_);
;     __device__ __forceinline__ void operator()(const f32x4 (&acc)[2][2][4][2], const pg8::Unit& u, int wr, int wc, int fr, int fq) const {
;     ...
;                     for (int n = 0; n < 2; ++n) { yv[bj][n] = *(const f32x4*)(Yin + (size_t)row * D_ + col0 + bj * 128 + 4 * n); gq[bj][n] = *(const f32x4*)(g + col0 + bj * 128 + 4 * n); bq_[bj][n] = *(const f32x4*)(b + col0 + bj * 128 + 4 * n); }
;                 asm volatile("" ::: "memory");
;                 float s1 = 0.f, s2 = 0.f;
; #pragma unroll
;                 for (int bj = 0; bj < 2; ++bj) { float* yp = Y + (size_t)row * D_ + col0 + bj * 128; f32x4 v[2];
; #pragma unroll
;                     for (int n = 0; n < 2; ++n) { v[n] = (((yv[bj][n] - mu) * rs) * gq[bj][n] + bq_[bj][n]) * ALPHA_ + acc[ai][bj][m][n] * sc;
;                         *(f32x4*)(yp + 4 * n) = v[n]; s1 += (v[n][0] + v[n][1]) + (v[n][2] + v[n][3]); s2 += (v[n][0] * v[n][0] + v[n][1] * v[n][1]) + (v[n][2] * v[n][2] + v[n][3] * v[n][3]); }
;                     *(u32x4*)(Yb + blk_off(row, col0 + bj * 128, D_)) = pack8(v[0], v[1]); }
;                 s1 = xsum32(xsum16(s1)); s2 = xsum32(xsum16(s2));
;                 if (fq == 0) *(f32x2*)(stn + (size_t)row * 32 + (u.pn * 4 + wc) * 2) = (f32x2){s1, s2}; asm volatile("" ::: "memory"); } }
	v_pk_fma_f32 v[26:27], v[46:47], v[26:27], v[50:51]
	v_pk_fma_f32 v[28:29], v[48:49], v[28:29], v[52:53]
	v_pk_fma_f32 v[22:23], v[26:27], s[2:3], v[22:23] op_sel_hi:[1,0,1]
	v_pk_fma_f32 v[24:25], v[28:29], s[2:3], v[24:25] op_sel_hi:[1,0,1]
	v_add_f32_e32 v26, v22, v23
	v_add_f32_e32 v27, v24, v25
	v_add_f32_e32 v26, v26, v27
	v_add_f32_e32 v31, v31, v26
	v_mul_f32_e32 v26, v23, v23
	v_mul_f32_e32 v27, v25, v25
	v_fmac_f32_e32 v26, v22, v22
	v_fmac_f32_e32 v27, v24, v24
	v_add_f32_e32 v26, v26, v27
	v_add_f32_e32 v30, v30, v26
	v_sub_f32_e32 v27, v35, v59
	v_sub_f32_e32 v26, v34, v59
	v_sub_f32_e32 v29, v37, v59
	v_sub_f32_e32 v28, v36, v59
	v_pk_mul_f32 v[28:29], v[58:59], v[28:29] op_sel_hi:[0,1]
	v_pk_mul_f32 v[26:27], v[58:59], v[26:27] op_sel_hi:[0,1]
	v_pk_fma_f32 v[26:27], v[38:39], v[26:27], v[42:43]
	v_pk_fma_f32 v[28:29], v[40:41], v[28:29], v[44:45]
	v_pk_fma_f32 v[18:19], v[26:27], s[2:3], v[18:19] op_sel_hi:[1,0,1]
	v_pk_fma_f32 v[20:21], v[28:29], s[2:3], v[20:21] op_sel_hi:[1,0,1]
	v_add_f32_e32 v26, v18, v19
	v_add_f32_e32 v27, v20, v21
	v_add_f32_e32 v26, v26, v27
	v_mul_f32_e32 v27, v19, v19
	v_mul_f32_e32 v28, v21, v21
	v_add_f32_e32 v26, v31, v26
	v_fmac_f32_e32 v27, v18, v18
	v_fmac_f32_e32 v28, v20, v20
	s_nop 0
	s_nop 1
	v_bfe_u32 v33, v227, 4, 2
	v_sub_u32_e32 v32, 0, v33
	v_lshlrev_b32_e32 v32, 4, v32
	v_ashrrev_i32_e32 v33, 31, v32
	v_lshl_add_u64 v[32:33], v[60:61], 0, v[32:33]
	v_permlane16_swap_b32_e32 v22, v18
	v_permlane16_swap_b32_e32 v23, v19
	v_permlane16_swap_b32_e32 v24, v20
	v_permlane16_swap_b32_e32 v25, v21
	v_permlane32_swap_b32_e32 v22, v18
	v_permlane32_swap_b32_e32 v23, v19
	v_permlane32_swap_b32_e32 v24, v20
	v_permlane32_swap_b32_e32 v25, v21
	global_store_dwordx4 v[32:33], v[22:25], off offset:512
	global_store_dwordx4 v[32:33], v[18:21], off offset:576
	s_nop 1
	v_permlane32_swap_b32_e32 v22, v18
	v_permlane32_swap_b32_e32 v23, v19
	v_permlane32_swap_b32_e32 v24, v20
	v_permlane32_swap_b32_e32 v25, v21
	v_permlane16_swap_b32_e32 v22, v18
	v_permlane16_swap_b32_e32 v23, v19
	v_permlane16_swap_b32_e32 v24, v20
	v_permlane16_swap_b32_e32 v25, v21
	v_add_f32_e32 v27, v27, v28
	v_cvt_pk_bf16_f32 v22, v22, v23
	v_cvt_pk_bf16_f32 v23, v24, v25
	v_cvt_pk_bf16_f32 v24, v18, v19
	v_lshl_add_u64 v[18:19], v[74:75], 0, v[0:1]
	v_mov_b32_e32 v0, v26
	v_add_f32_e32 v27, v30, v27
	v_cvt_pk_bf16_f32 v25, v20, v21
	v_permlane16_swap_b32_e32 v26, v0
	global_store_dwordx4 v[18:19], v[22:25], off
	v_add_f32_e32 v18, v26, v0
	v_mov_b32_e32 v0, v27
	s_nop 1
	v_permlane16_swap_b32_e32 v27, v0
	v_add_f32_e32 v19, v27, v0
	v_mov_b32_e32 v20, v18
	v_mov_b32_e32 v21, v19
	s_nop 0
	v_permlane32_swap_b32_e32 v18, v20
	v_permlane32_swap_b32_e32 v19, v21
	s_and_saveexec_b64 s[24:25], s[44:45]
	s_cbranch_execz .LBB0_1549
	v_pk_add_f32 v[18:19], v[18:19], v[20:21]
	v_lshlrev_b64 v[20:21], 7, v[96:97]
	v_lshl_add_u64 v[20:21], s[6:7], 0, v[20:21]
	v_lshl_add_u64 v[20:21], s[52:53], 2, v[20:21]
	global_store_dwordx2 v[20:21], v[18:19], off
.LBB0_1549:
	s_or_b64 exec, exec, s[24:25]
	v_pk_add_f32 v[18:19], v[98:99], v[100:101]
	s_mov_b32 s2, 0x3a800000
	v_pk_mul_f32 v[42:43], v[18:19], s[2:3] op_sel_hi:[1,0]
	s_mov_b32 s1, 0x800000
	v_fma_f32 v0, -v43, v43, v42
	v_max_f32_e32 v0, 0, v0
	v_add_f32_e32 v0, 0x3727c5ac, v0
	v_cmp_gt_f32_e32 vcc, s1, v0
	v_mul_f32_e32 v18, 0x4b800000, v0
	s_load_dwordx16 s[64:79], s[34:35], 0x38
	v_cndmask_b32_e32 v0, v0, v18, vcc
	v_rsq_f32_e32 v0, v0
	s_mov_b32 s2, 0x3fd744fd
	s_movk_i32 s1, 0x3fc0
	v_mul_f32_e32 v18, 0x45800000, v0
	v_cndmask_b32_e32 v42, v0, v18, vcc
	v_lshlrev_b64 v[18:19], 12, v[94:95]
	s_waitcnt lgkmcnt(0)
	v_lshl_add_u64 v[18:19], s[78:79], 0, v[18:19]
	v_lshl_add_u64 v[44:45], v[152:153], 2, v[18:19]
	global_load_dwordx4 v[46:49], v[44:45], off offset:16 nt
	global_load_dwordx4 v[50:53], v[44:45], off nt
	global_load_dwordx4 v[54:57], v[156:157], off offset:16
	global_load_dwordx4 v[58:61], v[156:157], off
	global_load_dwordx4 v[62:65], v[154:155], off offset:16
	global_load_dwordx4 v[66:69], v[154:155], off
	global_load_dwordx4 v[18:21], v[44:45], off offset:528 nt
	global_load_dwordx4 v[38:41], v[44:45], off offset:512 nt
	global_load_dwordx4 v[22:25], v[156:157], off offset:528
	global_load_dwordx4 v[30:33], v[156:157], off offset:512
	global_load_dwordx4 v[26:29], v[154:155], off offset:528
	global_load_dwordx4 v[34:37], v[154:155], off offset:512
	v_lshlrev_b32_e32 v0, 6, v94
	v_and_or_b32 v0, v0, s1, v196
	v_lshlrev_b32_e32 v0, 1, v0
	s_waitcnt vmcnt(10)
	v_sub_f32_e32 v51, v51, v43
	v_sub_f32_e32 v50, v50, v43
	v_sub_f32_e32 v53, v53, v43
	v_sub_f32_e32 v52, v52, v43
	v_pk_mul_f32 v[52:53], v[42:43], v[52:53] op_sel_hi:[0,1]
	v_pk_mul_f32 v[50:51], v[42:43], v[50:51] op_sel_hi:[0,1]
	s_waitcnt vmcnt(6)
; __device__ __forceinline__ float xsum16(float v) { const auto r = __builtin_amdgcn_permlane16_swap(__float_as_uint(v), __float_as_uint(v), false, false); return __uint_as_float(r[0]) + __uint_as_float(r[1]); }
; __device__ __forceinline__ float xsum32(float v) { const auto r = __builtin_amdgcn_permlane32_swap(__float_as_uint(v), __float_as_uint(v), false, false); return __uint_as_float(r[0]) + __uint_as_float(r[1]); }
; __device__ __forceinline__ size_t blk_off(int r, int c, int K) { return (size_t)(r >> 8) * 256 * K + (size_t)(c >> 6) * (256 * 64) + (size_t)((r & 255) * 64 + (c & 63)); }
; __device__ __forceinline__ u32x4 pack8(const f32x4 a, const f32x4 b) { u32x4 w; w.x = cvt_pk_bf16(a[0], a[1]); w.y = cvt_pk_bf16(a[2], a[3]); w.z = cvt_pk_bf16(b[0], b[1]); w.w = cvt_pk_bf16(b[2], b[3]); return w; }
;     __device__ __forceinline__ void operator()(const f32x4 (&acc)[2][2][4][2], const pg8::Unit& u, int wr, int wc, int fr, int fq) const {
;     ...
;                     for (int n = 0; n < 2; ++n) { yv[bj][n] = *(const f32x4*)(Yin + (size_t)row * D_ + col0 + bj * 128 + 4 * n); gq[bj][n] = *(const f32x4*)(g + col0 + bj * 128 + 4 * n); bq_[bj][n] = *(const f32x4*)(b + col0 + bj * 128 + 4 * n); }
;                 asm volatile("" ::: "memory");
;                 float s1 = 0.f, s2 = 0.f;
; #pragma unroll
;                 for (int bj = 0; bj < 2; ++bj) { float* yp = Y + (size_t)row * D_ + col0 + bj * 128; f32x4 v[2];
; #pragma unroll
;                     for (int n = 0; n < 2; ++n) { v[n] = (((yv[bj][n] - mu) * rs) * gq[bj][n] + bq_[bj][n]) * ALPHA_ + acc[ai][bj][m][n] * sc;
;                         *(f32x4*)(yp + 4 * n) = v[n]; s1 += (v[n][0] + v[n][1]) + (v[n][2] + v[n][3]); s2 += (v[n][0] * v[n][0] + v[n][1] * v[n][1]) + (v[n][2] * v[n][2] + v[n][3] * v[n][3]); }
;                     *(u32x4*)(Yb + blk_off(row, col0 + bj * 128, D_)) = pack8(v[0], v[1]); }
;                 s1 = xsum32(xsum16(s1)); s2 = xsum32(xsum16(s2));
;                 if (fq == 0) *(f32x2*)(stn + (size_t)row * 32 + (u.pn * 4 + wc) * 2) = (f32x2){s1, s2}; asm volatile("" ::: "memory"); } }
	v_pk_fma_f32 v[50:51], v[58:59], v[50:51], v[66:67]
	v_pk_fma_f32 v[52:53], v[60:61], v[52:53], v[68:69]
	v_pk_fma_f32 v[50:51], v[50:51], s[2:3], v[14:15] op_sel_hi:[1,0,1]
	v_pk_fma_f32 v[52:53], v[52:53], s[2:3], v[16:17] op_sel_hi:[1,0,1]
	v_add_f32_e32 v14, v50, v51
	v_add_f32_e32 v15, v52, v53
	v_add_f32_e32 v14, v14, v15
	v_add_f32_e32 v58, 0, v14
	v_mul_f32_e32 v14, v51, v51
	v_mul_f32_e32 v15, v53, v53
	v_fmac_f32_e32 v14, v50, v50
	v_fmac_f32_e32 v15, v52, v52
	v_add_f32_e32 v59, v14, v15
	v_sub_f32_e32 v15, v47, v43
	v_sub_f32_e32 v14, v46, v43
	v_sub_f32_e32 v17, v49, v43
	v_sub_f32_e32 v16, v48, v43
	v_pk_mul_f32 v[16:17], v[42:43], v[16:17] op_sel_hi:[0,1]
	v_pk_mul_f32 v[14:15], v[42:43], v[14:15] op_sel_hi:[0,1]
	v_pk_fma_f32 v[14:15], v[54:55], v[14:15], v[62:63]
	v_pk_fma_f32 v[16:17], v[56:57], v[16:17], v[64:65]
	v_pk_fma_f32 v[46:47], v[14:15], s[2:3], v[10:11] op_sel_hi:[1,0,1]
	v_pk_fma_f32 v[48:49], v[16:17], s[2:3], v[12:13] op_sel_hi:[1,0,1]
	v_add_f32_e32 v10, v46, v47
	v_add_f32_e32 v11, v48, v49
	v_add_f32_e32 v10, v10, v11
	v_add_f32_e32 v15, v58, v10
	v_mul_f32_e32 v10, v47, v47
	v_mul_f32_e32 v11, v49, v49
	v_fmac_f32_e32 v10, v46, v46
	v_fmac_f32_e32 v11, v48, v48
	v_add_f32_e32 v10, v10, v11
	v_add_f32_e32 v14, v59, v10
	v_cvt_pk_bf16_f32 v10, v50, v51
	v_cvt_pk_bf16_f32 v11, v52, v53
	v_cvt_pk_bf16_f32 v12, v46, v47
	v_cvt_pk_bf16_f32 v13, v48, v49
	v_lshl_add_u64 v[16:17], v[76:77], 0, v[0:1]
	s_nop 0
	s_nop 1
	v_bfe_u32 v55, v227, 4, 2
	v_sub_u32_e32 v54, 0, v55
	v_lshlrev_b32_e32 v54, 4, v54
	v_ashrrev_i32_e32 v55, 31, v54
	v_lshl_add_u64 v[54:55], v[44:45], 0, v[54:55]
	v_permlane16_swap_b32_e32 v50, v46
	v_permlane16_swap_b32_e32 v51, v47
	v_permlane16_swap_b32_e32 v52, v48
	v_permlane16_swap_b32_e32 v53, v49
	v_permlane32_swap_b32_e32 v50, v46
	v_permlane32_swap_b32_e32 v51, v47
	v_permlane32_swap_b32_e32 v52, v48
	v_permlane32_swap_b32_e32 v53, v49
	global_store_dwordx4 v[54:55], v[50:53], off
	global_store_dwordx4 v[54:55], v[46:49], off offset:64
	s_nop 1
	v_permlane32_swap_b32_e32 v50, v46
	v_permlane32_swap_b32_e32 v51, v47
	v_permlane32_swap_b32_e32 v52, v48
	v_permlane32_swap_b32_e32 v53, v49
	v_permlane16_swap_b32_e32 v50, v46
	v_permlane16_swap_b32_e32 v51, v47
	v_permlane16_swap_b32_e32 v52, v48
	v_permlane16_swap_b32_e32 v53, v49
	global_store_dwordx4 v[16:17], v[10:13], off
	s_waitcnt vmcnt(7)
	s_nop 0
	v_sub_f32_e32 v11, v39, v43
	v_sub_f32_e32 v10, v38, v43
	v_sub_f32_e32 v13, v41, v43
	v_sub_f32_e32 v12, v40, v43
	v_pk_mul_f32 v[12:13], v[42:43], v[12:13] op_sel_hi:[0,1]
	v_pk_mul_f32 v[10:11], v[42:43], v[10:11] op_sel_hi:[0,1]
	s_waitcnt vmcnt(3)
	v_pk_fma_f32 v[10:11], v[30:31], v[10:11], v[34:35]
	v_pk_fma_f32 v[12:13], v[32:33], v[12:13], v[36:37]
	v_pk_fma_f32 v[6:7], v[10:11], s[2:3], v[6:7] op_sel_hi:[1,0,1]
	v_pk_fma_f32 v[8:9], v[12:13], s[2:3], v[8:9] op_sel_hi:[1,0,1]
	v_add_f32_e32 v10, v6, v7
	v_add_f32_e32 v11, v8, v9
	v_add_f32_e32 v10, v10, v11
	v_add_f32_e32 v15, v15, v10
	v_mul_f32_e32 v10, v7, v7
	v_mul_f32_e32 v11, v9, v9
	v_fmac_f32_e32 v10, v6, v6
	v_fmac_f32_e32 v11, v8, v8
	v_add_f32_e32 v10, v10, v11
	v_add_f32_e32 v14, v14, v10
	v_sub_f32_e32 v11, v19, v43
	v_sub_f32_e32 v10, v18, v43
	v_sub_f32_e32 v13, v21, v43
	v_sub_f32_e32 v12, v20, v43
	v_pk_mul_f32 v[12:13], v[42:43], v[12:13] op_sel_hi:[0,1]
	v_pk_mul_f32 v[10:11], v[42:43], v[10:11] op_sel_hi:[0,1]
	v_pk_fma_f32 v[10:11], v[22:23], v[10:11], v[26:27]
	v_pk_fma_f32 v[12:13], v[24:25], v[12:13], v[28:29]
	v_pk_fma_f32 v[2:3], v[10:11], s[2:3], v[2:3] op_sel_hi:[1,0,1]
	v_pk_fma_f32 v[4:5], v[12:13], s[2:3], v[4:5] op_sel_hi:[1,0,1]
	v_add_f32_e32 v10, v2, v3
	v_add_f32_e32 v11, v4, v5
	v_add_f32_e32 v10, v10, v11
	v_mul_f32_e32 v11, v3, v3
	v_mul_f32_e32 v12, v5, v5
	v_add_f32_e32 v10, v15, v10
	v_fmac_f32_e32 v11, v2, v2
	v_fmac_f32_e32 v12, v4, v4
	s_nop 0
	s_nop 1
	v_bfe_u32 v17, v227, 4, 2
	v_sub_u32_e32 v16, 0, v17
	v_lshlrev_b32_e32 v16, 4, v16
	v_ashrrev_i32_e32 v17, 31, v16
	v_lshl_add_u64 v[16:17], v[44:45], 0, v[16:17]
	v_permlane16_swap_b32_e32 v6, v2
	v_permlane16_swap_b32_e32 v7, v3
	v_permlane16_swap_b32_e32 v8, v4
	v_permlane16_swap_b32_e32 v9, v5
	v_permlane32_swap_b32_e32 v6, v2
	v_permlane32_swap_b32_e32 v7, v3
	v_permlane32_swap_b32_e32 v8, v4
	v_permlane32_swap_b32_e32 v9, v5
	global_store_dwordx4 v[16:17], v[6:9], off offset:512
	global_store_dwordx4 v[16:17], v[2:5], off offset:576
	s_nop 1
	v_permlane32_swap_b32_e32 v6, v2
	v_permlane32_swap_b32_e32 v7, v3
	v_permlane32_swap_b32_e32 v8, v4
	v_permlane32_swap_b32_e32 v9, v5
	v_permlane16_swap_b32_e32 v6, v2
	v_permlane16_swap_b32_e32 v7, v3
	v_permlane16_swap_b32_e32 v8, v4
	v_permlane16_swap_b32_e32 v9, v5
	v_add_f32_e32 v11, v11, v12
	v_cvt_pk_bf16_f32 v6, v6, v7
	v_cvt_pk_bf16_f32 v7, v8, v9
	v_cvt_pk_bf16_f32 v8, v2, v3
	v_lshl_add_u64 v[2:3], v[74:75], 0, v[0:1]
	v_mov_b32_e32 v0, v10
	v_add_f32_e32 v11, v14, v11
	v_cvt_pk_bf16_f32 v9, v4, v5
	v_permlane16_swap_b32_e32 v10, v0
	global_store_dwordx4 v[2:3], v[6:9], off
	v_add_f32_e32 v2, v10, v0
	v_mov_b32_e32 v0, v11
	s_nop 1
	v_permlane16_swap_b32_e32 v11, v0
	v_add_f32_e32 v3, v11, v0
	v_mov_b32_e32 v4, v2
	v_mov_b32_e32 v5, v3
	s_nop 0
	v_permlane32_swap_b32_e32 v2, v4
	v_permlane32_swap_b32_e32 v3, v5
	s_and_saveexec_b64 s[24:25], s[44:45]
	s_cbranch_execz .LBB0_1551
	v_pk_add_f32 v[2:3], v[2:3], v[4:5]
	v_lshlrev_b64 v[4:5], 7, v[94:95]
	v_lshl_add_u64 v[4:5], s[6:7], 0, v[4:5]
	v_lshl_add_u64 v[4:5], s[52:53], 2, v[4:5]
	global_store_dwordx2 v[4:5], v[2:3], off

; __device__ __forceinline__ float xsum16(float v) { const auto r = __builtin_amdgcn_permlane16_swap(__float_as_uint(v), __float_as_uint(v), false, false); return __uint_as_float(r[0]) + __uint_as_float(r[1]); }
; __device__ __forceinline__ float xsum32(float v) { const auto r = __builtin_amdgcn_permlane32_swap(__float_as_uint(v), __float_as_uint(v), false, false); return __uint_as_float(r[0]) + __uint_as_float(r[1]); }
; __device__ __forceinline__ void row_stats4(const float* st, int rowb, int fq, float (&mu)[4], float (&rs)[4]) {
;     ...
;     for (int m = 0; m < 4; ++m) { const f32x4* p = (const f32x4*)(st + (size_t)(rowb + m * 16) * 32 + fq * 8); a[m] = p[0]; b[m] = p[1]; }
; #pragma unroll
;     for (int m = 0; m < 4; ++m) { float s1 = (a[m][0] + a[m][2]) + (b[m][0] + b[m][2]), s2 = (a[m][1] + a[m][3]) + (b[m][1] + b[m][3]);
;         s1 = xsum32(xsum16(s1)); s2 = xsum32(xsum16(s2));
;         const float mm = s1 * (1.0f / 1024.0f); mu[m] = mm; rs[m] = rsqrtf(fmaxf(s2 * (1.0f / 1024.0f) - mm * mm, 0.f) + LN_EPS_); }
;     __device__ __forceinline__ void operator()(const f32x4 (&acc)[2][2][4][2], const pg8::Unit& u, int wr, int wc, int fr, int fq) const {
;     ...
;         for (int ai = 0; ai < 2; ++ai) { float mu4[4], rs4[4]; row_stats4(stp, row0 + ai * 128, fq, mu4, rs4);
; #pragma unroll
;             for (int m = 0; m < 4; ++m) { const int row = row0 + ai * 128 + m * 16; const float mu = mu4[m], rs = rs4[m];
;                 f32x4 yv[2][2], gq[2][2], bq_[2][2];
; #pragma unroll
;                 for (int bj = 0; bj < 2; ++bj)
; #pragma unroll
;                     for (int n = 0; n < 2; ++n) { yv[bj][n] = *(const f32x4*)(Yin + (size_t)row * D_ + col0 + bj * 128 + 4 * n); gq[bj][n] = *(const f32x4*)(g + col0 + bj * 128 + 4 * n); bq_[bj][n] = *(const f32x4*)(b + col0 + bj * 128 + 4 * n); }
;                 asm volatile("" ::: "memory");
;                 float s1 = 0.f, s2 = 0.f;
; #pragma unroll
;                 for (int bj = 0; bj < 2; ++bj) { float* yp = Y + (size_t)row * D_ + col0 + bj * 128; f32x4 v[2];
; #pragma unroll
;                     for (int n = 0; n < 2; ++n) { v[n] = (((yv[bj][n] - mu) * rs) * gq[bj][n] + bq_[bj][n]) * ALPHA_ + acc[ai][bj][m][n] * sc;
;                         *(f32x4*)(yp + 4 * n) = v[n]; s1 += (v[n][0] + v[n][1]) + (v[n][2] + v[n][3]); s2 += (v[n][0] * v[n][0] + v[n][1] * v[n][1]) + (v[n][2] * v[n][2] + v[n][3] * v[n][3]); }
.LBB0_1703:
	s_lshl_b32 s3, s3, 8
	s_add_i32 s3, s3, s0
	v_or_b32_e32 v158, s3, v184
	v_ashrrev_i32_e32 v159, 31, v158
	v_lshlrev_b64 v[130:131], 7, v[158:159]
	v_lshl_add_u64 v[136:137], v[146:147], 0, v[130:131]
	v_or_b32_e32 v182, 16, v158
	global_load_dwordx4 v[132:135], v[136:137], off nt
	global_load_dwordx4 v[166:169], v[136:137], off offset:16 nt
	v_ashrrev_i32_e32 v183, 31, v182
	v_lshlrev_b64 v[172:173], 7, v[182:183]
	v_lshl_add_u64 v[136:137], v[146:147], 0, v[172:173]
	global_load_dwordx4 v[174:177], v[136:137], off nt
	global_load_dwordx4 v[178:181], v[136:137], off offset:16 nt
	v_or_b32_e32 v170, 32, v158
	v_ashrrev_i32_e32 v171, 31, v170
	v_lshlrev_b64 v[164:165], 7, v[170:171]
	v_lshl_add_u64 v[136:137], v[146:147], 0, v[164:165]
	global_load_dwordx4 v[186:189], v[136:137], off nt
	global_load_dwordx4 v[190:193], v[136:137], off offset:16 nt
	s_load_dwordx16 s[60:75], s[34:35], 0x38
	s_lshl_b32 s1, s2, 8
	s_lshl_b32 s16, s2, 3
	s_or_b32 s2, s1, s53
	v_or_b32_e32 v162, 48, v158
	v_or_b32_e32 v152, s2, v185
	v_ashrrev_i32_e32 v163, 31, v162
	v_ashrrev_i32_e32 v153, 31, v152
	v_lshlrev_b64 v[136:137], 12, v[158:159]
	v_lshlrev_b64 v[160:161], 7, v[162:163]
	v_lshlrev_b64 v[198:199], 2, v[152:153]
	s_waitcnt lgkmcnt(0)
	v_lshl_add_u64 v[136:137], s[74:75], 0, v[136:137]
	v_lshl_add_u64 v[202:203], v[146:147], 0, v[160:161]
	v_lshl_add_u64 v[156:157], s[10:11], 0, v[198:199]
	v_lshl_add_u64 v[154:155], s[12:13], 0, v[198:199]
	v_lshl_add_u64 v[136:137], v[136:137], 0, v[198:199]
	global_load_dwordx4 v[198:201], v[202:203], off nt
	s_nop 0
	global_load_dwordx4 v[202:205], v[202:203], off offset:16 nt
	s_or_b32 s38, s16, s15
	s_mov_b32 s16, 0x3a800000
	s_mov_b32 s1, 0x800000
	global_load_dwordx4 v[206:209], v[136:137], off offset:16 nt
	global_load_dwordx4 v[210:213], v[136:137], off nt
	global_load_dwordx4 v[214:217], v[156:157], off offset:16
	global_load_dwordx4 v[218:221], v[156:157], off
	global_load_dwordx4 v[222:225], v[154:155], off offset:16
	global_load_dwordx4 v[234:237], v[154:155], off
	s_mov_b32 s18, 0x3fd744fd
	s_ashr_i32 s44, s2, 6
	v_bitop3_b32 v196, s2, 56, v185 bitop3:0xc8
	s_ashr_i32 s39, s38, 31
	s_ashr_i32 s45, s44, 31
	s_waitcnt vmcnt(0)
	v_mov_b32_e32 v228, v132
	v_mov_b32_e32 v229, v166
	v_mov_b32_e32 v238, v134
	v_mov_b32_e32 v239, v168
	v_mov_b32_e32 v166, v133
	v_mov_b32_e32 v168, v135
	v_pk_add_f32 v[132:133], v[228:229], v[238:239]
	v_pk_add_f32 v[134:135], v[166:167], v[168:169]
	v_pk_add_f32 v[132:133], v[132:133], v[132:133] op_sel:[0,1] op_sel_hi:[1,0]
	v_pk_add_f32 v[134:135], v[134:135], v[134:135] op_sel:[0,1] op_sel_hi:[1,0]
	v_mov_b32_e32 v166, v174
	v_mov_b32_e32 v167, v178
	v_mov_b32_e32 v168, v176
	v_mov_b32_e32 v169, v180
	v_mov_b32_e32 v0, v132
	v_mov_b32_e32 v133, v134
	v_pk_add_f32 v[166:167], v[166:167], v[168:169]
	v_permlane16_swap_b32_e32 v132, v0
	v_permlane16_swap_b32_e32 v134, v133
	v_mov_b32_e32 v178, v175
	v_mov_b32_e32 v180, v177
	v_pk_add_f32 v[166:167], v[166:167], v[166:167] op_sel:[0,1] op_sel_hi:[1,0]
	v_add_f32_e32 v177, v132, v0
	v_add_f32_e32 v176, v134, v133
	v_pk_add_f32 v[168:169], v[178:179], v[180:181]
	v_mov_b32_e32 v135, v166
	v_mov_b32_e32 v179, v177
	v_mov_b32_e32 v178, v176
	v_permlane16_swap_b32_e32 v166, v135
	v_permlane32_swap_b32_e32 v177, v179
	v_permlane32_swap_b32_e32 v176, v178
	v_add_f32_e32 v133, v166, v135
	v_pk_add_f32 v[166:167], v[176:177], v[178:179]
	v_pk_add_f32 v[168:169], v[168:169], v[168:169] op_sel:[0,1] op_sel_hi:[1,0]
	v_pk_mul_f32 v[228:229], v[166:167], s[16:17] op_sel_hi:[1,0]
	v_mov_b32_e32 v159, v168
	v_fma_f32 v0, -v229, v229, v228
	v_max_f32_e32 v0, 0, v0
	v_permlane16_swap_b32_e32 v168, v159
	v_add_f32_e32 v0, 0x3727c5ac, v0
	v_add_f32_e32 v132, v168, v159
	v_mul_f32_e32 v159, 0x4b800000, v0
	v_cmp_gt_f32_e32 vcc, s1, v0
	v_mov_b32_e32 v174, v186
	v_mov_b32_e32 v175, v190
	v_cndmask_b32_e32 v0, v0, v159, vcc
	v_rsq_f32_e32 v0, v0
	v_mov_b32_e32 v166, v188
	v_mov_b32_e32 v167, v192
	v_pk_add_f32 v[166:167], v[174:175], v[166:167]
	v_mul_f32_e32 v159, 0x45800000, v0
	v_pk_add_f32 v[166:167], v[166:167], v[166:167] op_sel:[0,1] op_sel_hi:[1,0]
	v_mov_b32_e32 v190, v187
	v_mov_b32_e32 v192, v189
	v_cndmask_b32_e32 v0, v0, v159, vcc
	v_pk_add_f32 v[168:169], v[190:191], v[192:193]
	v_mov_b32_e32 v159, v166
	v_pk_add_f32 v[168:169], v[168:169], v[168:169] op_sel:[0,1] op_sel_hi:[1,0]
	s_nop 0
	v_permlane16_swap_b32_e32 v166, v159
	v_add_f32_e32 v175, v166, v159
	v_mov_b32_e32 v159, v168
	s_nop 1
	v_permlane16_swap_b32_e32 v168, v159
	global_load_dwordx4 v[178:181], v[136:137], off offset:528 nt
	global_load_dwordx4 v[186:189], v[136:137], off offset:512 nt
	v_add_f32_e32 v174, v168, v159
	v_mov_b32_e32 v166, v198
	v_mov_b32_e32 v167, v202
	v_mov_b32_e32 v168, v200
	v_mov_b32_e32 v169, v204
	v_mov_b32_e32 v202, v199
	v_mov_b32_e32 v204, v201
	v_pk_add_f32 v[166:167], v[166:167], v[168:169]
	v_pk_add_f32 v[168:169], v[202:203], v[204:205]
	global_load_dwordx4 v[190:193], v[156:157], off offset:528
	global_load_dwordx4 v[198:201], v[156:157], off offset:512
	global_load_dwordx4 v[202:205], v[154:155], off offset:528
	global_load_dwordx4 v[238:241], v[154:155], off offset:512
	v_sub_f32_e32 v213, v213, v229
	v_sub_f32_e32 v212, v212, v229
	v_sub_f32_e32 v211, v211, v229
	v_sub_f32_e32 v210, v210, v229
	v_pk_mul_f32 v[210:211], v[0:1], v[210:211] op_sel_hi:[0,1]
	v_pk_mul_f32 v[212:213], v[0:1], v[212:213] op_sel_hi:[0,1]
	v_sub_f32_e32 v209, v209, v229
	v_sub_f32_e32 v208, v208, v229
	v_sub_f32_e32 v207, v207, v229
	v_sub_f32_e32 v206, v206, v229
	v_pk_fma_f32 v[212:213], v[220:221], v[212:213], v[236:237]
; __device__ __forceinline__ float xsum16(float v) { const auto r = __builtin_amdgcn_permlane16_swap(__float_as_uint(v), __float_as_uint(v), false, false); return __uint_as_float(r[0]) + __uint_as_float(r[1]); }
; __device__ __forceinline__ float xsum32(float v) { const auto r = __builtin_amdgcn_permlane32_swap(__float_as_uint(v), __float_as_uint(v), false, false); return __uint_as_float(r[0]) + __uint_as_float(r[1]); }
; __device__ __forceinline__ size_t blk_off(int r, int c, int K) { return (size_t)(r >> 8) * 256 * K + (size_t)(c >> 6) * (256 * 64) + (size_t)((r & 255) * 64 + (c & 63)); }
; __device__ __forceinline__ u32x4 pack8(const f32x4 a, const f32x4 b) { u32x4 w; w.x = cvt_pk_bf16(a[0], a[1]); w.y = cvt_pk_bf16(a[2], a[3]); w.z = cvt_pk_bf16(b[0], b[1]); w.w = cvt_pk_bf16(b[2], b[3]); return w; }
;     __device__ __forceinline__ void operator()(const f32x4 (&acc)[2][2][4][2], const pg8::Unit& u, int wr, int wc, int fr, int fq) const {
;     ...
;                 for (int bj = 0; bj < 2; ++bj) { float* yp = Y + (size_t)row * D_ + col0 + bj * 128; f32x4 v[2];
; #pragma unroll
;                     for (int n = 0; n < 2; ++n) { v[n] = (((yv[bj][n] - mu) * rs) * gq[bj][n] + bq_[bj][n]) * ALPHA_ + acc[ai][bj][m][n] * sc;
;                         *(f32x4*)(yp + 4 * n) = v[n]; s1 += (v[n][0] + v[n][1]) + (v[n][2] + v[n][3]); s2 += (v[n][0] * v[n][0] + v[n][1] * v[n][1]) + (v[n][2] * v[n][2] + v[n][3] * v[n][3]); }
;                     *(u32x4*)(Yb + blk_off(row, col0 + bj * 128, D_)) = pack8(v[0], v[1]); }
;                 s1 = xsum32(xsum16(s1)); s2 = xsum32(xsum16(s2));
	v_pk_fma_f32 v[210:211], v[218:219], v[210:211], v[234:235]
	v_pk_mul_f32 v[206:207], v[0:1], v[206:207] op_sel_hi:[0,1]
	v_pk_mul_f32 v[208:209], v[0:1], v[208:209] op_sel_hi:[0,1]
	v_pk_mul_f32 v[210:211], v[210:211], s[18:19] op_sel_hi:[1,0]
	v_pk_mul_f32 v[212:213], v[212:213], s[18:19] op_sel_hi:[1,0]
	v_pk_fma_f32 v[208:209], v[216:217], v[208:209], v[224:225]
	v_pk_fma_f32 v[206:207], v[214:215], v[206:207], v[222:223]
	v_pk_fma_f32 v[128:129], v[128:129], 0.5, v[212:213] op_sel_hi:[1,0,1]
	v_pk_fma_f32 v[126:127], v[126:127], 0.5, v[210:211] op_sel_hi:[1,0,1]
	v_pk_mul_f32 v[206:207], v[206:207], s[18:19] op_sel_hi:[1,0]
	v_pk_mul_f32 v[208:209], v[208:209], s[18:19] op_sel_hi:[1,0]
	v_add_f32_e32 v197, v126, v127
	v_add_f32_e32 v210, v128, v129
	v_pk_fma_f32 v[124:125], v[124:125], 0.5, v[208:209] op_sel_hi:[1,0,1]
	v_pk_fma_f32 v[122:123], v[122:123], 0.5, v[206:207] op_sel_hi:[1,0,1]
	v_pk_add_f32 v[166:167], v[166:167], v[166:167] op_sel:[0,1] op_sel_hi:[1,0]
	v_add_f32_e32 v197, v197, v210
	v_add_f32_e32 v206, v122, v123
	v_add_f32_e32 v207, v124, v125
	v_mov_b32_e32 v159, v166
	v_add_f32_e32 v197, 0, v197
	v_add_f32_e32 v206, v206, v207
	v_pk_add_f32 v[168:169], v[168:169], v[168:169] op_sel:[0,1] op_sel_hi:[1,0]
	v_permlane16_swap_b32_e32 v166, v159
	v_mul_f32_e32 v210, v127, v127
	v_mul_f32_e32 v211, v129, v129
	v_add_f32_e32 v197, v197, v206
	v_mul_f32_e32 v206, v123, v123
	v_mul_f32_e32 v207, v125, v125
	v_add_f32_e32 v167, v166, v159
	v_mov_b32_e32 v159, v168
	s_ashr_i32 s16, s3, 8
	s_nop 0
	v_fmac_f32_e32 v210, v126, v126
	v_fmac_f32_e32 v211, v128, v128
	s_nop 1
	v_bfe_u32 v135, v227, 4, 2
	v_sub_u32_e32 v134, 0, v135
	v_lshlrev_b32_e32 v134, 4, v134
	v_ashrrev_i32_e32 v135, 31, v134
	v_lshl_add_u64 v[134:135], v[136:137], 0, v[134:135]
	v_permlane16_swap_b32_e32 v126, v122
	v_permlane16_swap_b32_e32 v127, v123
	v_permlane16_swap_b32_e32 v128, v124
	v_permlane16_swap_b32_e32 v129, v125
	v_permlane32_swap_b32_e32 v126, v122
	v_permlane32_swap_b32_e32 v127, v123
	v_permlane32_swap_b32_e32 v128, v124
	v_permlane32_swap_b32_e32 v129, v125
	global_store_dwordx4 v[134:135], v[126:129], off
	global_store_dwordx4 v[134:135], v[122:125], off offset:64
	s_nop 1
	v_permlane32_swap_b32_e32 v126, v122
	v_permlane32_swap_b32_e32 v127, v123
	v_permlane32_swap_b32_e32 v128, v124
	v_permlane32_swap_b32_e32 v129, v125
	v_permlane16_swap_b32_e32 v126, v122
	v_permlane16_swap_b32_e32 v127, v123
	v_permlane16_swap_b32_e32 v128, v124
	v_permlane16_swap_b32_e32 v129, v125
	v_fmac_f32_e32 v206, v122, v122
	v_fmac_f32_e32 v207, v124, v124
	v_cvt_pk_bf16_f32 v126, v126, v127
	v_cvt_pk_bf16_f32 v127, v128, v129
	v_cvt_pk_bf16_f32 v128, v122, v123
	v_cvt_pk_bf16_f32 v129, v124, v125
	v_permlane16_swap_b32_e32 v168, v159
	s_ashr_i32 s17, s16, 31
	v_add_f32_e32 v166, v168, v159
	s_lshl_b64 s[16:17], s[16:17], 19
	v_lshlrev_b32_e32 v159, 6, v158
	s_movk_i32 s1, 0x33c0
	v_readlane_b32 s2, v253, 59
	v_and_or_b32 v159, v159, s1, v196
	v_readlane_b32 s3, v253, 60
	s_add_u32 s1, s2, s16
	s_addc_u32 s16, s3, s17
	s_lshl_b64 s[24:25], s[44:45], 15
	s_add_u32 s48, s1, s24
	s_waitcnt vmcnt(6)
	v_sub_f32_e32 v123, v189, v229
	v_sub_f32_e32 v122, v188, v229
	v_sub_f32_e32 v125, v187, v229
	v_sub_f32_e32 v124, v186, v229
	v_pk_mul_f32 v[124:125], v[0:1], v[124:125] op_sel_hi:[0,1]
	v_pk_mul_f32 v[122:123], v[0:1], v[122:123] op_sel_hi:[0,1]
	s_addc_u32 s49, s16, s25
	v_lshlrev_b32_e32 v159, 1, v159
	global_store_dwordx4 v159, v[126:129], s[48:49]
	v_add_f32_e32 v210, v210, v211
	s_waitcnt vmcnt(3)
	v_pk_fma_f32 v[122:123], v[200:201], v[122:123], v[240:241]
	v_pk_fma_f32 v[124:125], v[198:199], v[124:125], v[238:239]
	v_pk_mul_f32 v[122:123], v[122:123], s[18:19] op_sel_hi:[1,0]
	v_pk_mul_f32 v[124:125], v[124:125], s[18:19] op_sel_hi:[1,0]
	v_pk_fma_f32 v[120:121], v[120:121], 0.5, v[122:123] op_sel_hi:[1,0,1]
	v_pk_fma_f32 v[118:119], v[118:119], 0.5, v[124:125] op_sel_hi:[1,0,1]
	v_add_f32_e32 v123, v120, v121
	v_add_f32_e32 v122, v118, v119
	v_add_f32_e32 v122, v122, v123
	v_add_f32_e32 v126, v197, v122
	v_mul_f32_e32 v122, v119, v119
	v_mul_f32_e32 v123, v121, v121
	v_add_f32_e32 v206, v206, v207
	v_fmac_f32_e32 v122, v118, v118
	v_fmac_f32_e32 v123, v120, v120
	v_add_f32_e32 v206, v210, v206
	v_add_f32_e32 v122, v122, v123
	v_add_f32_e32 v127, v206, v122
	v_sub_f32_e32 v123, v181, v229
	v_sub_f32_e32 v122, v180, v229
	v_sub_f32_e32 v125, v179, v229
	v_sub_f32_e32 v124, v178, v229
	v_pk_mul_f32 v[124:125], v[0:1], v[124:125] op_sel_hi:[0,1]
	v_pk_mul_f32 v[122:123], v[0:1], v[122:123] op_sel_hi:[0,1]
	v_pk_fma_f32 v[122:123], v[192:193], v[122:123], v[204:205]
	v_pk_fma_f32 v[124:125], v[190:191], v[124:125], v[202:203]
	v_pk_mul_f32 v[122:123], v[122:123], s[18:19] op_sel_hi:[1,0]
	v_pk_mul_f32 v[124:125], v[124:125], s[18:19] op_sel_hi:[1,0]
	v_pk_fma_f32 v[116:117], v[116:117], 0.5, v[122:123] op_sel_hi:[1,0,1]
	v_pk_fma_f32 v[114:115], v[114:115], 0.5, v[124:125] op_sel_hi:[1,0,1]
	v_add_f32_e32 v122, v116, v117
	v_add_f32_e32 v0, v114, v115
	v_add_f32_e32 v0, v0, v122
	v_mul_f32_e32 v122, v115, v115
	v_mul_f32_e32 v123, v117, v117
	v_add_f32_e32 v0, v126, v0
	v_fmac_f32_e32 v122, v114, v114
	v_fmac_f32_e32 v123, v116, v116
	s_nop 0
	s_nop 1
	v_bfe_u32 v125, v227, 4, 2
	v_sub_u32_e32 v124, 0, v125
	v_lshlrev_b32_e32 v124, 4, v124
	v_ashrrev_i32_e32 v125, 31, v124
	v_lshl_add_u64 v[124:125], v[136:137], 0, v[124:125]
	v_permlane16_swap_b32_e32 v118, v114
	v_permlane16_swap_b32_e32 v119, v115
	v_permlane16_swap_b32_e32 v120, v116
	v_permlane16_swap_b32_e32 v121, v117
	v_permlane32_swap_b32_e32 v118, v114
	v_permlane32_swap_b32_e32 v119, v115
; __device__ __forceinline__ float xsum16(float v) { const auto r = __builtin_amdgcn_permlane16_swap(__float_as_uint(v), __float_as_uint(v), false, false); return __uint_as_float(r[0]) + __uint_as_float(r[1]); }
; __device__ __forceinline__ float xsum32(float v) { const auto r = __builtin_amdgcn_permlane32_swap(__float_as_uint(v), __float_as_uint(v), false, false); return __uint_as_float(r[0]) + __uint_as_float(r[1]); }
; __device__ __forceinline__ size_t blk_off(int r, int c, int K) { return (size_t)(r >> 8) * 256 * K + (size_t)(c >> 6) * (256 * 64) + (size_t)((r & 255) * 64 + (c & 63)); }
; __device__ __forceinline__ u32x4 pack8(const f32x4 a, const f32x4 b) { u32x4 w; w.x = cvt_pk_bf16(a[0], a[1]); w.y = cvt_pk_bf16(a[2], a[3]); w.z = cvt_pk_bf16(b[0], b[1]); w.w = cvt_pk_bf16(b[2], b[3]); return w; }
;     __device__ __forceinline__ void operator()(const f32x4 (&acc)[2][2][4][2], const pg8::Unit& u, int wr, int wc, int fr, int fq) const {
;     ...
;             for (int m = 0; m < 4; ++m) { const int row = row0 + ai * 128 + m * 16; const float mu = mu4[m], rs = rs4[m];
;                 f32x4 yv[2][2], gq[2][2], bq_[2][2];
; #pragma unroll
;                 for (int bj = 0; bj < 2; ++bj)
; #pragma unroll
;                     for (int n = 0; n < 2; ++n) { yv[bj][n] = *(const f32x4*)(Yin + (size_t)row * D_ + col0 + bj * 128 + 4 * n); gq[bj][n] = *(const f32x4*)(g + col0 + bj * 128 + 4 * n); bq_[bj][n] = *(const f32x4*)(b + col0 + bj * 128 + 4 * n); }
;                 asm volatile("" ::: "memory");
;                 float s1 = 0.f, s2 = 0.f;
; #pragma unroll
;                 for (int bj = 0; bj < 2; ++bj) { float* yp = Y + (size_t)row * D_ + col0 + bj * 128; f32x4 v[2];
; #pragma unroll
;                     for (int n = 0; n < 2; ++n) { v[n] = (((yv[bj][n] - mu) * rs) * gq[bj][n] + bq_[bj][n]) * ALPHA_ + acc[ai][bj][m][n] * sc;
;                         *(f32x4*)(yp + 4 * n) = v[n]; s1 += (v[n][0] + v[n][1]) + (v[n][2] + v[n][3]); s2 += (v[n][0] * v[n][0] + v[n][1] * v[n][1]) + (v[n][2] * v[n][2] + v[n][3] * v[n][3]); }
;                     *(u32x4*)(Yb + blk_off(row, col0 + bj * 128, D_)) = pack8(v[0], v[1]); }
;                 s1 = xsum32(xsum16(s1)); s2 = xsum32(xsum16(s2));
;                 if (fq == 0) *(f32x2*)(stn + (size_t)row * 32 + (u.pn * 4 + wc) * 2) = (f32x2){s1, s2}; asm volatile("" ::: "memory"); } }
	v_permlane32_swap_b32_e32 v120, v116
	v_permlane32_swap_b32_e32 v121, v117
	global_store_dwordx4 v[124:125], v[118:121], off offset:512
	global_store_dwordx4 v[124:125], v[114:117], off offset:576
	s_nop 1
	v_permlane32_swap_b32_e32 v118, v114
	v_permlane32_swap_b32_e32 v119, v115
	v_permlane32_swap_b32_e32 v120, v116
	v_permlane32_swap_b32_e32 v121, v117
	v_permlane16_swap_b32_e32 v118, v114
	v_permlane16_swap_b32_e32 v119, v115
	v_permlane16_swap_b32_e32 v120, v116
	v_permlane16_swap_b32_e32 v121, v117
	v_add_f32_e32 v122, v122, v123
	v_cvt_pk_bf16_f32 v118, v118, v119
	v_cvt_pk_bf16_f32 v119, v120, v121
	v_cvt_pk_bf16_f32 v120, v114, v115
	v_mov_b32_e32 v114, v0
	v_add_f32_e32 v122, v127, v122
	s_nop 0
	v_permlane16_swap_b32_e32 v0, v114
	s_or_b32 s2, s44, 2
	v_add_f32_e32 v114, v0, v114
	v_mov_b32_e32 v0, v122
	s_ashr_i32 s3, s2, 31
	s_nop 0
	v_permlane16_swap_b32_e32 v122, v0
	s_lshl_b64 s[44:45], s[2:3], 15
	v_add_f32_e32 v115, v122, v0
	v_mov_b32_e32 v135, v133
	v_mov_b32_e32 v134, v132
	v_mov_b32_e32 v177, v175
	v_mov_b32_e32 v176, v174
	v_mov_b32_e32 v169, v167
	v_mov_b32_e32 v168, v166
	v_cvt_pk_bf16_f32 v121, v116, v117
	s_add_u32 s46, s1, s44
	v_mov_b32_e32 v116, v114
	v_mov_b32_e32 v117, v115
	v_permlane32_swap_b32_e32 v133, v135
	v_permlane32_swap_b32_e32 v132, v134
	v_permlane32_swap_b32_e32 v175, v177
	v_permlane32_swap_b32_e32 v174, v176
	v_permlane32_swap_b32_e32 v167, v169
	v_permlane32_swap_b32_e32 v166, v168
	s_addc_u32 s47, s16, s45
	v_permlane32_swap_b32_e32 v114, v116
	v_permlane32_swap_b32_e32 v115, v117
	global_store_dwordx4 v159, v[118:121], s[46:47]
	s_and_saveexec_b64 s[26:27], s[40:41]
	s_cbranch_execz .LBB0_1705
	v_pk_add_f32 v[114:115], v[114:115], v[116:117]
	v_lshl_add_u64 v[116:117], s[8:9], 0, v[130:131]
	v_lshl_add_u64 v[116:117], s[38:39], 2, v[116:117]
	global_store_dwordx2 v[116:117], v[114:115], off
.LBB0_1705:
	s_or_b64 exec, exec, s[26:27]
	v_pk_add_f32 v[114:115], v[132:133], v[134:135]
	s_mov_b32 s2, 0x3a800000
	v_pk_mul_f32 v[178:179], v[114:115], s[2:3] op_sel_hi:[1,0]
	s_mov_b32 s1, 0x800000
	v_fma_f32 v0, -v179, v179, v178
	v_max_f32_e32 v0, 0, v0
	v_add_f32_e32 v0, 0x3727c5ac, v0
	v_cmp_gt_f32_e32 vcc, s1, v0
	v_mul_f32_e32 v114, 0x4b800000, v0
	s_load_dwordx16 s[60:75], s[34:35], 0x38
	v_cndmask_b32_e32 v0, v0, v114, vcc
	v_rsq_f32_e32 v0, v0
	v_lshlrev_b32_e32 v159, 6, v182
	s_mov_b32 s2, 0x3fd744fd
	v_mul_f32_e32 v114, 0x45800000, v0
	v_cndmask_b32_e32 v0, v0, v114, vcc
	v_lshlrev_b64 v[114:115], 12, v[182:183]
	s_waitcnt lgkmcnt(0)
	v_lshl_add_u64 v[114:115], s[74:75], 0, v[114:115]
	v_lshl_add_u64 v[180:181], v[152:153], 2, v[114:115]
	global_load_dwordx4 v[186:189], v[180:181], off offset:16 nt
	global_load_dwordx4 v[190:193], v[180:181], off nt
	global_load_dwordx4 v[198:201], v[156:157], off offset:16
	global_load_dwordx4 v[202:205], v[156:157], off
	global_load_dwordx4 v[206:209], v[154:155], off offset:16
	global_load_dwordx4 v[210:213], v[154:155], off
	global_load_dwordx4 v[114:117], v[180:181], off offset:528 nt
	global_load_dwordx4 v[134:137], v[180:181], off offset:512 nt
	global_load_dwordx4 v[118:121], v[156:157], off offset:528
	global_load_dwordx4 v[126:129], v[156:157], off offset:512
	global_load_dwordx4 v[122:125], v[154:155], off offset:528
	global_load_dwordx4 v[130:133], v[154:155], off offset:512
	s_movk_i32 s1, 0x37c0
	v_and_or_b32 v159, v159, s1, v196
	v_lshlrev_b32_e32 v159, 1, v159
	s_waitcnt vmcnt(11)
	v_sub_f32_e32 v187, v187, v179
	s_waitcnt vmcnt(10)
	v_sub_f32_e32 v183, v193, v179
	v_sub_f32_e32 v182, v192, v179
	v_sub_f32_e32 v191, v191, v179
	v_sub_f32_e32 v190, v190, v179
	v_pk_mul_f32 v[190:191], v[0:1], v[190:191] op_sel_hi:[0,1]
	v_pk_mul_f32 v[182:183], v[0:1], v[182:183] op_sel_hi:[0,1]
	s_waitcnt vmcnt(6)
	v_pk_fma_f32 v[182:183], v[204:205], v[182:183], v[212:213]
	v_pk_fma_f32 v[190:191], v[202:203], v[190:191], v[210:211]
	v_pk_mul_f32 v[182:183], v[182:183], s[2:3] op_sel_hi:[1,0]
	v_pk_mul_f32 v[190:191], v[190:191], s[2:3] op_sel_hi:[1,0]
	v_pk_fma_f32 v[112:113], v[112:113], 0.5, v[182:183] op_sel_hi:[1,0,1]
	v_pk_fma_f32 v[110:111], v[110:111], 0.5, v[190:191] op_sel_hi:[1,0,1]
	v_add_f32_e32 v182, v112, v113
	v_add_f32_e32 v178, v110, v111
	v_add_f32_e32 v178, v178, v182
	v_mul_f32_e32 v182, v111, v111
	v_mul_f32_e32 v183, v113, v113
	v_fmac_f32_e32 v182, v110, v110
	v_fmac_f32_e32 v183, v112, v112
	v_add_f32_e32 v190, v182, v183
	v_sub_f32_e32 v183, v189, v179
	v_sub_f32_e32 v182, v188, v179
	v_sub_f32_e32 v186, v186, v179
	v_pk_mul_f32 v[186:187], v[0:1], v[186:187] op_sel_hi:[0,1]
	v_pk_mul_f32 v[182:183], v[0:1], v[182:183] op_sel_hi:[0,1]
	v_pk_fma_f32 v[182:183], v[200:201], v[182:183], v[208:209]
	v_pk_fma_f32 v[186:187], v[198:199], v[186:187], v[206:207]
	v_pk_mul_f32 v[182:183], v[182:183], s[2:3] op_sel_hi:[1,0]
	v_pk_mul_f32 v[186:187], v[186:187], s[2:3] op_sel_hi:[1,0]
	v_pk_fma_f32 v[108:109], v[108:109], 0.5, v[182:183] op_sel_hi:[1,0,1]
	v_pk_fma_f32 v[106:107], v[106:107], 0.5, v[186:187] op_sel_hi:[1,0,1]
	v_add_f32_e32 v183, v108, v109
	v_add_f32_e32 v182, v106, v107
	v_add_f32_e32 v178, 0, v178
	v_add_f32_e32 v182, v182, v183
	v_add_f32_e32 v178, v178, v182
	v_mul_f32_e32 v182, v107, v107
	v_mul_f32_e32 v183, v109, v109
	s_nop 0
	s_nop 1
	v_bfe_u32 v187, v227, 4, 2
	v_sub_u32_e32 v186, 0, v187
	v_lshlrev_b32_e32 v186, 4, v186
	v_ashrrev_i32_e32 v187, 31, v186
	v_lshl_add_u64 v[186:187], v[180:181], 0, v[186:187]
	v_permlane16_swap_b32_e32 v110, v106
	v_permlane16_swap_b32_e32 v111, v107
	v_permlane16_swap_b32_e32 v112, v108
	v_permlane16_swap_b32_e32 v113, v109
	v_permlane32_swap_b32_e32 v110, v106
	v_permlane32_swap_b32_e32 v111, v107
	v_permlane32_swap_b32_e32 v112, v108
	v_permlane32_swap_b32_e32 v113, v109
	global_store_dwordx4 v[186:187], v[110:113], off
	global_store_dwordx4 v[186:187], v[106:109], off offset:64
	s_nop 1
	v_permlane32_swap_b32_e32 v110, v106
	v_permlane32_swap_b32_e32 v111, v107
	v_permlane32_swap_b32_e32 v112, v108
	v_permlane32_swap_b32_e32 v113, v109
	v_permlane16_swap_b32_e32 v110, v106
	v_permlane16_swap_b32_e32 v111, v107
	v_permlane16_swap_b32_e32 v112, v108
	v_permlane16_swap_b32_e32 v113, v109
	v_fmac_f32_e32 v182, v106, v106
	v_fmac_f32_e32 v183, v108, v108
	v_cvt_pk_bf16_f32 v110, v110, v111
	v_cvt_pk_bf16_f32 v111, v112, v113
	v_cvt_pk_bf16_f32 v112, v106, v107
	v_cvt_pk_bf16_f32 v113, v108, v109
	s_waitcnt vmcnt(6)
; __device__ __forceinline__ float xsum16(float v) { const auto r = __builtin_amdgcn_permlane16_swap(__float_as_uint(v), __float_as_uint(v), false, false); return __uint_as_float(r[0]) + __uint_as_float(r[1]); }
; __device__ __forceinline__ float xsum32(float v) { const auto r = __builtin_amdgcn_permlane32_swap(__float_as_uint(v), __float_as_uint(v), false, false); return __uint_as_float(r[0]) + __uint_as_float(r[1]); }
; __device__ __forceinline__ size_t blk_off(int r, int c, int K) { return (size_t)(r >> 8) * 256 * K + (size_t)(c >> 6) * (256 * 64) + (size_t)((r & 255) * 64 + (c & 63)); }
; __device__ __forceinline__ u32x4 pack8(const f32x4 a, const f32x4 b) { u32x4 w; w.x = cvt_pk_bf16(a[0], a[1]); w.y = cvt_pk_bf16(a[2], a[3]); w.z = cvt_pk_bf16(b[0], b[1]); w.w = cvt_pk_bf16(b[2], b[3]); return w; }
;     __device__ __forceinline__ void operator()(const f32x4 (&acc)[2][2][4][2], const pg8::Unit& u, int wr, int wc, int fr, int fq) const {
;     ...
;             for (int m = 0; m < 4; ++m) { const int row = row0 + ai * 128 + m * 16; const float mu = mu4[m], rs = rs4[m];
;                 f32x4 yv[2][2], gq[2][2], bq_[2][2];
; #pragma unroll
;                 for (int bj = 0; bj < 2; ++bj)
; #pragma unroll
;                     for (int n = 0; n < 2; ++n) { yv[bj][n] = *(const f32x4*)(Yin + (size_t)row * D_ + col0 + bj * 128 + 4 * n); gq[bj][n] = *(const f32x4*)(g + col0 + bj * 128 + 4 * n); bq_[bj][n] = *(const f32x4*)(b + col0 + bj * 128 + 4 * n); }
;                 asm volatile("" ::: "memory");
;                 float s1 = 0.f, s2 = 0.f;
; #pragma unroll
;                 for (int bj = 0; bj < 2; ++bj) { float* yp = Y + (size_t)row * D_ + col0 + bj * 128; f32x4 v[2];
; #pragma unroll
;                     for (int n = 0; n < 2; ++n) { v[n] = (((yv[bj][n] - mu) * rs) * gq[bj][n] + bq_[bj][n]) * ALPHA_ + acc[ai][bj][m][n] * sc;
;                         *(f32x4*)(yp + 4 * n) = v[n]; s1 += (v[n][0] + v[n][1]) + (v[n][2] + v[n][3]); s2 += (v[n][0] * v[n][0] + v[n][1] * v[n][1]) + (v[n][2] * v[n][2] + v[n][3] * v[n][3]); }
;                     *(u32x4*)(Yb + blk_off(row, col0 + bj * 128, D_)) = pack8(v[0], v[1]); }
;                 s1 = xsum32(xsum16(s1)); s2 = xsum32(xsum16(s2));
;                 if (fq == 0) *(f32x2*)(stn + (size_t)row * 32 + (u.pn * 4 + wc) * 2) = (f32x2){s1, s2}; asm volatile("" ::: "memory"); } }
	v_sub_f32_e32 v107, v137, v179
	v_sub_f32_e32 v106, v136, v179
	v_sub_f32_e32 v109, v135, v179
	v_sub_f32_e32 v108, v134, v179
	v_pk_mul_f32 v[108:109], v[0:1], v[108:109] op_sel_hi:[0,1]
	v_pk_mul_f32 v[106:107], v[0:1], v[106:107] op_sel_hi:[0,1]
	s_waitcnt vmcnt(2)
	v_pk_fma_f32 v[106:107], v[128:129], v[106:107], v[132:133]
	v_pk_fma_f32 v[108:109], v[126:127], v[108:109], v[130:131]
	v_pk_mul_f32 v[106:107], v[106:107], s[2:3] op_sel_hi:[1,0]
	v_pk_mul_f32 v[108:109], v[108:109], s[2:3] op_sel_hi:[1,0]
	v_pk_fma_f32 v[104:105], v[104:105], 0.5, v[106:107] op_sel_hi:[1,0,1]
	v_pk_fma_f32 v[102:103], v[102:103], 0.5, v[108:109] op_sel_hi:[1,0,1]
	v_add_f32_e32 v107, v104, v105
	v_add_f32_e32 v106, v102, v103
	v_add_f32_e32 v106, v106, v107
	global_store_dwordx4 v159, v[110:113], s[48:49]
	v_mul_f32_e32 v107, v105, v105
	v_add_f32_e32 v182, v182, v183
	v_add_f32_e32 v110, v178, v106
	v_mul_f32_e32 v106, v103, v103
	v_fmac_f32_e32 v106, v102, v102
	v_fmac_f32_e32 v107, v104, v104
	v_add_f32_e32 v182, v190, v182
	v_add_f32_e32 v106, v106, v107
	v_add_f32_e32 v111, v182, v106
	v_sub_f32_e32 v107, v117, v179
	v_sub_f32_e32 v106, v116, v179
	v_sub_f32_e32 v109, v115, v179
	v_sub_f32_e32 v108, v114, v179
	v_pk_mul_f32 v[108:109], v[0:1], v[108:109] op_sel_hi:[0,1]
	v_pk_mul_f32 v[106:107], v[0:1], v[106:107] op_sel_hi:[0,1]
	v_pk_fma_f32 v[106:107], v[120:121], v[106:107], v[124:125]
	v_pk_fma_f32 v[108:109], v[118:119], v[108:109], v[122:123]
	v_pk_mul_f32 v[106:107], v[106:107], s[2:3] op_sel_hi:[1,0]
	v_pk_mul_f32 v[108:109], v[108:109], s[2:3] op_sel_hi:[1,0]
	v_pk_fma_f32 v[100:101], v[100:101], 0.5, v[106:107] op_sel_hi:[1,0,1]
	v_pk_fma_f32 v[98:99], v[98:99], 0.5, v[108:109] op_sel_hi:[1,0,1]
	v_add_f32_e32 v106, v100, v101
	v_add_f32_e32 v0, v98, v99
	v_add_f32_e32 v0, v0, v106
	v_mul_f32_e32 v106, v99, v99
	v_mul_f32_e32 v107, v101, v101
	v_add_f32_e32 v0, v110, v0
	v_fmac_f32_e32 v106, v98, v98
	v_fmac_f32_e32 v107, v100, v100
	s_nop 0
	s_nop 1
	v_bfe_u32 v109, v227, 4, 2
	v_sub_u32_e32 v108, 0, v109
	v_lshlrev_b32_e32 v108, 4, v108
	v_ashrrev_i32_e32 v109, 31, v108
	v_lshl_add_u64 v[108:109], v[180:181], 0, v[108:109]
	v_permlane16_swap_b32_e32 v102, v98
	v_permlane16_swap_b32_e32 v103, v99
	v_permlane16_swap_b32_e32 v104, v100
	v_permlane16_swap_b32_e32 v105, v101
	v_permlane32_swap_b32_e32 v102, v98
	v_permlane32_swap_b32_e32 v103, v99
	v_permlane32_swap_b32_e32 v104, v100
	v_permlane32_swap_b32_e32 v105, v101
	global_store_dwordx4 v[108:109], v[102:105], off offset:512
	global_store_dwordx4 v[108:109], v[98:101], off offset:576
	s_nop 1
	v_permlane32_swap_b32_e32 v102, v98
	v_permlane32_swap_b32_e32 v103, v99
	v_permlane32_swap_b32_e32 v104, v100
	v_permlane32_swap_b32_e32 v105, v101
	v_permlane16_swap_b32_e32 v102, v98
	v_permlane16_swap_b32_e32 v103, v99
	v_permlane16_swap_b32_e32 v104, v100
	v_permlane16_swap_b32_e32 v105, v101
	v_add_f32_e32 v106, v106, v107
	v_cvt_pk_bf16_f32 v102, v102, v103
	v_cvt_pk_bf16_f32 v103, v104, v105
	v_cvt_pk_bf16_f32 v104, v98, v99
	v_mov_b32_e32 v98, v0
	v_add_f32_e32 v106, v111, v106
	s_nop 0
	v_permlane16_swap_b32_e32 v0, v98
	v_add_f32_e32 v98, v0, v98
	v_mov_b32_e32 v0, v106
	s_nop 1
	v_permlane16_swap_b32_e32 v106, v0
	v_add_f32_e32 v99, v106, v0
	v_cvt_pk_bf16_f32 v105, v100, v101
	v_mov_b32_e32 v100, v98
	v_mov_b32_e32 v101, v99
	s_nop 0
	v_permlane32_swap_b32_e32 v98, v100
	v_permlane32_swap_b32_e32 v99, v101
	global_store_dwordx4 v159, v[102:105], s[46:47]
	s_and_saveexec_b64 s[26:27], s[40:41]
	s_cbranch_execz .LBB0_1707
	v_pk_add_f32 v[98:99], v[98:99], v[100:101]
	v_lshl_add_u64 v[100:101], s[8:9], 0, v[172:173]
	v_lshl_add_u64 v[100:101], s[38:39], 2, v[100:101]
	global_store_dwordx2 v[100:101], v[98:99], off
.LBB0_1707:
	s_or_b64 exec, exec, s[26:27]
	v_pk_add_f32 v[98:99], v[174:175], v[176:177]
	s_mov_b32 s2, 0x3a800000
	v_pk_mul_f32 v[122:123], v[98:99], s[2:3] op_sel_hi:[1,0]
	s_mov_b32 s1, 0x800000
	v_fma_f32 v0, -v123, v123, v122
	v_max_f32_e32 v0, 0, v0
	v_add_f32_e32 v0, 0x3727c5ac, v0
	v_cmp_gt_f32_e32 vcc, s1, v0
	v_mul_f32_e32 v98, 0x4b800000, v0
	s_load_dwordx16 s[60:75], s[34:35], 0x38
	v_cndmask_b32_e32 v0, v0, v98, vcc
	v_rsq_f32_e32 v0, v0
	s_mov_b32 s2, 0x3fd744fd
	v_lshlrev_b32_e32 v122, 6, v170
	v_mul_f32_e32 v98, 0x45800000, v0
	v_cndmask_b32_e32 v0, v0, v98, vcc
	v_lshlrev_b64 v[98:99], 12, v[170:171]
	s_waitcnt lgkmcnt(0)
	v_lshl_add_u64 v[98:99], s[74:75], 0, v[98:99]
	v_lshl_add_u64 v[124:125], v[152:153], 2, v[98:99]
	global_load_dwordx4 v[126:129], v[124:125], off offset:16 nt
	global_load_dwordx4 v[130:133], v[124:125], off nt
	global_load_dwordx4 v[134:137], v[156:157], off offset:16
	global_load_dwordx4 v[172:175], v[156:157], off
	global_load_dwordx4 v[176:179], v[154:155], off offset:16
	global_load_dwordx4 v[180:183], v[154:155], off
	global_load_dwordx4 v[98:101], v[124:125], off offset:528 nt
	global_load_dwordx4 v[118:121], v[124:125], off offset:512 nt
	global_load_dwordx4 v[102:105], v[156:157], off offset:528
	global_load_dwordx4 v[110:113], v[156:157], off offset:512
	global_load_dwordx4 v[106:109], v[154:155], off offset:528
	global_load_dwordx4 v[114:117], v[154:155], off offset:512
	s_movk_i32 s1, 0x3bc0
	v_and_or_b32 v122, v122, s1, v196
	v_lshlrev_b32_e32 v122, 1, v122
	s_waitcnt vmcnt(11)
	v_sub_f32_e32 v129, v129, v123
	s_waitcnt vmcnt(10)
	v_sub_f32_e32 v133, v133, v123
	v_sub_f32_e32 v132, v132, v123
	v_sub_f32_e32 v131, v131, v123
	v_sub_f32_e32 v130, v130, v123
	v_sub_f32_e32 v128, v128, v123
	v_sub_f32_e32 v127, v127, v123
	v_sub_f32_e32 v126, v126, v123
	v_pk_mul_f32 v[130:131], v[0:1], v[130:131] op_sel_hi:[0,1]
	v_pk_mul_f32 v[132:133], v[0:1], v[132:133] op_sel_hi:[0,1]
	v_pk_mul_f32 v[126:127], v[0:1], v[126:127] op_sel_hi:[0,1]
	v_pk_mul_f32 v[128:129], v[0:1], v[128:129] op_sel_hi:[0,1]
	s_waitcnt vmcnt(6)
; __device__ __forceinline__ float xsum16(float v) { const auto r = __builtin_amdgcn_permlane16_swap(__float_as_uint(v), __float_as_uint(v), false, false); return __uint_as_float(r[0]) + __uint_as_float(r[1]); }
; __device__ __forceinline__ float xsum32(float v) { const auto r = __builtin_amdgcn_permlane32_swap(__float_as_uint(v), __float_as_uint(v), false, false); return __uint_as_float(r[0]) + __uint_as_float(r[1]); }
; __device__ __forceinline__ size_t blk_off(int r, int c, int K) { return (size_t)(r >> 8) * 256 * K + (size_t)(c >> 6) * (256 * 64) + (size_t)((r & 255) * 64 + (c & 63)); }
; __device__ __forceinline__ u32x4 pack8(const f32x4 a, const f32x4 b) { u32x4 w; w.x = cvt_pk_bf16(a[0], a[1]); w.y = cvt_pk_bf16(a[2], a[3]); w.z = cvt_pk_bf16(b[0], b[1]); w.w = cvt_pk_bf16(b[2], b[3]); return w; }
;     __device__ __forceinline__ void operator()(const f32x4 (&acc)[2][2][4][2], const pg8::Unit& u, int wr, int wc, int fr, int fq) const {
;     ...
;                     for (int n = 0; n < 2; ++n) { yv[bj][n] = *(const f32x4*)(Yin + (size_t)row * D_ + col0 + bj * 128 + 4 * n); gq[bj][n] = *(const f32x4*)(g + col0 + bj * 128 + 4 * n); bq_[bj][n] = *(const f32x4*)(b + col0 + bj * 128 + 4 * n); }
;                 asm volatile("" ::: "memory");
;                 float s1 = 0.f, s2 = 0.f;
; #pragma unroll
;                 for (int bj = 0; bj < 2; ++bj) { float* yp = Y + (size_t)row * D_ + col0 + bj * 128; f32x4 v[2];
; #pragma unroll
;                     for (int n = 0; n < 2; ++n) { v[n] = (((yv[bj][n] - mu) * rs) * gq[bj][n] + bq_[bj][n]) * ALPHA_ + acc[ai][bj][m][n] * sc;
;                         *(f32x4*)(yp + 4 * n) = v[n]; s1 += (v[n][0] + v[n][1]) + (v[n][2] + v[n][3]); s2 += (v[n][0] * v[n][0] + v[n][1] * v[n][1]) + (v[n][2] * v[n][2] + v[n][3] * v[n][3]); }
;                     *(u32x4*)(Yb + blk_off(row, col0 + bj * 128, D_)) = pack8(v[0], v[1]); }
;                 s1 = xsum32(xsum16(s1)); s2 = xsum32(xsum16(s2));
;                 if (fq == 0) *(f32x2*)(stn + (size_t)row * 32 + (u.pn * 4 + wc) * 2) = (f32x2){s1, s2}; asm volatile("" ::: "memory"); } }
	v_pk_fma_f32 v[132:133], v[174:175], v[132:133], v[182:183]
	v_pk_fma_f32 v[130:131], v[172:173], v[130:131], v[180:181]
	v_pk_fma_f32 v[128:129], v[136:137], v[128:129], v[178:179]
	v_pk_fma_f32 v[126:127], v[134:135], v[126:127], v[176:177]
	v_pk_mul_f32 v[130:131], v[130:131], s[2:3] op_sel_hi:[1,0]
	v_pk_mul_f32 v[132:133], v[132:133], s[2:3] op_sel_hi:[1,0]
	v_pk_mul_f32 v[126:127], v[126:127], s[2:3] op_sel_hi:[1,0]
	v_pk_mul_f32 v[128:129], v[128:129], s[2:3] op_sel_hi:[1,0]
	v_pk_fma_f32 v[96:97], v[96:97], 0.5, v[132:133] op_sel_hi:[1,0,1]
	v_pk_fma_f32 v[94:95], v[94:95], 0.5, v[130:131] op_sel_hi:[1,0,1]
	v_pk_fma_f32 v[92:93], v[92:93], 0.5, v[128:129] op_sel_hi:[1,0,1]
	v_pk_fma_f32 v[90:91], v[90:91], 0.5, v[126:127] op_sel_hi:[1,0,1]
	v_add_f32_e32 v130, v94, v95
	v_add_f32_e32 v131, v96, v97
	v_add_f32_e32 v126, v90, v91
	v_add_f32_e32 v127, v92, v93
	v_add_f32_e32 v130, v130, v131
	v_mul_f32_e32 v131, v95, v95
	v_mul_f32_e32 v132, v97, v97
	v_add_f32_e32 v126, v126, v127
	v_mul_f32_e32 v127, v91, v91
	v_mul_f32_e32 v128, v93, v93
	s_nop 0
	v_fmac_f32_e32 v131, v94, v94
	v_fmac_f32_e32 v132, v96, v96
	s_nop 1
	v_bfe_u32 v135, v227, 4, 2
	v_sub_u32_e32 v134, 0, v135
	v_lshlrev_b32_e32 v134, 4, v134
	v_ashrrev_i32_e32 v135, 31, v134
	v_lshl_add_u64 v[134:135], v[124:125], 0, v[134:135]
	v_permlane16_swap_b32_e32 v94, v90
	v_permlane16_swap_b32_e32 v95, v91
	v_permlane16_swap_b32_e32 v96, v92
	v_permlane16_swap_b32_e32 v97, v93
	v_permlane32_swap_b32_e32 v94, v90
	v_permlane32_swap_b32_e32 v95, v91
	v_permlane32_swap_b32_e32 v96, v92
	v_permlane32_swap_b32_e32 v97, v93
	global_store_dwordx4 v[134:135], v[94:97], off
	global_store_dwordx4 v[134:135], v[90:93], off offset:64
	s_nop 1
	v_permlane32_swap_b32_e32 v94, v90
	v_permlane32_swap_b32_e32 v95, v91
	v_permlane32_swap_b32_e32 v96, v92
	v_permlane32_swap_b32_e32 v97, v93
	v_permlane16_swap_b32_e32 v94, v90
	v_permlane16_swap_b32_e32 v95, v91
	v_permlane16_swap_b32_e32 v96, v92
	v_permlane16_swap_b32_e32 v97, v93
	v_fmac_f32_e32 v127, v90, v90
	v_fmac_f32_e32 v128, v92, v92
	v_cvt_pk_bf16_f32 v94, v94, v95
	v_cvt_pk_bf16_f32 v95, v96, v97
	v_cvt_pk_bf16_f32 v96, v90, v91
	v_cvt_pk_bf16_f32 v97, v92, v93
	s_waitcnt vmcnt(6)
	v_sub_f32_e32 v91, v121, v123
	v_sub_f32_e32 v90, v120, v123
	v_sub_f32_e32 v93, v119, v123
	v_sub_f32_e32 v92, v118, v123
	v_pk_mul_f32 v[92:93], v[0:1], v[92:93] op_sel_hi:[0,1]
	v_pk_mul_f32 v[90:91], v[0:1], v[90:91] op_sel_hi:[0,1]
	s_waitcnt vmcnt(2)
	v_pk_fma_f32 v[90:91], v[112:113], v[90:91], v[116:117]
	v_pk_fma_f32 v[92:93], v[110:111], v[92:93], v[114:115]
	v_pk_mul_f32 v[90:91], v[90:91], s[2:3] op_sel_hi:[1,0]
	v_pk_mul_f32 v[92:93], v[92:93], s[2:3] op_sel_hi:[1,0]
	v_pk_fma_f32 v[88:89], v[88:89], 0.5, v[90:91] op_sel_hi:[1,0,1]
	v_pk_fma_f32 v[86:87], v[86:87], 0.5, v[92:93] op_sel_hi:[1,0,1]
	v_add_f32_e32 v130, 0, v130
	v_add_f32_e32 v90, v86, v87
	v_add_f32_e32 v91, v88, v89
	v_add_f32_e32 v126, v130, v126
	v_add_f32_e32 v90, v90, v91
	global_store_dwordx4 v122, v[94:97], s[48:49]
	v_mul_f32_e32 v91, v89, v89
	v_add_f32_e32 v131, v131, v132
	v_add_f32_e32 v94, v126, v90
	v_mul_f32_e32 v90, v87, v87
	v_add_f32_e32 v127, v127, v128
	v_fmac_f32_e32 v90, v86, v86
	v_fmac_f32_e32 v91, v88, v88
	v_add_f32_e32 v127, v131, v127
	v_add_f32_e32 v90, v90, v91
	v_add_f32_e32 v95, v127, v90
	v_sub_f32_e32 v91, v101, v123
	v_sub_f32_e32 v90, v100, v123
	v_sub_f32_e32 v93, v99, v123
	v_sub_f32_e32 v92, v98, v123
	v_pk_mul_f32 v[92:93], v[0:1], v[92:93] op_sel_hi:[0,1]
	v_pk_mul_f32 v[90:91], v[0:1], v[90:91] op_sel_hi:[0,1]
	v_pk_fma_f32 v[90:91], v[104:105], v[90:91], v[108:109]
	v_pk_fma_f32 v[92:93], v[102:103], v[92:93], v[106:107]
	v_pk_mul_f32 v[90:91], v[90:91], s[2:3] op_sel_hi:[1,0]
	v_pk_mul_f32 v[92:93], v[92:93], s[2:3] op_sel_hi:[1,0]
	v_pk_fma_f32 v[84:85], v[84:85], 0.5, v[90:91] op_sel_hi:[1,0,1]
	v_pk_fma_f32 v[82:83], v[82:83], 0.5, v[92:93] op_sel_hi:[1,0,1]
	v_add_f32_e32 v90, v84, v85
	v_add_f32_e32 v0, v82, v83
	v_add_f32_e32 v0, v0, v90
	v_mul_f32_e32 v90, v83, v83
	v_mul_f32_e32 v91, v85, v85
	v_add_f32_e32 v0, v94, v0
	v_fmac_f32_e32 v90, v82, v82
	v_fmac_f32_e32 v91, v84, v84
	s_nop 0
	s_nop 1
	v_bfe_u32 v93, v227, 4, 2
	v_sub_u32_e32 v92, 0, v93
	v_lshlrev_b32_e32 v92, 4, v92
	v_ashrrev_i32_e32 v93, 31, v92
	v_lshl_add_u64 v[92:93], v[124:125], 0, v[92:93]
	v_permlane16_swap_b32_e32 v86, v82
	v_permlane16_swap_b32_e32 v87, v83
	v_permlane16_swap_b32_e32 v88, v84
	v_permlane16_swap_b32_e32 v89, v85
	v_permlane32_swap_b32_e32 v86, v82
	v_permlane32_swap_b32_e32 v87, v83
	v_permlane32_swap_b32_e32 v88, v84
	v_permlane32_swap_b32_e32 v89, v85
	global_store_dwordx4 v[92:93], v[86:89], off offset:512
	global_store_dwordx4 v[92:93], v[82:85], off offset:576
	s_nop 1
	v_permlane32_swap_b32_e32 v86, v82
	v_permlane32_swap_b32_e32 v87, v83
	v_permlane32_swap_b32_e32 v88, v84
	v_permlane32_swap_b32_e32 v89, v85
	v_permlane16_swap_b32_e32 v86, v82
	v_permlane16_swap_b32_e32 v87, v83
	v_permlane16_swap_b32_e32 v88, v84
	v_permlane16_swap_b32_e32 v89, v85
	v_add_f32_e32 v90, v90, v91
	v_cvt_pk_bf16_f32 v86, v86, v87
	v_cvt_pk_bf16_f32 v87, v88, v89
	v_cvt_pk_bf16_f32 v88, v82, v83
	v_mov_b32_e32 v82, v0
	v_add_f32_e32 v90, v95, v90
	s_nop 0
	v_permlane16_swap_b32_e32 v0, v82
	v_add_f32_e32 v82, v0, v82
	v_mov_b32_e32 v0, v90
	s_nop 1
	v_permlane16_swap_b32_e32 v90, v0
	v_add_f32_e32 v83, v90, v0
	v_cvt_pk_bf16_f32 v89, v84, v85
	v_mov_b32_e32 v84, v82
	v_mov_b32_e32 v85, v83
	s_nop 0
	v_permlane32_swap_b32_e32 v82, v84
	v_permlane32_swap_b32_e32 v83, v85
	global_store_dwordx4 v122, v[86:89], s[46:47]
	s_and_saveexec_b64 s[26:27], s[40:41]
	s_cbranch_execz .LBB0_1709
	v_pk_add_f32 v[82:83], v[82:83], v[84:85]
	v_lshl_add_u64 v[84:85], s[8:9], 0, v[164:165]
	v_lshl_add_u64 v[84:85], s[38:39], 2, v[84:85]
	global_store_dwordx2 v[84:85], v[82:83], off
;     __device__ __forceinline__ void operator()(const f32x4 (&acc)[2][2][4][2], const pg8::Unit& u, int wr, int wc, int fr, int fq) const {
;     ...
;             for (int m = 0; m < 4; ++m) { const int row = row0 + ai * 128 + m * 16; const float mu = mu4[m], rs = rs4[m];
;                 f32x4 yv[2][2], gq[2][2], bq_[2][2];
; #pragma unroll
;                 for (int bj = 0; bj < 2; ++bj)
; #pragma unroll
;                     for (int n = 0; n < 2; ++n) { yv[bj][n] = *(const f32x4*)(Yin + (size_t)row * D_ + col0 + bj * 128 + 4 * n); gq[bj][n] = *(const f32x4*)(g + col0 + bj * 128 + 4 * n); bq_[bj][n] = *(const f32x4*)(b + col0 + bj * 128 + 4 * n); }
;                 asm volatile("" ::: "memory");
;                 float s1 = 0.f, s2 = 0.f;
; #pragma unroll
;                 for (int bj = 0; bj < 2; ++bj) { float* yp = Y + (size_t)row * D_ + col0 + bj * 128; f32x4 v[2];
; #pragma unroll
;                     for (int n = 0; n < 2; ++n) { v[n] = (((yv[bj][n] - mu) * rs) * gq[bj][n] + bq_[bj][n]) * ALPHA_ + acc[ai][bj][m][n] * sc;
;                         *(f32x4*)(yp + 4 * n) = v[n]; s1 += (v[n][0] + v[n][1]) + (v[n][2] + v[n][3]); s2 += (v[n][0] * v[n][0] + v[n][1] * v[n][1]) + (v[n][2] * v[n][2] + v[n][3] * v[n][3]); }
.LBB0_1709:
	s_or_b64 exec, exec, s[26:27]
	v_pk_add_f32 v[82:83], v[166:167], v[168:169]
	s_mov_b32 s2, 0x3a800000
	v_pk_mul_f32 v[106:107], v[82:83], s[2:3] op_sel_hi:[1,0]
	s_mov_b32 s1, 0x800000
	v_fma_f32 v0, -v107, v107, v106
	v_max_f32_e32 v0, 0, v0
	v_add_f32_e32 v0, 0x3727c5ac, v0
	v_cmp_gt_f32_e32 vcc, s1, v0
	v_mul_f32_e32 v82, 0x4b800000, v0
	s_load_dwordx16 s[60:75], s[34:35], 0x38
	v_cndmask_b32_e32 v0, v0, v82, vcc
	v_rsq_f32_e32 v0, v0
	s_mov_b32 s2, 0x3fd744fd
	v_lshlrev_b32_e32 v106, 6, v162
	v_mul_f32_e32 v82, 0x45800000, v0
	v_cndmask_b32_e32 v0, v0, v82, vcc
	v_lshlrev_b64 v[82:83], 12, v[162:163]
	s_waitcnt lgkmcnt(0)
	v_lshl_add_u64 v[82:83], s[74:75], 0, v[82:83]
	v_lshl_add_u64 v[108:109], v[152:153], 2, v[82:83]
	global_load_dwordx4 v[110:113], v[108:109], off offset:16 nt
	global_load_dwordx4 v[114:117], v[108:109], off nt
	global_load_dwordx4 v[118:121], v[156:157], off offset:16
	global_load_dwordx4 v[122:125], v[156:157], off
	global_load_dwordx4 v[126:129], v[154:155], off offset:16
	global_load_dwordx4 v[130:133], v[154:155], off
	global_load_dwordx4 v[82:85], v[108:109], off offset:528 nt
	global_load_dwordx4 v[102:105], v[108:109], off offset:512 nt
	global_load_dwordx4 v[86:89], v[156:157], off offset:528
	global_load_dwordx4 v[94:97], v[156:157], off offset:512
	global_load_dwordx4 v[90:93], v[154:155], off offset:528
	global_load_dwordx4 v[98:101], v[154:155], off offset:512
	s_movk_i32 s1, 0x3fc0
	v_and_or_b32 v106, v106, s1, v196
	v_lshlrev_b32_e32 v106, 1, v106
	s_waitcnt vmcnt(11)
	v_sub_f32_e32 v113, v113, v107
	s_waitcnt vmcnt(10)
	v_sub_f32_e32 v117, v117, v107
	v_sub_f32_e32 v116, v116, v107
	v_sub_f32_e32 v115, v115, v107
	v_sub_f32_e32 v114, v114, v107
	v_sub_f32_e32 v112, v112, v107
	v_sub_f32_e32 v111, v111, v107
	v_sub_f32_e32 v110, v110, v107
	v_pk_mul_f32 v[114:115], v[0:1], v[114:115] op_sel_hi:[0,1]
	v_pk_mul_f32 v[116:117], v[0:1], v[116:117] op_sel_hi:[0,1]
	v_pk_mul_f32 v[110:111], v[0:1], v[110:111] op_sel_hi:[0,1]
	v_pk_mul_f32 v[112:113], v[0:1], v[112:113] op_sel_hi:[0,1]
	s_waitcnt vmcnt(6)
	v_pk_fma_f32 v[116:117], v[124:125], v[116:117], v[132:133]
	v_pk_fma_f32 v[114:115], v[122:123], v[114:115], v[130:131]
	v_pk_fma_f32 v[112:113], v[120:121], v[112:113], v[128:129]
	v_pk_fma_f32 v[110:111], v[118:119], v[110:111], v[126:127]
	v_pk_mul_f32 v[114:115], v[114:115], s[2:3] op_sel_hi:[1,0]
	v_pk_mul_f32 v[116:117], v[116:117], s[2:3] op_sel_hi:[1,0]
	v_pk_mul_f32 v[110:111], v[110:111], s[2:3] op_sel_hi:[1,0]
	v_pk_mul_f32 v[112:113], v[112:113], s[2:3] op_sel_hi:[1,0]
	v_pk_fma_f32 v[80:81], v[80:81], 0.5, v[116:117] op_sel_hi:[1,0,1]
	v_pk_fma_f32 v[78:79], v[78:79], 0.5, v[114:115] op_sel_hi:[1,0,1]
	v_pk_fma_f32 v[76:77], v[76:77], 0.5, v[112:113] op_sel_hi:[1,0,1]
	v_pk_fma_f32 v[74:75], v[74:75], 0.5, v[110:111] op_sel_hi:[1,0,1]
	v_add_f32_e32 v114, v78, v79
	v_add_f32_e32 v115, v80, v81
	v_add_f32_e32 v110, v74, v75
	v_add_f32_e32 v111, v76, v77
	v_add_f32_e32 v114, v114, v115
	v_mul_f32_e32 v115, v79, v79
	v_mul_f32_e32 v116, v81, v81
	v_add_f32_e32 v110, v110, v111
	v_mul_f32_e32 v111, v75, v75
	v_mul_f32_e32 v112, v77, v77
	s_nop 0
	v_fmac_f32_e32 v115, v78, v78
	v_fmac_f32_e32 v116, v80, v80
	s_nop 1
	v_bfe_u32 v119, v227, 4, 2
	v_sub_u32_e32 v118, 0, v119
	v_lshlrev_b32_e32 v118, 4, v118
	v_ashrrev_i32_e32 v119, 31, v118
	v_lshl_add_u64 v[118:119], v[108:109], 0, v[118:119]
	v_permlane16_swap_b32_e32 v78, v74
	v_permlane16_swap_b32_e32 v79, v75
	v_permlane16_swap_b32_e32 v80, v76
	v_permlane16_swap_b32_e32 v81, v77
	v_permlane32_swap_b32_e32 v78, v74
	v_permlane32_swap_b32_e32 v79, v75
	v_permlane32_swap_b32_e32 v80, v76
	v_permlane32_swap_b32_e32 v81, v77
	global_store_dwordx4 v[118:119], v[78:81], off
	global_store_dwordx4 v[118:119], v[74:77], off offset:64
	s_nop 1
	v_permlane32_swap_b32_e32 v78, v74
	v_permlane32_swap_b32_e32 v79, v75
	v_permlane32_swap_b32_e32 v80, v76
	v_permlane32_swap_b32_e32 v81, v77
	v_permlane16_swap_b32_e32 v78, v74
	v_permlane16_swap_b32_e32 v79, v75
	v_permlane16_swap_b32_e32 v80, v76
	v_permlane16_swap_b32_e32 v81, v77
	v_fmac_f32_e32 v111, v74, v74
	v_fmac_f32_e32 v112, v76, v76
	v_cvt_pk_bf16_f32 v78, v78, v79
	v_cvt_pk_bf16_f32 v79, v80, v81
	v_cvt_pk_bf16_f32 v80, v74, v75
	v_cvt_pk_bf16_f32 v81, v76, v77
	s_waitcnt vmcnt(6)
	v_sub_f32_e32 v75, v105, v107
	v_sub_f32_e32 v74, v104, v107
	v_sub_f32_e32 v77, v103, v107
	v_sub_f32_e32 v76, v102, v107
	v_pk_mul_f32 v[76:77], v[0:1], v[76:77] op_sel_hi:[0,1]
	v_pk_mul_f32 v[74:75], v[0:1], v[74:75] op_sel_hi:[0,1]
	s_waitcnt vmcnt(2)
; __device__ __forceinline__ float xsum16(float v) { const auto r = __builtin_amdgcn_permlane16_swap(__float_as_uint(v), __float_as_uint(v), false, false); return __uint_as_float(r[0]) + __uint_as_float(r[1]); }
; __device__ __forceinline__ float xsum32(float v) { const auto r = __builtin_amdgcn_permlane32_swap(__float_as_uint(v), __float_as_uint(v), false, false); return __uint_as_float(r[0]) + __uint_as_float(r[1]); }
; __device__ __forceinline__ size_t blk_off(int r, int c, int K) { return (size_t)(r >> 8) * 256 * K + (size_t)(c >> 6) * (256 * 64) + (size_t)((r & 255) * 64 + (c & 63)); }
; __device__ __forceinline__ u32x4 pack8(const f32x4 a, const f32x4 b) { u32x4 w; w.x = cvt_pk_bf16(a[0], a[1]); w.y = cvt_pk_bf16(a[2], a[3]); w.z = cvt_pk_bf16(b[0], b[1]); w.w = cvt_pk_bf16(b[2], b[3]); return w; }
; __device__ __forceinline__ void row_stats4(const float* st, int rowb, int fq, float (&mu)[4], float (&rs)[4]) {
;     ...
;     for (int m = 0; m < 4; ++m) { const f32x4* p = (const f32x4*)(st + (size_t)(rowb + m * 16) * 32 + fq * 8); a[m] = p[0]; b[m] = p[1]; }
; #pragma unroll
;     for (int m = 0; m < 4; ++m) { float s1 = (a[m][0] + a[m][2]) + (b[m][0] + b[m][2]), s2 = (a[m][1] + a[m][3]) + (b[m][1] + b[m][3]);
;         s1 = xsum32(xsum16(s1)); s2 = xsum32(xsum16(s2));
;         const float mm = s1 * (1.0f / 1024.0f); mu[m] = mm; rs[m] = rsqrtf(fmaxf(s2 * (1.0f / 1024.0f) - mm * mm, 0.f) + LN_EPS_); }
;     __device__ __forceinline__ void operator()(const f32x4 (&acc)[2][2][4][2], const pg8::Unit& u, int wr, int wc, int fr, int fq) const {
;     ...
;                 for (int bj = 0; bj < 2; ++bj) { float* yp = Y + (size_t)row * D_ + col0 + bj * 128; f32x4 v[2];
; #pragma unroll
;                     for (int n = 0; n < 2; ++n) { v[n] = (((yv[bj][n] - mu) * rs) * gq[bj][n] + bq_[bj][n]) * ALPHA_ + acc[ai][bj][m][n] * sc;
;                         *(f32x4*)(yp + 4 * n) = v[n]; s1 += (v[n][0] + v[n][1]) + (v[n][2] + v[n][3]); s2 += (v[n][0] * v[n][0] + v[n][1] * v[n][1]) + (v[n][2] * v[n][2] + v[n][3] * v[n][3]); }
;                     *(u32x4*)(Yb + blk_off(row, col0 + bj * 128, D_)) = pack8(v[0], v[1]); }
;                 s1 = xsum32(xsum16(s1)); s2 = xsum32(xsum16(s2));
;                 if (fq == 0) *(f32x2*)(stn + (size_t)row * 32 + (u.pn * 4 + wc) * 2) = (f32x2){s1, s2}; asm volatile("" ::: "memory"); } }
	v_pk_fma_f32 v[74:75], v[96:97], v[74:75], v[100:101]
	v_pk_fma_f32 v[76:77], v[94:95], v[76:77], v[98:99]
	v_pk_mul_f32 v[74:75], v[74:75], s[2:3] op_sel_hi:[1,0]
	v_pk_mul_f32 v[76:77], v[76:77], s[2:3] op_sel_hi:[1,0]
	v_pk_fma_f32 v[72:73], v[72:73], 0.5, v[74:75] op_sel_hi:[1,0,1]
	v_pk_fma_f32 v[70:71], v[70:71], 0.5, v[76:77] op_sel_hi:[1,0,1]
	v_add_f32_e32 v114, 0, v114
	v_add_f32_e32 v74, v70, v71
	v_add_f32_e32 v75, v72, v73
	v_add_f32_e32 v110, v114, v110
	v_add_f32_e32 v74, v74, v75
	global_store_dwordx4 v106, v[78:81], s[48:49]
	v_mul_f32_e32 v75, v73, v73
	v_add_f32_e32 v115, v115, v116
	v_add_f32_e32 v78, v110, v74
	v_mul_f32_e32 v74, v71, v71
	v_add_f32_e32 v111, v111, v112
	v_fmac_f32_e32 v74, v70, v70
	v_fmac_f32_e32 v75, v72, v72
	v_add_f32_e32 v111, v115, v111
	v_add_f32_e32 v74, v74, v75
	v_add_f32_e32 v79, v111, v74
	v_sub_f32_e32 v75, v85, v107
	v_sub_f32_e32 v74, v84, v107
	v_sub_f32_e32 v77, v83, v107
	v_sub_f32_e32 v76, v82, v107
	v_pk_mul_f32 v[76:77], v[0:1], v[76:77] op_sel_hi:[0,1]
	v_pk_mul_f32 v[74:75], v[0:1], v[74:75] op_sel_hi:[0,1]
	v_pk_fma_f32 v[74:75], v[88:89], v[74:75], v[92:93]
	v_pk_fma_f32 v[76:77], v[86:87], v[76:77], v[90:91]
	v_pk_mul_f32 v[74:75], v[74:75], s[2:3] op_sel_hi:[1,0]
	v_pk_mul_f32 v[76:77], v[76:77], s[2:3] op_sel_hi:[1,0]
	v_pk_fma_f32 v[68:69], v[68:69], 0.5, v[74:75] op_sel_hi:[1,0,1]
	v_pk_fma_f32 v[66:67], v[66:67], 0.5, v[76:77] op_sel_hi:[1,0,1]
	v_add_f32_e32 v74, v68, v69
	v_add_f32_e32 v0, v66, v67
	v_add_f32_e32 v0, v0, v74
	v_mul_f32_e32 v74, v67, v67
	v_mul_f32_e32 v75, v69, v69
	v_add_f32_e32 v0, v78, v0
	v_fmac_f32_e32 v74, v66, v66
	v_fmac_f32_e32 v75, v68, v68
	s_nop 0
	s_nop 1
	v_bfe_u32 v77, v227, 4, 2
	v_sub_u32_e32 v76, 0, v77
	v_lshlrev_b32_e32 v76, 4, v76
	v_ashrrev_i32_e32 v77, 31, v76
	v_lshl_add_u64 v[76:77], v[108:109], 0, v[76:77]
	v_permlane16_swap_b32_e32 v70, v66
	v_permlane16_swap_b32_e32 v71, v67
	v_permlane16_swap_b32_e32 v72, v68
	v_permlane16_swap_b32_e32 v73, v69
	v_permlane32_swap_b32_e32 v70, v66
	v_permlane32_swap_b32_e32 v71, v67
	v_permlane32_swap_b32_e32 v72, v68
	v_permlane32_swap_b32_e32 v73, v69
	global_store_dwordx4 v[76:77], v[70:73], off offset:512
	global_store_dwordx4 v[76:77], v[66:69], off offset:576
	s_nop 1
	v_permlane32_swap_b32_e32 v70, v66
	v_permlane32_swap_b32_e32 v71, v67
	v_permlane32_swap_b32_e32 v72, v68
	v_permlane32_swap_b32_e32 v73, v69
	v_permlane16_swap_b32_e32 v70, v66
	v_permlane16_swap_b32_e32 v71, v67
	v_permlane16_swap_b32_e32 v72, v68
	v_permlane16_swap_b32_e32 v73, v69
	v_add_f32_e32 v74, v74, v75
	v_cvt_pk_bf16_f32 v70, v70, v71
	v_cvt_pk_bf16_f32 v71, v72, v73
	v_cvt_pk_bf16_f32 v72, v66, v67
	v_mov_b32_e32 v66, v0
	v_add_f32_e32 v74, v79, v74
	s_nop 0
	v_permlane16_swap_b32_e32 v0, v66
	v_add_f32_e32 v66, v0, v66
	v_mov_b32_e32 v0, v74
	s_nop 1
	v_permlane16_swap_b32_e32 v74, v0
	v_add_f32_e32 v67, v74, v0
	v_cvt_pk_bf16_f32 v73, v68, v69
	v_mov_b32_e32 v68, v66
	v_mov_b32_e32 v69, v67
	s_nop 0
	v_permlane32_swap_b32_e32 v66, v68
	v_permlane32_swap_b32_e32 v67, v69
	global_store_dwordx4 v106, v[70:73], s[46:47]
	s_and_saveexec_b64 s[26:27], s[40:41]
	s_cbranch_execz .LBB0_1711
	v_pk_add_f32 v[66:67], v[66:67], v[68:69]
	v_lshl_add_u64 v[68:69], s[8:9], 0, v[160:161]
	v_lshl_add_u64 v[68:69], s[38:39], 2, v[68:69]
	global_store_dwordx2 v[68:69], v[66:67], off
.LBB0_1711:
	s_or_b64 exec, exec, s[26:27]
	v_add_u32_e32 v68, 0x80, v158
	v_ashrrev_i32_e32 v69, 31, v68
	v_lshlrev_b64 v[66:67], 7, v[68:69]
	v_lshl_add_u64 v[74:75], v[146:147], 0, v[66:67]
	v_add_u32_e32 v96, 0x90, v158
	global_load_dwordx4 v[70:73], v[74:75], off nt
	global_load_dwordx4 v[82:85], v[74:75], off offset:16 nt
	v_ashrrev_i32_e32 v97, 31, v96
	v_lshlrev_b64 v[86:87], 7, v[96:97]
	v_add_u32_e32 v80, 0xa0, v158
	v_lshl_add_u64 v[74:75], v[146:147], 0, v[86:87]
	v_ashrrev_i32_e32 v81, 31, v80
	global_load_dwordx4 v[88:91], v[74:75], off nt
	global_load_dwordx4 v[92:95], v[74:75], off offset:16 nt
	v_lshlrev_b64 v[74:75], 7, v[80:81]
	v_lshl_add_u64 v[74:75], v[146:147], 0, v[74:75]
	global_load_dwordx4 v[98:101], v[74:75], off nt
	global_load_dwordx4 v[102:105], v[74:75], off offset:16 nt
	v_add_u32_e32 v74, 0xb0, v158
	v_ashrrev_i32_e32 v75, 31, v74
	v_lshlrev_b64 v[76:77], 7, v[74:75]
	v_lshl_add_u64 v[76:77], v[146:147], 0, v[76:77]
	global_load_dwordx4 v[106:109], v[76:77], off nt
	global_load_dwordx4 v[110:113], v[76:77], off offset:16 nt
	s_load_dwordx16 s[60:75], s[34:35], 0x38
	v_lshlrev_b64 v[78:79], 12, v[68:69]
	s_mov_b32 s2, 0x3a800000
	s_mov_b32 s1, 0x800000
	s_waitcnt lgkmcnt(0)
	v_lshl_add_u64 v[78:79], s[74:75], 0, v[78:79]
	v_lshl_add_u64 v[76:77], v[152:153], 2, v[78:79]
	global_load_dwordx4 v[114:117], v[76:77], off offset:16 nt
	global_load_dwordx4 v[118:121], v[76:77], off nt
	global_load_dwordx4 v[122:125], v[156:157], off offset:16
	global_load_dwordx4 v[126:129], v[156:157], off
	global_load_dwordx4 v[130:133], v[154:155], off offset:16
	global_load_dwordx4 v[134:137], v[154:155], off
	s_mov_b32 s16, 0x3fd744fd
	s_waitcnt vmcnt(13)
	v_mov_b32_e32 v78, v70
	s_waitcnt vmcnt(12)
	v_mov_b32_e32 v79, v82
	v_mov_b32_e32 v158, v72
	v_mov_b32_e32 v159, v84
	v_mov_b32_e32 v82, v71
	v_mov_b32_e32 v84, v73
	v_pk_add_f32 v[78:79], v[78:79], v[158:159]
	v_pk_add_f32 v[82:83], v[82:83], v[84:85]
	v_pk_add_f32 v[78:79], v[78:79], v[78:79] op_sel:[0,1] op_sel_hi:[1,0]
	v_pk_add_f32 v[82:83], v[82:83], v[82:83] op_sel:[0,1] op_sel_hi:[1,0]
	v_mov_b32_e32 v0, v78
	v_mov_b32_e32 v69, v82
	s_nop 0
	v_permlane16_swap_b32_e32 v78, v0
	v_permlane16_swap_b32_e32 v82, v69
	v_add_f32_e32 v79, v78, v0
	v_add_f32_e32 v78, v82, v69
	v_mov_b32_e32 v83, v79
	v_mov_b32_e32 v82, v78
	s_waitcnt vmcnt(11)
; __device__ __forceinline__ float xsum16(float v) { const auto r = __builtin_amdgcn_permlane16_swap(__float_as_uint(v), __float_as_uint(v), false, false); return __uint_as_float(r[0]) + __uint_as_float(r[1]); }
; __device__ __forceinline__ float xsum32(float v) { const auto r = __builtin_amdgcn_permlane32_swap(__float_as_uint(v), __float_as_uint(v), false, false); return __uint_as_float(r[0]) + __uint_as_float(r[1]); }
; __device__ __forceinline__ void row_stats4(const float* st, int rowb, int fq, float (&mu)[4], float (&rs)[4]) {
;     ...
;     for (int m = 0; m < 4; ++m) { float s1 = (a[m][0] + a[m][2]) + (b[m][0] + b[m][2]), s2 = (a[m][1] + a[m][3]) + (b[m][1] + b[m][3]);
;         s1 = xsum32(xsum16(s1)); s2 = xsum32(xsum16(s2));
;         const float mm = s1 * (1.0f / 1024.0f); mu[m] = mm; rs[m] = rsqrtf(fmaxf(s2 * (1.0f / 1024.0f) - mm * mm, 0.f) + LN_EPS_); }
;     __device__ __forceinline__ void operator()(const f32x4 (&acc)[2][2][4][2], const pg8::Unit& u, int wr, int wc, int fr, int fq) const {
;     ...
;                     for (int n = 0; n < 2; ++n) { yv[bj][n] = *(const f32x4*)(Yin + (size_t)row * D_ + col0 + bj * 128 + 4 * n); gq[bj][n] = *(const f32x4*)(g + col0 + bj * 128 + 4 * n); bq_[bj][n] = *(const f32x4*)(b + col0 + bj * 128 + 4 * n); }
;                 asm volatile("" ::: "memory");
;                 float s1 = 0.f, s2 = 0.f;
; #pragma unroll
;                 for (int bj = 0; bj < 2; ++bj) { float* yp = Y + (size_t)row * D_ + col0 + bj * 128; f32x4 v[2];
; #pragma unroll
;                     for (int n = 0; n < 2; ++n) { v[n] = (((yv[bj][n] - mu) * rs) * gq[bj][n] + bq_[bj][n]) * ALPHA_ + acc[ai][bj][m][n] * sc;
;                         *(f32x4*)(yp + 4 * n) = v[n]; s1 += (v[n][0] + v[n][1]) + (v[n][2] + v[n][3]); s2 += (v[n][0] * v[n][0] + v[n][1] * v[n][1]) + (v[n][2] * v[n][2] + v[n][3] * v[n][3]); }
	v_mov_b32_e32 v70, v88
	s_waitcnt vmcnt(10)
	v_mov_b32_e32 v71, v92
	v_mov_b32_e32 v72, v90
	v_mov_b32_e32 v73, v94
	v_mov_b32_e32 v92, v89
	v_mov_b32_e32 v94, v91
	v_permlane32_swap_b32_e32 v79, v83
	v_permlane32_swap_b32_e32 v78, v82
	s_waitcnt vmcnt(9)
	v_mov_b32_e32 v88, v98
	s_waitcnt vmcnt(8)
	v_mov_b32_e32 v89, v102
	v_mov_b32_e32 v90, v100
	v_mov_b32_e32 v91, v104
	v_mov_b32_e32 v102, v99
	v_mov_b32_e32 v104, v101
	v_pk_add_f32 v[70:71], v[70:71], v[72:73]
	v_pk_add_f32 v[72:73], v[92:93], v[94:95]
	v_pk_add_f32 v[78:79], v[78:79], v[82:83]
	global_load_dwordx4 v[92:95], v[76:77], off offset:528 nt
	global_load_dwordx4 v[98:101], v[76:77], off offset:512 nt
	v_pk_mul_f32 v[162:163], v[78:79], s[2:3] op_sel_hi:[1,0]
	s_waitcnt vmcnt(9)
	v_mov_b32_e32 v78, v106
	s_waitcnt vmcnt(8)
	v_mov_b32_e32 v79, v110
	v_mov_b32_e32 v82, v108
	v_mov_b32_e32 v83, v112
	v_mov_b32_e32 v110, v107
	v_mov_b32_e32 v112, v109
	v_pk_add_f32 v[84:85], v[88:89], v[90:91]
	v_pk_add_f32 v[88:89], v[102:103], v[104:105]
	v_pk_add_f32 v[78:79], v[78:79], v[82:83]
	v_pk_add_f32 v[82:83], v[110:111], v[112:113]
	global_load_dwordx4 v[102:105], v[156:157], off offset:528
	global_load_dwordx4 v[106:109], v[156:157], off offset:512
	global_load_dwordx4 v[110:113], v[154:155], off offset:528
	global_load_dwordx4 v[158:161], v[154:155], off offset:512
	v_fma_f32 v0, -v163, v163, v162
	v_max_f32_e32 v0, 0, v0
	v_add_f32_e32 v0, 0x3727c5ac, v0
	v_mul_f32_e32 v69, 0x4b800000, v0
	v_cmp_gt_f32_e32 vcc, s1, v0
	v_pk_add_f32 v[88:89], v[88:89], v[88:89] op_sel:[0,1] op_sel_hi:[1,0]
	v_pk_add_f32 v[78:79], v[78:79], v[78:79] op_sel:[0,1] op_sel_hi:[1,0]
	v_cndmask_b32_e32 v0, v0, v69, vcc
	v_rsq_f32_e32 v0, v0
	v_pk_add_f32 v[82:83], v[82:83], v[82:83] op_sel:[0,1] op_sel_hi:[1,0]
	s_waitcnt vmcnt(10)
	v_sub_f32_e32 v119, v119, v163
	v_sub_f32_e32 v118, v118, v163
	v_mul_f32_e32 v69, 0x45800000, v0
	v_cndmask_b32_e32 v162, v0, v69, vcc
	v_mov_b32_e32 v0, v88
	s_nop 1
	v_permlane16_swap_b32_e32 v88, v0
	v_add_f32_e32 v88, v88, v0
	v_mov_b32_e32 v0, v78
	s_nop 1
	v_permlane16_swap_b32_e32 v78, v0
	v_add_f32_e32 v83, v78, v0
	v_mov_b32_e32 v0, v82
	s_nop 1
	v_permlane16_swap_b32_e32 v82, v0
	v_add_f32_e32 v82, v82, v0
	v_ashrrev_i32_e32 v78, 8, v68
	v_lshlrev_b32_e32 v0, 6, v68
	v_sub_f32_e32 v69, v121, v163
	v_sub_f32_e32 v68, v120, v163
	v_pk_mul_f32 v[118:119], v[162:163], v[118:119] op_sel_hi:[0,1]
	v_pk_mul_f32 v[68:69], v[162:163], v[68:69] op_sel_hi:[0,1]
	s_waitcnt vmcnt(6)
	v_pk_fma_f32 v[68:69], v[128:129], v[68:69], v[136:137]
	v_pk_fma_f32 v[118:119], v[126:127], v[118:119], v[134:135]
	v_pk_mul_f32 v[68:69], v[68:69], s[16:17] op_sel_hi:[1,0]
	v_pk_mul_f32 v[118:119], v[118:119], s[16:17] op_sel_hi:[1,0]
	v_pk_fma_f32 v[64:65], v[64:65], 0.5, v[68:69] op_sel_hi:[1,0,1]
	v_pk_fma_f32 v[62:63], v[62:63], 0.5, v[118:119] op_sel_hi:[1,0,1]
	v_add_f32_e32 v69, v64, v65
	v_add_f32_e32 v68, v62, v63
	v_add_f32_e32 v68, v68, v69
	v_add_f32_e32 v118, 0, v68
	v_mul_f32_e32 v68, v63, v63
	v_mul_f32_e32 v69, v65, v65
	v_fmac_f32_e32 v68, v62, v62
	v_fmac_f32_e32 v69, v64, v64
	v_add_f32_e32 v119, v68, v69
	v_sub_f32_e32 v69, v117, v163
	v_sub_f32_e32 v68, v116, v163
	v_sub_f32_e32 v115, v115, v163
	v_sub_f32_e32 v114, v114, v163
	v_pk_mul_f32 v[114:115], v[162:163], v[114:115] op_sel_hi:[0,1]
	v_pk_mul_f32 v[68:69], v[162:163], v[68:69] op_sel_hi:[0,1]
	v_pk_fma_f32 v[68:69], v[124:125], v[68:69], v[132:133]
	v_pk_fma_f32 v[114:115], v[122:123], v[114:115], v[130:131]
	v_pk_mul_f32 v[68:69], v[68:69], s[16:17] op_sel_hi:[1,0]
	v_pk_mul_f32 v[114:115], v[114:115], s[16:17] op_sel_hi:[1,0]
	v_pk_fma_f32 v[60:61], v[60:61], 0.5, v[68:69] op_sel_hi:[1,0,1]
	v_pk_fma_f32 v[58:59], v[58:59], 0.5, v[114:115] op_sel_hi:[1,0,1]
	v_ashrrev_i32_e32 v79, 31, v78
	v_add_f32_e32 v68, v58, v59
	v_add_f32_e32 v69, v60, v61
	v_readlane_b32 s2, v253, 59
	v_lshlrev_b64 v[78:79], 19, v[78:79]
	s_movk_i32 s1, 0x33c0
	v_add_f32_e32 v68, v68, v69
	v_mul_f32_e32 v69, v59, v59
	v_readlane_b32 s3, v253, 60
	v_and_or_b32 v0, v0, s1, v196
	s_nop 0
	s_nop 1
	v_bfe_u32 v91, v227, 4, 2
	v_sub_u32_e32 v90, 0, v91
	v_lshlrev_b32_e32 v90, 4, v90
	v_ashrrev_i32_e32 v91, 31, v90
	v_lshl_add_u64 v[90:91], v[76:77], 0, v[90:91]
	v_permlane16_swap_b32_e32 v62, v58
	v_permlane16_swap_b32_e32 v63, v59
	v_permlane16_swap_b32_e32 v64, v60
	v_permlane16_swap_b32_e32 v65, v61
	v_permlane32_swap_b32_e32 v62, v58
	v_permlane32_swap_b32_e32 v63, v59
	v_permlane32_swap_b32_e32 v64, v60
	v_permlane32_swap_b32_e32 v65, v61
	global_store_dwordx4 v[90:91], v[62:65], off
	global_store_dwordx4 v[90:91], v[58:61], off offset:64
	s_nop 1
	v_permlane32_swap_b32_e32 v62, v58
	v_permlane32_swap_b32_e32 v63, v59
	v_permlane32_swap_b32_e32 v64, v60
	v_permlane32_swap_b32_e32 v65, v61
	v_permlane16_swap_b32_e32 v62, v58
	v_permlane16_swap_b32_e32 v63, v59
	v_permlane16_swap_b32_e32 v64, v60
	v_permlane16_swap_b32_e32 v65, v61
	v_fmac_f32_e32 v69, v58, v58
	v_cvt_pk_bf16_f32 v62, v62, v63
	v_cvt_pk_bf16_f32 v63, v64, v65
	v_cvt_pk_bf16_f32 v64, v58, v59
	v_lshl_add_u64 v[58:59], s[2:3], 0, v[78:79]
	v_mul_f32_e32 v114, v61, v61
	v_lshl_add_u64 v[78:79], v[58:59], 0, s[24:25]
	v_lshlrev_b32_e32 v0, 1, v0
	v_fmac_f32_e32 v114, v60, v60
	v_cvt_pk_bf16_f32 v65, v60, v61
	v_lshl_add_u64 v[60:61], v[78:79], 0, v[0:1]
	global_store_dwordx4 v[60:61], v[62:65], off
	s_waitcnt vmcnt(7)
	v_sub_f32_e32 v61, v101, v163
	v_sub_f32_e32 v60, v100, v163
	v_sub_f32_e32 v63, v99, v163
	v_sub_f32_e32 v62, v98, v163
	v_pk_mul_f32 v[62:63], v[162:163], v[62:63] op_sel_hi:[0,1]
	v_pk_mul_f32 v[60:61], v[162:163], v[60:61] op_sel_hi:[0,1]
	s_waitcnt vmcnt(3)
; __device__ __forceinline__ float xsum16(float v) { const auto r = __builtin_amdgcn_permlane16_swap(__float_as_uint(v), __float_as_uint(v), false, false); return __uint_as_float(r[0]) + __uint_as_float(r[1]); }
; __device__ __forceinline__ float xsum32(float v) { const auto r = __builtin_amdgcn_permlane32_swap(__float_as_uint(v), __float_as_uint(v), false, false); return __uint_as_float(r[0]) + __uint_as_float(r[1]); }
; __device__ __forceinline__ size_t blk_off(int r, int c, int K) { return (size_t)(r >> 8) * 256 * K + (size_t)(c >> 6) * (256 * 64) + (size_t)((r & 255) * 64 + (c & 63)); }
; __device__ __forceinline__ u32x4 pack8(const f32x4 a, const f32x4 b) { u32x4 w; w.x = cvt_pk_bf16(a[0], a[1]); w.y = cvt_pk_bf16(a[2], a[3]); w.z = cvt_pk_bf16(b[0], b[1]); w.w = cvt_pk_bf16(b[2], b[3]); return w; }
;     __device__ __forceinline__ void operator()(const f32x4 (&acc)[2][2][4][2], const pg8::Unit& u, int wr, int wc, int fr, int fq) const {
;     ...
;                     for (int n = 0; n < 2; ++n) { yv[bj][n] = *(const f32x4*)(Yin + (size_t)row * D_ + col0 + bj * 128 + 4 * n); gq[bj][n] = *(const f32x4*)(g + col0 + bj * 128 + 4 * n); bq_[bj][n] = *(const f32x4*)(b + col0 + bj * 128 + 4 * n); }
;                 asm volatile("" ::: "memory");
;                 float s1 = 0.f, s2 = 0.f;
; #pragma unroll
;                 for (int bj = 0; bj < 2; ++bj) { float* yp = Y + (size_t)row * D_ + col0 + bj * 128; f32x4 v[2];
; #pragma unroll
;                     for (int n = 0; n < 2; ++n) { v[n] = (((yv[bj][n] - mu) * rs) * gq[bj][n] + bq_[bj][n]) * ALPHA_ + acc[ai][bj][m][n] * sc;
;                         *(f32x4*)(yp + 4 * n) = v[n]; s1 += (v[n][0] + v[n][1]) + (v[n][2] + v[n][3]); s2 += (v[n][0] * v[n][0] + v[n][1] * v[n][1]) + (v[n][2] * v[n][2] + v[n][3] * v[n][3]); }
;                     *(u32x4*)(Yb + blk_off(row, col0 + bj * 128, D_)) = pack8(v[0], v[1]); }
;                 s1 = xsum32(xsum16(s1)); s2 = xsum32(xsum16(s2));
;                 if (fq == 0) *(f32x2*)(stn + (size_t)row * 32 + (u.pn * 4 + wc) * 2) = (f32x2){s1, s2}; asm volatile("" ::: "memory"); } }
	v_pk_fma_f32 v[60:61], v[108:109], v[60:61], v[160:161]
	v_pk_fma_f32 v[62:63], v[106:107], v[62:63], v[158:159]
	v_pk_mul_f32 v[60:61], v[60:61], s[16:17] op_sel_hi:[1,0]
	v_pk_mul_f32 v[62:63], v[62:63], s[16:17] op_sel_hi:[1,0]
	v_pk_fma_f32 v[56:57], v[56:57], 0.5, v[60:61] op_sel_hi:[1,0,1]
	v_pk_fma_f32 v[54:55], v[54:55], 0.5, v[62:63] op_sel_hi:[1,0,1]
	v_add_f32_e32 v61, v56, v57
	v_add_f32_e32 v60, v54, v55
	v_add_f32_e32 v68, v118, v68
	v_add_f32_e32 v60, v60, v61
	v_add_f32_e32 v64, v68, v60
	v_mul_f32_e32 v60, v55, v55
	v_mul_f32_e32 v61, v57, v57
	v_add_f32_e32 v69, v69, v114
	v_fmac_f32_e32 v60, v54, v54
	v_fmac_f32_e32 v61, v56, v56
	v_add_f32_e32 v69, v119, v69
	v_add_f32_e32 v60, v60, v61
	v_add_f32_e32 v65, v69, v60
	v_sub_f32_e32 v61, v95, v163
	v_sub_f32_e32 v60, v94, v163
	v_sub_f32_e32 v63, v93, v163
	v_sub_f32_e32 v62, v92, v163
	v_pk_mul_f32 v[62:63], v[162:163], v[62:63] op_sel_hi:[0,1]
	v_pk_mul_f32 v[60:61], v[162:163], v[60:61] op_sel_hi:[0,1]
	v_pk_fma_f32 v[60:61], v[104:105], v[60:61], v[112:113]
	v_pk_fma_f32 v[62:63], v[102:103], v[62:63], v[110:111]
	v_pk_mul_f32 v[60:61], v[60:61], s[16:17] op_sel_hi:[1,0]
	v_pk_mul_f32 v[62:63], v[62:63], s[16:17] op_sel_hi:[1,0]
	v_pk_fma_f32 v[52:53], v[52:53], 0.5, v[60:61] op_sel_hi:[1,0,1]
	v_pk_fma_f32 v[50:51], v[50:51], 0.5, v[62:63] op_sel_hi:[1,0,1]
	v_add_f32_e32 v61, v52, v53
	v_add_f32_e32 v60, v50, v51
	v_add_f32_e32 v60, v60, v61
	v_mul_f32_e32 v61, v51, v51
	v_mul_f32_e32 v62, v53, v53
	s_nop 0
	s_nop 1
	v_bfe_u32 v69, v227, 4, 2
	v_sub_u32_e32 v68, 0, v69
	v_lshlrev_b32_e32 v68, 4, v68
	v_ashrrev_i32_e32 v69, 31, v68
	v_lshl_add_u64 v[68:69], v[76:77], 0, v[68:69]
	v_permlane16_swap_b32_e32 v54, v50
	v_permlane16_swap_b32_e32 v55, v51
	v_permlane16_swap_b32_e32 v56, v52
	v_permlane16_swap_b32_e32 v57, v53
	v_permlane32_swap_b32_e32 v54, v50
	v_permlane32_swap_b32_e32 v55, v51
	v_permlane32_swap_b32_e32 v56, v52
	v_permlane32_swap_b32_e32 v57, v53
	global_store_dwordx4 v[68:69], v[54:57], off offset:512
	global_store_dwordx4 v[68:69], v[50:53], off offset:576
	s_nop 1
	v_permlane32_swap_b32_e32 v54, v50
	v_permlane32_swap_b32_e32 v55, v51
	v_permlane32_swap_b32_e32 v56, v52
	v_permlane32_swap_b32_e32 v57, v53
	v_permlane16_swap_b32_e32 v54, v50
	v_permlane16_swap_b32_e32 v55, v51
	v_permlane16_swap_b32_e32 v56, v52
	v_permlane16_swap_b32_e32 v57, v53
	v_add_f32_e32 v60, v64, v60
	v_fmac_f32_e32 v61, v50, v50
	v_fmac_f32_e32 v62, v52, v52
	v_lshl_add_u64 v[76:77], v[58:59], 0, s[44:45]
	v_add_f32_e32 v61, v61, v62
	v_cvt_pk_bf16_f32 v54, v54, v55
	v_cvt_pk_bf16_f32 v55, v56, v57
	v_cvt_pk_bf16_f32 v56, v50, v51
	v_lshl_add_u64 v[50:51], v[76:77], 0, v[0:1]
	v_mov_b32_e32 v0, v60
	v_pk_add_f32 v[70:71], v[70:71], v[70:71] op_sel:[0,1] op_sel_hi:[1,0]
	v_pk_add_f32 v[72:73], v[72:73], v[72:73] op_sel:[0,1] op_sel_hi:[1,0]
	v_pk_add_f32 v[84:85], v[84:85], v[84:85] op_sel:[0,1] op_sel_hi:[1,0]
	v_add_f32_e32 v61, v65, v61
	v_cvt_pk_bf16_f32 v57, v52, v53
	v_permlane16_swap_b32_e32 v60, v0
	v_mov_b32_e32 v71, v70
	v_mov_b32_e32 v73, v72
	v_mov_b32_e32 v85, v84
	global_store_dwordx4 v[50:51], v[54:57], off
	v_add_f32_e32 v50, v60, v0
	v_mov_b32_e32 v0, v61
	v_permlane16_swap_b32_e32 v70, v71
	v_permlane16_swap_b32_e32 v72, v73
	v_permlane16_swap_b32_e32 v84, v85
	v_permlane16_swap_b32_e32 v61, v0
	v_add_f32_e32 v71, v70, v71
	v_add_f32_e32 v70, v72, v73
	v_add_f32_e32 v89, v84, v85
	v_add_f32_e32 v51, v61, v0
	v_mov_b32_e32 v73, v71
	v_mov_b32_e32 v72, v70
	v_mov_b32_e32 v91, v89
	v_mov_b32_e32 v90, v88
	v_mov_b32_e32 v85, v83
	v_mov_b32_e32 v84, v82
	v_mov_b32_e32 v52, v50
	v_mov_b32_e32 v53, v51
	v_permlane32_swap_b32_e32 v71, v73
	v_permlane32_swap_b32_e32 v70, v72
	v_permlane32_swap_b32_e32 v89, v91
	v_permlane32_swap_b32_e32 v88, v90
	v_permlane32_swap_b32_e32 v83, v85
	v_permlane32_swap_b32_e32 v82, v84
	v_permlane32_swap_b32_e32 v50, v52
	v_permlane32_swap_b32_e32 v51, v53
	s_and_saveexec_b64 s[24:25], s[40:41]
	s_cbranch_execz .LBB0_1713
	v_pk_add_f32 v[50:51], v[50:51], v[52:53]
	v_lshl_add_u64 v[52:53], s[8:9], 0, v[66:67]
	v_lshl_add_u64 v[52:53], s[38:39], 2, v[52:53]
	global_store_dwordx2 v[52:53], v[50:51], off
.LBB0_1713:
	s_or_b64 exec, exec, s[24:25]
	v_pk_add_f32 v[50:51], v[70:71], v[72:73]
	s_mov_b32 s2, 0x3a800000
	v_pk_mul_f32 v[92:93], v[50:51], s[2:3] op_sel_hi:[1,0]
	s_mov_b32 s1, 0x800000
	v_fma_f32 v0, -v93, v93, v92
	v_max_f32_e32 v0, 0, v0
	v_add_f32_e32 v0, 0x3727c5ac, v0
	v_cmp_gt_f32_e32 vcc, s1, v0
	v_mul_f32_e32 v50, 0x4b800000, v0
	s_load_dwordx16 s[60:75], s[34:35], 0x38
	v_cndmask_b32_e32 v0, v0, v50, vcc
	v_rsq_f32_e32 v0, v0
	s_mov_b32 s2, 0x3fd744fd
	s_movk_i32 s1, 0x37c0
	v_mul_f32_e32 v50, 0x45800000, v0
	v_cndmask_b32_e32 v92, v0, v50, vcc
	v_lshlrev_b64 v[50:51], 12, v[96:97]
	s_waitcnt lgkmcnt(0)
	v_lshl_add_u64 v[50:51], s[74:75], 0, v[50:51]
	v_lshl_add_u64 v[94:95], v[152:153], 2, v[50:51]
	global_load_dwordx4 v[98:101], v[94:95], off offset:16 nt
	global_load_dwordx4 v[102:105], v[94:95], off nt
	global_load_dwordx4 v[106:109], v[156:157], off offset:16
	global_load_dwordx4 v[110:113], v[156:157], off
	global_load_dwordx4 v[114:117], v[154:155], off offset:16
	global_load_dwordx4 v[118:121], v[154:155], off
	global_load_dwordx4 v[50:53], v[94:95], off offset:528 nt
	global_load_dwordx4 v[70:73], v[94:95], off offset:512 nt
	global_load_dwordx4 v[54:57], v[156:157], off offset:528
	global_load_dwordx4 v[62:65], v[156:157], off offset:512
	global_load_dwordx4 v[58:61], v[154:155], off offset:528
	global_load_dwordx4 v[66:69], v[154:155], off offset:512
	v_lshlrev_b32_e32 v0, 6, v96
	v_and_or_b32 v0, v0, s1, v196
	v_lshlrev_b32_e32 v0, 1, v0
	s_waitcnt vmcnt(10)
; __device__ __forceinline__ float xsum16(float v) { const auto r = __builtin_amdgcn_permlane16_swap(__float_as_uint(v), __float_as_uint(v), false, false); return __uint_as_float(r[0]) + __uint_as_float(r[1]); }
; __device__ __forceinline__ float xsum32(float v) { const auto r = __builtin_amdgcn_permlane32_swap(__float_as_uint(v), __float_as_uint(v), false, false); return __uint_as_float(r[0]) + __uint_as_float(r[1]); }
; __device__ __forceinline__ size_t blk_off(int r, int c, int K) { return (size_t)(r >> 8) * 256 * K + (size_t)(c >> 6) * (256 * 64) + (size_t)((r & 255) * 64 + (c & 63)); }
; __device__ __forceinline__ u32x4 pack8(const f32x4 a, const f32x4 b) { u32x4 w; w.x = cvt_pk_bf16(a[0], a[1]); w.y = cvt_pk_bf16(a[2], a[3]); w.z = cvt_pk_bf16(b[0], b[1]); w.w = cvt_pk_bf16(b[2], b[3]); return w; }
;     __device__ __forceinline__ void operator()(const f32x4 (&acc)[2][2][4][2], const pg8::Unit& u, int wr, int wc, int fr, int fq) const {
;     ...
;                     for (int n = 0; n < 2; ++n) { yv[bj][n] = *(const f32x4*)(Yin + (size_t)row * D_ + col0 + bj * 128 + 4 * n); gq[bj][n] = *(const f32x4*)(g + col0 + bj * 128 + 4 * n); bq_[bj][n] = *(const f32x4*)(b + col0 + bj * 128 + 4 * n); }
;                 asm volatile("" ::: "memory");
;                 float s1 = 0.f, s2 = 0.f;
; #pragma unroll
;                 for (int bj = 0; bj < 2; ++bj) { float* yp = Y + (size_t)row * D_ + col0 + bj * 128; f32x4 v[2];
; #pragma unroll
;                     for (int n = 0; n < 2; ++n) { v[n] = (((yv[bj][n] - mu) * rs) * gq[bj][n] + bq_[bj][n]) * ALPHA_ + acc[ai][bj][m][n] * sc;
;                         *(f32x4*)(yp + 4 * n) = v[n]; s1 += (v[n][0] + v[n][1]) + (v[n][2] + v[n][3]); s2 += (v[n][0] * v[n][0] + v[n][1] * v[n][1]) + (v[n][2] * v[n][2] + v[n][3] * v[n][3]); }
;                     *(u32x4*)(Yb + blk_off(row, col0 + bj * 128, D_)) = pack8(v[0], v[1]); }
;                 s1 = xsum32(xsum16(s1)); s2 = xsum32(xsum16(s2));
;                 if (fq == 0) *(f32x2*)(stn + (size_t)row * 32 + (u.pn * 4 + wc) * 2) = (f32x2){s1, s2}; asm volatile("" ::: "memory"); } }
	v_sub_f32_e32 v97, v105, v93
	v_sub_f32_e32 v96, v104, v93
	v_sub_f32_e32 v103, v103, v93
	v_sub_f32_e32 v102, v102, v93
	v_pk_mul_f32 v[102:103], v[92:93], v[102:103] op_sel_hi:[0,1]
	v_pk_mul_f32 v[96:97], v[92:93], v[96:97] op_sel_hi:[0,1]
	s_waitcnt vmcnt(6)
	v_pk_fma_f32 v[96:97], v[112:113], v[96:97], v[120:121]
	v_pk_fma_f32 v[102:103], v[110:111], v[102:103], v[118:119]
	v_pk_mul_f32 v[96:97], v[96:97], s[2:3] op_sel_hi:[1,0]
	v_pk_mul_f32 v[102:103], v[102:103], s[2:3] op_sel_hi:[1,0]
	v_pk_fma_f32 v[104:105], v[48:49], 0.5, v[96:97] op_sel_hi:[1,0,1]
	v_pk_fma_f32 v[102:103], v[46:47], 0.5, v[102:103] op_sel_hi:[1,0,1]
	v_add_f32_e32 v47, v104, v105
	v_add_f32_e32 v46, v102, v103
	v_add_f32_e32 v46, v46, v47
	v_add_f32_e32 v110, 0, v46
	v_mul_f32_e32 v46, v103, v103
	v_mul_f32_e32 v47, v105, v105
	v_fmac_f32_e32 v46, v102, v102
	v_fmac_f32_e32 v47, v104, v104
	v_add_f32_e32 v111, v46, v47
	v_sub_f32_e32 v47, v101, v93
	v_sub_f32_e32 v46, v100, v93
	v_sub_f32_e32 v49, v99, v93
	v_sub_f32_e32 v48, v98, v93
	v_pk_mul_f32 v[48:49], v[92:93], v[48:49] op_sel_hi:[0,1]
	v_pk_mul_f32 v[46:47], v[92:93], v[46:47] op_sel_hi:[0,1]
	v_pk_fma_f32 v[46:47], v[108:109], v[46:47], v[116:117]
	v_pk_fma_f32 v[48:49], v[106:107], v[48:49], v[114:115]
	v_pk_mul_f32 v[46:47], v[46:47], s[2:3] op_sel_hi:[1,0]
	v_pk_mul_f32 v[48:49], v[48:49], s[2:3] op_sel_hi:[1,0]
	v_pk_fma_f32 v[98:99], v[44:45], 0.5, v[46:47] op_sel_hi:[1,0,1]
	v_pk_fma_f32 v[96:97], v[42:43], 0.5, v[48:49] op_sel_hi:[1,0,1]
	v_add_f32_e32 v43, v98, v99
	v_add_f32_e32 v42, v96, v97
	v_add_f32_e32 v42, v42, v43
	v_add_f32_e32 v47, v110, v42
	v_mul_f32_e32 v42, v97, v97
	v_mul_f32_e32 v43, v99, v99
	v_fmac_f32_e32 v42, v96, v96
	v_fmac_f32_e32 v43, v98, v98
	v_add_f32_e32 v42, v42, v43
	v_add_f32_e32 v46, v111, v42
	v_cvt_pk_bf16_f32 v42, v102, v103
	v_cvt_pk_bf16_f32 v43, v104, v105
	v_cvt_pk_bf16_f32 v44, v96, v97
	v_cvt_pk_bf16_f32 v45, v98, v99
	v_lshl_add_u64 v[48:49], v[78:79], 0, v[0:1]
	s_nop 0
	s_nop 1
	v_bfe_u32 v101, v227, 4, 2
	v_sub_u32_e32 v100, 0, v101
	v_lshlrev_b32_e32 v100, 4, v100
	v_ashrrev_i32_e32 v101, 31, v100
	v_lshl_add_u64 v[100:101], v[94:95], 0, v[100:101]
	v_permlane16_swap_b32_e32 v102, v96
	v_permlane16_swap_b32_e32 v103, v97
	v_permlane16_swap_b32_e32 v104, v98
	v_permlane16_swap_b32_e32 v105, v99
	v_permlane32_swap_b32_e32 v102, v96
	v_permlane32_swap_b32_e32 v103, v97
	v_permlane32_swap_b32_e32 v104, v98
	v_permlane32_swap_b32_e32 v105, v99
	global_store_dwordx4 v[100:101], v[102:105], off
	global_store_dwordx4 v[100:101], v[96:99], off offset:64
	s_nop 1
	v_permlane32_swap_b32_e32 v102, v96
	v_permlane32_swap_b32_e32 v103, v97
	v_permlane32_swap_b32_e32 v104, v98
	v_permlane32_swap_b32_e32 v105, v99
	v_permlane16_swap_b32_e32 v102, v96
	v_permlane16_swap_b32_e32 v103, v97
	v_permlane16_swap_b32_e32 v104, v98
	v_permlane16_swap_b32_e32 v105, v99
	global_store_dwordx4 v[48:49], v[42:45], off
	s_waitcnt vmcnt(7)
	s_nop 0
	v_sub_f32_e32 v43, v73, v93
	v_sub_f32_e32 v42, v72, v93
	v_sub_f32_e32 v45, v71, v93
	v_sub_f32_e32 v44, v70, v93
	v_pk_mul_f32 v[44:45], v[92:93], v[44:45] op_sel_hi:[0,1]
	v_pk_mul_f32 v[42:43], v[92:93], v[42:43] op_sel_hi:[0,1]
	s_waitcnt vmcnt(3)
	v_pk_fma_f32 v[42:43], v[64:65], v[42:43], v[68:69]
	v_pk_fma_f32 v[44:45], v[62:63], v[44:45], v[66:67]
	v_pk_mul_f32 v[42:43], v[42:43], s[2:3] op_sel_hi:[1,0]
	v_pk_mul_f32 v[44:45], v[44:45], s[2:3] op_sel_hi:[1,0]
	v_pk_fma_f32 v[40:41], v[40:41], 0.5, v[42:43] op_sel_hi:[1,0,1]
	v_pk_fma_f32 v[38:39], v[38:39], 0.5, v[44:45] op_sel_hi:[1,0,1]
	v_add_f32_e32 v43, v40, v41
	v_add_f32_e32 v42, v38, v39
	v_add_f32_e32 v42, v42, v43
	v_add_f32_e32 v47, v47, v42
	v_mul_f32_e32 v42, v39, v39
	v_mul_f32_e32 v43, v41, v41
	v_fmac_f32_e32 v42, v38, v38
	v_fmac_f32_e32 v43, v40, v40
	v_add_f32_e32 v42, v42, v43
	v_add_f32_e32 v46, v46, v42
	v_sub_f32_e32 v43, v53, v93
	v_sub_f32_e32 v42, v52, v93
	v_sub_f32_e32 v45, v51, v93
	v_sub_f32_e32 v44, v50, v93
	v_pk_mul_f32 v[44:45], v[92:93], v[44:45] op_sel_hi:[0,1]
	v_pk_mul_f32 v[42:43], v[92:93], v[42:43] op_sel_hi:[0,1]
	v_pk_fma_f32 v[42:43], v[56:57], v[42:43], v[60:61]
	v_pk_fma_f32 v[44:45], v[54:55], v[44:45], v[58:59]
	v_pk_mul_f32 v[42:43], v[42:43], s[2:3] op_sel_hi:[1,0]
	v_pk_mul_f32 v[44:45], v[44:45], s[2:3] op_sel_hi:[1,0]
	v_pk_fma_f32 v[36:37], v[36:37], 0.5, v[42:43] op_sel_hi:[1,0,1]
	v_pk_fma_f32 v[34:35], v[34:35], 0.5, v[44:45] op_sel_hi:[1,0,1]
	v_add_f32_e32 v43, v36, v37
	v_add_f32_e32 v42, v34, v35
	v_add_f32_e32 v42, v42, v43
	v_mul_f32_e32 v43, v35, v35
	v_mul_f32_e32 v44, v37, v37
	v_add_f32_e32 v42, v47, v42
	v_fmac_f32_e32 v43, v34, v34
	v_fmac_f32_e32 v44, v36, v36
	s_nop 0
	s_nop 1
	v_bfe_u32 v49, v227, 4, 2
	v_sub_u32_e32 v48, 0, v49
	v_lshlrev_b32_e32 v48, 4, v48
	v_ashrrev_i32_e32 v49, 31, v48
	v_lshl_add_u64 v[48:49], v[94:95], 0, v[48:49]
	v_permlane16_swap_b32_e32 v38, v34
	v_permlane16_swap_b32_e32 v39, v35
	v_permlane16_swap_b32_e32 v40, v36
	v_permlane16_swap_b32_e32 v41, v37
	v_permlane32_swap_b32_e32 v38, v34
	v_permlane32_swap_b32_e32 v39, v35
	v_permlane32_swap_b32_e32 v40, v36
	v_permlane32_swap_b32_e32 v41, v37
	global_store_dwordx4 v[48:49], v[38:41], off offset:512
	global_store_dwordx4 v[48:49], v[34:37], off offset:576
	s_nop 1
	v_permlane32_swap_b32_e32 v38, v34
	v_permlane32_swap_b32_e32 v39, v35
	v_permlane32_swap_b32_e32 v40, v36
	v_permlane32_swap_b32_e32 v41, v37
	v_permlane16_swap_b32_e32 v38, v34
	v_permlane16_swap_b32_e32 v39, v35
	v_permlane16_swap_b32_e32 v40, v36
	v_permlane16_swap_b32_e32 v41, v37
	v_add_f32_e32 v43, v43, v44
	v_cvt_pk_bf16_f32 v38, v38, v39
	v_cvt_pk_bf16_f32 v39, v40, v41
	v_cvt_pk_bf16_f32 v40, v34, v35
	v_lshl_add_u64 v[34:35], v[76:77], 0, v[0:1]
	v_mov_b32_e32 v0, v42
	v_add_f32_e32 v43, v46, v43
	v_cvt_pk_bf16_f32 v41, v36, v37
	v_permlane16_swap_b32_e32 v42, v0
	global_store_dwordx4 v[34:35], v[38:41], off
	v_add_f32_e32 v34, v42, v0
	v_mov_b32_e32 v0, v43
	s_nop 1
	v_permlane16_swap_b32_e32 v43, v0
	v_add_f32_e32 v35, v43, v0
	v_mov_b32_e32 v36, v34
	v_mov_b32_e32 v37, v35
	s_nop 0
	v_permlane32_swap_b32_e32 v34, v36
	v_permlane32_swap_b32_e32 v35, v37
	s_and_saveexec_b64 s[24:25], s[40:41]
	s_cbranch_execz .LBB0_1715
	v_pk_add_f32 v[34:35], v[34:35], v[36:37]
	v_lshl_add_u64 v[36:37], s[8:9], 0, v[86:87]
	v_lshl_add_u64 v[36:37], s[38:39], 2, v[36:37]
	global_store_dwordx2 v[36:37], v[34:35], off
;     __device__ __forceinline__ void operator()(const f32x4 (&acc)[2][2][4][2], const pg8::Unit& u, int wr, int wc, int fr, int fq) const {
;     ...
;             for (int m = 0; m < 4; ++m) { const int row = row0 + ai * 128 + m * 16; const float mu = mu4[m], rs = rs4[m];
;                 f32x4 yv[2][2], gq[2][2], bq_[2][2];
; #pragma unroll
;                 for (int bj = 0; bj < 2; ++bj)
; #pragma unroll
;                     for (int n = 0; n < 2; ++n) { yv[bj][n] = *(const f32x4*)(Yin + (size_t)row * D_ + col0 + bj * 128 + 4 * n); gq[bj][n] = *(const f32x4*)(g + col0 + bj * 128 + 4 * n); bq_[bj][n] = *(const f32x4*)(b + col0 + bj * 128 + 4 * n); }
;                 asm volatile("" ::: "memory");
;                 float s1 = 0.f, s2 = 0.f;
; #pragma unroll
;                 for (int bj = 0; bj < 2; ++bj) { float* yp = Y + (size_t)row * D_ + col0 + bj * 128; f32x4 v[2];
; #pragma unroll
;                     for (int n = 0; n < 2; ++n) { v[n] = (((yv[bj][n] - mu) * rs) * gq[bj][n] + bq_[bj][n]) * ALPHA_ + acc[ai][bj][m][n] * sc;
;                         *(f32x4*)(yp + 4 * n) = v[n]; s1 += (v[n][0] + v[n][1]) + (v[n][2] + v[n][3]); s2 += (v[n][0] * v[n][0] + v[n][1] * v[n][1]) + (v[n][2] * v[n][2] + v[n][3] * v[n][3]); }
.LBB0_1715:
	s_or_b64 exec, exec, s[24:25]
	v_pk_add_f32 v[34:35], v[88:89], v[90:91]
	s_mov_b32 s2, 0x3a800000
	v_pk_mul_f32 v[58:59], v[34:35], s[2:3] op_sel_hi:[1,0]
	s_mov_b32 s1, 0x800000
	v_fma_f32 v0, -v59, v59, v58
	v_max_f32_e32 v0, 0, v0
	v_add_f32_e32 v0, 0x3727c5ac, v0
	v_cmp_gt_f32_e32 vcc, s1, v0
	v_mul_f32_e32 v34, 0x4b800000, v0
	s_load_dwordx16 s[60:75], s[34:35], 0x38
	v_cndmask_b32_e32 v0, v0, v34, vcc
	v_rsq_f32_e32 v0, v0
	s_mov_b32 s2, 0x3fd744fd
	s_movk_i32 s1, 0x3bc0
	v_mul_f32_e32 v34, 0x45800000, v0
	v_cndmask_b32_e32 v58, v0, v34, vcc
	v_lshlrev_b64 v[34:35], 12, v[80:81]
	s_waitcnt lgkmcnt(0)
	v_lshl_add_u64 v[34:35], s[74:75], 0, v[34:35]
	v_lshl_add_u64 v[60:61], v[152:153], 2, v[34:35]
	global_load_dwordx4 v[62:65], v[60:61], off offset:16 nt
	global_load_dwordx4 v[66:69], v[60:61], off nt
	global_load_dwordx4 v[70:73], v[156:157], off offset:16
	global_load_dwordx4 v[86:89], v[156:157], off
	global_load_dwordx4 v[90:93], v[154:155], off offset:16
	global_load_dwordx4 v[94:97], v[154:155], off
	global_load_dwordx4 v[34:37], v[60:61], off offset:528 nt
	global_load_dwordx4 v[54:57], v[60:61], off offset:512 nt
	global_load_dwordx4 v[38:41], v[156:157], off offset:528
	global_load_dwordx4 v[46:49], v[156:157], off offset:512
	global_load_dwordx4 v[42:45], v[154:155], off offset:528
	global_load_dwordx4 v[50:53], v[154:155], off offset:512
	v_lshlrev_b32_e32 v0, 6, v80
	v_and_or_b32 v0, v0, s1, v196
	v_lshlrev_b32_e32 v0, 1, v0
	s_waitcnt vmcnt(10)
	v_sub_f32_e32 v69, v69, v59
	v_sub_f32_e32 v68, v68, v59
	v_sub_f32_e32 v67, v67, v59
	v_sub_f32_e32 v66, v66, v59
	v_pk_mul_f32 v[66:67], v[58:59], v[66:67] op_sel_hi:[0,1]
	v_pk_mul_f32 v[68:69], v[58:59], v[68:69] op_sel_hi:[0,1]
	s_waitcnt vmcnt(6)
	v_pk_fma_f32 v[68:69], v[88:89], v[68:69], v[96:97]
	v_pk_fma_f32 v[66:67], v[86:87], v[66:67], v[94:95]
	v_pk_mul_f32 v[68:69], v[68:69], s[2:3] op_sel_hi:[1,0]
	v_pk_mul_f32 v[66:67], v[66:67], s[2:3] op_sel_hi:[1,0]
	v_pk_fma_f32 v[68:69], v[32:33], 0.5, v[68:69] op_sel_hi:[1,0,1]
	v_pk_fma_f32 v[66:67], v[30:31], 0.5, v[66:67] op_sel_hi:[1,0,1]
	v_add_f32_e32 v31, v68, v69
	v_add_f32_e32 v30, v66, v67
	v_add_f32_e32 v30, v30, v31
	v_add_f32_e32 v86, 0, v30
	v_mul_f32_e32 v30, v67, v67
	v_mul_f32_e32 v31, v69, v69
	v_fmac_f32_e32 v30, v66, v66
	v_fmac_f32_e32 v31, v68, v68
	v_add_f32_e32 v87, v30, v31
	v_sub_f32_e32 v31, v65, v59
	v_sub_f32_e32 v30, v64, v59
	v_sub_f32_e32 v33, v63, v59
	v_sub_f32_e32 v32, v62, v59
	v_pk_mul_f32 v[32:33], v[58:59], v[32:33] op_sel_hi:[0,1]
	v_pk_mul_f32 v[30:31], v[58:59], v[30:31] op_sel_hi:[0,1]
	v_pk_fma_f32 v[30:31], v[72:73], v[30:31], v[92:93]
	v_pk_fma_f32 v[32:33], v[70:71], v[32:33], v[90:91]
	v_pk_mul_f32 v[30:31], v[30:31], s[2:3] op_sel_hi:[1,0]
	v_pk_mul_f32 v[32:33], v[32:33], s[2:3] op_sel_hi:[1,0]
	v_pk_fma_f32 v[64:65], v[28:29], 0.5, v[30:31] op_sel_hi:[1,0,1]
	v_pk_fma_f32 v[62:63], v[26:27], 0.5, v[32:33] op_sel_hi:[1,0,1]
	v_add_f32_e32 v27, v64, v65
	v_add_f32_e32 v26, v62, v63
	v_add_f32_e32 v26, v26, v27
	v_add_f32_e32 v31, v86, v26
	v_mul_f32_e32 v26, v63, v63
	v_mul_f32_e32 v27, v65, v65
	v_fmac_f32_e32 v26, v62, v62
	v_fmac_f32_e32 v27, v64, v64
	v_add_f32_e32 v26, v26, v27
	v_add_f32_e32 v30, v87, v26
	v_cvt_pk_bf16_f32 v26, v66, v67
	v_cvt_pk_bf16_f32 v27, v68, v69
	v_cvt_pk_bf16_f32 v28, v62, v63
	v_cvt_pk_bf16_f32 v29, v64, v65
	v_lshl_add_u64 v[32:33], v[78:79], 0, v[0:1]
	s_nop 0
	s_nop 1
	v_bfe_u32 v71, v227, 4, 2
	v_sub_u32_e32 v70, 0, v71
	v_lshlrev_b32_e32 v70, 4, v70
	v_ashrrev_i32_e32 v71, 31, v70
	v_lshl_add_u64 v[70:71], v[60:61], 0, v[70:71]
	v_permlane16_swap_b32_e32 v66, v62
	v_permlane16_swap_b32_e32 v67, v63
	v_permlane16_swap_b32_e32 v68, v64
	v_permlane16_swap_b32_e32 v69, v65
	v_permlane32_swap_b32_e32 v66, v62
	v_permlane32_swap_b32_e32 v67, v63
	v_permlane32_swap_b32_e32 v68, v64
	v_permlane32_swap_b32_e32 v69, v65
	global_store_dwordx4 v[70:71], v[66:69], off
	global_store_dwordx4 v[70:71], v[62:65], off offset:64
	s_nop 1
	v_permlane32_swap_b32_e32 v66, v62
	v_permlane32_swap_b32_e32 v67, v63
	v_permlane32_swap_b32_e32 v68, v64
	v_permlane32_swap_b32_e32 v69, v65
	v_permlane16_swap_b32_e32 v66, v62
	v_permlane16_swap_b32_e32 v67, v63
	v_permlane16_swap_b32_e32 v68, v64
	v_permlane16_swap_b32_e32 v69, v65
	global_store_dwordx4 v[32:33], v[26:29], off
	s_waitcnt vmcnt(7)
	s_nop 0
	v_sub_f32_e32 v27, v57, v59
	v_sub_f32_e32 v26, v56, v59
	v_sub_f32_e32 v29, v55, v59
	v_sub_f32_e32 v28, v54, v59
	v_pk_mul_f32 v[28:29], v[58:59], v[28:29] op_sel_hi:[0,1]
	v_pk_mul_f32 v[26:27], v[58:59], v[26:27] op_sel_hi:[0,1]
	s_waitcnt vmcnt(3)
; __device__ __forceinline__ float xsum16(float v) { const auto r = __builtin_amdgcn_permlane16_swap(__float_as_uint(v), __float_as_uint(v), false, false); return __uint_as_float(r[0]) + __uint_as_float(r[1]); }
; __device__ __forceinline__ float xsum32(float v) { const auto r = __builtin_amdgcn_permlane32_swap(__float_as_uint(v), __float_as_uint(v), false, false); return __uint_as_float(r[0]) + __uint_as_float(r[1]); }
; __device__ __forceinline__ size_t blk_off(int r, int c, int K) { return (size_t)(r >> 8) * 256 * K + (size_t)(c >> 6) * (256 * 64) + (size_t)((r & 255) * 64 + (c & 63)); }
; __device__ __forceinline__ u32x4 pack8(const f32x4 a, const f32x4 b) { u32x4 w; w.x = cvt_pk_bf16(a[0], a[1]); w.y = cvt_pk_bf16(a[2], a[3]); w.z = cvt_pk_bf16(b[0], b[1]); w.w = cvt_pk_bf16(b[2], b[3]); return w; }
;     __device__ __forceinline__ void operator()(const f32x4 (&acc)[2][2][4][2], const pg8::Unit& u, int wr, int wc, int fr, int fq) const {
;     ...
;                     for (int n = 0; n < 2; ++n) { yv[bj][n] = *(const f32x4*)(Yin + (size_t)row * D_ + col0 + bj * 128 + 4 * n); gq[bj][n] = *(const f32x4*)(g + col0 + bj * 128 + 4 * n); bq_[bj][n] = *(const f32x4*)(b + col0 + bj * 128 + 4 * n); }
;                 asm volatile("" ::: "memory");
;                 float s1 = 0.f, s2 = 0.f;
; #pragma unroll
;                 for (int bj = 0; bj < 2; ++bj) { float* yp = Y + (size_t)row * D_ + col0 + bj * 128; f32x4 v[2];
; #pragma unroll
;                     for (int n = 0; n < 2; ++n) { v[n] = (((yv[bj][n] - mu) * rs) * gq[bj][n] + bq_[bj][n]) * ALPHA_ + acc[ai][bj][m][n] * sc;
;                         *(f32x4*)(yp + 4 * n) = v[n]; s1 += (v[n][0] + v[n][1]) + (v[n][2] + v[n][3]); s2 += (v[n][0] * v[n][0] + v[n][1] * v[n][1]) + (v[n][2] * v[n][2] + v[n][3] * v[n][3]); }
;                     *(u32x4*)(Yb + blk_off(row, col0 + bj * 128, D_)) = pack8(v[0], v[1]); }
;                 s1 = xsum32(xsum16(s1)); s2 = xsum32(xsum16(s2));
;                 if (fq == 0) *(f32x2*)(stn + (size_t)row * 32 + (u.pn * 4 + wc) * 2) = (f32x2){s1, s2}; asm volatile("" ::: "memory"); } }
	v_pk_fma_f32 v[26:27], v[48:49], v[26:27], v[52:53]
	v_pk_fma_f32 v[28:29], v[46:47], v[28:29], v[50:51]
	v_pk_mul_f32 v[26:27], v[26:27], s[2:3] op_sel_hi:[1,0]
	v_pk_mul_f32 v[28:29], v[28:29], s[2:3] op_sel_hi:[1,0]
	v_pk_fma_f32 v[24:25], v[24:25], 0.5, v[26:27] op_sel_hi:[1,0,1]
	v_pk_fma_f32 v[22:23], v[22:23], 0.5, v[28:29] op_sel_hi:[1,0,1]
	v_add_f32_e32 v27, v24, v25
	v_add_f32_e32 v26, v22, v23
	v_add_f32_e32 v26, v26, v27
	v_add_f32_e32 v31, v31, v26
	v_mul_f32_e32 v26, v23, v23
	v_mul_f32_e32 v27, v25, v25
	v_fmac_f32_e32 v26, v22, v22
	v_fmac_f32_e32 v27, v24, v24
	v_add_f32_e32 v26, v26, v27
	v_add_f32_e32 v30, v30, v26
	v_sub_f32_e32 v27, v37, v59
	v_sub_f32_e32 v26, v36, v59
	v_sub_f32_e32 v29, v35, v59
	v_sub_f32_e32 v28, v34, v59
	v_pk_mul_f32 v[28:29], v[58:59], v[28:29] op_sel_hi:[0,1]
	v_pk_mul_f32 v[26:27], v[58:59], v[26:27] op_sel_hi:[0,1]
	v_pk_fma_f32 v[26:27], v[40:41], v[26:27], v[44:45]
	v_pk_fma_f32 v[28:29], v[38:39], v[28:29], v[42:43]
	v_pk_mul_f32 v[26:27], v[26:27], s[2:3] op_sel_hi:[1,0]
	v_pk_mul_f32 v[28:29], v[28:29], s[2:3] op_sel_hi:[1,0]
	v_pk_fma_f32 v[20:21], v[20:21], 0.5, v[26:27] op_sel_hi:[1,0,1]
	v_pk_fma_f32 v[18:19], v[18:19], 0.5, v[28:29] op_sel_hi:[1,0,1]
	v_add_f32_e32 v27, v20, v21
	v_add_f32_e32 v26, v18, v19
	v_add_f32_e32 v26, v26, v27
	v_mul_f32_e32 v27, v19, v19
	v_mul_f32_e32 v28, v21, v21
	v_add_f32_e32 v26, v31, v26
	v_fmac_f32_e32 v27, v18, v18
	v_fmac_f32_e32 v28, v20, v20
	s_nop 0
	s_nop 1
	v_bfe_u32 v33, v227, 4, 2
	v_sub_u32_e32 v32, 0, v33
	v_lshlrev_b32_e32 v32, 4, v32
	v_ashrrev_i32_e32 v33, 31, v32
	v_lshl_add_u64 v[32:33], v[60:61], 0, v[32:33]
	v_permlane16_swap_b32_e32 v22, v18
	v_permlane16_swap_b32_e32 v23, v19
	v_permlane16_swap_b32_e32 v24, v20
	v_permlane16_swap_b32_e32 v25, v21
	v_permlane32_swap_b32_e32 v22, v18
	v_permlane32_swap_b32_e32 v23, v19
	v_permlane32_swap_b32_e32 v24, v20
	v_permlane32_swap_b32_e32 v25, v21
	global_store_dwordx4 v[32:33], v[22:25], off offset:512
	global_store_dwordx4 v[32:33], v[18:21], off offset:576
	s_nop 1
	v_permlane32_swap_b32_e32 v22, v18
	v_permlane32_swap_b32_e32 v23, v19
	v_permlane32_swap_b32_e32 v24, v20
	v_permlane32_swap_b32_e32 v25, v21
	v_permlane16_swap_b32_e32 v22, v18
	v_permlane16_swap_b32_e32 v23, v19
	v_permlane16_swap_b32_e32 v24, v20
	v_permlane16_swap_b32_e32 v25, v21
	v_add_f32_e32 v27, v27, v28
	v_cvt_pk_bf16_f32 v22, v22, v23
	v_cvt_pk_bf16_f32 v23, v24, v25
	v_cvt_pk_bf16_f32 v24, v18, v19
	v_lshl_add_u64 v[18:19], v[76:77], 0, v[0:1]
	v_mov_b32_e32 v0, v26
	v_add_f32_e32 v27, v30, v27
	v_cvt_pk_bf16_f32 v25, v20, v21
	v_permlane16_swap_b32_e32 v26, v0
	global_store_dwordx4 v[18:19], v[22:25], off
	v_add_f32_e32 v18, v26, v0
	v_mov_b32_e32 v0, v27
	s_nop 1
	v_permlane16_swap_b32_e32 v27, v0
	v_add_f32_e32 v19, v27, v0
	v_mov_b32_e32 v20, v18
	v_mov_b32_e32 v21, v19
	s_nop 0
	v_permlane32_swap_b32_e32 v18, v20
	v_permlane32_swap_b32_e32 v19, v21
	s_and_saveexec_b64 s[24:25], s[40:41]
	s_cbranch_execz .LBB0_1717
	v_pk_add_f32 v[18:19], v[18:19], v[20:21]
	v_lshlrev_b64 v[20:21], 7, v[80:81]
	v_lshl_add_u64 v[20:21], s[8:9], 0, v[20:21]
	v_lshl_add_u64 v[20:21], s[38:39], 2, v[20:21]
	global_store_dwordx2 v[20:21], v[18:19], off
.LBB0_1717:
	s_or_b64 exec, exec, s[24:25]
	v_pk_add_f32 v[18:19], v[82:83], v[84:85]
	s_mov_b32 s2, 0x3a800000
	v_pk_mul_f32 v[42:43], v[18:19], s[2:3] op_sel_hi:[1,0]
	s_mov_b32 s1, 0x800000
	v_fma_f32 v0, -v43, v43, v42
	v_max_f32_e32 v0, 0, v0
	v_add_f32_e32 v0, 0x3727c5ac, v0
	v_cmp_gt_f32_e32 vcc, s1, v0
	v_mul_f32_e32 v18, 0x4b800000, v0
	s_load_dwordx16 s[60:75], s[34:35], 0x38
	v_cndmask_b32_e32 v0, v0, v18, vcc
	v_rsq_f32_e32 v0, v0
	s_mov_b32 s2, 0x3fd744fd
	s_movk_i32 s1, 0x3fc0
	v_mul_f32_e32 v18, 0x45800000, v0
	v_cndmask_b32_e32 v42, v0, v18, vcc
	v_lshlrev_b64 v[18:19], 12, v[74:75]
	s_waitcnt lgkmcnt(0)
	v_lshl_add_u64 v[18:19], s[74:75], 0, v[18:19]
	v_lshl_add_u64 v[44:45], v[152:153], 2, v[18:19]
	global_load_dwordx4 v[46:49], v[44:45], off offset:16 nt
	global_load_dwordx4 v[50:53], v[44:45], off nt
	global_load_dwordx4 v[54:57], v[156:157], off offset:16
	global_load_dwordx4 v[58:61], v[156:157], off
	global_load_dwordx4 v[62:65], v[154:155], off offset:16
	global_load_dwordx4 v[66:69], v[154:155], off
	global_load_dwordx4 v[18:21], v[44:45], off offset:528 nt
	global_load_dwordx4 v[38:41], v[44:45], off offset:512 nt
	global_load_dwordx4 v[22:25], v[156:157], off offset:528
	global_load_dwordx4 v[30:33], v[156:157], off offset:512
	global_load_dwordx4 v[26:29], v[154:155], off offset:528
	global_load_dwordx4 v[34:37], v[154:155], off offset:512
	v_lshlrev_b32_e32 v0, 6, v74
	v_and_or_b32 v0, v0, s1, v196
	v_lshlrev_b32_e32 v0, 1, v0
	s_waitcnt vmcnt(10)
	v_sub_f32_e32 v53, v53, v43
	v_sub_f32_e32 v52, v52, v43
	v_sub_f32_e32 v51, v51, v43
	v_sub_f32_e32 v50, v50, v43
	v_pk_mul_f32 v[50:51], v[42:43], v[50:51] op_sel_hi:[0,1]
	v_pk_mul_f32 v[52:53], v[42:43], v[52:53] op_sel_hi:[0,1]
	s_waitcnt vmcnt(6)
; __device__ __forceinline__ float xsum16(float v) { const auto r = __builtin_amdgcn_permlane16_swap(__float_as_uint(v), __float_as_uint(v), false, false); return __uint_as_float(r[0]) + __uint_as_float(r[1]); }
; __device__ __forceinline__ float xsum32(float v) { const auto r = __builtin_amdgcn_permlane32_swap(__float_as_uint(v), __float_as_uint(v), false, false); return __uint_as_float(r[0]) + __uint_as_float(r[1]); }
; __device__ __forceinline__ size_t blk_off(int r, int c, int K) { return (size_t)(r >> 8) * 256 * K + (size_t)(c >> 6) * (256 * 64) + (size_t)((r & 255) * 64 + (c & 63)); }
; __device__ __forceinline__ u32x4 pack8(const f32x4 a, const f32x4 b) { u32x4 w; w.x = cvt_pk_bf16(a[0], a[1]); w.y = cvt_pk_bf16(a[2], a[3]); w.z = cvt_pk_bf16(b[0], b[1]); w.w = cvt_pk_bf16(b[2], b[3]); return w; }
;     __device__ __forceinline__ void operator()(const f32x4 (&acc)[2][2][4][2], const pg8::Unit& u, int wr, int wc, int fr, int fq) const {
;     ...
;                     for (int n = 0; n < 2; ++n) { yv[bj][n] = *(const f32x4*)(Yin + (size_t)row * D_ + col0 + bj * 128 + 4 * n); gq[bj][n] = *(const f32x4*)(g + col0 + bj * 128 + 4 * n); bq_[bj][n] = *(const f32x4*)(b + col0 + bj * 128 + 4 * n); }
;                 asm volatile("" ::: "memory");
;                 float s1 = 0.f, s2 = 0.f;
; #pragma unroll
;                 for (int bj = 0; bj < 2; ++bj) { float* yp = Y + (size_t)row * D_ + col0 + bj * 128; f32x4 v[2];
; #pragma unroll
;                     for (int n = 0; n < 2; ++n) { v[n] = (((yv[bj][n] - mu) * rs) * gq[bj][n] + bq_[bj][n]) * ALPHA_ + acc[ai][bj][m][n] * sc;
;                         *(f32x4*)(yp + 4 * n) = v[n]; s1 += (v[n][0] + v[n][1]) + (v[n][2] + v[n][3]); s2 += (v[n][0] * v[n][0] + v[n][1] * v[n][1]) + (v[n][2] * v[n][2] + v[n][3] * v[n][3]); }
;                     *(u32x4*)(Yb + blk_off(row, col0 + bj * 128, D_)) = pack8(v[0], v[1]); }
;                 s1 = xsum32(xsum16(s1)); s2 = xsum32(xsum16(s2));
;                 if (fq == 0) *(f32x2*)(stn + (size_t)row * 32 + (u.pn * 4 + wc) * 2) = (f32x2){s1, s2}; asm volatile("" ::: "memory"); } }
	v_pk_fma_f32 v[52:53], v[60:61], v[52:53], v[68:69]
	v_pk_fma_f32 v[50:51], v[58:59], v[50:51], v[66:67]
	v_pk_mul_f32 v[52:53], v[52:53], s[2:3] op_sel_hi:[1,0]
	v_pk_mul_f32 v[50:51], v[50:51], s[2:3] op_sel_hi:[1,0]
	v_pk_fma_f32 v[52:53], v[16:17], 0.5, v[52:53] op_sel_hi:[1,0,1]
	v_pk_fma_f32 v[50:51], v[14:15], 0.5, v[50:51] op_sel_hi:[1,0,1]
	v_add_f32_e32 v15, v52, v53
	v_add_f32_e32 v14, v50, v51
	v_add_f32_e32 v14, v14, v15
	v_add_f32_e32 v58, 0, v14
	v_mul_f32_e32 v14, v51, v51
	v_mul_f32_e32 v15, v53, v53
	v_fmac_f32_e32 v14, v50, v50
	v_fmac_f32_e32 v15, v52, v52
	v_add_f32_e32 v59, v14, v15
	v_sub_f32_e32 v15, v49, v43
	v_sub_f32_e32 v14, v48, v43
	v_sub_f32_e32 v17, v47, v43
	v_sub_f32_e32 v16, v46, v43
	v_pk_mul_f32 v[16:17], v[42:43], v[16:17] op_sel_hi:[0,1]
	v_pk_mul_f32 v[14:15], v[42:43], v[14:15] op_sel_hi:[0,1]
	v_pk_fma_f32 v[14:15], v[56:57], v[14:15], v[64:65]
	v_pk_fma_f32 v[16:17], v[54:55], v[16:17], v[62:63]
	v_pk_mul_f32 v[14:15], v[14:15], s[2:3] op_sel_hi:[1,0]
	v_pk_mul_f32 v[16:17], v[16:17], s[2:3] op_sel_hi:[1,0]
	v_pk_fma_f32 v[48:49], v[12:13], 0.5, v[14:15] op_sel_hi:[1,0,1]
	v_pk_fma_f32 v[46:47], v[10:11], 0.5, v[16:17] op_sel_hi:[1,0,1]
	v_add_f32_e32 v11, v48, v49
	v_add_f32_e32 v10, v46, v47
	v_add_f32_e32 v10, v10, v11
	v_add_f32_e32 v15, v58, v10
	v_mul_f32_e32 v10, v47, v47
	v_mul_f32_e32 v11, v49, v49
	v_fmac_f32_e32 v10, v46, v46
	v_fmac_f32_e32 v11, v48, v48
	v_add_f32_e32 v10, v10, v11
	v_add_f32_e32 v14, v59, v10
	v_cvt_pk_bf16_f32 v10, v50, v51
	v_cvt_pk_bf16_f32 v11, v52, v53
	v_cvt_pk_bf16_f32 v12, v46, v47
	v_cvt_pk_bf16_f32 v13, v48, v49
	v_lshl_add_u64 v[16:17], v[78:79], 0, v[0:1]
	s_nop 0
	s_nop 1
	v_bfe_u32 v55, v227, 4, 2
	v_sub_u32_e32 v54, 0, v55
	v_lshlrev_b32_e32 v54, 4, v54
	v_ashrrev_i32_e32 v55, 31, v54
	v_lshl_add_u64 v[54:55], v[44:45], 0, v[54:55]
	v_permlane16_swap_b32_e32 v50, v46
	v_permlane16_swap_b32_e32 v51, v47
	v_permlane16_swap_b32_e32 v52, v48
	v_permlane16_swap_b32_e32 v53, v49
	v_permlane32_swap_b32_e32 v50, v46
	v_permlane32_swap_b32_e32 v51, v47
	v_permlane32_swap_b32_e32 v52, v48
	v_permlane32_swap_b32_e32 v53, v49
	global_store_dwordx4 v[54:55], v[50:53], off
	global_store_dwordx4 v[54:55], v[46:49], off offset:64
	s_nop 1
	v_permlane32_swap_b32_e32 v50, v46
	v_permlane32_swap_b32_e32 v51, v47
	v_permlane32_swap_b32_e32 v52, v48
	v_permlane32_swap_b32_e32 v53, v49
	v_permlane16_swap_b32_e32 v50, v46
	v_permlane16_swap_b32_e32 v51, v47
	v_permlane16_swap_b32_e32 v52, v48
	v_permlane16_swap_b32_e32 v53, v49
	global_store_dwordx4 v[16:17], v[10:13], off
	s_waitcnt vmcnt(7)
	s_nop 0
	v_sub_f32_e32 v11, v41, v43
	v_sub_f32_e32 v10, v40, v43
	v_sub_f32_e32 v13, v39, v43
	v_sub_f32_e32 v12, v38, v43
	v_pk_mul_f32 v[12:13], v[42:43], v[12:13] op_sel_hi:[0,1]
	v_pk_mul_f32 v[10:11], v[42:43], v[10:11] op_sel_hi:[0,1]
	s_waitcnt vmcnt(3)
	v_pk_fma_f32 v[10:11], v[32:33], v[10:11], v[36:37]
	v_pk_fma_f32 v[12:13], v[30:31], v[12:13], v[34:35]
	v_pk_mul_f32 v[10:11], v[10:11], s[2:3] op_sel_hi:[1,0]
	v_pk_mul_f32 v[12:13], v[12:13], s[2:3] op_sel_hi:[1,0]
	v_pk_fma_f32 v[8:9], v[8:9], 0.5, v[10:11] op_sel_hi:[1,0,1]
	v_pk_fma_f32 v[6:7], v[6:7], 0.5, v[12:13] op_sel_hi:[1,0,1]
	v_add_f32_e32 v11, v8, v9
	v_add_f32_e32 v10, v6, v7
	v_add_f32_e32 v10, v10, v11
	v_add_f32_e32 v15, v15, v10
	v_mul_f32_e32 v10, v7, v7
	v_mul_f32_e32 v11, v9, v9
	v_fmac_f32_e32 v10, v6, v6
	v_fmac_f32_e32 v11, v8, v8
	v_add_f32_e32 v10, v10, v11
	v_add_f32_e32 v14, v14, v10
	v_sub_f32_e32 v11, v21, v43
	v_sub_f32_e32 v10, v20, v43
	v_sub_f32_e32 v13, v19, v43
	v_sub_f32_e32 v12, v18, v43
	v_pk_mul_f32 v[12:13], v[42:43], v[12:13] op_sel_hi:[0,1]
	v_pk_mul_f32 v[10:11], v[42:43], v[10:11] op_sel_hi:[0,1]
	v_pk_fma_f32 v[10:11], v[24:25], v[10:11], v[28:29]
	v_pk_fma_f32 v[12:13], v[22:23], v[12:13], v[26:27]
	v_pk_mul_f32 v[10:11], v[10:11], s[2:3] op_sel_hi:[1,0]
	v_pk_mul_f32 v[12:13], v[12:13], s[2:3] op_sel_hi:[1,0]
	v_pk_fma_f32 v[4:5], v[4:5], 0.5, v[10:11] op_sel_hi:[1,0,1]
	v_pk_fma_f32 v[2:3], v[2:3], 0.5, v[12:13] op_sel_hi:[1,0,1]
	v_add_f32_e32 v11, v4, v5
	v_add_f32_e32 v10, v2, v3
	v_add_f32_e32 v10, v10, v11
	v_mul_f32_e32 v11, v3, v3
	v_mul_f32_e32 v12, v5, v5
	v_add_f32_e32 v10, v15, v10
	v_fmac_f32_e32 v11, v2, v2
	v_fmac_f32_e32 v12, v4, v4
	s_nop 0
	s_nop 1
	v_bfe_u32 v17, v227, 4, 2
	v_sub_u32_e32 v16, 0, v17
	v_lshlrev_b32_e32 v16, 4, v16
	v_ashrrev_i32_e32 v17, 31, v16
	v_lshl_add_u64 v[16:17], v[44:45], 0, v[16:17]
	v_permlane16_swap_b32_e32 v6, v2
	v_permlane16_swap_b32_e32 v7, v3
	v_permlane16_swap_b32_e32 v8, v4
	v_permlane16_swap_b32_e32 v9, v5
	v_permlane32_swap_b32_e32 v6, v2
	v_permlane32_swap_b32_e32 v7, v3
	v_permlane32_swap_b32_e32 v8, v4
	v_permlane32_swap_b32_e32 v9, v5
	global_store_dwordx4 v[16:17], v[6:9], off offset:512
	global_store_dwordx4 v[16:17], v[2:5], off offset:576
	s_nop 1
	v_permlane32_swap_b32_e32 v6, v2
	v_permlane32_swap_b32_e32 v7, v3
	v_permlane32_swap_b32_e32 v8, v4
	v_permlane32_swap_b32_e32 v9, v5
	v_permlane16_swap_b32_e32 v6, v2
	v_permlane16_swap_b32_e32 v7, v3
	v_permlane16_swap_b32_e32 v8, v4
	v_permlane16_swap_b32_e32 v9, v5
	v_add_f32_e32 v11, v11, v12
	v_cvt_pk_bf16_f32 v6, v6, v7
	v_cvt_pk_bf16_f32 v7, v8, v9
	v_cvt_pk_bf16_f32 v8, v2, v3
	v_lshl_add_u64 v[2:3], v[76:77], 0, v[0:1]
	v_mov_b32_e32 v0, v10
	v_add_f32_e32 v11, v14, v11
	v_cvt_pk_bf16_f32 v9, v4, v5
	v_permlane16_swap_b32_e32 v10, v0
	global_store_dwordx4 v[2:3], v[6:9], off
	v_add_f32_e32 v2, v10, v0
	v_mov_b32_e32 v0, v11
	s_nop 1
	v_permlane16_swap_b32_e32 v11, v0
	v_add_f32_e32 v3, v11, v0
	v_mov_b32_e32 v4, v2
	v_mov_b32_e32 v5, v3
	s_nop 0
	v_permlane32_swap_b32_e32 v2, v4
	v_permlane32_swap_b32_e32 v3, v5
	s_and_saveexec_b64 s[24:25], s[40:41]
	s_cbranch_execz .LBB0_1719
	v_pk_add_f32 v[2:3], v[2:3], v[4:5]
	v_lshlrev_b64 v[4:5], 7, v[74:75]
	v_lshl_add_u64 v[4:5], s[8:9], 0, v[4:5]
	v_lshl_add_u64 v[4:5], s[38:39], 2, v[4:5]
	global_store_dwordx2 v[4:5], v[2:3], off
